# FFT twiddles cached in registers for the whole conv phase; twiddle LDS reads become register moves
# speedup vs baseline: 1.0164x; 1.0164x over previous
; __device__ __forceinline__ void phase_conv(const Params& p, int o, unsigned char* smem, int wave) {
;     ...
;     for (int rd = 0; rd < nrounds; ++rd) {
;         bool samp; int c;
;         if (g256) { samp = ((blockIdx.x + rd) & 1) == 0; c = (rd >> 1) * 256 + blockIdx.x; }
;         else { const int it = blockIdx.x + rd * gridDim.x; if (it >= 1024) break; samp = it < 512; c = it & 511; }
;         const int lsel = samp ? 1 : 0; const int L = samp ? TS : TP;
;         const float* filt = (const float*)(p.ws + (samp ? WS_FILTS : WS_FILTP));
;         const float* hf = filt + (size_t)((o * 2 + 0) * 512 + c) * L; const float* hb = filt + (size_t)((o * 2 + 1) * 512 + c) * L;
;         const float nrm = normsum[lsel * 2048 + (o * 2) * 512 + c] + normsum[lsel * 2048 + (o * 2 + 1) * 512 + c];
;         const float scale = 1.f / (4096.f * nrm);
;         const float skip = p.hy_skip[o * 512 + c];
;         const int zc = c, gc = (o == 0 ? 512 : 1024) + c;
;         const float zw0 = p.hy_short_w[zc], zw1 = p.hy_short_w[1536 + zc], zw2 = p.hy_short_w[3072 + zc], zb = p.hy_short_b[zc];
;         const float gw0 = p.hy_short_w[gc], gw1 = p.hy_short_w[1536 + gc], gw2 = p.hy_short_w[3072 + gc], gb = p.hy_short_b[gc];
;         const bf16_t* grow = uhy + (size_t)gc * NTOK;
;         const bf16_t* zrow = (o == 0) ? uhy + (size_t)zc * NTOK : z1 + (size_t)c * NTOK;
;         bf16_t* orow = outp + (size_t)c * NTOK;
;         const bf16_t* rg = raw + 4 * RAWROW;
;     ...
;         if (!samp) {
;             c2 K[8], dmy[8];
; #pragma unroll
;             for (int r = 0; r < 8; ++r) { K[r] = (c2){subfilt(hf, hb, L, 0, tid + 512 * r), 0.f}; dmy[r] = (c2){0.f, 0.f}; }
.LBB0_213:
	s_cmp_lt_i32 s17, 1
	s_cbranch_scc1 .LBB0_700
	s_and_b64 s[4:5], s[0:1], exec
	s_mov_b32 s3, 0x1fb00000
	v_readlane_b32 s12, v253, 8
	s_cselect_b32 s3, s3, 0x24b00000
	v_readlane_b32 s14, v253, 10
	v_writelane_b32 v254, s22, 20
	v_readlane_b32 s15, v253, 11
	s_add_u32 s95, s14, s3
	v_writelane_b32 v254, s23, 21
	s_addc_u32 s3, s15, 0
	s_lshl_b32 s27, s41, 10
	v_writelane_b32 v254, s3, 22
	s_or_b32 s3, s27, 0x200
	v_writelane_b32 v254, s3, 23
	s_and_b64 s[0:1], s[0:1], exec
	v_readlane_b32 s0, v254, 0
	s_cselect_b32 s0, s97, s0
	v_lshrrev_b32_e32 v0, 3, v113
	v_writelane_b32 v254, s0, 24
	v_readlane_b32 s0, v253, 63
	v_add_u32_e32 v0, v0, v113
	s_cselect_b32 s0, s96, s0
	v_lshl_add_u32 v115, v0, 3, 0
	v_and_b32_e32 v0, 63, v3
	s_movk_i32 s16, 0xfe00
	v_writelane_b32 v254, s0, 25
	v_and_or_b32 v1, v2, s16, v0
	v_readlane_b32 s0, v254, 7
	v_lshrrev_b32_e32 v4, 3, v1
	v_add_u32_e32 v1, v4, v1
	v_add_u32_e32 v114, s0, v2
	v_readlane_b32 s0, v254, 8
	v_lshl_add_u32 v117, v1, 3, 0
	v_and_b32_e32 v1, 0xffffffc0, v2
	v_lshl_add_u32 v118, v0, 3, s0
	v_and_b32_e32 v0, 7, v3
	v_or_b32_e32 v3, v1, v0
	v_lshrrev_b32_e32 v1, 3, v1
	v_add_u32_e32 v1, v3, v1
	v_lshl_add_u32 v119, v1, 3, 0
	v_ashrrev_i32_e32 v1, 6, v113
	v_and_b32_e32 v1, 0x7fffffc, v1
	s_movk_i32 s3, 0x1020
	v_mul_lo_u32 v1, v1, s3
	v_readlane_b32 s26, v254, 10
	s_movk_i32 s40, 0x800
	v_cmp_gt_i32_e32 vcc, s40, v113
	v_add_u32_e32 v122, s26, v1
	v_lshlrev_b32_e32 v1, 4, v113
	v_and_b32_e32 v123, 0xff0, v1
	v_add_u32_e32 v1, 0xfffff000, v113
	v_readlane_b32 s13, v253, 9
	v_cndmask_b32_e32 v125, v1, v113, vcc
	v_cmp_gt_i32_e64 s[12:13], 0, v125
	v_readlane_b32 s0, v254, 9
	v_sub_u32_e32 v126, 0, v125
	v_writelane_b32 v254, s12, 26
	s_movk_i32 s3, 0x600
	v_add_u32_e32 v127, 0x200, v113
	v_writelane_b32 v254, s13, 27
	v_cmp_gt_u32_e64 s[12:13], s40, v126
	v_cmp_gt_i32_e32 vcc, s3, v113
	v_add_u32_e32 v1, 0xfffff200, v113
	v_writelane_b32 v254, s12, 28
	v_cndmask_b32_e32 v128, v1, v127, vcc
	v_cmp_gt_i32_e64 s[22:23], 0, v128
	v_writelane_b32 v254, s13, 29
	v_cmp_gt_u32_e64 s[12:13], s40, v125
	v_sub_u32_e32 v129, 0, v128
	s_movk_i32 s7, 0x400
	v_writelane_b32 v254, s12, 30
	v_add_u32_e32 v130, 0x400, v113
	v_cmp_gt_i32_e32 vcc, s7, v113
	v_writelane_b32 v254, s13, 31
	v_writelane_b32 v254, s22, 32
	v_add_u32_e32 v1, 0xfffff400, v113
	v_cndmask_b32_e32 v131, v1, v130, vcc
	v_writelane_b32 v254, s23, 33
	v_cmp_gt_u32_e64 s[22:23], s40, v129
	v_cmp_gt_i32_e64 s[34:35], 0, v131
	v_sub_u32_e32 v132, 0, v131
	v_writelane_b32 v254, s22, 34
	s_movk_i32 s3, 0x200
	v_add_u32_e32 v133, 0x600, v113
	v_writelane_b32 v254, s23, 35
	v_cmp_gt_u32_e64 s[22:23], s40, v128
	v_cmp_gt_i32_e32 vcc, s3, v113
	v_add_u32_e32 v1, 0xfffff600, v113
	v_writelane_b32 v254, s22, 36
	v_cndmask_b32_e32 v134, v1, v133, vcc
	v_cmp_gt_i32_e64 s[38:39], 0, v134
	v_writelane_b32 v254, s23, 37
	v_writelane_b32 v254, s34, 38
	v_sub_u32_e32 v135, 0, v134
	v_cmp_gt_i32_e32 vcc, 0, v113
	v_writelane_b32 v254, s35, 39
	v_cmp_gt_u32_e64 s[34:35], s40, v132
	v_cndmask_b32_e32 v1, v110, v111, vcc
	v_add_u32_e32 v136, v1, v113
	v_writelane_b32 v254, s34, 40
	v_sub_u32_e32 v137, 0, v136
	v_lshl_add_u32 v120, v0, 3, s0
	v_writelane_b32 v254, s35, 41
	v_cmp_gt_u32_e64 s[34:35], s40, v131
	s_movk_i32 s0, 0x48
	v_mul_lo_u32 v0, v113, s0
	v_writelane_b32 v254, s34, 42
	v_add_u32_e32 v121, 0, v0
	v_and_b32_e32 v0, 0x7f8, v2
	v_writelane_b32 v254, s35, 43
	v_writelane_b32 v254, s38, 44
	v_add_u32_e32 v1, 0xa00, v113
	v_cmp_gt_i32_e32 vcc, s16, v113
	v_writelane_b32 v254, s39, 45
	v_cmp_gt_u32_e64 s[38:39], s40, v135
	v_add_u32_e32 v2, 0xfffffa00, v113
	v_cndmask_b32_e32 v138, v2, v1, vcc
	v_writelane_b32 v254, s38, 46
	v_sub_u32_e32 v139, 0, v138
	s_movk_i32 s3, 0xfc00
	v_writelane_b32 v254, s39, 47
	v_cmp_gt_u32_e64 s[38:39], s40, v134
	v_cmp_eq_u32_e64 s[54:55], s40, v1
	v_cmp_ne_u32_e64 s[56:57], s40, v1
	v_writelane_b32 v254, s38, 48
	v_add_u32_e32 v1, 0xc00, v113
	v_cmp_gt_i32_e32 vcc, s3, v113
	v_writelane_b32 v254, s39, 49
	v_cmp_gt_i32_e64 s[38:39], 0, v136
	v_add_u32_e32 v2, 0xfffffc00, v113
	v_cndmask_b32_e32 v140, v2, v1, vcc
	v_writelane_b32 v254, s38, 50
	v_sub_u32_e32 v141, 0, v140
	s_movk_i32 s3, 0xfa00
	v_writelane_b32 v254, s39, 51
	v_cmp_gt_u32_e64 s[38:39], s40, v137
	v_cmp_eq_u32_e64 s[64:65], s40, v1
	v_cmp_ne_u32_e64 s[66:67], s40, v1
	v_writelane_b32 v254, s38, 52
	v_add_u32_e32 v1, 0xe00, v113
	v_cmp_gt_i32_e32 vcc, s3, v113
	v_writelane_b32 v254, s39, 53
	v_cmp_gt_u32_e64 s[38:39], s40, v136
; __device__ __forceinline__ void phase_conv(const Params& p, int o, unsigned char* smem, int wave) {
;     ...
;     for (int rd = 0; rd < nrounds; ++rd) {
;         bool samp; int c;
;         if (g256) { samp = ((blockIdx.x + rd) & 1) == 0; c = (rd >> 1) * 256 + blockIdx.x; }
;         else { const int it = blockIdx.x + rd * gridDim.x; if (it >= 1024) break; samp = it < 512; c = it & 511; }
;         const int lsel = samp ? 1 : 0; const int L = samp ? TS : TP;
;         const float* filt = (const float*)(p.ws + (samp ? WS_FILTS : WS_FILTP));
;         const float* hf = filt + (size_t)((o * 2 + 0) * 512 + c) * L; const float* hb = filt + (size_t)((o * 2 + 1) * 512 + c) * L;
;         const float nrm = normsum[lsel * 2048 + (o * 2) * 512 + c] + normsum[lsel * 2048 + (o * 2 + 1) * 512 + c];
;         const float scale = 1.f / (4096.f * nrm);
;         const float skip = p.hy_skip[o * 512 + c];
;         const int zc = c, gc = (o == 0 ? 512 : 1024) + c;
;         const float zw0 = p.hy_short_w[zc], zw1 = p.hy_short_w[1536 + zc], zw2 = p.hy_short_w[3072 + zc], zb = p.hy_short_b[zc];
;         const float gw0 = p.hy_short_w[gc], gw1 = p.hy_short_w[1536 + gc], gw2 = p.hy_short_w[3072 + gc], gb = p.hy_short_b[gc];
;         const bf16_t* grow = uhy + (size_t)gc * NTOK;
;         const bf16_t* zrow = (o == 0) ? uhy + (size_t)zc * NTOK : z1 + (size_t)c * NTOK;
;         bf16_t* orow = outp + (size_t)c * NTOK;
;         const bf16_t* rg = raw + 4 * RAWROW;
;     ...
;         if (!samp) {
;             c2 K[8], dmy[8];
; #pragma unroll
;             for (int r = 0; r < 8; ++r) { K[r] = (c2){subfilt(hf, hb, L, 0, tid + 512 * r), 0.f}; dmy[r] = (c2){0.f, 0.f}; }
	v_add_u32_e32 v2, 0xfffffe00, v113
	v_cndmask_b32_e32 v142, v2, v1, vcc
	v_writelane_b32 v254, s38, 54
	v_cmp_gt_i32_e64 s[50:51], 0, v142
	v_sub_u32_e32 v143, 0, v142
	v_writelane_b32 v254, s39, 55
	v_cmp_gt_i32_e64 s[38:39], 0, v138
	s_cselect_b32 s58, 0x200, s7
	v_cmp_eq_u32_e64 s[74:75], s40, v1
	v_writelane_b32 v254, s38, 56
	v_lshlrev_b32_e32 v2, 1, v127
	v_lshlrev_b32_e32 v3, 1, v130
	v_writelane_b32 v254, s39, 57
	v_cmp_gt_u32_e64 s[38:39], s40, v139
	v_lshlrev_b32_e32 v4, 1, v133
	s_movk_i32 s0, 0x100
	v_writelane_b32 v254, s38, 58
	s_mov_b32 s6, 0
	v_add_u32_e32 v116, 0x9000, v115
	v_writelane_b32 v254, s39, 59
	v_cmp_gt_u32_e64 s[38:39], s40, v138
	v_cmp_gt_u32_e64 s[0:1], s0, v113
	v_lshlrev_b32_sdwa v58, v109, v113 dst_sel:DWORD dst_unused:UNUSED_PAD src0_sel:DWORD src1_sel:BYTE_0
	v_writelane_b32 v254, s38, 60
	v_cmp_eq_u32_sdwa s[42:43], v113, s94 src0_sel:BYTE_0 src1_sel:DWORD
	v_add_u32_e32 v124, 0x1000, v113
	v_writelane_b32 v254, s39, 61
	v_cmp_gt_i32_e64 s[38:39], 0, v140
	v_cmp_eq_u32_e64 s[48:49], s40, v113
	v_cmp_ne_u32_e64 s[4:5], s40, v113
	v_writelane_b32 v254, s38, 62
	v_cmp_eq_u32_e64 s[12:13], s40, v127
	v_cmp_ne_u32_e64 s[14:15], s40, v127
	v_writelane_b32 v254, s39, 63
	v_cmp_gt_u32_e64 s[38:39], s40, v141
	v_readlane_b32 s3, v254, 11
	v_readlane_b32 s7, v254, 12
	v_writelane_b32 v252, s38, 0
	v_add_u32_e32 v149, s3, v2
	v_add_u32_e32 v150, s7, v2
	v_writelane_b32 v252, s39, 1
	v_cmp_gt_u32_e64 s[38:39], s40, v140
	v_add_u32_e32 v153, s3, v3
	v_add_u32_e32 v154, s7, v3
	v_writelane_b32 v252, s38, 2
	v_add_u32_e32 v157, s3, v4
	v_add_u32_e32 v158, s7, v4
	v_writelane_b32 v252, s39, 3
	v_writelane_b32 v252, s50, 4
	v_cmp_ne_u32_e64 s[38:39], s40, v1
	v_lshlrev_b32_e32 v1, 1, v113
	v_writelane_b32 v252, s51, 5
	v_cmp_gt_u32_e64 s[50:51], s40, v143
	v_add_u32_e32 v145, s3, v1
	v_add_u32_e32 v146, s7, v1
	v_writelane_b32 v252, s50, 6
	v_readlane_b32 s3, v254, 14
	v_readlane_b32 s7, v254, 15
	v_writelane_b32 v252, s51, 7
	v_cmp_gt_u32_e64 s[50:51], s40, v142
	v_readlane_b32 s16, v254, 13
	v_add_u32_e32 v160, s3, v1
	v_writelane_b32 v252, s50, 8
	v_add_u32_e32 v161, s7, v1
	v_add_u32_e32 v162, s3, v2
	v_add_u32_e32 v163, s7, v2
	v_add_u32_e32 v164, s3, v3
	v_add_u32_e32 v165, s7, v3
	v_add_u32_e32 v166, s3, v4
	v_add_u32_e32 v167, s7, v4
	v_readlane_b32 s3, v254, 16
	v_readlane_b32 s7, v254, 17
	v_cmp_eq_u32_e64 s[22:23], s40, v130
	v_cmp_ne_u32_e64 s[24:25], s40, v130
	v_cmp_eq_u32_e64 s[34:35], s40, v133
	v_cmp_ne_u32_e64 s[36:37], s40, v133
	v_cmp_eq_u32_e64 s[44:45], 0, v113
	v_cmp_ne_u32_e64 s[46:47], 0, v113
	v_writelane_b32 v252, s51, 9
	v_add_u32_e32 v144, s26, v1
	v_add_u32_e32 v147, s16, v1
	v_add_u32_e32 v148, s26, v2
	v_add_u32_e32 v151, s16, v2
	v_add_u32_e32 v152, s26, v3
	v_add_u32_e32 v155, s16, v3
	v_add_u32_e32 v156, s26, v4
	v_add_u32_e32 v159, s16, v4
	v_add_u32_e32 v168, s3, v1
	v_add_u32_e32 v169, s7, v1
	v_add_u32_e32 v170, s3, v2
	v_add_u32_e32 v171, s7, v2
	v_add_u32_e32 v172, s3, v3
	v_add_u32_e32 v173, s7, v3
	v_add_u32_e32 v174, s3, v4
	v_add_u32_e32 v175, s7, v4
	v_add_u32_e32 v176, 0x7200, v113
	v_add_u32_e32 v177, 0x7400, v113
	v_add_u32_e32 v178, 0x8400, v113
	v_add_u32_e32 v179, 0x7600, v113
	v_add_u32_e32 v180, 0x8600, v113
	v_add_u32_e32 v181, 0x7c00, v113
	v_add_u32_e32 v182, 0x7e00, v113
	v_add_u32_e32 v183, 0x8e00, v113
	s_lshl_b32 s26, s41, 9
	v_lshlrev_b32_sdwa v60, v112, v113 dst_sel:DWORD dst_unused:UNUSED_PAD src0_sel:DWORD src1_sel:BYTE_0
	v_mov_b32_e32 v61, v57
	s_lshl_b32 s59, s58, 2
	v_lshlrev_b32_e32 v62, 1, v0
	v_writelane_b32 v252, s41, 10
	ds_read_b64 v[210:211], v114 offset:4096
	ds_read_b64 v[212:213], v114 offset:8192
	ds_read_b64 v[214:215], v114 offset:12288
	ds_read_b64 v[216:217], v114 offset:16384
	ds_read_b64 v[218:219], v114 offset:20480
	ds_read_b64 v[220:221], v114 offset:24576
	ds_read_b64 v[222:223], v114 offset:28672
	ds_read_b64 v[224:225], v118 offset:512
	ds_read_b64 v[226:227], v118 offset:1024
	ds_read_b64 v[228:229], v118 offset:1536
	ds_read_b64 v[230:231], v118 offset:2048
	ds_read_b64 v[232:233], v118 offset:2560
	ds_read_b64 v[234:235], v118 offset:3072
	ds_read_b64 v[236:237], v118 offset:3584
	ds_read_b64 v[238:239], v120 offset:64
	ds_read_b64 v[240:241], v120 offset:128
	ds_read_b64 v[242:243], v120 offset:192
	ds_read_b64 v[244:245], v120 offset:256
	ds_read_b64 v[246:247], v120 offset:320
	ds_read_b64 v[248:249], v120 offset:384
	ds_read_b64 v[250:251], v120 offset:448
	s_waitcnt lgkmcnt(0)
	s_branch .LBB0_217

; __device__ __forceinline__ c2 cmul(c2 a, c2 b) { return (c2){a.x * b.x - a.y * b.y, a.x * b.y + a.y * b.x}; }
; __device__ __forceinline__ void fwd_s0(c2 (&x)[8], c2* buf, const c2* tws, int tid) {
;     dft8(x);
; #pragma unroll
;     for (int q = 1; q < 8; ++q) x[q] = cmul(x[q], tws[(q - 1) * 512 + tid]);
;     { c2* bp_ = buf + LP(tid);
; #pragma unroll
;     for (int q = 0; q < 8; ++q) bp_[576 * q] = x[q]; }
; }
; __device__ __forceinline__ void phase_conv(const Params& p, int o, unsigned char* smem, int wave) {
;     ...
;             c2 K[8], dmy[8];
; #pragma unroll
;             for (int r = 0; r < 8; ++r) { K[r] = (c2){subfilt(hf, hb, L, 0, tid + 512 * r), 0.f}; dmy[r] = (c2){0.f, 0.f}; }
;             __syncthreads();
;             fft_fwd_regs2(K, dmy, buf0, buf1, tws, tid);
.LBB0_287:
	s_or_b64 exec, exec, s[72:73]
	s_waitcnt vmcnt(0)
	v_pk_add_f32 v[8:9], v[0:1], v[4:5]
	v_sub_f32_e32 v56, v0, v4
	v_sub_f32_e32 v4, v1, v5
	v_pk_add_f32 v[0:1], v[2:3], v[6:7]
	v_sub_f32_e32 v7, v3, v7
	s_barrier
	v_sub_f32_e32 v5, v2, v6
	v_sub_f32_e32 v6, 0, v7
	v_add_f32_e32 v7, 0, v7
	v_pk_add_f32 v[10:11], v[8:9], v[0:1] neg_lo:[0,1] neg_hi:[0,1]
	v_mov_b64_e32 v[18:19], v[210:211]
	v_add_f32_e32 v2, 0, v4
	v_sub_f32_e32 v3, 0, v4
	v_pk_mul_f32 v[6:7], v[6:7], s[20:21]
	v_pk_add_f32 v[0:1], v[8:9], v[0:1]
	v_pk_add_f32 v[8:9], v[10:11], 0 neg_lo:[1,1] neg_hi:[1,1]
	v_xor_b32_e32 v5, 0x80000000, v5
	v_mov_b32_e32 v4, v57
	v_mov_b32_e32 v12, v10
	v_mov_b32_e32 v13, v57
	v_mov_b32_e32 v8, v57
	v_pk_fma_f32 v[16:17], v[2:3], s[20:21], v[6:7] op_sel_hi:[1,0,1]
	v_pk_fma_f32 v[2:3], v[2:3], s[20:21], v[6:7] op_sel_hi:[1,0,1] neg_lo:[0,0,1] neg_hi:[0,0,1]
	v_pk_add_f32 v[14:15], v[12:13], v[8:9]
	v_pk_add_f32 v[8:9], v[12:13], v[8:9] neg_lo:[0,1] neg_hi:[0,1]
	v_pk_add_f32 v[12:13], v[56:57], v[4:5]
	v_pk_add_f32 v[4:5], v[56:57], v[4:5] neg_lo:[0,1] neg_hi:[0,1]
	v_xor_b32_e32 v7, 0x80000000, v2
	v_mov_b32_e32 v6, v3
	v_pk_add_f32 v[2:3], v[12:13], v[16:17]
	v_pk_add_f32 v[12:13], v[12:13], v[16:17] neg_lo:[0,1] neg_hi:[0,1]
	v_pk_add_f32 v[16:17], v[4:5], v[6:7]
	v_pk_add_f32 v[4:5], v[4:5], v[6:7] neg_lo:[0,1] neg_hi:[0,1]
	v_mov_b64_e32 v[6:7], v[212:213]
	v_mov_b64_e32 v[20:21], v[214:215]
	v_mov_b64_e32 v[22:23], v[216:217]
	s_waitcnt lgkmcnt(0)
	v_pk_mul_f32 v[24:25], v[18:19], v[2:3] op_sel:[1,1] op_sel_hi:[0,1]
	v_pk_fma_f32 v[26:27], v[18:19], v[2:3], v[24:25] neg_lo:[0,0,1] neg_hi:[0,0,1]
	v_pk_fma_f32 v[2:3], v[18:19], v[2:3], v[24:25] op_sel_hi:[1,0,1]
	v_pk_add_f32 v[10:11], v[0:1], v[0:1] op_sel:[0,1] op_sel_hi:[1,0]
	v_mov_b32_e32 v27, v3
	s_waitcnt lgkmcnt(0)
	v_pk_mul_f32 v[2:3], v[14:15], v[6:7] op_sel:[1,1] op_sel_hi:[1,0]
	v_pk_add_f32 v[0:1], v[0:1], v[0:1] op_sel:[0,1] op_sel_hi:[0,1] neg_lo:[0,1] neg_hi:[0,1]
	v_pk_fma_f32 v[18:19], v[14:15], v[6:7], v[2:3] neg_lo:[0,0,1] neg_hi:[0,0,1]
	v_pk_fma_f32 v[2:3], v[14:15], v[6:7], v[2:3] op_sel_hi:[0,1,1]
	v_mov_b32_e32 v19, v3
	s_waitcnt lgkmcnt(0)
	v_pk_mul_f32 v[2:3], v[20:21], v[16:17] op_sel:[1,1] op_sel_hi:[0,1]
	v_pk_fma_f32 v[6:7], v[20:21], v[16:17], v[2:3] neg_lo:[0,0,1] neg_hi:[0,0,1]
	v_pk_fma_f32 v[2:3], v[20:21], v[16:17], v[2:3] op_sel_hi:[1,0,1]
	v_mov_b64_e32 v[16:17], v[218:219]
	v_mov_b32_e32 v7, v3
	s_waitcnt lgkmcnt(0)
	v_pk_mul_f32 v[2:3], v[22:23], 0 op_sel_hi:[1,0]
	v_mov_b32_e32 v11, v57
	v_pk_fma_f32 v[14:15], v[0:1], v[22:23], v[2:3] op_sel:[0,0,1] op_sel_hi:[1,1,0] neg_lo:[0,0,1] neg_hi:[0,0,1]
	v_pk_fma_f32 v[0:1], v[0:1], v[22:23], v[2:3] op_sel:[0,0,1] op_sel_hi:[1,1,0]
	s_waitcnt lgkmcnt(0)
	v_pk_mul_f32 v[20:21], v[12:13], v[16:17] op_sel:[1,1] op_sel_hi:[1,0]
	v_mov_b32_e32 v15, v1
	v_mov_b64_e32 v[0:1], v[220:221]
	v_mov_b64_e32 v[2:3], v[222:223]
	v_pk_fma_f32 v[22:23], v[12:13], v[16:17], v[20:21] neg_lo:[0,0,1] neg_hi:[0,0,1]
	v_pk_fma_f32 v[12:13], v[12:13], v[16:17], v[20:21] op_sel_hi:[0,1,1]
	v_mov_b32_e32 v23, v13
	s_waitcnt lgkmcnt(0)
	v_pk_mul_f32 v[12:13], v[8:9], v[0:1] op_sel:[1,1] op_sel_hi:[1,0]
	v_mov_b32_e32 v56, v57
	v_pk_fma_f32 v[16:17], v[8:9], v[0:1], v[12:13] neg_lo:[0,0,1] neg_hi:[0,0,1]
	v_pk_fma_f32 v[0:1], v[8:9], v[0:1], v[12:13] op_sel_hi:[0,1,1]
	v_mov_b32_e32 v17, v1
	s_waitcnt lgkmcnt(0)
	v_pk_mul_f32 v[0:1], v[4:5], v[2:3] op_sel:[1,1] op_sel_hi:[1,0]
	v_add_u32_e32 v191, 0x9000, v117
	v_pk_fma_f32 v[8:9], v[4:5], v[2:3], v[0:1] neg_lo:[0,0,1] neg_hi:[0,0,1]
	v_pk_fma_f32 v[0:1], v[4:5], v[2:3], v[0:1] op_sel_hi:[0,1,1]
	v_mov_b32_e32 v9, v1
	ds_write2st64_b64 v115, v[10:11], v[26:27] offset1:9
	ds_write2st64_b64 v115, v[18:19], v[6:7] offset0:18 offset1:27
	ds_write2st64_b64 v115, v[14:15], v[22:23] offset0:36 offset1:45
	ds_write2st64_b64 v115, v[16:17], v[8:9] offset0:54 offset1:63
	v_mov_b64_e32 v[0:1], v[210:211]
	v_mov_b64_e32 v[2:3], v[212:213]
	v_mov_b64_e32 v[4:5], v[214:215]
	v_mov_b64_e32 v[6:7], v[216:217]
	v_mov_b64_e32 v[12:13], v[218:219]
	s_waitcnt lgkmcnt(0)
	v_pk_mul_f32 v[8:9], v[0:1], 0 op_sel_hi:[1,0]
	v_add_u32_e32 v192, 0x9800, v117
	v_pk_fma_f32 v[10:11], v[0:1], 0, v[8:9] op_sel:[0,0,1] op_sel_hi:[1,0,0] neg_lo:[0,0,1] neg_hi:[0,0,1]
	v_pk_fma_f32 v[0:1], v[0:1], 0, v[8:9] op_sel_hi:[1,0,0]
	s_waitcnt lgkmcnt(0)
	v_pk_mul_f32 v[14:15], v[12:13], 0 op_sel_hi:[1,0]
	v_mov_b32_e32 v11, v1
	v_pk_mul_f32 v[0:1], v[2:3], 0 op_sel_hi:[1,0]
	v_pk_fma_f32 v[16:17], v[12:13], 0, v[14:15] op_sel:[0,0,1] op_sel_hi:[1,0,0] neg_lo:[0,0,1] neg_hi:[0,0,1]
	v_pk_fma_f32 v[8:9], v[2:3], 0, v[0:1] op_sel:[0,0,1] op_sel_hi:[1,0,0] neg_lo:[0,0,1] neg_hi:[0,0,1]
	v_pk_fma_f32 v[0:1], v[2:3], 0, v[0:1] op_sel_hi:[1,0,0]
	v_pk_fma_f32 v[12:13], v[12:13], 0, v[14:15] op_sel_hi:[1,0,0]
	v_mov_b32_e32 v9, v1
	v_pk_mul_f32 v[0:1], v[4:5], 0 op_sel_hi:[1,0]
	v_mov_b32_e32 v17, v13
	v_pk_fma_f32 v[2:3], v[4:5], 0, v[0:1] op_sel:[0,0,1] op_sel_hi:[1,0,0] neg_lo:[0,0,1] neg_hi:[0,0,1]
	v_pk_fma_f32 v[0:1], v[4:5], 0, v[0:1] op_sel_hi:[1,0,0]
	v_add_u32_e32 v193, 0x9000, v119
	v_mov_b32_e32 v3, v1
	v_pk_mul_f32 v[0:1], v[6:7], 0 op_sel_hi:[1,0]
	v_mov_b32_e32 v63, v57
	v_pk_fma_f32 v[4:5], v[6:7], 0, v[0:1] op_sel:[0,0,1] op_sel_hi:[1,0,0] neg_lo:[0,0,1] neg_hi:[0,0,1]
	v_pk_fma_f32 v[0:1], v[6:7], 0, v[0:1] op_sel_hi:[1,0,0]
	s_movk_i32 s3, 0x2000
	v_mov_b32_e32 v5, v1
	v_mov_b64_e32 v[0:1], v[220:221]
	v_mov_b64_e32 v[6:7], v[222:223]
	s_mov_b32 s92, 0
	v_mov_b32_e32 v67, v66
	s_waitcnt lgkmcnt(0)
	v_pk_mul_f32 v[12:13], v[0:1], 0 op_sel_hi:[1,0]
	s_nop 0
	v_pk_fma_f32 v[14:15], v[0:1], 0, v[12:13] op_sel:[0,0,1] op_sel_hi:[1,0,0] neg_lo:[0,0,1] neg_hi:[0,0,1]
	v_pk_fma_f32 v[0:1], v[0:1], 0, v[12:13] op_sel_hi:[1,0,0]
	s_nop 0
	v_mov_b32_e32 v15, v1
	s_waitcnt lgkmcnt(0)
	v_pk_mul_f32 v[0:1], v[6:7], 0 op_sel_hi:[1,0]
	s_nop 0
	v_pk_fma_f32 v[12:13], v[6:7], 0, v[0:1] op_sel:[0,0,1] op_sel_hi:[1,0,0] neg_lo:[0,0,1] neg_hi:[0,0,1]
	v_pk_fma_f32 v[0:1], v[6:7], 0, v[0:1] op_sel_hi:[1,0,0]
	s_nop 0
	v_mov_b32_e32 v13, v1
	ds_write2st64_b64 v115, v[56:57], v[10:11] offset0:72 offset1:81
	ds_write2st64_b64 v115, v[8:9], v[2:3] offset0:90 offset1:99
	ds_write2st64_b64 v115, v[4:5], v[16:17] offset0:108 offset1:117
	ds_write_b64 v115, v[14:15] offset:64512
	ds_write_b64 v116, v[12:13] offset:32256
	s_waitcnt lgkmcnt(0)
	s_barrier
; __device__ __forceinline__ c2 cmul(c2 a, c2 b) { return (c2){a.x * b.x - a.y * b.y, a.x * b.y + a.y * b.x}; }
; template <int S> __device__ __forceinline__ void fwd_mid(c2* buf, const c2* tws, int tid) {
;     constexpr int lq = 9 - 3 * S, Q = 1 << lq; const c2* T = tws + (S == 1 ? 3584 : 4032);
;     const int k = tid & (Q - 1), base = ((tid >> lq) << (lq + 3)) + k;
;     c2 x[8];
;     c2* bp_ = buf + LP(base); constexpr int QP = Q + Q / 8;
; #pragma unroll
;     for (int r = 0; r < 8; ++r) x[r] = bp_[r * QP];
;     dft8(x);
; #pragma unroll
;     for (int q = 1; q < 8; ++q) x[q] = cmul(x[q], T[(q - 1) * Q + k]);
; #pragma unroll
;     for (int q = 0; q < 8; ++q) bp_[q * QP] = x[q];
; }
	ds_read2_b64 v[0:3], v117 offset1:72
	v_add_u32_e32 v56, 0x800, v117
	ds_read2_b64 v[4:7], v56 offset0:32 offset1:104
	ds_read2_b64 v[8:11], v117 offset0:144 offset1:216
	ds_read2_b64 v[12:15], v56 offset0:176 offset1:248
	v_mov_b64_e32 v[18:19], v[224:225]
	s_waitcnt lgkmcnt(0)
	v_pk_add_f32 v[16:17], v[0:1], v[4:5]
	v_pk_add_f32 v[0:1], v[0:1], v[4:5] neg_lo:[0,1] neg_hi:[0,1]
	v_pk_add_f32 v[4:5], v[2:3], v[6:7]
	v_pk_add_f32 v[2:3], v[2:3], v[6:7] neg_lo:[0,1] neg_hi:[0,1]
	s_waitcnt lgkmcnt(0)
	v_pk_add_f32 v[6:7], v[8:9], v[12:13]
	v_pk_add_f32 v[8:9], v[8:9], v[12:13] neg_lo:[0,1] neg_hi:[0,1]
	v_pk_add_f32 v[12:13], v[10:11], v[14:15]
	v_pk_add_f32 v[10:11], v[10:11], v[14:15] neg_lo:[0,1] neg_hi:[0,1]
	v_pk_add_f32 v[14:15], v[2:3], v[2:3] op_sel:[1,0]
	v_pk_add_f32 v[2:3], v[2:3], v[2:3] op_sel_hi:[1,0] neg_lo:[0,1] neg_hi:[0,1]
	s_nop 0
	v_mov_b32_e32 v15, v3
	v_xor_b32_e32 v3, 0x80000000, v8
	v_mov_b32_e32 v2, v9
	v_pk_add_f32 v[8:9], v[10:11], v[10:11] op_sel:[1,0] neg_lo:[0,1] neg_hi:[0,1]
	v_pk_add_f32 v[10:11], v[10:11], v[10:11] op_sel_hi:[1,0]
	s_nop 0
	v_mov_b32_e32 v9, v11
	v_pk_add_f32 v[10:11], v[16:17], v[6:7]
	v_pk_add_f32 v[6:7], v[16:17], v[6:7] neg_lo:[0,1] neg_hi:[0,1]
	v_pk_add_f32 v[16:17], v[4:5], v[12:13]
	v_pk_add_f32 v[4:5], v[4:5], v[12:13] neg_lo:[0,1] neg_hi:[0,1]
	v_pk_mul_f32 v[8:9], v[8:9], s[20:21]
	v_xor_b32_e32 v13, 0x80000000, v4
	v_mov_b32_e32 v12, v5
	v_pk_add_f32 v[4:5], v[10:11], v[16:17]
	v_pk_add_f32 v[10:11], v[10:11], v[16:17] neg_lo:[0,1] neg_hi:[0,1]
	v_pk_add_f32 v[16:17], v[6:7], v[12:13]
	v_pk_add_f32 v[6:7], v[6:7], v[12:13] neg_lo:[0,1] neg_hi:[0,1]
	v_pk_add_f32 v[12:13], v[0:1], v[2:3]
	v_pk_add_f32 v[0:1], v[0:1], v[2:3] neg_lo:[0,1] neg_hi:[0,1]
	v_pk_fma_f32 v[2:3], v[14:15], s[20:21], v[8:9] op_sel_hi:[1,0,1]
	v_pk_fma_f32 v[8:9], v[14:15], s[20:21], v[8:9] op_sel_hi:[1,0,1] neg_lo:[0,0,1] neg_hi:[0,0,1]
	s_nop 0
	v_xor_b32_e32 v15, 0x80000000, v8
	v_mov_b32_e32 v14, v9
	v_pk_add_f32 v[8:9], v[12:13], v[2:3]
	v_pk_add_f32 v[2:3], v[12:13], v[2:3] neg_lo:[0,1] neg_hi:[0,1]
	v_pk_add_f32 v[12:13], v[0:1], v[14:15]
	v_pk_add_f32 v[0:1], v[0:1], v[14:15] neg_lo:[0,1] neg_hi:[0,1]
	v_mov_b64_e32 v[14:15], v[226:227]
	v_mov_b64_e32 v[20:21], v[228:229]
	v_mov_b64_e32 v[22:23], v[230:231]
	s_waitcnt lgkmcnt(0)
	v_pk_mul_f32 v[24:25], v[18:19], v[8:9] op_sel:[1,1] op_sel_hi:[0,1]
	v_pk_fma_f32 v[26:27], v[18:19], v[8:9], v[24:25] neg_lo:[0,0,1] neg_hi:[0,0,1]
	v_pk_fma_f32 v[8:9], v[18:19], v[8:9], v[24:25] op_sel_hi:[1,0,1]
	s_nop 0
	v_mov_b32_e32 v27, v9
	s_waitcnt lgkmcnt(0)
	v_pk_mul_f32 v[8:9], v[14:15], v[16:17] op_sel:[1,1] op_sel_hi:[0,1]
	v_pk_fma_f32 v[18:19], v[14:15], v[16:17], v[8:9] neg_lo:[0,0,1] neg_hi:[0,0,1]
	v_pk_fma_f32 v[8:9], v[14:15], v[16:17], v[8:9] op_sel_hi:[1,0,1]
	v_mov_b64_e32 v[16:17], v[232:233]
	v_mov_b32_e32 v19, v9
	s_waitcnt lgkmcnt(0)
	v_pk_mul_f32 v[8:9], v[20:21], v[12:13] op_sel:[1,1] op_sel_hi:[0,1]
	v_pk_fma_f32 v[14:15], v[20:21], v[12:13], v[8:9] neg_lo:[0,0,1] neg_hi:[0,0,1]
	v_pk_fma_f32 v[8:9], v[20:21], v[12:13], v[8:9] op_sel_hi:[1,0,1]
	s_waitcnt lgkmcnt(0)
	v_pk_mul_f32 v[20:21], v[16:17], v[2:3] op_sel:[1,1] op_sel_hi:[0,1]
	v_mov_b32_e32 v15, v9
	v_pk_mul_f32 v[8:9], v[10:11], v[22:23] op_sel:[1,1] op_sel_hi:[1,0]
	s_nop 0
	v_pk_fma_f32 v[12:13], v[10:11], v[22:23], v[8:9] neg_lo:[0,0,1] neg_hi:[0,0,1]
	v_pk_fma_f32 v[8:9], v[10:11], v[22:23], v[8:9] op_sel_hi:[0,1,1]
	v_mov_b32_e32 v13, v9
	v_mov_b64_e32 v[8:9], v[234:235]
	v_mov_b64_e32 v[10:11], v[236:237]
	v_pk_fma_f32 v[22:23], v[16:17], v[2:3], v[20:21] neg_lo:[0,0,1] neg_hi:[0,0,1]
	v_pk_fma_f32 v[2:3], v[16:17], v[2:3], v[20:21] op_sel_hi:[1,0,1]
	ds_write2_b64 v117, v[4:5], v[26:27] offset1:72
	ds_write2_b64 v117, v[18:19], v[14:15] offset0:144 offset1:216
	v_mov_b32_e32 v23, v3
	s_waitcnt lgkmcnt(0)
	v_pk_mul_f32 v[2:3], v[6:7], v[8:9] op_sel:[1,1] op_sel_hi:[1,0]
	s_nop 0
	v_pk_fma_f32 v[16:17], v[6:7], v[8:9], v[2:3] neg_lo:[0,0,1] neg_hi:[0,0,1]
	v_pk_fma_f32 v[2:3], v[6:7], v[8:9], v[2:3] op_sel_hi:[0,1,1]
	v_mov_b32_e32 v17, v3
	s_waitcnt lgkmcnt(0)
	v_pk_mul_f32 v[2:3], v[10:11], v[0:1] op_sel:[1,1] op_sel_hi:[0,1]
	v_pk_fma_f32 v[8:9], v[10:11], v[0:1], v[2:3] neg_lo:[0,0,1] neg_hi:[0,0,1]
	v_pk_fma_f32 v[0:1], v[10:11], v[0:1], v[2:3] op_sel_hi:[1,0,1]
	ds_read2_b64 v[4:7], v192 offset0:32 offset1:104
	v_mov_b32_e32 v9, v1
	ds_read2_b64 v[0:3], v191 offset1:72
	ds_write2_b64 v56, v[12:13], v[22:23] offset0:32 offset1:104
	ds_write2_b64 v56, v[16:17], v[8:9] offset0:176 offset1:248
	ds_read2_b64 v[8:11], v191 offset0:144 offset1:216
	ds_read2_b64 v[12:15], v192 offset0:176 offset1:248
	v_mov_b64_e32 v[18:19], v[224:225]
	s_waitcnt lgkmcnt(0)
	v_pk_add_f32 v[16:17], v[0:1], v[4:5]
	v_pk_add_f32 v[0:1], v[0:1], v[4:5] neg_lo:[0,1] neg_hi:[0,1]
	v_pk_add_f32 v[4:5], v[2:3], v[6:7]
	v_pk_add_f32 v[2:3], v[2:3], v[6:7] neg_lo:[0,1] neg_hi:[0,1]
	s_waitcnt lgkmcnt(0)
; __device__ __forceinline__ c2 cmul(c2 a, c2 b) { return (c2){a.x * b.x - a.y * b.y, a.x * b.y + a.y * b.x}; }
; template <int S> __device__ __forceinline__ void fwd_mid(c2* buf, const c2* tws, int tid) {
;     constexpr int lq = 9 - 3 * S, Q = 1 << lq; const c2* T = tws + (S == 1 ? 3584 : 4032);
;     const int k = tid & (Q - 1), base = ((tid >> lq) << (lq + 3)) + k;
;     c2 x[8];
;     c2* bp_ = buf + LP(base); constexpr int QP = Q + Q / 8;
; #pragma unroll
;     for (int r = 0; r < 8; ++r) x[r] = bp_[r * QP];
;     dft8(x);
; #pragma unroll
;     for (int q = 1; q < 8; ++q) x[q] = cmul(x[q], T[(q - 1) * Q + k]);
; #pragma unroll
;     for (int q = 0; q < 8; ++q) bp_[q * QP] = x[q];
; }
	v_pk_add_f32 v[6:7], v[8:9], v[12:13]
	v_pk_add_f32 v[8:9], v[8:9], v[12:13] neg_lo:[0,1] neg_hi:[0,1]
	v_pk_add_f32 v[12:13], v[10:11], v[14:15]
	v_pk_add_f32 v[10:11], v[10:11], v[14:15] neg_lo:[0,1] neg_hi:[0,1]
	v_pk_add_f32 v[14:15], v[2:3], v[2:3] op_sel:[1,0]
	v_pk_add_f32 v[2:3], v[2:3], v[2:3] op_sel_hi:[1,0] neg_lo:[0,1] neg_hi:[0,1]
	s_nop 0
	v_mov_b32_e32 v15, v3
	v_xor_b32_e32 v3, 0x80000000, v8
	v_mov_b32_e32 v2, v9
	v_pk_add_f32 v[8:9], v[10:11], v[10:11] op_sel:[1,0] neg_lo:[0,1] neg_hi:[0,1]
	v_pk_add_f32 v[10:11], v[10:11], v[10:11] op_sel_hi:[1,0]
	s_nop 0
	v_mov_b32_e32 v9, v11
	v_pk_add_f32 v[10:11], v[16:17], v[6:7]
	v_pk_add_f32 v[6:7], v[16:17], v[6:7] neg_lo:[0,1] neg_hi:[0,1]
	v_pk_add_f32 v[16:17], v[4:5], v[12:13]
	v_pk_add_f32 v[4:5], v[4:5], v[12:13] neg_lo:[0,1] neg_hi:[0,1]
	v_pk_mul_f32 v[8:9], v[8:9], s[20:21]
	v_xor_b32_e32 v13, 0x80000000, v4
	v_mov_b32_e32 v12, v5
	v_pk_add_f32 v[4:5], v[10:11], v[16:17]
	v_pk_add_f32 v[10:11], v[10:11], v[16:17] neg_lo:[0,1] neg_hi:[0,1]
	v_pk_add_f32 v[16:17], v[6:7], v[12:13]
	v_pk_add_f32 v[6:7], v[6:7], v[12:13] neg_lo:[0,1] neg_hi:[0,1]
	v_pk_add_f32 v[12:13], v[0:1], v[2:3]
	v_pk_add_f32 v[0:1], v[0:1], v[2:3] neg_lo:[0,1] neg_hi:[0,1]
	v_pk_fma_f32 v[2:3], v[14:15], s[20:21], v[8:9] op_sel_hi:[1,0,1]
	v_pk_fma_f32 v[8:9], v[14:15], s[20:21], v[8:9] op_sel_hi:[1,0,1] neg_lo:[0,0,1] neg_hi:[0,0,1]
	s_nop 0
	v_xor_b32_e32 v15, 0x80000000, v8
	v_mov_b32_e32 v14, v9
	v_pk_add_f32 v[8:9], v[12:13], v[2:3]
	v_pk_add_f32 v[2:3], v[12:13], v[2:3] neg_lo:[0,1] neg_hi:[0,1]
	v_pk_add_f32 v[12:13], v[0:1], v[14:15]
	v_pk_add_f32 v[0:1], v[0:1], v[14:15] neg_lo:[0,1] neg_hi:[0,1]
	v_mov_b64_e32 v[14:15], v[226:227]
	v_mov_b64_e32 v[20:21], v[228:229]
	v_mov_b64_e32 v[22:23], v[230:231]
	s_waitcnt lgkmcnt(0)
	v_pk_mul_f32 v[24:25], v[18:19], v[8:9] op_sel:[1,1] op_sel_hi:[0,1]
	v_pk_fma_f32 v[26:27], v[18:19], v[8:9], v[24:25] neg_lo:[0,0,1] neg_hi:[0,0,1]
	v_pk_fma_f32 v[8:9], v[18:19], v[8:9], v[24:25] op_sel_hi:[1,0,1]
	s_nop 0
	v_mov_b32_e32 v27, v9
	s_waitcnt lgkmcnt(0)
	v_pk_mul_f32 v[8:9], v[14:15], v[16:17] op_sel:[1,1] op_sel_hi:[0,1]
	v_pk_fma_f32 v[18:19], v[14:15], v[16:17], v[8:9] neg_lo:[0,0,1] neg_hi:[0,0,1]
	v_pk_fma_f32 v[8:9], v[14:15], v[16:17], v[8:9] op_sel_hi:[1,0,1]
	v_mov_b64_e32 v[16:17], v[232:233]
	v_mov_b32_e32 v19, v9
	s_waitcnt lgkmcnt(0)
	v_pk_mul_f32 v[8:9], v[20:21], v[12:13] op_sel:[1,1] op_sel_hi:[0,1]
	v_pk_fma_f32 v[14:15], v[20:21], v[12:13], v[8:9] neg_lo:[0,0,1] neg_hi:[0,0,1]
	v_pk_fma_f32 v[8:9], v[20:21], v[12:13], v[8:9] op_sel_hi:[1,0,1]
	s_waitcnt lgkmcnt(0)
	v_pk_mul_f32 v[20:21], v[16:17], v[2:3] op_sel:[1,1] op_sel_hi:[0,1]
	v_mov_b32_e32 v15, v9
	v_pk_mul_f32 v[8:9], v[10:11], v[22:23] op_sel:[1,1] op_sel_hi:[1,0]
	s_nop 0
	v_pk_fma_f32 v[12:13], v[10:11], v[22:23], v[8:9] neg_lo:[0,0,1] neg_hi:[0,0,1]
	v_pk_fma_f32 v[8:9], v[10:11], v[22:23], v[8:9] op_sel_hi:[0,1,1]
	v_mov_b32_e32 v13, v9
	v_mov_b64_e32 v[8:9], v[234:235]
	v_mov_b64_e32 v[10:11], v[236:237]
	v_pk_fma_f32 v[22:23], v[16:17], v[2:3], v[20:21] neg_lo:[0,0,1] neg_hi:[0,0,1]
	v_pk_fma_f32 v[2:3], v[16:17], v[2:3], v[20:21] op_sel_hi:[1,0,1]
	s_nop 0
	v_mov_b32_e32 v23, v3
	s_waitcnt lgkmcnt(0)
	v_pk_mul_f32 v[2:3], v[6:7], v[8:9] op_sel:[1,1] op_sel_hi:[1,0]
	s_nop 0
	v_pk_fma_f32 v[16:17], v[6:7], v[8:9], v[2:3] neg_lo:[0,0,1] neg_hi:[0,0,1]
	v_pk_fma_f32 v[2:3], v[6:7], v[8:9], v[2:3] op_sel_hi:[0,1,1]
	v_mov_b32_e32 v17, v3
	s_waitcnt lgkmcnt(0)
	v_pk_mul_f32 v[2:3], v[10:11], v[0:1] op_sel:[1,1] op_sel_hi:[0,1]
	v_pk_fma_f32 v[6:7], v[10:11], v[0:1], v[2:3] neg_lo:[0,0,1] neg_hi:[0,0,1]
	v_pk_fma_f32 v[0:1], v[10:11], v[0:1], v[2:3] op_sel_hi:[1,0,1]
	s_nop 0
	v_mov_b32_e32 v7, v1
	ds_write2_b64 v191, v[4:5], v[26:27] offset1:72
	ds_write2_b64 v191, v[18:19], v[14:15] offset0:144 offset1:216
	ds_write2_b64 v192, v[12:13], v[22:23] offset0:32 offset1:104
	ds_write2_b64 v192, v[16:17], v[6:7] offset0:176 offset1:248
	s_waitcnt lgkmcnt(0)
	s_barrier
	ds_read2_b64 v[0:3], v119 offset1:9
	ds_read2_b64 v[4:7], v119 offset0:36 offset1:45
	ds_read2_b64 v[8:11], v119 offset0:18 offset1:27
	ds_read2_b64 v[12:15], v119 offset0:54 offset1:63
	v_mov_b64_e32 v[18:19], v[238:239]
	s_waitcnt lgkmcnt(0)
	v_pk_add_f32 v[16:17], v[0:1], v[4:5]
	v_pk_add_f32 v[0:1], v[0:1], v[4:5] neg_lo:[0,1] neg_hi:[0,1]
	v_pk_add_f32 v[4:5], v[2:3], v[6:7]
	v_pk_add_f32 v[2:3], v[2:3], v[6:7] neg_lo:[0,1] neg_hi:[0,1]
	s_waitcnt lgkmcnt(0)
	v_pk_add_f32 v[6:7], v[8:9], v[12:13]
	v_pk_add_f32 v[8:9], v[8:9], v[12:13] neg_lo:[0,1] neg_hi:[0,1]
	v_pk_add_f32 v[12:13], v[10:11], v[14:15]
	v_pk_add_f32 v[10:11], v[10:11], v[14:15] neg_lo:[0,1] neg_hi:[0,1]
	v_pk_add_f32 v[14:15], v[2:3], v[2:3] op_sel:[1,0]
	v_pk_add_f32 v[2:3], v[2:3], v[2:3] op_sel_hi:[1,0] neg_lo:[0,1] neg_hi:[0,1]
	s_nop 0
	v_mov_b32_e32 v15, v3
	v_xor_b32_e32 v3, 0x80000000, v8
	v_mov_b32_e32 v2, v9
	v_pk_add_f32 v[8:9], v[10:11], v[10:11] op_sel:[1,0] neg_lo:[0,1] neg_hi:[0,1]
	v_pk_add_f32 v[10:11], v[10:11], v[10:11] op_sel_hi:[1,0]
	s_nop 0
	v_mov_b32_e32 v9, v11
	v_pk_add_f32 v[10:11], v[16:17], v[6:7]
	v_pk_add_f32 v[6:7], v[16:17], v[6:7] neg_lo:[0,1] neg_hi:[0,1]
	v_pk_add_f32 v[16:17], v[4:5], v[12:13]
	v_pk_add_f32 v[4:5], v[4:5], v[12:13] neg_lo:[0,1] neg_hi:[0,1]
	v_pk_mul_f32 v[8:9], v[8:9], s[20:21]
	v_xor_b32_e32 v13, 0x80000000, v4
	v_mov_b32_e32 v12, v5
	v_pk_add_f32 v[4:5], v[10:11], v[16:17]
	v_pk_add_f32 v[10:11], v[10:11], v[16:17] neg_lo:[0,1] neg_hi:[0,1]
	v_pk_add_f32 v[16:17], v[6:7], v[12:13]
	v_pk_add_f32 v[6:7], v[6:7], v[12:13] neg_lo:[0,1] neg_hi:[0,1]
	v_pk_add_f32 v[12:13], v[0:1], v[2:3]
	v_pk_add_f32 v[0:1], v[0:1], v[2:3] neg_lo:[0,1] neg_hi:[0,1]
	v_pk_fma_f32 v[2:3], v[14:15], s[20:21], v[8:9] op_sel_hi:[1,0,1]
	v_pk_fma_f32 v[8:9], v[14:15], s[20:21], v[8:9] op_sel_hi:[1,0,1] neg_lo:[0,0,1] neg_hi:[0,0,1]
	s_nop 0
	v_xor_b32_e32 v15, 0x80000000, v8
	v_mov_b32_e32 v14, v9
	v_pk_add_f32 v[8:9], v[12:13], v[2:3]
	v_pk_add_f32 v[2:3], v[12:13], v[2:3] neg_lo:[0,1] neg_hi:[0,1]
	v_pk_add_f32 v[12:13], v[0:1], v[14:15]
	v_pk_add_f32 v[0:1], v[0:1], v[14:15] neg_lo:[0,1] neg_hi:[0,1]
	v_mov_b64_e32 v[14:15], v[240:241]
	v_mov_b64_e32 v[20:21], v[242:243]
	v_mov_b64_e32 v[22:23], v[244:245]
	s_waitcnt lgkmcnt(0)
; __device__ __forceinline__ c2 cmul(c2 a, c2 b) { return (c2){a.x * b.x - a.y * b.y, a.x * b.y + a.y * b.x}; }
; template <int S> __device__ __forceinline__ void fwd_mid(c2* buf, const c2* tws, int tid) {
;     constexpr int lq = 9 - 3 * S, Q = 1 << lq; const c2* T = tws + (S == 1 ? 3584 : 4032);
;     const int k = tid & (Q - 1), base = ((tid >> lq) << (lq + 3)) + k;
;     c2 x[8];
;     c2* bp_ = buf + LP(base); constexpr int QP = Q + Q / 8;
; #pragma unroll
;     for (int r = 0; r < 8; ++r) x[r] = bp_[r * QP];
;     dft8(x);
; #pragma unroll
;     for (int q = 1; q < 8; ++q) x[q] = cmul(x[q], T[(q - 1) * Q + k]);
; #pragma unroll
;     for (int q = 0; q < 8; ++q) bp_[q * QP] = x[q];
; }
; __device__ __forceinline__ QuadRegs quad_load(const bf16_t* zsrc, const bf16_t* gsrc, int gstart, bool joined, bool first, bool last, int tid) {
;     const bf16_t* src = ((tid >> 8) ? gsrc : zsrc) + gstart; const int ci = tid & 255;
;     QuadRegs R;
; #pragma unroll
;     for (int k = 0; k < 4; ++k) { R.v[k] = *(const u32x4*)(src + 2048 * k + 8 * ci); R.h[k] = 0u; }
	v_pk_mul_f32 v[24:25], v[18:19], v[8:9] op_sel:[1,1] op_sel_hi:[0,1]
	v_pk_fma_f32 v[26:27], v[18:19], v[8:9], v[24:25] neg_lo:[0,0,1] neg_hi:[0,0,1]
	v_pk_fma_f32 v[8:9], v[18:19], v[8:9], v[24:25] op_sel_hi:[1,0,1]
	s_nop 0
	v_mov_b32_e32 v27, v9
	s_waitcnt lgkmcnt(0)
	v_pk_mul_f32 v[8:9], v[14:15], v[16:17] op_sel:[1,1] op_sel_hi:[0,1]
	v_pk_fma_f32 v[18:19], v[14:15], v[16:17], v[8:9] neg_lo:[0,0,1] neg_hi:[0,0,1]
	v_pk_fma_f32 v[8:9], v[14:15], v[16:17], v[8:9] op_sel_hi:[1,0,1]
	v_mov_b64_e32 v[16:17], v[246:247]
	v_mov_b32_e32 v19, v9
	s_waitcnt lgkmcnt(0)
	v_pk_mul_f32 v[8:9], v[20:21], v[12:13] op_sel:[1,1] op_sel_hi:[0,1]
	v_pk_fma_f32 v[14:15], v[20:21], v[12:13], v[8:9] neg_lo:[0,0,1] neg_hi:[0,0,1]
	v_pk_fma_f32 v[8:9], v[20:21], v[12:13], v[8:9] op_sel_hi:[1,0,1]
	s_waitcnt lgkmcnt(0)
	v_pk_mul_f32 v[20:21], v[16:17], v[2:3] op_sel:[1,1] op_sel_hi:[0,1]
	v_mov_b32_e32 v15, v9
	v_pk_mul_f32 v[8:9], v[10:11], v[22:23] op_sel:[1,1] op_sel_hi:[1,0]
	s_nop 0
	v_pk_fma_f32 v[12:13], v[10:11], v[22:23], v[8:9] neg_lo:[0,0,1] neg_hi:[0,0,1]
	v_pk_fma_f32 v[8:9], v[10:11], v[22:23], v[8:9] op_sel_hi:[0,1,1]
	v_mov_b32_e32 v13, v9
	v_mov_b64_e32 v[8:9], v[248:249]
	v_mov_b64_e32 v[10:11], v[250:251]
	v_pk_fma_f32 v[22:23], v[16:17], v[2:3], v[20:21] neg_lo:[0,0,1] neg_hi:[0,0,1]
	v_pk_fma_f32 v[2:3], v[16:17], v[2:3], v[20:21] op_sel_hi:[1,0,1]
	ds_write2_b64 v119, v[4:5], v[26:27] offset1:9
	ds_write2_b64 v119, v[18:19], v[14:15] offset0:18 offset1:27
	v_mov_b32_e32 v23, v3
	s_waitcnt lgkmcnt(0)
	v_pk_mul_f32 v[2:3], v[6:7], v[8:9] op_sel:[1,1] op_sel_hi:[1,0]
	s_nop 0
	v_pk_fma_f32 v[16:17], v[6:7], v[8:9], v[2:3] neg_lo:[0,0,1] neg_hi:[0,0,1]
	v_pk_fma_f32 v[2:3], v[6:7], v[8:9], v[2:3] op_sel_hi:[0,1,1]
	v_mov_b32_e32 v17, v3
	s_waitcnt lgkmcnt(0)
	v_pk_mul_f32 v[2:3], v[10:11], v[0:1] op_sel:[1,1] op_sel_hi:[0,1]
	v_pk_fma_f32 v[8:9], v[10:11], v[0:1], v[2:3] neg_lo:[0,0,1] neg_hi:[0,0,1]
	v_pk_fma_f32 v[0:1], v[10:11], v[0:1], v[2:3] op_sel_hi:[1,0,1]
	s_nop 0
	v_mov_b32_e32 v9, v1
	ds_read2_b64 v[0:3], v193 offset1:9
	ds_read2_b64 v[4:7], v193 offset0:36 offset1:45
	ds_write2_b64 v119, v[12:13], v[22:23] offset0:36 offset1:45
	ds_write2_b64 v119, v[16:17], v[8:9] offset0:54 offset1:63
	ds_read2_b64 v[8:11], v193 offset0:18 offset1:27
	ds_read2_b64 v[12:15], v193 offset0:54 offset1:63
	v_mov_b64_e32 v[18:19], v[238:239]
	s_waitcnt lgkmcnt(0)
	v_pk_add_f32 v[16:17], v[0:1], v[4:5]
	v_pk_add_f32 v[0:1], v[0:1], v[4:5] neg_lo:[0,1] neg_hi:[0,1]
	v_pk_add_f32 v[4:5], v[2:3], v[6:7]
	v_pk_add_f32 v[2:3], v[2:3], v[6:7] neg_lo:[0,1] neg_hi:[0,1]
	s_waitcnt lgkmcnt(0)
	v_pk_add_f32 v[6:7], v[8:9], v[12:13]
	v_pk_add_f32 v[8:9], v[8:9], v[12:13] neg_lo:[0,1] neg_hi:[0,1]
	v_pk_add_f32 v[12:13], v[10:11], v[14:15]
	v_pk_add_f32 v[10:11], v[10:11], v[14:15] neg_lo:[0,1] neg_hi:[0,1]
	v_pk_add_f32 v[14:15], v[2:3], v[2:3] op_sel:[1,0]
	v_pk_add_f32 v[2:3], v[2:3], v[2:3] op_sel_hi:[1,0] neg_lo:[0,1] neg_hi:[0,1]
	s_nop 0
	v_mov_b32_e32 v15, v3
	v_xor_b32_e32 v3, 0x80000000, v8
	v_mov_b32_e32 v2, v9
	v_pk_add_f32 v[8:9], v[10:11], v[10:11] op_sel:[1,0] neg_lo:[0,1] neg_hi:[0,1]
	v_pk_add_f32 v[10:11], v[10:11], v[10:11] op_sel_hi:[1,0]
	s_nop 0
	v_mov_b32_e32 v9, v11
	v_pk_add_f32 v[10:11], v[16:17], v[6:7]
	v_pk_add_f32 v[6:7], v[16:17], v[6:7] neg_lo:[0,1] neg_hi:[0,1]
	v_pk_add_f32 v[16:17], v[4:5], v[12:13]
	v_pk_add_f32 v[4:5], v[4:5], v[12:13] neg_lo:[0,1] neg_hi:[0,1]
	v_pk_mul_f32 v[8:9], v[8:9], s[20:21]
	v_xor_b32_e32 v13, 0x80000000, v4
	v_mov_b32_e32 v12, v5
	v_pk_add_f32 v[4:5], v[10:11], v[16:17]
	v_pk_add_f32 v[10:11], v[10:11], v[16:17] neg_lo:[0,1] neg_hi:[0,1]
	v_pk_add_f32 v[16:17], v[6:7], v[12:13]
	v_pk_add_f32 v[6:7], v[6:7], v[12:13] neg_lo:[0,1] neg_hi:[0,1]
	v_pk_add_f32 v[12:13], v[0:1], v[2:3]
	v_pk_add_f32 v[0:1], v[0:1], v[2:3] neg_lo:[0,1] neg_hi:[0,1]
	v_pk_fma_f32 v[2:3], v[14:15], s[20:21], v[8:9] op_sel_hi:[1,0,1]
	v_pk_fma_f32 v[8:9], v[14:15], s[20:21], v[8:9] op_sel_hi:[1,0,1] neg_lo:[0,0,1] neg_hi:[0,0,1]
	s_nop 0
	v_xor_b32_e32 v15, 0x80000000, v8
	v_mov_b32_e32 v14, v9
	v_pk_add_f32 v[8:9], v[12:13], v[2:3]
	v_pk_add_f32 v[2:3], v[12:13], v[2:3] neg_lo:[0,1] neg_hi:[0,1]
	v_pk_add_f32 v[12:13], v[0:1], v[14:15]
	v_pk_add_f32 v[0:1], v[0:1], v[14:15] neg_lo:[0,1] neg_hi:[0,1]
	v_mov_b64_e32 v[14:15], v[240:241]
	v_mov_b64_e32 v[20:21], v[242:243]
	v_mov_b64_e32 v[22:23], v[244:245]
	s_waitcnt lgkmcnt(0)
	v_pk_mul_f32 v[24:25], v[18:19], v[8:9] op_sel:[1,1] op_sel_hi:[0,1]
	v_pk_fma_f32 v[26:27], v[18:19], v[8:9], v[24:25] neg_lo:[0,0,1] neg_hi:[0,0,1]
	v_pk_fma_f32 v[8:9], v[18:19], v[8:9], v[24:25] op_sel_hi:[1,0,1]
	s_nop 0
	v_mov_b32_e32 v27, v9
	s_waitcnt lgkmcnt(0)
	v_pk_mul_f32 v[8:9], v[14:15], v[16:17] op_sel:[1,1] op_sel_hi:[0,1]
	v_pk_fma_f32 v[18:19], v[14:15], v[16:17], v[8:9] neg_lo:[0,0,1] neg_hi:[0,0,1]
	v_pk_fma_f32 v[8:9], v[14:15], v[16:17], v[8:9] op_sel_hi:[1,0,1]
	v_mov_b64_e32 v[16:17], v[246:247]
	v_mov_b32_e32 v19, v9
	s_waitcnt lgkmcnt(0)
	v_pk_mul_f32 v[8:9], v[20:21], v[12:13] op_sel:[1,1] op_sel_hi:[0,1]
	v_pk_fma_f32 v[14:15], v[20:21], v[12:13], v[8:9] neg_lo:[0,0,1] neg_hi:[0,0,1]
	v_pk_fma_f32 v[8:9], v[20:21], v[12:13], v[8:9] op_sel_hi:[1,0,1]
	s_waitcnt lgkmcnt(0)
	v_pk_mul_f32 v[20:21], v[16:17], v[2:3] op_sel:[1,1] op_sel_hi:[0,1]
	v_mov_b32_e32 v15, v9
	v_pk_mul_f32 v[8:9], v[10:11], v[22:23] op_sel:[1,1] op_sel_hi:[1,0]
	s_nop 0
	v_pk_fma_f32 v[12:13], v[10:11], v[22:23], v[8:9] neg_lo:[0,0,1] neg_hi:[0,0,1]
	v_pk_fma_f32 v[8:9], v[10:11], v[22:23], v[8:9] op_sel_hi:[0,1,1]
	v_mov_b32_e32 v13, v9
	v_mov_b64_e32 v[8:9], v[248:249]
	v_mov_b64_e32 v[10:11], v[250:251]
	v_pk_fma_f32 v[22:23], v[16:17], v[2:3], v[20:21] neg_lo:[0,0,1] neg_hi:[0,0,1]
	v_pk_fma_f32 v[2:3], v[16:17], v[2:3], v[20:21] op_sel_hi:[1,0,1]
	s_nop 0
	v_mov_b32_e32 v23, v3
	s_waitcnt lgkmcnt(0)
	v_pk_mul_f32 v[2:3], v[6:7], v[8:9] op_sel:[1,1] op_sel_hi:[1,0]
	s_nop 0
	v_pk_fma_f32 v[16:17], v[6:7], v[8:9], v[2:3] neg_lo:[0,0,1] neg_hi:[0,0,1]
	v_pk_fma_f32 v[2:3], v[6:7], v[8:9], v[2:3] op_sel_hi:[0,1,1]
	v_mov_b32_e32 v17, v3
	s_waitcnt lgkmcnt(0)
	v_pk_mul_f32 v[2:3], v[10:11], v[0:1] op_sel:[1,1] op_sel_hi:[0,1]
	v_pk_fma_f32 v[6:7], v[10:11], v[0:1], v[2:3] neg_lo:[0,0,1] neg_hi:[0,0,1]
	v_pk_fma_f32 v[0:1], v[10:11], v[0:1], v[2:3] op_sel_hi:[1,0,1]
	s_nop 0
	v_mov_b32_e32 v7, v1
	v_mov_b32_e32 v0, s78
	v_mov_b32_e32 v1, s79
	v_cndmask_b32_e64 v69, v0, v1, s[0:1]
	v_mov_b32_e32 v0, s68
	v_mov_b32_e32 v1, s69
	v_cndmask_b32_e64 v68, v0, v1, s[0:1]
	v_lshl_add_u64 v[8:9], v[68:69], 0, v[62:63]
	ds_write2_b64 v193, v[4:5], v[26:27] offset1:9
	ds_write2_b64 v193, v[18:19], v[14:15] offset0:18 offset1:27
	ds_write2_b64 v193, v[12:13], v[22:23] offset0:36 offset1:45
	ds_write2_b64 v193, v[16:17], v[6:7] offset0:54 offset1:63
	v_add_co_u32_e32 v4, vcc, s3, v8
	s_movk_i32 s3, 0x3000
	s_nop 0
	v_addc_co_u32_e32 v5, vcc, 0, v9, vcc
	v_add_co_u32_e32 v12, vcc, s3, v8
	s_waitcnt lgkmcnt(0)
	s_nop 0
	v_addc_co_u32_e32 v13, vcc, 0, v9, vcc
	s_barrier
; __device__ __forceinline__ c2 cmul(c2 a, c2 b) { return (c2){a.x * b.x - a.y * b.y, a.x * b.y + a.y * b.x}; }
; __device__ __forceinline__ void fwd_s0(c2 (&x)[8], c2* buf, const c2* tws, int tid) {
;     dft8(x);
; #pragma unroll
;     for (int q = 1; q < 8; ++q) x[q] = cmul(x[q], tws[(q - 1) * 512 + tid]);
;     { c2* bp_ = buf + LP(tid);
; #pragma unroll
;     for (int q = 0; q < 8; ++q) bp_[576 * q] = x[q]; }
; }
; template <int S> __device__ __forceinline__ void fwd_mid(c2* buf, const c2* tws, int tid) {
;     constexpr int lq = 9 - 3 * S, Q = 1 << lq; const c2* T = tws + (S == 1 ? 3584 : 4032);
;     const int k = tid & (Q - 1), base = ((tid >> lq) << (lq + 3)) + k;
;     c2 x[8];
;     c2* bp_ = buf + LP(base); constexpr int QP = Q + Q / 8;
; #pragma unroll
;     for (int r = 0; r < 8; ++r) x[r] = bp_[r * QP];
;     dft8(x);
; #pragma unroll
;     for (int q = 1; q < 8; ++q) x[q] = cmul(x[q], T[(q - 1) * Q + k]);
; #pragma unroll
;     for (int q = 0; q < 8; ++q) bp_[q * QP] = x[q];
; }
; __device__ __forceinline__ void fwd_s3(c2 (&x)[8], const c2* buf, int tid) {
; #pragma unroll
;     for (int r = 0; r < 8; ++r) x[r] = buf[9 * tid + r];
;     dft8(x);
; }
	global_load_dwordx4 v[0:3], v[4:5], off offset:-4096
	s_nop 0
	global_load_dwordx4 v[4:7], v[4:5], off
	s_nop 0
	global_load_dwordx4 v[8:11], v[8:9], off
	s_nop 0
	global_load_dwordx4 v[12:15], v[12:13], off
	ds_read2_b64 v[16:19], v121 offset1:1
	ds_read2_b64 v[20:23], v121 offset0:4 offset1:5
	ds_read2_b64 v[24:27], v121 offset0:2 offset1:3
	ds_read2_b64 v[28:31], v121 offset0:6 offset1:7
	s_waitcnt lgkmcnt(0)
	v_pk_add_f32 v[32:33], v[16:17], v[20:21]
	v_pk_add_f32 v[16:17], v[16:17], v[20:21] neg_lo:[0,1] neg_hi:[0,1]
	v_pk_add_f32 v[20:21], v[18:19], v[22:23]
	v_pk_add_f32 v[18:19], v[18:19], v[22:23] neg_lo:[0,1] neg_hi:[0,1]
	s_waitcnt lgkmcnt(0)
	v_pk_add_f32 v[22:23], v[24:25], v[28:29]
	v_pk_add_f32 v[24:25], v[24:25], v[28:29] neg_lo:[0,1] neg_hi:[0,1]
	v_pk_add_f32 v[28:29], v[26:27], v[30:31]
	v_pk_add_f32 v[26:27], v[26:27], v[30:31] neg_lo:[0,1] neg_hi:[0,1]
	v_pk_add_f32 v[34:35], v[18:19], v[18:19] op_sel:[1,0]
	v_pk_add_f32 v[18:19], v[18:19], v[18:19] op_sel_hi:[1,0] neg_lo:[0,1] neg_hi:[0,1]
	v_pk_add_f32 v[30:31], v[20:21], v[28:29]
	v_mov_b32_e32 v35, v19
	v_xor_b32_e32 v19, 0x80000000, v24
	v_mov_b32_e32 v18, v25
	v_pk_add_f32 v[24:25], v[26:27], v[26:27] op_sel:[1,0] neg_lo:[0,1] neg_hi:[0,1]
	v_pk_add_f32 v[26:27], v[26:27], v[26:27] op_sel_hi:[1,0]
	v_pk_add_f32 v[20:21], v[20:21], v[28:29] neg_lo:[0,1] neg_hi:[0,1]
	v_mov_b32_e32 v25, v27
	v_pk_mul_f32 v[36:37], v[24:25], s[20:21]
	v_pk_add_f32 v[26:27], v[32:33], v[22:23]
	v_pk_add_f32 v[22:23], v[32:33], v[22:23] neg_lo:[0,1] neg_hi:[0,1]
	v_xor_b32_e32 v33, 0x80000000, v20
	v_mov_b32_e32 v32, v21
	v_pk_add_f32 v[24:25], v[26:27], v[30:31]
	v_pk_add_f32 v[26:27], v[26:27], v[30:31] neg_lo:[0,1] neg_hi:[0,1]
	v_pk_add_f32 v[28:29], v[22:23], v[32:33]
	v_pk_add_f32 v[30:31], v[22:23], v[32:33] neg_lo:[0,1] neg_hi:[0,1]
	v_pk_fma_f32 v[22:23], v[34:35], s[20:21], v[36:37] op_sel_hi:[1,0,1] neg_lo:[0,0,1] neg_hi:[0,0,1]
	v_pk_add_f32 v[20:21], v[16:17], v[18:19]
	v_pk_add_f32 v[16:17], v[16:17], v[18:19] neg_lo:[0,1] neg_hi:[0,1]
	v_pk_fma_f32 v[18:19], v[34:35], s[20:21], v[36:37] op_sel_hi:[1,0,1]
	v_xor_b32_e32 v39, 0x80000000, v22
	v_mov_b32_e32 v38, v23
	v_pk_add_f32 v[32:33], v[20:21], v[18:19]
	v_pk_add_f32 v[34:35], v[20:21], v[18:19] neg_lo:[0,1] neg_hi:[0,1]
	v_pk_add_f32 v[36:37], v[16:17], v[38:39]
	v_pk_add_f32 v[38:39], v[16:17], v[38:39] neg_lo:[0,1] neg_hi:[0,1]
	v_lshl_add_u64 v[16:17], v[68:69], 0, v[60:61]
	v_pk_mov_b32 v[40:41], v[24:25], v[24:25] op_sel:[1,0]
	v_pk_mov_b32 v[42:43], v[32:33], v[32:33] op_sel:[1,0]
	v_pk_mov_b32 v[44:45], v[28:29], v[28:29] op_sel:[1,0]
	v_pk_mov_b32 v[46:47], v[36:37], v[36:37] op_sel:[1,0]
	v_pk_mov_b32 v[48:49], v[26:27], v[26:27] op_sel:[1,0]
	v_pk_mov_b32 v[50:51], v[34:35], v[34:35] op_sel:[1,0]
	v_pk_mov_b32 v[52:53], v[30:31], v[30:31] op_sel:[1,0]
	v_pk_mov_b32 v[54:55], v[38:39], v[38:39] op_sel:[1,0]
	v_lshl_add_u64 v[68:69], v[16:17], 0, s[28:29]
	s_branch .LBB0_289
.LBB0_288:
	v_pk_add_f32 v[16:17], v[84:85], 0 op_sel_hi:[1,0]
	v_pk_add_f32 v[18:19], v[82:83], 0 op_sel_hi:[1,0]
	v_pk_add_f32 v[20:21], v[78:79], 0 op_sel_hi:[1,0]
	v_pk_add_f32 v[22:23], v[80:81], 0 op_sel_hi:[1,0]
	v_sub_f32_e32 v90, v81, v80
	v_add_f32_e32 v91, v81, v80
	v_add_f32_e32 v86, v83, v82
	v_sub_f32_e32 v87, v83, v82
	v_pk_mul_f32 v[90:91], v[90:91], s[20:21]
	v_pk_add_f32 v[92:93], v[16:17], v[20:21]
	v_pk_add_f32 v[20:21], v[16:17], v[20:21] neg_lo:[0,1] neg_hi:[0,1]
	v_pk_add_f32 v[94:95], v[18:19], v[22:23]
	v_pk_add_f32 v[16:17], v[18:19], v[22:23] neg_lo:[0,1] neg_hi:[0,1]
	v_xor_b32_e32 v89, 0x80000000, v78
	v_mov_b32_e32 v88, v79
	v_xor_b32_e32 v19, 0x80000000, v16
	v_mov_b32_e32 v18, v17
	v_pk_add_f32 v[16:17], v[92:93], v[94:95]
	v_pk_add_f32 v[22:23], v[92:93], v[94:95] neg_lo:[0,1] neg_hi:[0,1]
	v_pk_fma_f32 v[94:95], v[86:87], s[20:21], v[90:91] op_sel_hi:[1,0,1]
	v_pk_fma_f32 v[86:87], v[86:87], s[20:21], v[90:91] op_sel_hi:[1,0,1] neg_lo:[0,0,1] neg_hi:[0,0,1]
	v_pk_add_f32 v[92:93], v[20:21], v[18:19]
	v_pk_add_f32 v[18:19], v[20:21], v[18:19] neg_lo:[0,1] neg_hi:[0,1]
	v_pk_add_f32 v[20:21], v[84:85], v[88:89]
	v_pk_add_f32 v[88:89], v[84:85], v[88:89] neg_lo:[0,1] neg_hi:[0,1]
	v_xor_b32_e32 v91, 0x80000000, v86
	v_mov_b32_e32 v90, v87
	v_pk_add_f32 v[86:87], v[20:21], v[94:95]
	v_pk_add_f32 v[20:21], v[20:21], v[94:95] neg_lo:[0,1] neg_hi:[0,1]
	v_pk_add_f32 v[94:95], v[88:89], v[90:91]
	v_pk_add_f32 v[88:89], v[88:89], v[90:91] neg_lo:[0,1] neg_hi:[0,1]
	v_mov_b64_e32 v[90:91], v[210:211]
	v_add_u32_e32 v63, 0x9000, v121
	v_add_u32_e32 v205, 0x9020, v121
	v_add_u32_e32 v204, 0x9010, v121
	v_add_u32_e32 v206, 0x9030, v121
	s_waitcnt lgkmcnt(0)
	v_mul_f32_e32 v96, v87, v91
	v_mul_f32_e32 v98, v86, v91
	v_pk_fma_f32 v[96:97], v[86:87], v[90:91], v[96:97] op_sel_hi:[1,1,0] neg_lo:[0,0,1] neg_hi:[0,0,1]
	v_pk_fma_f32 v[86:87], v[86:87], v[90:91], v[98:99] op_sel:[0,1,0] op_sel_hi:[1,0,0]
	v_mov_b64_e32 v[90:91], v[212:213]
	v_mov_b32_e32 v97, v87
	s_mov_b32 s84, s21
	s_mov_b32 s85, s20
	v_lshl_add_u64 v[68:69], v[68:69], 0, s[28:29]
	s_waitcnt lgkmcnt(0)
	v_mul_f32_e32 v86, v93, v91
	v_pk_fma_f32 v[98:99], v[92:93], v[90:91], v[86:87] op_sel_hi:[1,1,0] neg_lo:[0,0,1] neg_hi:[0,0,1]
	v_mul_f32_e32 v86, v92, v91
	v_pk_fma_f32 v[90:91], v[92:93], v[90:91], v[86:87] op_sel:[0,1,0] op_sel_hi:[1,0,0]
	v_mov_b64_e32 v[92:93], v[214:215]
	v_mov_b32_e32 v99, v91
	v_sub_f32_e32 v90, v71, v70
	v_add_f32_e32 v91, v71, v70
	v_pk_mul_f32 v[90:91], v[90:91], s[20:21]
	s_waitcnt lgkmcnt(0)
; __device__ __forceinline__ c2 cmul(c2 a, c2 b) { return (c2){a.x * b.x - a.y * b.y, a.x * b.y + a.y * b.x}; }
; __device__ __forceinline__ void fwd_s0(c2 (&x)[8], c2* buf, const c2* tws, int tid) {
;     dft8(x);
; #pragma unroll
;     for (int q = 1; q < 8; ++q) x[q] = cmul(x[q], tws[(q - 1) * 512 + tid]);
;     { c2* bp_ = buf + LP(tid);
; #pragma unroll
;     for (int q = 0; q < 8; ++q) bp_[576 * q] = x[q]; }
; }
	v_mul_f32_e32 v86, v95, v93
	v_pk_fma_f32 v[100:101], v[94:95], v[92:93], v[86:87] op_sel_hi:[1,1,0] neg_lo:[0,0,1] neg_hi:[0,0,1]
	v_mul_f32_e32 v86, v94, v93
	v_pk_fma_f32 v[92:93], v[94:95], v[92:93], v[86:87] op_sel:[0,1,0] op_sel_hi:[1,0,0]
	v_mov_b64_e32 v[94:95], v[216:217]
	v_mov_b32_e32 v101, v93
	s_waitcnt lgkmcnt(0)
	v_mul_f32_e32 v86, v23, v95
	v_pk_fma_f32 v[102:103], v[22:23], v[94:95], v[86:87] op_sel_hi:[1,1,0] neg_lo:[0,0,1] neg_hi:[0,0,1]
	v_mul_f32_e32 v86, v22, v95
	v_pk_fma_f32 v[22:23], v[22:23], v[94:95], v[86:87] op_sel:[0,1,0] op_sel_hi:[1,0,0]
	v_mov_b64_e32 v[94:95], v[218:219]
	v_mov_b32_e32 v103, v23
	v_add_f32_e32 v86, v75, v74
	v_sub_f32_e32 v87, v75, v74
	s_waitcnt lgkmcnt(0)
	v_mul_f32_e32 v22, v21, v95
	v_pk_fma_f32 v[194:195], v[20:21], v[94:95], v[22:23] op_sel_hi:[1,1,0] neg_lo:[0,0,1] neg_hi:[0,0,1]
	v_mul_f32_e32 v22, v20, v95
	v_pk_fma_f32 v[20:21], v[20:21], v[94:95], v[22:23] op_sel:[0,1,0] op_sel_hi:[1,0,0]
	v_mov_b64_e32 v[94:95], v[220:221]
	v_mov_b32_e32 v195, v21
	v_pk_add_f32 v[22:23], v[70:71], 0 op_sel_hi:[1,0]
	s_waitcnt lgkmcnt(0)
	v_mul_f32_e32 v20, v19, v95
	v_pk_fma_f32 v[196:197], v[18:19], v[94:95], v[20:21] op_sel_hi:[1,1,0] neg_lo:[0,0,1] neg_hi:[0,0,1]
	v_mul_f32_e32 v20, v18, v95
	v_pk_fma_f32 v[18:19], v[18:19], v[94:95], v[20:21] op_sel:[0,1,0] op_sel_hi:[1,0,0]
	v_mov_b64_e32 v[94:95], v[222:223]
	ds_write2st64_b64 v115, v[16:17], v[96:97] offset1:9
	v_mov_b32_e32 v197, v19
	v_pk_add_f32 v[16:17], v[76:77], 0 op_sel_hi:[1,0]
	v_pk_add_f32 v[20:21], v[72:73], 0 op_sel_hi:[1,0]
	s_waitcnt lgkmcnt(0)
	v_mul_f32_e32 v18, v89, v95
	v_pk_fma_f32 v[198:199], v[88:89], v[94:95], v[18:19] op_sel_hi:[1,1,0] neg_lo:[0,0,1] neg_hi:[0,0,1]
	v_mul_f32_e32 v18, v88, v95
	v_pk_fma_f32 v[88:89], v[88:89], v[94:95], v[18:19] op_sel:[0,1,0] op_sel_hi:[1,0,0]
	v_pk_add_f32 v[18:19], v[74:75], 0 op_sel_hi:[1,0]
	v_pk_add_f32 v[92:93], v[16:17], v[20:21]
	v_pk_add_f32 v[20:21], v[16:17], v[20:21] neg_lo:[0,1] neg_hi:[0,1]
	v_pk_add_f32 v[94:95], v[18:19], v[22:23]
	v_pk_add_f32 v[16:17], v[18:19], v[22:23] neg_lo:[0,1] neg_hi:[0,1]
	v_mov_b32_e32 v199, v89
	v_xor_b32_e32 v89, 0x80000000, v72
	v_mov_b32_e32 v88, v73
	v_xor_b32_e32 v19, 0x80000000, v16
	v_mov_b32_e32 v18, v17
	v_pk_add_f32 v[16:17], v[92:93], v[94:95]
	v_pk_add_f32 v[22:23], v[92:93], v[94:95] neg_lo:[0,1] neg_hi:[0,1]
	v_pk_fma_f32 v[94:95], v[86:87], s[20:21], v[90:91] op_sel_hi:[1,0,1]
	v_pk_fma_f32 v[86:87], v[86:87], s[20:21], v[90:91] op_sel_hi:[1,0,1] neg_lo:[0,0,1] neg_hi:[0,0,1]
	ds_write2st64_b64 v115, v[98:99], v[100:101] offset0:18 offset1:27
	ds_write2st64_b64 v115, v[102:103], v[194:195] offset0:36 offset1:45
	ds_write2st64_b64 v115, v[196:197], v[198:199] offset0:54 offset1:63
	v_pk_add_f32 v[92:93], v[20:21], v[18:19]
	v_pk_add_f32 v[18:19], v[20:21], v[18:19] neg_lo:[0,1] neg_hi:[0,1]
	v_pk_add_f32 v[20:21], v[76:77], v[88:89]
	v_pk_add_f32 v[88:89], v[76:77], v[88:89] neg_lo:[0,1] neg_hi:[0,1]
	v_xor_b32_e32 v91, 0x80000000, v86
	v_mov_b32_e32 v90, v87
	v_pk_add_f32 v[86:87], v[20:21], v[94:95]
	v_pk_add_f32 v[20:21], v[20:21], v[94:95] neg_lo:[0,1] neg_hi:[0,1]
	v_pk_add_f32 v[94:95], v[88:89], v[90:91]
	v_pk_add_f32 v[88:89], v[88:89], v[90:91] neg_lo:[0,1] neg_hi:[0,1]
	v_mov_b64_e32 v[90:91], v[210:211]
	s_waitcnt lgkmcnt(0)
	v_mul_f32_e32 v96, v87, v91
	v_mul_f32_e32 v98, v86, v91
	v_pk_fma_f32 v[96:97], v[86:87], v[90:91], v[96:97] op_sel_hi:[1,1,0] neg_lo:[0,0,1] neg_hi:[0,0,1]
	v_pk_fma_f32 v[86:87], v[86:87], v[90:91], v[98:99] op_sel:[0,1,0] op_sel_hi:[1,0,0]
	v_mov_b64_e32 v[90:91], v[212:213]
	v_mov_b32_e32 v97, v87
	s_waitcnt lgkmcnt(0)
	v_mul_f32_e32 v86, v93, v91
	v_pk_fma_f32 v[98:99], v[92:93], v[90:91], v[86:87] op_sel_hi:[1,1,0] neg_lo:[0,0,1] neg_hi:[0,0,1]
	v_mul_f32_e32 v86, v92, v91
	v_pk_fma_f32 v[90:91], v[92:93], v[90:91], v[86:87] op_sel:[0,1,0] op_sel_hi:[1,0,0]
	v_mov_b64_e32 v[92:93], v[214:215]
	v_mov_b32_e32 v99, v91
	s_waitcnt lgkmcnt(0)
	v_mul_f32_e32 v86, v95, v93
	v_pk_fma_f32 v[100:101], v[94:95], v[92:93], v[86:87] op_sel_hi:[1,1,0] neg_lo:[0,0,1] neg_hi:[0,0,1]
	v_mul_f32_e32 v86, v94, v93
	v_pk_fma_f32 v[92:93], v[94:95], v[92:93], v[86:87] op_sel:[0,1,0] op_sel_hi:[1,0,0]
	v_mov_b64_e32 v[94:95], v[216:217]
	v_mov_b32_e32 v101, v93
	s_waitcnt lgkmcnt(0)
	v_mul_f32_e32 v86, v23, v95
	v_pk_fma_f32 v[102:103], v[22:23], v[94:95], v[86:87] op_sel_hi:[1,1,0] neg_lo:[0,0,1] neg_hi:[0,0,1]
	v_mul_f32_e32 v86, v22, v95
	v_pk_fma_f32 v[22:23], v[22:23], v[94:95], v[86:87] op_sel:[0,1,0] op_sel_hi:[1,0,0]
	v_mov_b64_e32 v[94:95], v[218:219]
	v_mov_b32_e32 v103, v23
	s_waitcnt lgkmcnt(0)
	v_mul_f32_e32 v22, v21, v95
	v_pk_fma_f32 v[194:195], v[20:21], v[94:95], v[22:23] op_sel_hi:[1,1,0] neg_lo:[0,0,1] neg_hi:[0,0,1]
	v_mul_f32_e32 v22, v20, v95
	v_pk_fma_f32 v[20:21], v[20:21], v[94:95], v[22:23] op_sel:[0,1,0] op_sel_hi:[1,0,0]
	v_mov_b64_e32 v[94:95], v[220:221]
	v_mov_b32_e32 v195, v21
	s_waitcnt lgkmcnt(0)
	v_mul_f32_e32 v20, v19, v95
	v_pk_fma_f32 v[196:197], v[18:19], v[94:95], v[20:21] op_sel_hi:[1,1,0] neg_lo:[0,0,1] neg_hi:[0,0,1]
	v_mul_f32_e32 v20, v18, v95
	v_pk_fma_f32 v[18:19], v[18:19], v[94:95], v[20:21] op_sel:[0,1,0] op_sel_hi:[1,0,0]
	v_mov_b64_e32 v[94:95], v[222:223]
	v_mov_b32_e32 v197, v19
	ds_write2st64_b64 v115, v[16:17], v[96:97] offset0:72 offset1:81
	ds_write2st64_b64 v115, v[98:99], v[100:101] offset0:90 offset1:99
	ds_write2st64_b64 v115, v[102:103], v[194:195] offset0:108 offset1:117
	s_waitcnt lgkmcnt(0)
	v_mul_f32_e32 v18, v89, v95
	v_pk_fma_f32 v[198:199], v[88:89], v[94:95], v[18:19] op_sel_hi:[1,1,0] neg_lo:[0,0,1] neg_hi:[0,0,1]
	v_mul_f32_e32 v18, v88, v95
	v_pk_fma_f32 v[88:89], v[88:89], v[94:95], v[18:19] op_sel:[0,1,0] op_sel_hi:[1,0,0]
	ds_write_b64 v115, v[196:197] offset:64512
	v_mov_b32_e32 v199, v89
	ds_write_b64 v116, v[198:199] offset:32256
	s_waitcnt lgkmcnt(0)
	s_barrier
; __device__ __forceinline__ c2 cmul(c2 a, c2 b) { return (c2){a.x * b.x - a.y * b.y, a.x * b.y + a.y * b.x}; }
; template <int S> __device__ __forceinline__ void fwd_mid(c2* buf, const c2* tws, int tid) {
;     constexpr int lq = 9 - 3 * S, Q = 1 << lq; const c2* T = tws + (S == 1 ? 3584 : 4032);
;     const int k = tid & (Q - 1), base = ((tid >> lq) << (lq + 3)) + k;
;     c2 x[8];
;     c2* bp_ = buf + LP(base); constexpr int QP = Q + Q / 8;
; #pragma unroll
;     for (int r = 0; r < 8; ++r) x[r] = bp_[r * QP];
;     dft8(x);
; #pragma unroll
;     for (int q = 1; q < 8; ++q) x[q] = cmul(x[q], T[(q - 1) * Q + k]);
; #pragma unroll
;     for (int q = 0; q < 8; ++q) bp_[q * QP] = x[q];
; }
	ds_read2_b64 v[16:19], v117 offset1:72
	ds_read2_b64 v[20:23], v117 offset0:144 offset1:216
	ds_read2_b64 v[86:89], v56 offset0:32 offset1:104
	ds_read2_b64 v[90:93], v56 offset0:176 offset1:248
	s_waitcnt lgkmcnt(0)
	v_pk_add_f32 v[94:95], v[16:17], v[86:87]
	v_pk_add_f32 v[16:17], v[16:17], v[86:87] neg_lo:[0,1] neg_hi:[0,1]
	v_pk_add_f32 v[86:87], v[18:19], v[88:89]
	v_pk_add_f32 v[18:19], v[18:19], v[88:89] neg_lo:[0,1] neg_hi:[0,1]
	s_waitcnt lgkmcnt(0)
	v_pk_add_f32 v[88:89], v[20:21], v[90:91]
	v_pk_add_f32 v[20:21], v[20:21], v[90:91] neg_lo:[0,1] neg_hi:[0,1]
	v_pk_add_f32 v[90:91], v[22:23], v[92:93]
	v_pk_add_f32 v[22:23], v[22:23], v[92:93] neg_lo:[0,1] neg_hi:[0,1]
	v_pk_add_f32 v[92:93], v[18:19], v[18:19] op_sel:[1,0]
	v_pk_add_f32 v[18:19], v[18:19], v[18:19] op_sel_hi:[1,0] neg_lo:[0,1] neg_hi:[0,1]
	s_nop 0
	v_mov_b32_e32 v93, v19
	v_xor_b32_e32 v19, 0x80000000, v20
	v_mov_b32_e32 v18, v21
	v_pk_add_f32 v[20:21], v[22:23], v[22:23] op_sel:[1,0] neg_lo:[0,1] neg_hi:[0,1]
	v_pk_add_f32 v[22:23], v[22:23], v[22:23] op_sel_hi:[1,0]
	s_nop 0
	v_mov_b32_e32 v21, v23
	v_pk_add_f32 v[22:23], v[94:95], v[88:89]
	v_pk_add_f32 v[88:89], v[94:95], v[88:89] neg_lo:[0,1] neg_hi:[0,1]
	v_pk_add_f32 v[94:95], v[86:87], v[90:91]
	v_pk_add_f32 v[86:87], v[86:87], v[90:91] neg_lo:[0,1] neg_hi:[0,1]
	v_pk_mul_f32 v[20:21], v[20:21], s[20:21]
	v_xor_b32_e32 v91, 0x80000000, v86
	v_mov_b32_e32 v90, v87
	v_pk_add_f32 v[86:87], v[22:23], v[94:95]
	v_pk_add_f32 v[22:23], v[22:23], v[94:95] neg_lo:[0,1] neg_hi:[0,1]
	v_pk_add_f32 v[94:95], v[88:89], v[90:91]
	v_pk_add_f32 v[88:89], v[88:89], v[90:91] neg_lo:[0,1] neg_hi:[0,1]
	v_pk_add_f32 v[90:91], v[16:17], v[18:19]
	v_pk_add_f32 v[16:17], v[16:17], v[18:19] neg_lo:[0,1] neg_hi:[0,1]
	v_pk_fma_f32 v[18:19], v[92:93], s[20:21], v[20:21] op_sel_hi:[1,0,1]
	v_pk_fma_f32 v[20:21], v[92:93], s[20:21], v[20:21] op_sel_hi:[1,0,1] neg_lo:[0,0,1] neg_hi:[0,0,1]
	s_nop 0
	v_xor_b32_e32 v93, 0x80000000, v20
	v_mov_b32_e32 v92, v21
	v_pk_add_f32 v[20:21], v[90:91], v[18:19]
	v_pk_add_f32 v[18:19], v[90:91], v[18:19] neg_lo:[0,1] neg_hi:[0,1]
	v_pk_add_f32 v[90:91], v[16:17], v[92:93]
	v_pk_add_f32 v[16:17], v[16:17], v[92:93] neg_lo:[0,1] neg_hi:[0,1]
	v_mov_b64_e32 v[92:93], v[224:225]
	s_waitcnt lgkmcnt(0)
	v_pk_mul_f32 v[96:97], v[92:93], v[20:21] op_sel:[1,1] op_sel_hi:[0,1]
	v_pk_fma_f32 v[98:99], v[92:93], v[20:21], v[96:97] neg_lo:[0,0,1] neg_hi:[0,0,1]
	v_pk_fma_f32 v[20:21], v[92:93], v[20:21], v[96:97] op_sel_hi:[1,0,1]
	s_nop 0
	v_mov_b32_e32 v99, v21
	v_mov_b64_e32 v[20:21], v[226:227]
	s_waitcnt lgkmcnt(0)
	v_pk_mul_f32 v[92:93], v[20:21], v[94:95] op_sel:[1,1] op_sel_hi:[0,1]
	v_pk_fma_f32 v[96:97], v[20:21], v[94:95], v[92:93] neg_lo:[0,0,1] neg_hi:[0,0,1]
	v_pk_fma_f32 v[20:21], v[20:21], v[94:95], v[92:93] op_sel_hi:[1,0,1]
	s_nop 0
	v_mov_b32_e32 v97, v21
	v_mov_b64_e32 v[20:21], v[228:229]
	s_waitcnt lgkmcnt(0)
	v_pk_mul_f32 v[92:93], v[20:21], v[90:91] op_sel:[1,1] op_sel_hi:[0,1]
	v_pk_fma_f32 v[94:95], v[20:21], v[90:91], v[92:93] neg_lo:[0,0,1] neg_hi:[0,0,1]
	v_pk_fma_f32 v[20:21], v[20:21], v[90:91], v[92:93] op_sel_hi:[1,0,1]
	s_nop 0
	v_mov_b32_e32 v95, v21
	v_mov_b64_e32 v[20:21], v[230:231]
	s_waitcnt lgkmcnt(0)
	v_pk_mul_f32 v[90:91], v[22:23], v[20:21] op_sel:[1,1] op_sel_hi:[1,0]
	s_nop 0
	v_pk_fma_f32 v[92:93], v[22:23], v[20:21], v[90:91] neg_lo:[0,0,1] neg_hi:[0,0,1]
	v_pk_fma_f32 v[20:21], v[22:23], v[20:21], v[90:91] op_sel_hi:[0,1,1]
	v_mov_b32_e32 v93, v21
	v_mov_b64_e32 v[20:21], v[232:233]
	s_waitcnt lgkmcnt(0)
	v_pk_mul_f32 v[22:23], v[20:21], v[18:19] op_sel:[1,1] op_sel_hi:[0,1]
	v_pk_fma_f32 v[90:91], v[20:21], v[18:19], v[22:23] neg_lo:[0,0,1] neg_hi:[0,0,1]
	v_pk_fma_f32 v[18:19], v[20:21], v[18:19], v[22:23] op_sel_hi:[1,0,1]
	s_nop 0
	v_mov_b32_e32 v91, v19
	v_mov_b64_e32 v[18:19], v[234:235]
	s_waitcnt lgkmcnt(0)
	v_pk_mul_f32 v[20:21], v[88:89], v[18:19] op_sel:[1,1] op_sel_hi:[1,0]
	s_nop 0
	v_pk_fma_f32 v[22:23], v[88:89], v[18:19], v[20:21] neg_lo:[0,0,1] neg_hi:[0,0,1]
	v_pk_fma_f32 v[18:19], v[88:89], v[18:19], v[20:21] op_sel_hi:[0,1,1]
	v_mov_b32_e32 v23, v19
	v_mov_b64_e32 v[18:19], v[236:237]
	s_waitcnt lgkmcnt(0)
	v_pk_mul_f32 v[20:21], v[18:19], v[16:17] op_sel:[1,1] op_sel_hi:[0,1]
	v_pk_fma_f32 v[88:89], v[18:19], v[16:17], v[20:21] neg_lo:[0,0,1] neg_hi:[0,0,1]
	v_pk_fma_f32 v[16:17], v[18:19], v[16:17], v[20:21] op_sel_hi:[1,0,1]
	s_nop 0
	v_mov_b32_e32 v89, v17
	ds_write2_b64 v117, v[86:87], v[98:99] offset1:72
	ds_write2_b64 v117, v[96:97], v[94:95] offset0:144 offset1:216
	ds_write2_b64 v56, v[92:93], v[90:91] offset0:32 offset1:104
	ds_write2_b64 v56, v[22:23], v[88:89] offset0:176 offset1:248
	ds_read2_b64 v[16:19], v191 offset1:72
	ds_read2_b64 v[20:23], v191 offset0:144 offset1:216
	ds_read2_b64 v[86:89], v192 offset0:32 offset1:104
	ds_read2_b64 v[90:93], v192 offset0:176 offset1:248
	s_waitcnt lgkmcnt(0)
	v_pk_add_f32 v[94:95], v[16:17], v[86:87]
	v_pk_add_f32 v[16:17], v[16:17], v[86:87] neg_lo:[0,1] neg_hi:[0,1]
	v_pk_add_f32 v[86:87], v[18:19], v[88:89]
	v_pk_add_f32 v[18:19], v[18:19], v[88:89] neg_lo:[0,1] neg_hi:[0,1]
	s_waitcnt lgkmcnt(0)
; __device__ __forceinline__ c2 cmul(c2 a, c2 b) { return (c2){a.x * b.x - a.y * b.y, a.x * b.y + a.y * b.x}; }
; template <int S> __device__ __forceinline__ void fwd_mid(c2* buf, const c2* tws, int tid) {
;     constexpr int lq = 9 - 3 * S, Q = 1 << lq; const c2* T = tws + (S == 1 ? 3584 : 4032);
;     const int k = tid & (Q - 1), base = ((tid >> lq) << (lq + 3)) + k;
;     c2 x[8];
;     c2* bp_ = buf + LP(base); constexpr int QP = Q + Q / 8;
; #pragma unroll
;     for (int r = 0; r < 8; ++r) x[r] = bp_[r * QP];
;     dft8(x);
; #pragma unroll
;     for (int q = 1; q < 8; ++q) x[q] = cmul(x[q], T[(q - 1) * Q + k]);
; #pragma unroll
;     for (int q = 0; q < 8; ++q) bp_[q * QP] = x[q];
; }
	v_pk_add_f32 v[88:89], v[20:21], v[90:91]
	v_pk_add_f32 v[20:21], v[20:21], v[90:91] neg_lo:[0,1] neg_hi:[0,1]
	v_pk_add_f32 v[90:91], v[22:23], v[92:93]
	v_pk_add_f32 v[22:23], v[22:23], v[92:93] neg_lo:[0,1] neg_hi:[0,1]
	v_pk_add_f32 v[92:93], v[18:19], v[18:19] op_sel:[1,0]
	v_pk_add_f32 v[18:19], v[18:19], v[18:19] op_sel_hi:[1,0] neg_lo:[0,1] neg_hi:[0,1]
	s_nop 0
	v_mov_b32_e32 v93, v19
	v_xor_b32_e32 v19, 0x80000000, v20
	v_mov_b32_e32 v18, v21
	v_pk_add_f32 v[20:21], v[22:23], v[22:23] op_sel:[1,0] neg_lo:[0,1] neg_hi:[0,1]
	v_pk_add_f32 v[22:23], v[22:23], v[22:23] op_sel_hi:[1,0]
	s_nop 0
	v_mov_b32_e32 v21, v23
	v_pk_add_f32 v[22:23], v[94:95], v[88:89]
	v_pk_add_f32 v[88:89], v[94:95], v[88:89] neg_lo:[0,1] neg_hi:[0,1]
	v_pk_add_f32 v[94:95], v[86:87], v[90:91]
	v_pk_add_f32 v[86:87], v[86:87], v[90:91] neg_lo:[0,1] neg_hi:[0,1]
	v_pk_mul_f32 v[20:21], v[20:21], s[20:21]
	v_xor_b32_e32 v91, 0x80000000, v86
	v_mov_b32_e32 v90, v87
	v_pk_add_f32 v[86:87], v[22:23], v[94:95]
	v_pk_add_f32 v[22:23], v[22:23], v[94:95] neg_lo:[0,1] neg_hi:[0,1]
	v_pk_add_f32 v[94:95], v[88:89], v[90:91]
	v_pk_add_f32 v[88:89], v[88:89], v[90:91] neg_lo:[0,1] neg_hi:[0,1]
	v_pk_add_f32 v[90:91], v[16:17], v[18:19]
	v_pk_add_f32 v[16:17], v[16:17], v[18:19] neg_lo:[0,1] neg_hi:[0,1]
	v_pk_fma_f32 v[18:19], v[92:93], s[20:21], v[20:21] op_sel_hi:[1,0,1]
	v_pk_fma_f32 v[20:21], v[92:93], s[20:21], v[20:21] op_sel_hi:[1,0,1] neg_lo:[0,0,1] neg_hi:[0,0,1]
	s_nop 0
	v_xor_b32_e32 v93, 0x80000000, v20
	v_mov_b32_e32 v92, v21
	v_pk_add_f32 v[20:21], v[90:91], v[18:19]
	v_pk_add_f32 v[18:19], v[90:91], v[18:19] neg_lo:[0,1] neg_hi:[0,1]
	v_pk_add_f32 v[90:91], v[16:17], v[92:93]
	v_pk_add_f32 v[16:17], v[16:17], v[92:93] neg_lo:[0,1] neg_hi:[0,1]
	v_mov_b64_e32 v[92:93], v[224:225]
	s_waitcnt lgkmcnt(0)
	v_pk_mul_f32 v[96:97], v[92:93], v[20:21] op_sel:[1,1] op_sel_hi:[0,1]
	v_pk_fma_f32 v[98:99], v[92:93], v[20:21], v[96:97] neg_lo:[0,0,1] neg_hi:[0,0,1]
	v_pk_fma_f32 v[20:21], v[92:93], v[20:21], v[96:97] op_sel_hi:[1,0,1]
	s_nop 0
	v_mov_b32_e32 v99, v21
	v_mov_b64_e32 v[20:21], v[226:227]
	s_waitcnt lgkmcnt(0)
	v_pk_mul_f32 v[92:93], v[20:21], v[94:95] op_sel:[1,1] op_sel_hi:[0,1]
	v_pk_fma_f32 v[96:97], v[20:21], v[94:95], v[92:93] neg_lo:[0,0,1] neg_hi:[0,0,1]
	v_pk_fma_f32 v[20:21], v[20:21], v[94:95], v[92:93] op_sel_hi:[1,0,1]
	s_nop 0
	v_mov_b32_e32 v97, v21
	v_mov_b64_e32 v[20:21], v[228:229]
	s_waitcnt lgkmcnt(0)
	v_pk_mul_f32 v[92:93], v[20:21], v[90:91] op_sel:[1,1] op_sel_hi:[0,1]
	v_pk_fma_f32 v[94:95], v[20:21], v[90:91], v[92:93] neg_lo:[0,0,1] neg_hi:[0,0,1]
	v_pk_fma_f32 v[20:21], v[20:21], v[90:91], v[92:93] op_sel_hi:[1,0,1]
	s_nop 0
	v_mov_b32_e32 v95, v21
	v_mov_b64_e32 v[20:21], v[230:231]
	s_waitcnt lgkmcnt(0)
	v_pk_mul_f32 v[90:91], v[22:23], v[20:21] op_sel:[1,1] op_sel_hi:[1,0]
	s_nop 0
	v_pk_fma_f32 v[92:93], v[22:23], v[20:21], v[90:91] neg_lo:[0,0,1] neg_hi:[0,0,1]
	v_pk_fma_f32 v[20:21], v[22:23], v[20:21], v[90:91] op_sel_hi:[0,1,1]
	v_mov_b32_e32 v93, v21
	v_mov_b64_e32 v[20:21], v[232:233]
	s_waitcnt lgkmcnt(0)
	v_pk_mul_f32 v[22:23], v[20:21], v[18:19] op_sel:[1,1] op_sel_hi:[0,1]
	v_pk_fma_f32 v[90:91], v[20:21], v[18:19], v[22:23] neg_lo:[0,0,1] neg_hi:[0,0,1]
	v_pk_fma_f32 v[18:19], v[20:21], v[18:19], v[22:23] op_sel_hi:[1,0,1]
	s_nop 0
	v_mov_b32_e32 v91, v19
	v_mov_b64_e32 v[18:19], v[234:235]
	s_waitcnt lgkmcnt(0)
	v_pk_mul_f32 v[20:21], v[88:89], v[18:19] op_sel:[1,1] op_sel_hi:[1,0]
	s_nop 0
	v_pk_fma_f32 v[22:23], v[88:89], v[18:19], v[20:21] neg_lo:[0,0,1] neg_hi:[0,0,1]
	v_pk_fma_f32 v[18:19], v[88:89], v[18:19], v[20:21] op_sel_hi:[0,1,1]
	v_mov_b32_e32 v23, v19
	v_mov_b64_e32 v[18:19], v[236:237]
	s_waitcnt lgkmcnt(0)
	v_pk_mul_f32 v[20:21], v[18:19], v[16:17] op_sel:[1,1] op_sel_hi:[0,1]
	v_pk_fma_f32 v[88:89], v[18:19], v[16:17], v[20:21] neg_lo:[0,0,1] neg_hi:[0,0,1]
	v_pk_fma_f32 v[16:17], v[18:19], v[16:17], v[20:21] op_sel_hi:[1,0,1]
	s_nop 0
	v_mov_b32_e32 v89, v17
	ds_write2_b64 v191, v[86:87], v[98:99] offset1:72
	ds_write2_b64 v191, v[96:97], v[94:95] offset0:144 offset1:216
	ds_write2_b64 v192, v[92:93], v[90:91] offset0:32 offset1:104
	ds_write2_b64 v192, v[22:23], v[88:89] offset0:176 offset1:248
	s_waitcnt lgkmcnt(0)
	s_barrier
; __device__ __forceinline__ c2 cmul(c2 a, c2 b) { return (c2){a.x * b.x - a.y * b.y, a.x * b.y + a.y * b.x}; }
; template <int S> __device__ __forceinline__ void fwd_mid(c2* buf, const c2* tws, int tid) {
;     constexpr int lq = 9 - 3 * S, Q = 1 << lq; const c2* T = tws + (S == 1 ? 3584 : 4032);
;     const int k = tid & (Q - 1), base = ((tid >> lq) << (lq + 3)) + k;
;     c2 x[8];
;     c2* bp_ = buf + LP(base); constexpr int QP = Q + Q / 8;
; #pragma unroll
;     for (int r = 0; r < 8; ++r) x[r] = bp_[r * QP];
;     dft8(x);
; #pragma unroll
;     for (int q = 1; q < 8; ++q) x[q] = cmul(x[q], T[(q - 1) * Q + k]);
; #pragma unroll
;     for (int q = 0; q < 8; ++q) bp_[q * QP] = x[q];
; }
	ds_read2_b64 v[16:19], v119 offset1:9
	ds_read2_b64 v[20:23], v119 offset0:18 offset1:27
	ds_read2_b64 v[86:89], v119 offset0:36 offset1:45
	ds_read2_b64 v[90:93], v119 offset0:54 offset1:63
	s_waitcnt lgkmcnt(0)
	v_pk_add_f32 v[94:95], v[16:17], v[86:87]
	v_pk_add_f32 v[16:17], v[16:17], v[86:87] neg_lo:[0,1] neg_hi:[0,1]
	v_pk_add_f32 v[86:87], v[18:19], v[88:89]
	v_pk_add_f32 v[18:19], v[18:19], v[88:89] neg_lo:[0,1] neg_hi:[0,1]
	s_waitcnt lgkmcnt(0)
	v_pk_add_f32 v[88:89], v[20:21], v[90:91]
	v_pk_add_f32 v[20:21], v[20:21], v[90:91] neg_lo:[0,1] neg_hi:[0,1]
	v_pk_add_f32 v[90:91], v[22:23], v[92:93]
	v_pk_add_f32 v[22:23], v[22:23], v[92:93] neg_lo:[0,1] neg_hi:[0,1]
	v_pk_add_f32 v[92:93], v[18:19], v[18:19] op_sel:[1,0]
	v_pk_add_f32 v[18:19], v[18:19], v[18:19] op_sel_hi:[1,0] neg_lo:[0,1] neg_hi:[0,1]
	s_nop 0
	v_mov_b32_e32 v93, v19
	v_xor_b32_e32 v19, 0x80000000, v20
	v_mov_b32_e32 v18, v21
	v_pk_add_f32 v[20:21], v[22:23], v[22:23] op_sel:[1,0] neg_lo:[0,1] neg_hi:[0,1]
	v_pk_add_f32 v[22:23], v[22:23], v[22:23] op_sel_hi:[1,0]
	s_nop 0
	v_mov_b32_e32 v21, v23
	v_pk_add_f32 v[22:23], v[94:95], v[88:89]
	v_pk_add_f32 v[88:89], v[94:95], v[88:89] neg_lo:[0,1] neg_hi:[0,1]
	v_pk_add_f32 v[94:95], v[86:87], v[90:91]
	v_pk_add_f32 v[86:87], v[86:87], v[90:91] neg_lo:[0,1] neg_hi:[0,1]
	v_pk_mul_f32 v[20:21], v[20:21], s[20:21]
	v_xor_b32_e32 v91, 0x80000000, v86
	v_mov_b32_e32 v90, v87
	v_pk_add_f32 v[86:87], v[22:23], v[94:95]
	v_pk_add_f32 v[22:23], v[22:23], v[94:95] neg_lo:[0,1] neg_hi:[0,1]
	v_pk_add_f32 v[94:95], v[88:89], v[90:91]
	v_pk_add_f32 v[88:89], v[88:89], v[90:91] neg_lo:[0,1] neg_hi:[0,1]
	v_pk_add_f32 v[90:91], v[16:17], v[18:19]
	v_pk_add_f32 v[16:17], v[16:17], v[18:19] neg_lo:[0,1] neg_hi:[0,1]
	v_pk_fma_f32 v[18:19], v[92:93], s[20:21], v[20:21] op_sel_hi:[1,0,1]
	v_pk_fma_f32 v[20:21], v[92:93], s[20:21], v[20:21] op_sel_hi:[1,0,1] neg_lo:[0,0,1] neg_hi:[0,0,1]
	s_nop 0
	v_xor_b32_e32 v93, 0x80000000, v20
	v_mov_b32_e32 v92, v21
	v_pk_add_f32 v[20:21], v[90:91], v[18:19]
	v_pk_add_f32 v[18:19], v[90:91], v[18:19] neg_lo:[0,1] neg_hi:[0,1]
	v_pk_add_f32 v[90:91], v[16:17], v[92:93]
	v_pk_add_f32 v[16:17], v[16:17], v[92:93] neg_lo:[0,1] neg_hi:[0,1]
	v_mov_b64_e32 v[92:93], v[238:239]
	s_waitcnt lgkmcnt(0)
	v_pk_mul_f32 v[96:97], v[92:93], v[20:21] op_sel:[1,1] op_sel_hi:[0,1]
	v_pk_fma_f32 v[98:99], v[92:93], v[20:21], v[96:97] neg_lo:[0,0,1] neg_hi:[0,0,1]
	v_pk_fma_f32 v[20:21], v[92:93], v[20:21], v[96:97] op_sel_hi:[1,0,1]
	s_nop 0
	v_mov_b32_e32 v99, v21
	v_mov_b64_e32 v[20:21], v[240:241]
	s_waitcnt lgkmcnt(0)
	v_pk_mul_f32 v[92:93], v[20:21], v[94:95] op_sel:[1,1] op_sel_hi:[0,1]
	v_pk_fma_f32 v[96:97], v[20:21], v[94:95], v[92:93] neg_lo:[0,0,1] neg_hi:[0,0,1]
	v_pk_fma_f32 v[20:21], v[20:21], v[94:95], v[92:93] op_sel_hi:[1,0,1]
	s_nop 0
	v_mov_b32_e32 v97, v21
	v_mov_b64_e32 v[20:21], v[242:243]
	s_waitcnt lgkmcnt(0)
	v_pk_mul_f32 v[92:93], v[20:21], v[90:91] op_sel:[1,1] op_sel_hi:[0,1]
	v_pk_fma_f32 v[94:95], v[20:21], v[90:91], v[92:93] neg_lo:[0,0,1] neg_hi:[0,0,1]
	v_pk_fma_f32 v[20:21], v[20:21], v[90:91], v[92:93] op_sel_hi:[1,0,1]
	s_nop 0
	v_mov_b32_e32 v95, v21
	v_mov_b64_e32 v[20:21], v[244:245]
	s_waitcnt lgkmcnt(0)
	v_pk_mul_f32 v[90:91], v[22:23], v[20:21] op_sel:[1,1] op_sel_hi:[1,0]
	s_nop 0
	v_pk_fma_f32 v[92:93], v[22:23], v[20:21], v[90:91] neg_lo:[0,0,1] neg_hi:[0,0,1]
	v_pk_fma_f32 v[20:21], v[22:23], v[20:21], v[90:91] op_sel_hi:[0,1,1]
	v_mov_b32_e32 v93, v21
	v_mov_b64_e32 v[20:21], v[246:247]
	s_waitcnt lgkmcnt(0)
	v_pk_mul_f32 v[22:23], v[20:21], v[18:19] op_sel:[1,1] op_sel_hi:[0,1]
	v_pk_fma_f32 v[90:91], v[20:21], v[18:19], v[22:23] neg_lo:[0,0,1] neg_hi:[0,0,1]
	v_pk_fma_f32 v[18:19], v[20:21], v[18:19], v[22:23] op_sel_hi:[1,0,1]
	s_nop 0
	v_mov_b32_e32 v91, v19
	v_mov_b64_e32 v[18:19], v[248:249]
	s_waitcnt lgkmcnt(0)
	v_pk_mul_f32 v[20:21], v[88:89], v[18:19] op_sel:[1,1] op_sel_hi:[1,0]
	s_nop 0
	v_pk_fma_f32 v[22:23], v[88:89], v[18:19], v[20:21] neg_lo:[0,0,1] neg_hi:[0,0,1]
	v_pk_fma_f32 v[18:19], v[88:89], v[18:19], v[20:21] op_sel_hi:[0,1,1]
	v_mov_b32_e32 v23, v19
	v_mov_b64_e32 v[18:19], v[250:251]
	s_waitcnt lgkmcnt(0)
	v_pk_mul_f32 v[20:21], v[18:19], v[16:17] op_sel:[1,1] op_sel_hi:[0,1]
	v_pk_fma_f32 v[88:89], v[18:19], v[16:17], v[20:21] neg_lo:[0,0,1] neg_hi:[0,0,1]
	v_pk_fma_f32 v[16:17], v[18:19], v[16:17], v[20:21] op_sel_hi:[1,0,1]
	s_nop 0
	v_mov_b32_e32 v89, v17
	ds_write2_b64 v119, v[86:87], v[98:99] offset1:9
	ds_write2_b64 v119, v[96:97], v[94:95] offset0:18 offset1:27
	ds_write2_b64 v119, v[92:93], v[90:91] offset0:36 offset1:45
	ds_write2_b64 v119, v[22:23], v[88:89] offset0:54 offset1:63
	ds_read2_b64 v[16:19], v193 offset1:9
	ds_read2_b64 v[20:23], v193 offset0:18 offset1:27
	ds_read2_b64 v[86:89], v193 offset0:36 offset1:45
	ds_read2_b64 v[90:93], v193 offset0:54 offset1:63
	s_waitcnt lgkmcnt(0)
	v_pk_add_f32 v[94:95], v[16:17], v[86:87]
	v_pk_add_f32 v[16:17], v[16:17], v[86:87] neg_lo:[0,1] neg_hi:[0,1]
	v_pk_add_f32 v[86:87], v[18:19], v[88:89]
	v_pk_add_f32 v[18:19], v[18:19], v[88:89] neg_lo:[0,1] neg_hi:[0,1]
	s_waitcnt lgkmcnt(0)
; __device__ __forceinline__ c2 cmul(c2 a, c2 b) { return (c2){a.x * b.x - a.y * b.y, a.x * b.y + a.y * b.x}; }
; template <int S> __device__ __forceinline__ void fwd_mid(c2* buf, const c2* tws, int tid) {
;     constexpr int lq = 9 - 3 * S, Q = 1 << lq; const c2* T = tws + (S == 1 ? 3584 : 4032);
;     const int k = tid & (Q - 1), base = ((tid >> lq) << (lq + 3)) + k;
;     c2 x[8];
;     c2* bp_ = buf + LP(base); constexpr int QP = Q + Q / 8;
; #pragma unroll
;     for (int r = 0; r < 8; ++r) x[r] = bp_[r * QP];
;     dft8(x);
; #pragma unroll
;     for (int q = 1; q < 8; ++q) x[q] = cmul(x[q], T[(q - 1) * Q + k]);
; #pragma unroll
;     for (int q = 0; q < 8; ++q) bp_[q * QP] = x[q];
; }
	v_pk_add_f32 v[88:89], v[20:21], v[90:91]
	v_pk_add_f32 v[20:21], v[20:21], v[90:91] neg_lo:[0,1] neg_hi:[0,1]
	v_pk_add_f32 v[90:91], v[22:23], v[92:93]
	v_pk_add_f32 v[22:23], v[22:23], v[92:93] neg_lo:[0,1] neg_hi:[0,1]
	v_pk_add_f32 v[92:93], v[18:19], v[18:19] op_sel:[1,0]
	v_pk_add_f32 v[18:19], v[18:19], v[18:19] op_sel_hi:[1,0] neg_lo:[0,1] neg_hi:[0,1]
	s_nop 0
	v_mov_b32_e32 v93, v19
	v_xor_b32_e32 v19, 0x80000000, v20
	v_mov_b32_e32 v18, v21
	v_pk_add_f32 v[20:21], v[22:23], v[22:23] op_sel:[1,0] neg_lo:[0,1] neg_hi:[0,1]
	v_pk_add_f32 v[22:23], v[22:23], v[22:23] op_sel_hi:[1,0]
	s_nop 0
	v_mov_b32_e32 v21, v23
	v_pk_add_f32 v[22:23], v[94:95], v[88:89]
	v_pk_add_f32 v[88:89], v[94:95], v[88:89] neg_lo:[0,1] neg_hi:[0,1]
	v_pk_add_f32 v[94:95], v[86:87], v[90:91]
	v_pk_add_f32 v[86:87], v[86:87], v[90:91] neg_lo:[0,1] neg_hi:[0,1]
	v_pk_mul_f32 v[20:21], v[20:21], s[20:21]
	v_xor_b32_e32 v91, 0x80000000, v86
	v_mov_b32_e32 v90, v87
	v_pk_add_f32 v[86:87], v[22:23], v[94:95]
	v_pk_add_f32 v[22:23], v[22:23], v[94:95] neg_lo:[0,1] neg_hi:[0,1]
	v_pk_add_f32 v[94:95], v[88:89], v[90:91]
	v_pk_add_f32 v[88:89], v[88:89], v[90:91] neg_lo:[0,1] neg_hi:[0,1]
	v_pk_add_f32 v[90:91], v[16:17], v[18:19]
	v_pk_add_f32 v[16:17], v[16:17], v[18:19] neg_lo:[0,1] neg_hi:[0,1]
	v_pk_fma_f32 v[18:19], v[92:93], s[20:21], v[20:21] op_sel_hi:[1,0,1]
	v_pk_fma_f32 v[20:21], v[92:93], s[20:21], v[20:21] op_sel_hi:[1,0,1] neg_lo:[0,0,1] neg_hi:[0,0,1]
	s_nop 0
	v_xor_b32_e32 v93, 0x80000000, v20
	v_mov_b32_e32 v92, v21
	v_pk_add_f32 v[20:21], v[90:91], v[18:19]
	v_pk_add_f32 v[18:19], v[90:91], v[18:19] neg_lo:[0,1] neg_hi:[0,1]
	v_pk_add_f32 v[90:91], v[16:17], v[92:93]
	v_pk_add_f32 v[16:17], v[16:17], v[92:93] neg_lo:[0,1] neg_hi:[0,1]
	v_mov_b64_e32 v[92:93], v[238:239]
	s_waitcnt lgkmcnt(0)
	v_pk_mul_f32 v[96:97], v[92:93], v[20:21] op_sel:[1,1] op_sel_hi:[0,1]
	v_pk_fma_f32 v[98:99], v[92:93], v[20:21], v[96:97] neg_lo:[0,0,1] neg_hi:[0,0,1]
	v_pk_fma_f32 v[20:21], v[92:93], v[20:21], v[96:97] op_sel_hi:[1,0,1]
	s_nop 0
	v_mov_b32_e32 v99, v21
	v_mov_b64_e32 v[20:21], v[240:241]
	s_waitcnt lgkmcnt(0)
	v_pk_mul_f32 v[92:93], v[20:21], v[94:95] op_sel:[1,1] op_sel_hi:[0,1]
	v_pk_fma_f32 v[96:97], v[20:21], v[94:95], v[92:93] neg_lo:[0,0,1] neg_hi:[0,0,1]
	v_pk_fma_f32 v[20:21], v[20:21], v[94:95], v[92:93] op_sel_hi:[1,0,1]
	s_nop 0
	v_mov_b32_e32 v97, v21
	v_mov_b64_e32 v[20:21], v[242:243]
	s_waitcnt lgkmcnt(0)
	v_pk_mul_f32 v[92:93], v[20:21], v[90:91] op_sel:[1,1] op_sel_hi:[0,1]
	v_pk_fma_f32 v[94:95], v[20:21], v[90:91], v[92:93] neg_lo:[0,0,1] neg_hi:[0,0,1]
	v_pk_fma_f32 v[20:21], v[20:21], v[90:91], v[92:93] op_sel_hi:[1,0,1]
	s_nop 0
	v_mov_b32_e32 v95, v21
	v_mov_b64_e32 v[20:21], v[244:245]
	s_waitcnt lgkmcnt(0)
	v_pk_mul_f32 v[90:91], v[22:23], v[20:21] op_sel:[1,1] op_sel_hi:[1,0]
	s_nop 0
	v_pk_fma_f32 v[92:93], v[22:23], v[20:21], v[90:91] neg_lo:[0,0,1] neg_hi:[0,0,1]
	v_pk_fma_f32 v[20:21], v[22:23], v[20:21], v[90:91] op_sel_hi:[0,1,1]
	v_mov_b32_e32 v93, v21
	v_mov_b64_e32 v[20:21], v[246:247]
	s_waitcnt lgkmcnt(0)
	v_pk_mul_f32 v[22:23], v[20:21], v[18:19] op_sel:[1,1] op_sel_hi:[0,1]
	v_pk_fma_f32 v[90:91], v[20:21], v[18:19], v[22:23] neg_lo:[0,0,1] neg_hi:[0,0,1]
	v_pk_fma_f32 v[18:19], v[20:21], v[18:19], v[22:23] op_sel_hi:[1,0,1]
	s_nop 0
	v_mov_b32_e32 v91, v19
	v_mov_b64_e32 v[18:19], v[248:249]
	s_waitcnt lgkmcnt(0)
	v_pk_mul_f32 v[20:21], v[88:89], v[18:19] op_sel:[1,1] op_sel_hi:[1,0]
	s_nop 0
	v_pk_fma_f32 v[22:23], v[88:89], v[18:19], v[20:21] neg_lo:[0,0,1] neg_hi:[0,0,1]
	v_pk_fma_f32 v[18:19], v[88:89], v[18:19], v[20:21] op_sel_hi:[0,1,1]
	v_mov_b32_e32 v23, v19
	v_mov_b64_e32 v[18:19], v[250:251]
	s_waitcnt lgkmcnt(0)
	v_pk_mul_f32 v[20:21], v[18:19], v[16:17] op_sel:[1,1] op_sel_hi:[0,1]
	v_pk_fma_f32 v[88:89], v[18:19], v[16:17], v[20:21] neg_lo:[0,0,1] neg_hi:[0,0,1]
	v_pk_fma_f32 v[16:17], v[18:19], v[16:17], v[20:21] op_sel_hi:[1,0,1]
	s_nop 0
	v_mov_b32_e32 v89, v17
	ds_write2_b64 v193, v[86:87], v[98:99] offset1:9
	ds_write2_b64 v193, v[96:97], v[94:95] offset0:18 offset1:27
	ds_write2_b64 v193, v[92:93], v[90:91] offset0:36 offset1:45
	ds_write2_b64 v193, v[22:23], v[88:89] offset0:54 offset1:63
	s_waitcnt lgkmcnt(0)
	s_barrier
; __device__ __forceinline__ c2 cmul(c2 a, c2 b) { return (c2){a.x * b.x - a.y * b.y, a.x * b.y + a.y * b.x}; }
; __device__ __forceinline__ void fwd_s3(c2 (&x)[8], const c2* buf, int tid) {
; #pragma unroll
;     for (int r = 0; r < 8; ++r) x[r] = buf[9 * tid + r];
;     dft8(x);
; }
; __device__ __forceinline__ void phase_conv(const Params& p, int o, unsigned char* smem, int wave) {
;     ...
;                 for (int q = 0; q < 8; ++q) { x0[q] = cmul(x0[q], K[q]); x1[q] = cmul(x1[q], K[q]); }
	ds_read2_b64 v[16:19], v121 offset1:1
	ds_read2_b64 v[20:23], v121 offset0:2 offset1:3
	ds_read2_b64 v[86:89], v121 offset0:4 offset1:5
	ds_read2_b64 v[90:93], v121 offset0:6 offset1:7
	s_waitcnt lgkmcnt(0)
	v_pk_add_f32 v[94:95], v[16:17], v[86:87]
	v_pk_add_f32 v[16:17], v[16:17], v[86:87] neg_lo:[0,1] neg_hi:[0,1]
	v_pk_add_f32 v[86:87], v[18:19], v[88:89]
	v_pk_add_f32 v[18:19], v[18:19], v[88:89] neg_lo:[0,1] neg_hi:[0,1]
	s_waitcnt lgkmcnt(0)
	v_pk_add_f32 v[88:89], v[20:21], v[90:91]
	v_pk_add_f32 v[20:21], v[20:21], v[90:91] neg_lo:[0,1] neg_hi:[0,1]
	v_pk_add_f32 v[90:91], v[22:23], v[92:93]
	v_pk_add_f32 v[22:23], v[22:23], v[92:93] neg_lo:[0,1] neg_hi:[0,1]
	v_pk_add_f32 v[92:93], v[18:19], v[18:19] op_sel:[1,0]
	v_pk_add_f32 v[18:19], v[18:19], v[18:19] op_sel_hi:[1,0] neg_lo:[0,1] neg_hi:[0,1]
	s_nop 0
	v_mov_b32_e32 v93, v19
	v_xor_b32_e32 v19, 0x80000000, v20
	v_mov_b32_e32 v18, v21
	v_pk_add_f32 v[20:21], v[22:23], v[22:23] op_sel:[1,0] neg_lo:[0,1] neg_hi:[0,1]
	v_pk_add_f32 v[22:23], v[22:23], v[22:23] op_sel_hi:[1,0]
	s_nop 0
	v_mov_b32_e32 v21, v23
	v_pk_mul_f32 v[20:21], v[20:21], s[20:21]
	v_pk_add_f32 v[22:23], v[94:95], v[88:89]
	v_pk_add_f32 v[88:89], v[94:95], v[88:89] neg_lo:[0,1] neg_hi:[0,1]
	v_pk_add_f32 v[94:95], v[86:87], v[90:91]
	v_pk_add_f32 v[86:87], v[86:87], v[90:91] neg_lo:[0,1] neg_hi:[0,1]
	v_pk_add_f32 v[96:97], v[22:23], v[94:95]
	v_pk_add_f32 v[94:95], v[22:23], v[94:95] neg_lo:[0,1] neg_hi:[0,1]
	v_pk_add_f32 v[22:23], v[16:17], v[18:19]
	v_pk_add_f32 v[16:17], v[16:17], v[18:19] neg_lo:[0,1] neg_hi:[0,1]
	v_pk_fma_f32 v[18:19], v[92:93], s[20:21], v[20:21] op_sel_hi:[1,0,1]
	v_pk_fma_f32 v[20:21], v[92:93], s[20:21], v[20:21] op_sel_hi:[1,0,1] neg_lo:[0,0,1] neg_hi:[0,0,1]
	v_xor_b32_e32 v91, 0x80000000, v86
	v_mov_b32_e32 v90, v87
	v_xor_b32_e32 v87, 0x80000000, v20
	v_mov_b32_e32 v86, v21
	v_pk_add_f32 v[98:99], v[88:89], v[90:91]
	v_pk_add_f32 v[100:101], v[88:89], v[90:91] neg_lo:[0,1] neg_hi:[0,1]
	v_pk_add_f32 v[102:103], v[22:23], v[18:19]
	v_pk_add_f32 v[194:195], v[22:23], v[18:19] neg_lo:[0,1] neg_hi:[0,1]
	v_pk_add_f32 v[196:197], v[16:17], v[86:87]
	v_pk_add_f32 v[198:199], v[16:17], v[86:87] neg_lo:[0,1] neg_hi:[0,1]
	ds_read2_b64 v[16:19], v63 offset1:1
	ds_read2_b64 v[20:23], v204 offset1:1
	ds_read2_b64 v[86:89], v205 offset1:1
	ds_read2_b64 v[90:93], v206 offset1:1
	s_waitcnt lgkmcnt(0)
	v_pk_add_f32 v[200:201], v[16:17], v[86:87]
	v_pk_add_f32 v[16:17], v[16:17], v[86:87] neg_lo:[0,1] neg_hi:[0,1]
	v_pk_add_f32 v[86:87], v[18:19], v[88:89]
	v_pk_add_f32 v[18:19], v[18:19], v[88:89] neg_lo:[0,1] neg_hi:[0,1]
	s_waitcnt lgkmcnt(0)
	v_pk_add_f32 v[88:89], v[20:21], v[90:91]
	v_pk_add_f32 v[20:21], v[20:21], v[90:91] neg_lo:[0,1] neg_hi:[0,1]
	v_pk_add_f32 v[90:91], v[22:23], v[92:93]
	v_pk_add_f32 v[22:23], v[22:23], v[92:93] neg_lo:[0,1] neg_hi:[0,1]
	v_pk_add_f32 v[92:93], v[18:19], v[18:19] op_sel:[1,0]
	v_pk_add_f32 v[18:19], v[18:19], v[18:19] op_sel_hi:[1,0] neg_lo:[0,1] neg_hi:[0,1]
	s_nop 0
	v_mov_b32_e32 v93, v19
	v_xor_b32_e32 v19, 0x80000000, v20
	v_mov_b32_e32 v18, v21
	v_pk_add_f32 v[20:21], v[22:23], v[22:23] op_sel:[1,0] neg_lo:[0,1] neg_hi:[0,1]
	v_pk_add_f32 v[22:23], v[22:23], v[22:23] op_sel_hi:[1,0]
	s_nop 0
	v_mov_b32_e32 v21, v23
	v_pk_add_f32 v[22:23], v[200:201], v[88:89]
	v_pk_add_f32 v[88:89], v[200:201], v[88:89] neg_lo:[0,1] neg_hi:[0,1]
	v_pk_add_f32 v[200:201], v[86:87], v[90:91]
	v_pk_add_f32 v[86:87], v[86:87], v[90:91] neg_lo:[0,1] neg_hi:[0,1]
	v_pk_mul_f32 v[20:21], v[20:21], s[20:21]
	v_xor_b32_e32 v91, 0x80000000, v86
	v_mov_b32_e32 v90, v87
	v_pk_add_f32 v[86:87], v[22:23], v[200:201]
	v_pk_add_f32 v[22:23], v[22:23], v[200:201] neg_lo:[0,1] neg_hi:[0,1]
	v_pk_add_f32 v[200:201], v[88:89], v[90:91]
	v_pk_add_f32 v[88:89], v[88:89], v[90:91] neg_lo:[0,1] neg_hi:[0,1]
	v_pk_add_f32 v[90:91], v[16:17], v[18:19]
	v_pk_add_f32 v[16:17], v[16:17], v[18:19] neg_lo:[0,1] neg_hi:[0,1]
	v_pk_fma_f32 v[18:19], v[92:93], s[20:21], v[20:21] op_sel_hi:[1,0,1]
	v_pk_fma_f32 v[20:21], v[92:93], s[20:21], v[20:21] op_sel_hi:[1,0,1] neg_lo:[0,0,1] neg_hi:[0,0,1]
	s_nop 0
	v_xor_b32_e32 v93, 0x80000000, v20
	v_mov_b32_e32 v92, v21
	v_pk_add_f32 v[20:21], v[90:91], v[18:19]
	v_pk_add_f32 v[18:19], v[90:91], v[18:19] neg_lo:[0,1] neg_hi:[0,1]
	v_pk_add_f32 v[90:91], v[16:17], v[92:93]
	v_pk_add_f32 v[16:17], v[16:17], v[92:93] neg_lo:[0,1] neg_hi:[0,1]
	v_pk_mul_f32 v[92:93], v[40:41], v[96:97] op_sel:[0,1]
	s_nop 0
	v_pk_fma_f32 v[202:203], v[24:25], v[96:97], v[92:93] neg_lo:[0,0,1] neg_hi:[0,0,1]
	v_pk_fma_f32 v[92:93], v[24:25], v[96:97], v[92:93] op_sel_hi:[1,0,1]
	s_nop 0
	v_mov_b32_e32 v203, v93
	v_pk_mul_f32 v[92:93], v[40:41], v[86:87] op_sel:[0,1]
	s_nop 0
	v_pk_fma_f32 v[96:97], v[24:25], v[86:87], v[92:93] neg_lo:[0,0,1] neg_hi:[0,0,1]
	v_pk_fma_f32 v[86:87], v[24:25], v[86:87], v[92:93] op_sel_hi:[1,0,1]
	s_nop 0
	v_mov_b32_e32 v97, v87
	v_pk_mul_f32 v[86:87], v[42:43], v[102:103] op_sel:[0,1]
	s_nop 0
	v_pk_fma_f32 v[92:93], v[32:33], v[102:103], v[86:87] neg_lo:[0,0,1] neg_hi:[0,0,1]
	v_pk_fma_f32 v[86:87], v[32:33], v[102:103], v[86:87] op_sel_hi:[1,0,1]
	s_nop 0
	v_mov_b32_e32 v93, v87
	v_pk_mul_f32 v[86:87], v[42:43], v[20:21] op_sel:[0,1]
	s_nop 0
	v_pk_fma_f32 v[102:103], v[32:33], v[20:21], v[86:87] neg_lo:[0,0,1] neg_hi:[0,0,1]
	v_pk_fma_f32 v[20:21], v[32:33], v[20:21], v[86:87] op_sel_hi:[1,0,1]
	s_nop 0
	v_mov_b32_e32 v103, v21
	v_pk_mul_f32 v[20:21], v[44:45], v[98:99] op_sel:[0,1]
	s_nop 0
	v_pk_fma_f32 v[86:87], v[28:29], v[98:99], v[20:21] neg_lo:[0,0,1] neg_hi:[0,0,1]
	v_pk_fma_f32 v[20:21], v[28:29], v[98:99], v[20:21] op_sel_hi:[1,0,1]
; __device__ __forceinline__ c2 cmul(c2 a, c2 b) { return (c2){a.x * b.x - a.y * b.y, a.x * b.y + a.y * b.x}; }
; __device__ __forceinline__ c2 mpi(c2 a) { return (c2){-a.y, a.x}; }
; __device__ __forceinline__ void idft8(c2 (&x)[8]) {
;     const float s = 0.70710678118654752f;
;     const c2 a0 = x[0] + x[4], a4 = x[0] - x[4], a1 = x[1] + x[5], a5 = x[1] - x[5], a2 = x[2] + x[6], a6 = x[2] - x[6], a3 = x[3] + x[7], a7 = x[3] - x[7];
;     const c2 a5w = (c2){(a5.x - a5.y) * s, (a5.x + a5.y) * s};
;     const c2 a6w = mpi(a6);
;     const c2 a7w = (c2){-(a7.x + a7.y) * s, (a7.x - a7.y) * s};
;     const c2 b0 = a0 + a2, b1 = a0 - a2, b2 = a1 + a3, b3 = mpi(a1 - a3);
;     x[0] = b0 + b2; x[4] = b0 - b2; x[2] = b1 + b3; x[6] = b1 - b3;
;     const c2 c0 = a4 + a6w, c1 = a4 - a6w, c2_ = a5w + a7w, c3 = mpi(a5w - a7w);
;     x[1] = c0 + c2_; x[5] = c0 - c2_; x[3] = c1 + c3; x[7] = c1 - c3;
; }
; __device__ __forceinline__ void phase_conv(const Params& p, int o, unsigned char* smem, int wave) {
;     ...
;                 for (int q = 0; q < 8; ++q) { x0[q] = cmul(x0[q], K[q]); x1[q] = cmul(x1[q], K[q]); }
	s_nop 0
	v_mov_b32_e32 v87, v21
	v_pk_mul_f32 v[20:21], v[44:45], v[200:201] op_sel:[0,1]
	s_nop 0
	v_pk_fma_f32 v[98:99], v[28:29], v[200:201], v[20:21] neg_lo:[0,0,1] neg_hi:[0,0,1]
	v_pk_fma_f32 v[20:21], v[28:29], v[200:201], v[20:21] op_sel_hi:[1,0,1]
	s_nop 0
	v_mov_b32_e32 v99, v21
	v_pk_mul_f32 v[20:21], v[46:47], v[196:197] op_sel:[0,1]
	s_nop 0
	v_pk_fma_f32 v[200:201], v[36:37], v[196:197], v[20:21] neg_lo:[0,0,1] neg_hi:[0,0,1]
	v_pk_fma_f32 v[20:21], v[36:37], v[196:197], v[20:21] op_sel_hi:[1,0,1]
	s_nop 0
	v_mov_b32_e32 v201, v21
	v_pk_mul_f32 v[20:21], v[46:47], v[90:91] op_sel:[0,1]
	s_nop 0
	v_pk_fma_f32 v[196:197], v[36:37], v[90:91], v[20:21] neg_lo:[0,0,1] neg_hi:[0,0,1]
	v_pk_fma_f32 v[20:21], v[36:37], v[90:91], v[20:21] op_sel_hi:[1,0,1]
	s_nop 0
	v_mov_b32_e32 v197, v21
	v_pk_mul_f32 v[20:21], v[48:49], v[94:95] op_sel:[0,1]
	s_nop 0
	v_pk_fma_f32 v[90:91], v[26:27], v[94:95], v[20:21] neg_lo:[0,0,1] neg_hi:[0,0,1]
	v_pk_fma_f32 v[20:21], v[26:27], v[94:95], v[20:21] op_sel_hi:[1,0,1]
	s_nop 0
	v_mov_b32_e32 v91, v21
	v_pk_mul_f32 v[20:21], v[48:49], v[22:23] op_sel:[0,1]
	s_nop 0
	v_pk_fma_f32 v[94:95], v[26:27], v[22:23], v[20:21] neg_lo:[0,0,1] neg_hi:[0,0,1]
	v_pk_fma_f32 v[20:21], v[26:27], v[22:23], v[20:21] op_sel_hi:[1,0,1]
	s_nop 0
	v_mov_b32_e32 v95, v21
	v_pk_mul_f32 v[20:21], v[50:51], v[194:195] op_sel:[0,1]
	s_nop 0
	v_pk_fma_f32 v[22:23], v[34:35], v[194:195], v[20:21] neg_lo:[0,0,1] neg_hi:[0,0,1]
	v_pk_fma_f32 v[20:21], v[34:35], v[194:195], v[20:21] op_sel_hi:[1,0,1]
	s_nop 0
	v_mov_b32_e32 v23, v21
	v_pk_mul_f32 v[20:21], v[50:51], v[18:19] op_sel:[0,1]
	s_nop 0
	v_pk_fma_f32 v[194:195], v[34:35], v[18:19], v[20:21] neg_lo:[0,0,1] neg_hi:[0,0,1]
	v_pk_fma_f32 v[18:19], v[34:35], v[18:19], v[20:21] op_sel_hi:[1,0,1]
	s_nop 0
	v_mov_b32_e32 v195, v19
	v_pk_mul_f32 v[18:19], v[52:53], v[100:101] op_sel:[0,1]
	s_nop 0
	v_pk_fma_f32 v[20:21], v[30:31], v[100:101], v[18:19] neg_lo:[0,0,1] neg_hi:[0,0,1]
	v_pk_fma_f32 v[18:19], v[30:31], v[100:101], v[18:19] op_sel_hi:[1,0,1]
	s_nop 0
	v_mov_b32_e32 v21, v19
	v_pk_mul_f32 v[18:19], v[52:53], v[88:89] op_sel:[0,1]
	s_nop 0
	v_pk_fma_f32 v[100:101], v[30:31], v[88:89], v[18:19] neg_lo:[0,0,1] neg_hi:[0,0,1]
	v_pk_fma_f32 v[18:19], v[30:31], v[88:89], v[18:19] op_sel_hi:[1,0,1]
	s_nop 0
	v_mov_b32_e32 v101, v19
	v_pk_mul_f32 v[18:19], v[54:55], v[198:199] op_sel:[0,1]
	s_nop 0
	v_pk_fma_f32 v[88:89], v[38:39], v[198:199], v[18:19] neg_lo:[0,0,1] neg_hi:[0,0,1]
	v_pk_fma_f32 v[18:19], v[38:39], v[198:199], v[18:19] op_sel_hi:[1,0,1]
	s_nop 0
	v_mov_b32_e32 v89, v19
	v_pk_mul_f32 v[18:19], v[54:55], v[16:17] op_sel:[0,1]
	s_nop 0
	v_pk_fma_f32 v[198:199], v[38:39], v[16:17], v[18:19] neg_lo:[0,0,1] neg_hi:[0,0,1]
	v_pk_fma_f32 v[16:17], v[38:39], v[16:17], v[18:19] op_sel_hi:[1,0,1]
	v_pk_add_f32 v[18:19], v[202:203], v[90:91] neg_lo:[0,1] neg_hi:[0,1]
	v_mov_b32_e32 v199, v17
	v_pk_add_f32 v[16:17], v[202:203], v[90:91]
	v_pk_add_f32 v[90:91], v[92:93], v[22:23]
	v_pk_add_f32 v[22:23], v[92:93], v[22:23] neg_lo:[0,1] neg_hi:[0,1]
	v_pk_add_f32 v[92:93], v[86:87], v[20:21]
	v_pk_add_f32 v[20:21], v[86:87], v[20:21] neg_lo:[0,1] neg_hi:[0,1]
	v_pk_add_f32 v[86:87], v[200:201], v[88:89]
	v_pk_add_f32 v[88:89], v[200:201], v[88:89] neg_lo:[0,1] neg_hi:[0,1]
	v_pk_add_f32 v[200:201], v[22:23], v[22:23] op_sel:[0,1] neg_lo:[0,1] neg_hi:[0,1]
	v_pk_add_f32 v[22:23], v[22:23], v[22:23] op_sel_hi:[0,1]
	v_mov_b32_e32 v201, v23
	v_xor_b32_e32 v22, 0x80000000, v21
	v_mov_b32_e32 v23, v20
	v_pk_add_f32 v[20:21], v[88:89], v[88:89] op_sel:[0,1]
	v_pk_add_f32 v[88:89], v[88:89], v[88:89] op_sel_hi:[0,1] neg_lo:[0,1] neg_hi:[0,1]
	v_mov_b32_e32 v21, v89
	v_pk_add_f32 v[88:89], v[16:17], v[92:93]
	v_pk_add_f32 v[16:17], v[16:17], v[92:93] neg_lo:[0,1] neg_hi:[0,1]
	v_pk_add_f32 v[92:93], v[90:91], v[86:87]
	v_pk_add_f32 v[86:87], v[90:91], v[86:87] neg_lo:[0,1] neg_hi:[0,1]
	v_pk_mul_f32 v[20:21], v[20:21], s[84:85]
	v_xor_b32_e32 v90, 0x80000000, v87
	v_mov_b32_e32 v91, v86
	v_pk_add_f32 v[86:87], v[88:89], v[92:93]
	v_pk_add_f32 v[88:89], v[88:89], v[92:93] neg_lo:[0,1] neg_hi:[0,1]
	v_pk_add_f32 v[92:93], v[16:17], v[90:91]
	v_pk_add_f32 v[16:17], v[16:17], v[90:91] neg_lo:[0,1] neg_hi:[0,1]
	v_pk_add_f32 v[90:91], v[18:19], v[22:23]
	v_pk_add_f32 v[18:19], v[18:19], v[22:23] neg_lo:[0,1] neg_hi:[0,1]
	v_pk_fma_f32 v[22:23], v[200:201], s[20:21], v[20:21] op_sel_hi:[1,0,1]
	v_pk_fma_f32 v[20:21], v[200:201], s[20:21], v[20:21] op_sel_hi:[1,0,1] neg_lo:[0,0,1] neg_hi:[0,0,1]
	s_nop 0
	v_xor_b32_e32 v200, 0x80000000, v21
	v_mov_b32_e32 v201, v20
	v_pk_add_f32 v[20:21], v[90:91], v[22:23]
	v_pk_add_f32 v[22:23], v[90:91], v[22:23] neg_lo:[0,1] neg_hi:[0,1]
	v_pk_add_f32 v[90:91], v[18:19], v[200:201]
	v_pk_add_f32 v[18:19], v[18:19], v[200:201] neg_lo:[0,1] neg_hi:[0,1]
	ds_write2_b64 v121, v[86:87], v[20:21] offset1:1
	ds_write2_b64 v121, v[92:93], v[90:91] offset0:2 offset1:3
	ds_write2_b64 v121, v[88:89], v[22:23] offset0:4 offset1:5
	ds_write2_b64 v121, v[16:17], v[18:19] offset0:6 offset1:7
	v_pk_add_f32 v[22:23], v[102:103], v[194:195] neg_lo:[0,1] neg_hi:[0,1]
	v_pk_add_f32 v[16:17], v[96:97], v[94:95]
	v_pk_add_f32 v[18:19], v[96:97], v[94:95] neg_lo:[0,1] neg_hi:[0,1]
	v_pk_add_f32 v[88:89], v[98:99], v[100:101] neg_lo:[0,1] neg_hi:[0,1]
	v_pk_add_f32 v[92:93], v[196:197], v[198:199] neg_lo:[0,1] neg_hi:[0,1]
	v_pk_add_f32 v[94:95], v[22:23], v[22:23] op_sel:[0,1] neg_lo:[0,1] neg_hi:[0,1]
	v_pk_add_f32 v[22:23], v[22:23], v[22:23] op_sel_hi:[0,1]
	v_pk_add_f32 v[20:21], v[102:103], v[194:195]
	v_pk_add_f32 v[86:87], v[98:99], v[100:101]
; __device__ __forceinline__ c2 cmulc(c2 a, c2 b) { return (c2){a.x * b.x + a.y * b.y, a.y * b.x - a.x * b.y}; }
; __device__ __forceinline__ void inv_s3(c2 (&x)[8], c2* buf, int tid) {
;     idft8(x);
; #pragma unroll
;     for (int q = 0; q < 8; ++q) buf[9 * tid + q] = x[q];
; }
; template <int S> __device__ __forceinline__ void inv_mid(c2* buf, const c2* tws, int tid) {
;     constexpr int lq = 9 - 3 * S, Q = 1 << lq; const c2* T = tws + (S == 1 ? 3584 : 4032);
;     const int k = tid & (Q - 1), base = ((tid >> lq) << (lq + 3)) + k;
;     c2 x[8];
;     c2* bp_ = buf + LP(base); constexpr int QP = Q + Q / 8;
; #pragma unroll
;     for (int r = 0; r < 8; ++r) { c2 v = bp_[r * QP]; if (r) v = cmulc(v, T[(r - 1) * Q + k]); x[r] = v; }
;     idft8(x);
; #pragma unroll
;     for (int q = 0; q < 8; ++q) bp_[q * QP] = x[q];
; }
	v_pk_add_f32 v[90:91], v[196:197], v[198:199]
	v_mov_b32_e32 v95, v23
	v_xor_b32_e32 v22, 0x80000000, v89
	v_mov_b32_e32 v23, v88
	v_pk_add_f32 v[88:89], v[92:93], v[92:93] op_sel:[0,1]
	v_pk_add_f32 v[92:93], v[92:93], v[92:93] op_sel_hi:[0,1] neg_lo:[0,1] neg_hi:[0,1]
	v_mov_b32_e32 v89, v93
	v_pk_add_f32 v[92:93], v[16:17], v[86:87]
	v_pk_add_f32 v[16:17], v[16:17], v[86:87] neg_lo:[0,1] neg_hi:[0,1]
	v_pk_add_f32 v[86:87], v[20:21], v[90:91]
	v_pk_add_f32 v[20:21], v[20:21], v[90:91] neg_lo:[0,1] neg_hi:[0,1]
	v_pk_mul_f32 v[88:89], v[88:89], s[84:85]
	v_xor_b32_e32 v90, 0x80000000, v21
	v_mov_b32_e32 v91, v20
	v_pk_add_f32 v[20:21], v[92:93], v[86:87]
	v_pk_add_f32 v[86:87], v[92:93], v[86:87] neg_lo:[0,1] neg_hi:[0,1]
	v_pk_add_f32 v[92:93], v[16:17], v[90:91]
	v_pk_add_f32 v[16:17], v[16:17], v[90:91] neg_lo:[0,1] neg_hi:[0,1]
	v_pk_add_f32 v[90:91], v[18:19], v[22:23]
	v_pk_add_f32 v[18:19], v[18:19], v[22:23] neg_lo:[0,1] neg_hi:[0,1]
	v_pk_fma_f32 v[22:23], v[94:95], s[20:21], v[88:89] op_sel_hi:[1,0,1]
	v_pk_fma_f32 v[88:89], v[94:95], s[20:21], v[88:89] op_sel_hi:[1,0,1] neg_lo:[0,0,1] neg_hi:[0,0,1]
	s_nop 0
	v_xor_b32_e32 v94, 0x80000000, v89
	v_mov_b32_e32 v95, v88
	v_pk_add_f32 v[88:89], v[90:91], v[22:23]
	v_pk_add_f32 v[22:23], v[90:91], v[22:23] neg_lo:[0,1] neg_hi:[0,1]
	v_pk_add_f32 v[90:91], v[18:19], v[94:95]
	v_pk_add_f32 v[18:19], v[18:19], v[94:95] neg_lo:[0,1] neg_hi:[0,1]
	ds_write2_b64 v63, v[20:21], v[88:89] offset1:1
	ds_write2_b64 v204, v[92:93], v[90:91] offset1:1
	ds_write2_b64 v205, v[86:87], v[22:23] offset1:1
	ds_write2_b64 v206, v[16:17], v[18:19] offset1:1
	s_waitcnt lgkmcnt(0)
	s_barrier
	ds_read2_b64 v[16:19], v119 offset1:9
	v_mov_b64_e32 v[94:95], v[238:239]
	ds_read2_b64 v[20:23], v119 offset0:18 offset1:27
	v_mov_b64_e32 v[96:97], v[240:241]
	v_mov_b64_e32 v[98:99], v[242:243]
	ds_read2_b64 v[86:89], v119 offset0:36 offset1:45
	v_mov_b64_e32 v[100:101], v[244:245]
	v_mov_b64_e32 v[102:103], v[246:247]
	ds_read2_b64 v[90:93], v119 offset0:54 offset1:63
	v_mov_b64_e32 v[194:195], v[248:249]
	v_mov_b64_e32 v[196:197], v[250:251]
	s_waitcnt lgkmcnt(0)
	v_pk_mul_f32 v[198:199], v[92:93], v[196:197] op_sel:[1,1] op_sel_hi:[0,1]
	v_pk_fma_f32 v[200:201], v[92:93], v[196:197], v[198:199]
	v_pk_fma_f32 v[92:93], v[92:93], v[196:197], v[198:199] op_sel_hi:[1,0,1] neg_lo:[0,0,1] neg_hi:[0,0,1]
	s_nop 0
	v_mov_b32_e32 v201, v93
	v_pk_mul_f32 v[92:93], v[18:19], v[94:95] op_sel:[1,1] op_sel_hi:[0,1]
	v_pk_fma_f32 v[196:197], v[18:19], v[94:95], v[92:93]
	v_pk_fma_f32 v[18:19], v[18:19], v[94:95], v[92:93] op_sel_hi:[1,0,1] neg_lo:[0,0,1] neg_hi:[0,0,1]
	s_nop 0
	v_mov_b32_e32 v197, v19
	v_pk_mul_f32 v[18:19], v[20:21], v[96:97] op_sel:[1,1] op_sel_hi:[0,1]
	v_pk_fma_f32 v[92:93], v[20:21], v[96:97], v[18:19]
	v_pk_fma_f32 v[18:19], v[20:21], v[96:97], v[18:19] op_sel_hi:[1,0,1] neg_lo:[0,0,1] neg_hi:[0,0,1]
	s_nop 0
	v_mov_b32_e32 v93, v19
	v_pk_mul_f32 v[18:19], v[22:23], v[98:99] op_sel:[1,1] op_sel_hi:[0,1]
	v_pk_fma_f32 v[20:21], v[22:23], v[98:99], v[18:19]
	v_pk_fma_f32 v[18:19], v[22:23], v[98:99], v[18:19] op_sel_hi:[1,0,1] neg_lo:[0,0,1] neg_hi:[0,0,1]
	s_nop 0
	v_mov_b32_e32 v21, v19
	v_pk_mul_f32 v[18:19], v[86:87], v[100:101] op_sel:[1,1] op_sel_hi:[0,1]
	v_pk_fma_f32 v[22:23], v[86:87], v[100:101], v[18:19]
	v_pk_fma_f32 v[18:19], v[86:87], v[100:101], v[18:19] op_sel_hi:[1,0,1] neg_lo:[0,0,1] neg_hi:[0,0,1]
	s_nop 0
	v_mov_b32_e32 v23, v19
	v_pk_mul_f32 v[18:19], v[88:89], v[102:103] op_sel:[1,1] op_sel_hi:[0,1]
	v_pk_fma_f32 v[86:87], v[88:89], v[102:103], v[18:19]
	v_pk_fma_f32 v[18:19], v[88:89], v[102:103], v[18:19] op_sel_hi:[1,0,1] neg_lo:[0,0,1] neg_hi:[0,0,1]
	s_nop 0
	v_mov_b32_e32 v87, v19
	v_pk_mul_f32 v[18:19], v[90:91], v[194:195] op_sel:[1,1] op_sel_hi:[0,1]
	v_pk_fma_f32 v[88:89], v[90:91], v[194:195], v[18:19]
	v_pk_fma_f32 v[18:19], v[90:91], v[194:195], v[18:19] op_sel_hi:[1,0,1] neg_lo:[0,0,1] neg_hi:[0,0,1]
	s_nop 0
	v_mov_b32_e32 v89, v19
	v_pk_add_f32 v[18:19], v[16:17], v[22:23]
	v_pk_add_f32 v[16:17], v[16:17], v[22:23] neg_lo:[0,1] neg_hi:[0,1]
	v_pk_add_f32 v[22:23], v[196:197], v[86:87]
	v_pk_add_f32 v[86:87], v[196:197], v[86:87] neg_lo:[0,1] neg_hi:[0,1]
	v_pk_add_f32 v[90:91], v[92:93], v[88:89]
	v_pk_add_f32 v[88:89], v[92:93], v[88:89] neg_lo:[0,1] neg_hi:[0,1]
	v_pk_add_f32 v[92:93], v[20:21], v[200:201]
	v_pk_add_f32 v[20:21], v[20:21], v[200:201] neg_lo:[0,1] neg_hi:[0,1]
	v_pk_add_f32 v[94:95], v[86:87], v[86:87] op_sel:[0,1] neg_lo:[0,1] neg_hi:[0,1]
	v_pk_add_f32 v[86:87], v[86:87], v[86:87] op_sel_hi:[0,1]
	v_mov_b32_e32 v95, v87
	v_xor_b32_e32 v86, 0x80000000, v89
	v_mov_b32_e32 v87, v88
	v_pk_add_f32 v[88:89], v[20:21], v[20:21] op_sel:[0,1]
	v_pk_add_f32 v[20:21], v[20:21], v[20:21] op_sel_hi:[0,1] neg_lo:[0,1] neg_hi:[0,1]
	v_mov_b32_e32 v89, v21
	v_pk_mul_f32 v[20:21], v[88:89], s[84:85]
	v_pk_add_f32 v[88:89], v[18:19], v[90:91]
	v_pk_add_f32 v[18:19], v[18:19], v[90:91] neg_lo:[0,1] neg_hi:[0,1]
	v_pk_add_f32 v[90:91], v[22:23], v[92:93]
	v_pk_add_f32 v[22:23], v[22:23], v[92:93] neg_lo:[0,1] neg_hi:[0,1]
	s_nop 0
	v_xor_b32_e32 v92, 0x80000000, v23
	v_mov_b32_e32 v93, v22
	v_pk_add_f32 v[22:23], v[88:89], v[90:91]
	v_pk_add_f32 v[88:89], v[88:89], v[90:91] neg_lo:[0,1] neg_hi:[0,1]
	v_pk_add_f32 v[90:91], v[18:19], v[92:93]
	v_pk_add_f32 v[18:19], v[18:19], v[92:93] neg_lo:[0,1] neg_hi:[0,1]
	v_pk_add_f32 v[92:93], v[16:17], v[86:87]
	v_pk_add_f32 v[16:17], v[16:17], v[86:87] neg_lo:[0,1] neg_hi:[0,1]
	v_pk_fma_f32 v[86:87], v[94:95], s[20:21], v[20:21] op_sel_hi:[1,0,1]
	v_pk_fma_f32 v[20:21], v[94:95], s[20:21], v[20:21] op_sel_hi:[1,0,1] neg_lo:[0,0,1] neg_hi:[0,0,1]
	s_nop 0
	v_xor_b32_e32 v94, 0x80000000, v21
	v_mov_b32_e32 v95, v20
	v_pk_add_f32 v[20:21], v[92:93], v[86:87]
	v_pk_add_f32 v[86:87], v[92:93], v[86:87] neg_lo:[0,1] neg_hi:[0,1]
	v_pk_add_f32 v[92:93], v[16:17], v[94:95]
	v_pk_add_f32 v[16:17], v[16:17], v[94:95] neg_lo:[0,1] neg_hi:[0,1]
	ds_write2_b64 v119, v[22:23], v[20:21] offset1:9
	ds_write2_b64 v119, v[90:91], v[92:93] offset0:18 offset1:27
	ds_write2_b64 v119, v[88:89], v[86:87] offset0:36 offset1:45
	ds_write2_b64 v119, v[18:19], v[16:17] offset0:54 offset1:63
	ds_read2_b64 v[16:19], v193 offset1:9
	v_mov_b64_e32 v[94:95], v[238:239]
	ds_read2_b64 v[20:23], v193 offset0:18 offset1:27
	v_mov_b64_e32 v[96:97], v[240:241]
	v_mov_b64_e32 v[98:99], v[242:243]
	ds_read2_b64 v[86:89], v193 offset0:36 offset1:45
	v_mov_b64_e32 v[100:101], v[244:245]
	v_mov_b64_e32 v[102:103], v[246:247]
	ds_read2_b64 v[90:93], v193 offset0:54 offset1:63
	v_mov_b64_e32 v[194:195], v[248:249]
	v_mov_b64_e32 v[196:197], v[250:251]
	s_waitcnt lgkmcnt(0)
; __device__ __forceinline__ c2 cmulc(c2 a, c2 b) { return (c2){a.x * b.x + a.y * b.y, a.y * b.x - a.x * b.y}; }
; template <int S> __device__ __forceinline__ void inv_mid(c2* buf, const c2* tws, int tid) {
;     constexpr int lq = 9 - 3 * S, Q = 1 << lq; const c2* T = tws + (S == 1 ? 3584 : 4032);
;     const int k = tid & (Q - 1), base = ((tid >> lq) << (lq + 3)) + k;
;     c2 x[8];
;     c2* bp_ = buf + LP(base); constexpr int QP = Q + Q / 8;
; #pragma unroll
;     for (int r = 0; r < 8; ++r) { c2 v = bp_[r * QP]; if (r) v = cmulc(v, T[(r - 1) * Q + k]); x[r] = v; }
;     idft8(x);
; #pragma unroll
;     for (int q = 0; q < 8; ++q) bp_[q * QP] = x[q];
; }
	v_pk_mul_f32 v[198:199], v[92:93], v[196:197] op_sel:[1,1] op_sel_hi:[0,1]
	v_pk_fma_f32 v[200:201], v[92:93], v[196:197], v[198:199]
	v_pk_fma_f32 v[92:93], v[92:93], v[196:197], v[198:199] op_sel_hi:[1,0,1] neg_lo:[0,0,1] neg_hi:[0,0,1]
	s_nop 0
	v_mov_b32_e32 v201, v93
	v_pk_mul_f32 v[92:93], v[18:19], v[94:95] op_sel:[1,1] op_sel_hi:[0,1]
	v_pk_fma_f32 v[196:197], v[18:19], v[94:95], v[92:93]
	v_pk_fma_f32 v[18:19], v[18:19], v[94:95], v[92:93] op_sel_hi:[1,0,1] neg_lo:[0,0,1] neg_hi:[0,0,1]
	s_nop 0
	v_mov_b32_e32 v197, v19
	v_pk_mul_f32 v[18:19], v[20:21], v[96:97] op_sel:[1,1] op_sel_hi:[0,1]
	v_pk_fma_f32 v[92:93], v[20:21], v[96:97], v[18:19]
	v_pk_fma_f32 v[18:19], v[20:21], v[96:97], v[18:19] op_sel_hi:[1,0,1] neg_lo:[0,0,1] neg_hi:[0,0,1]
	s_nop 0
	v_mov_b32_e32 v93, v19
	v_pk_mul_f32 v[18:19], v[22:23], v[98:99] op_sel:[1,1] op_sel_hi:[0,1]
	v_pk_fma_f32 v[20:21], v[22:23], v[98:99], v[18:19]
	v_pk_fma_f32 v[18:19], v[22:23], v[98:99], v[18:19] op_sel_hi:[1,0,1] neg_lo:[0,0,1] neg_hi:[0,0,1]
	s_nop 0
	v_mov_b32_e32 v21, v19
	v_pk_mul_f32 v[18:19], v[86:87], v[100:101] op_sel:[1,1] op_sel_hi:[0,1]
	v_pk_fma_f32 v[22:23], v[86:87], v[100:101], v[18:19]
	v_pk_fma_f32 v[18:19], v[86:87], v[100:101], v[18:19] op_sel_hi:[1,0,1] neg_lo:[0,0,1] neg_hi:[0,0,1]
	s_nop 0
	v_mov_b32_e32 v23, v19
	v_pk_mul_f32 v[18:19], v[88:89], v[102:103] op_sel:[1,1] op_sel_hi:[0,1]
	v_pk_fma_f32 v[86:87], v[88:89], v[102:103], v[18:19]
	v_pk_fma_f32 v[18:19], v[88:89], v[102:103], v[18:19] op_sel_hi:[1,0,1] neg_lo:[0,0,1] neg_hi:[0,0,1]
	s_nop 0
	v_mov_b32_e32 v87, v19
	v_pk_mul_f32 v[18:19], v[90:91], v[194:195] op_sel:[1,1] op_sel_hi:[0,1]
	v_pk_fma_f32 v[88:89], v[90:91], v[194:195], v[18:19]
	v_pk_fma_f32 v[18:19], v[90:91], v[194:195], v[18:19] op_sel_hi:[1,0,1] neg_lo:[0,0,1] neg_hi:[0,0,1]
	s_nop 0
	v_mov_b32_e32 v89, v19
	v_pk_add_f32 v[18:19], v[16:17], v[22:23]
	v_pk_add_f32 v[16:17], v[16:17], v[22:23] neg_lo:[0,1] neg_hi:[0,1]
	v_pk_add_f32 v[22:23], v[196:197], v[86:87]
	v_pk_add_f32 v[86:87], v[196:197], v[86:87] neg_lo:[0,1] neg_hi:[0,1]
	v_pk_add_f32 v[90:91], v[92:93], v[88:89]
	v_pk_add_f32 v[88:89], v[92:93], v[88:89] neg_lo:[0,1] neg_hi:[0,1]
	v_pk_add_f32 v[92:93], v[20:21], v[200:201]
	v_pk_add_f32 v[20:21], v[20:21], v[200:201] neg_lo:[0,1] neg_hi:[0,1]
	v_pk_add_f32 v[94:95], v[86:87], v[86:87] op_sel:[0,1] neg_lo:[0,1] neg_hi:[0,1]
	v_pk_add_f32 v[86:87], v[86:87], v[86:87] op_sel_hi:[0,1]
	v_mov_b32_e32 v95, v87
	v_xor_b32_e32 v86, 0x80000000, v89
	v_mov_b32_e32 v87, v88
	v_pk_add_f32 v[88:89], v[20:21], v[20:21] op_sel:[0,1]
	v_pk_add_f32 v[20:21], v[20:21], v[20:21] op_sel_hi:[0,1] neg_lo:[0,1] neg_hi:[0,1]
	v_mov_b32_e32 v89, v21
	v_pk_mul_f32 v[20:21], v[88:89], s[84:85]
	v_pk_add_f32 v[88:89], v[18:19], v[90:91]
	v_pk_add_f32 v[18:19], v[18:19], v[90:91] neg_lo:[0,1] neg_hi:[0,1]
	v_pk_add_f32 v[90:91], v[22:23], v[92:93]
	v_pk_add_f32 v[22:23], v[22:23], v[92:93] neg_lo:[0,1] neg_hi:[0,1]
	s_nop 0
	v_xor_b32_e32 v92, 0x80000000, v23
	v_mov_b32_e32 v93, v22
	v_pk_add_f32 v[22:23], v[88:89], v[90:91]
	v_pk_add_f32 v[88:89], v[88:89], v[90:91] neg_lo:[0,1] neg_hi:[0,1]
	v_pk_add_f32 v[90:91], v[18:19], v[92:93]
	v_pk_add_f32 v[18:19], v[18:19], v[92:93] neg_lo:[0,1] neg_hi:[0,1]
	v_pk_add_f32 v[92:93], v[16:17], v[86:87]
	v_pk_add_f32 v[16:17], v[16:17], v[86:87] neg_lo:[0,1] neg_hi:[0,1]
	v_pk_fma_f32 v[86:87], v[94:95], s[20:21], v[20:21] op_sel_hi:[1,0,1]
	v_pk_fma_f32 v[20:21], v[94:95], s[20:21], v[20:21] op_sel_hi:[1,0,1] neg_lo:[0,0,1] neg_hi:[0,0,1]
	s_nop 0
	v_xor_b32_e32 v94, 0x80000000, v21
	v_mov_b32_e32 v95, v20
	v_pk_add_f32 v[20:21], v[92:93], v[86:87]
	v_pk_add_f32 v[86:87], v[92:93], v[86:87] neg_lo:[0,1] neg_hi:[0,1]
	v_pk_add_f32 v[92:93], v[16:17], v[94:95]
	v_pk_add_f32 v[16:17], v[16:17], v[94:95] neg_lo:[0,1] neg_hi:[0,1]
	ds_write2_b64 v193, v[22:23], v[20:21] offset1:9
	ds_write2_b64 v193, v[90:91], v[92:93] offset0:18 offset1:27
	ds_write2_b64 v193, v[88:89], v[86:87] offset0:36 offset1:45
	ds_write2_b64 v193, v[18:19], v[16:17] offset0:54 offset1:63
	s_waitcnt lgkmcnt(0)
	s_barrier
	ds_read2_b64 v[16:19], v117 offset1:72
	v_mov_b64_e32 v[94:95], v[224:225]
	ds_read2_b64 v[20:23], v117 offset0:144 offset1:216
	v_mov_b64_e32 v[96:97], v[226:227]
	v_mov_b64_e32 v[98:99], v[228:229]
	ds_read2_b64 v[86:89], v56 offset0:32 offset1:104
	v_mov_b64_e32 v[100:101], v[230:231]
	v_mov_b64_e32 v[102:103], v[232:233]
	ds_read2_b64 v[90:93], v56 offset0:176 offset1:248
	v_mov_b64_e32 v[194:195], v[234:235]
	v_mov_b64_e32 v[196:197], v[236:237]
	s_waitcnt lgkmcnt(0)
; __device__ __forceinline__ c2 cmulc(c2 a, c2 b) { return (c2){a.x * b.x + a.y * b.y, a.y * b.x - a.x * b.y}; }
; template <int S> __device__ __forceinline__ void inv_mid(c2* buf, const c2* tws, int tid) {
;     constexpr int lq = 9 - 3 * S, Q = 1 << lq; const c2* T = tws + (S == 1 ? 3584 : 4032);
;     const int k = tid & (Q - 1), base = ((tid >> lq) << (lq + 3)) + k;
;     c2 x[8];
;     c2* bp_ = buf + LP(base); constexpr int QP = Q + Q / 8;
; #pragma unroll
;     for (int r = 0; r < 8; ++r) { c2 v = bp_[r * QP]; if (r) v = cmulc(v, T[(r - 1) * Q + k]); x[r] = v; }
;     idft8(x);
; #pragma unroll
;     for (int q = 0; q < 8; ++q) bp_[q * QP] = x[q];
; }
	v_pk_mul_f32 v[198:199], v[92:93], v[196:197] op_sel:[1,1] op_sel_hi:[0,1]
	v_pk_fma_f32 v[200:201], v[92:93], v[196:197], v[198:199]
	v_pk_fma_f32 v[92:93], v[92:93], v[196:197], v[198:199] op_sel_hi:[1,0,1] neg_lo:[0,0,1] neg_hi:[0,0,1]
	s_nop 0
	v_mov_b32_e32 v201, v93
	v_pk_mul_f32 v[92:93], v[18:19], v[94:95] op_sel:[1,1] op_sel_hi:[0,1]
	v_pk_fma_f32 v[196:197], v[18:19], v[94:95], v[92:93]
	v_pk_fma_f32 v[18:19], v[18:19], v[94:95], v[92:93] op_sel_hi:[1,0,1] neg_lo:[0,0,1] neg_hi:[0,0,1]
	s_nop 0
	v_mov_b32_e32 v197, v19
	v_pk_mul_f32 v[18:19], v[20:21], v[96:97] op_sel:[1,1] op_sel_hi:[0,1]
	v_pk_fma_f32 v[92:93], v[20:21], v[96:97], v[18:19]
	v_pk_fma_f32 v[18:19], v[20:21], v[96:97], v[18:19] op_sel_hi:[1,0,1] neg_lo:[0,0,1] neg_hi:[0,0,1]
	s_nop 0
	v_mov_b32_e32 v93, v19
	v_pk_mul_f32 v[18:19], v[22:23], v[98:99] op_sel:[1,1] op_sel_hi:[0,1]
	v_pk_fma_f32 v[20:21], v[22:23], v[98:99], v[18:19]
	v_pk_fma_f32 v[18:19], v[22:23], v[98:99], v[18:19] op_sel_hi:[1,0,1] neg_lo:[0,0,1] neg_hi:[0,0,1]
	s_nop 0
	v_mov_b32_e32 v21, v19
	v_pk_mul_f32 v[18:19], v[86:87], v[100:101] op_sel:[1,1] op_sel_hi:[0,1]
	v_pk_fma_f32 v[22:23], v[86:87], v[100:101], v[18:19]
	v_pk_fma_f32 v[18:19], v[86:87], v[100:101], v[18:19] op_sel_hi:[1,0,1] neg_lo:[0,0,1] neg_hi:[0,0,1]
	s_nop 0
	v_mov_b32_e32 v23, v19
	v_pk_mul_f32 v[18:19], v[88:89], v[102:103] op_sel:[1,1] op_sel_hi:[0,1]
	v_pk_fma_f32 v[86:87], v[88:89], v[102:103], v[18:19]
	v_pk_fma_f32 v[18:19], v[88:89], v[102:103], v[18:19] op_sel_hi:[1,0,1] neg_lo:[0,0,1] neg_hi:[0,0,1]
	s_nop 0
	v_mov_b32_e32 v87, v19
	v_pk_mul_f32 v[18:19], v[90:91], v[194:195] op_sel:[1,1] op_sel_hi:[0,1]
	v_pk_fma_f32 v[88:89], v[90:91], v[194:195], v[18:19]
	v_pk_fma_f32 v[18:19], v[90:91], v[194:195], v[18:19] op_sel_hi:[1,0,1] neg_lo:[0,0,1] neg_hi:[0,0,1]
	s_nop 0
	v_mov_b32_e32 v89, v19
	v_pk_add_f32 v[18:19], v[16:17], v[22:23]
	v_pk_add_f32 v[16:17], v[16:17], v[22:23] neg_lo:[0,1] neg_hi:[0,1]
	v_pk_add_f32 v[22:23], v[196:197], v[86:87]
	v_pk_add_f32 v[86:87], v[196:197], v[86:87] neg_lo:[0,1] neg_hi:[0,1]
	v_pk_add_f32 v[90:91], v[92:93], v[88:89]
	v_pk_add_f32 v[88:89], v[92:93], v[88:89] neg_lo:[0,1] neg_hi:[0,1]
	v_pk_add_f32 v[92:93], v[20:21], v[200:201]
	v_pk_add_f32 v[20:21], v[20:21], v[200:201] neg_lo:[0,1] neg_hi:[0,1]
	v_pk_add_f32 v[94:95], v[86:87], v[86:87] op_sel:[0,1] neg_lo:[0,1] neg_hi:[0,1]
	v_pk_add_f32 v[86:87], v[86:87], v[86:87] op_sel_hi:[0,1]
	v_mov_b32_e32 v95, v87
	v_xor_b32_e32 v86, 0x80000000, v89
	v_mov_b32_e32 v87, v88
	v_pk_add_f32 v[88:89], v[20:21], v[20:21] op_sel:[0,1]
	v_pk_add_f32 v[20:21], v[20:21], v[20:21] op_sel_hi:[0,1] neg_lo:[0,1] neg_hi:[0,1]
	v_mov_b32_e32 v89, v21
	v_pk_mul_f32 v[20:21], v[88:89], s[84:85]
	v_pk_add_f32 v[88:89], v[18:19], v[90:91]
	v_pk_add_f32 v[18:19], v[18:19], v[90:91] neg_lo:[0,1] neg_hi:[0,1]
	v_pk_add_f32 v[90:91], v[22:23], v[92:93]
	v_pk_add_f32 v[22:23], v[22:23], v[92:93] neg_lo:[0,1] neg_hi:[0,1]
	s_nop 0
	v_xor_b32_e32 v92, 0x80000000, v23
	v_mov_b32_e32 v93, v22
	v_pk_add_f32 v[22:23], v[88:89], v[90:91]
	v_pk_add_f32 v[88:89], v[88:89], v[90:91] neg_lo:[0,1] neg_hi:[0,1]
	v_pk_add_f32 v[90:91], v[18:19], v[92:93]
	v_pk_add_f32 v[18:19], v[18:19], v[92:93] neg_lo:[0,1] neg_hi:[0,1]
	v_pk_add_f32 v[92:93], v[16:17], v[86:87]
	v_pk_add_f32 v[16:17], v[16:17], v[86:87] neg_lo:[0,1] neg_hi:[0,1]
	v_pk_fma_f32 v[86:87], v[94:95], s[20:21], v[20:21] op_sel_hi:[1,0,1]
	v_pk_fma_f32 v[20:21], v[94:95], s[20:21], v[20:21] op_sel_hi:[1,0,1] neg_lo:[0,0,1] neg_hi:[0,0,1]
	s_nop 0
	v_xor_b32_e32 v94, 0x80000000, v21
	v_mov_b32_e32 v95, v20
	v_pk_add_f32 v[20:21], v[92:93], v[86:87]
	v_pk_add_f32 v[86:87], v[92:93], v[86:87] neg_lo:[0,1] neg_hi:[0,1]
	v_pk_add_f32 v[92:93], v[16:17], v[94:95]
	v_pk_add_f32 v[16:17], v[16:17], v[94:95] neg_lo:[0,1] neg_hi:[0,1]
	ds_write2_b64 v117, v[22:23], v[20:21] offset1:72
	ds_write2_b64 v117, v[90:91], v[92:93] offset0:144 offset1:216
	ds_write2_b64 v56, v[88:89], v[86:87] offset0:32 offset1:104
	ds_write2_b64 v56, v[18:19], v[16:17] offset0:176 offset1:248
	ds_read2_b64 v[16:19], v191 offset1:72
	v_mov_b64_e32 v[94:95], v[224:225]
	ds_read2_b64 v[20:23], v191 offset0:144 offset1:216
	v_mov_b64_e32 v[96:97], v[226:227]
	v_mov_b64_e32 v[98:99], v[228:229]
	ds_read2_b64 v[86:89], v192 offset0:32 offset1:104
	v_mov_b64_e32 v[100:101], v[230:231]
	v_mov_b64_e32 v[102:103], v[232:233]
	ds_read2_b64 v[90:93], v192 offset0:176 offset1:248
	v_mov_b64_e32 v[194:195], v[234:235]
	v_mov_b64_e32 v[196:197], v[236:237]
	s_waitcnt lgkmcnt(0)
; __device__ __forceinline__ c2 cmulc(c2 a, c2 b) { return (c2){a.x * b.x + a.y * b.y, a.y * b.x - a.x * b.y}; }
; template <int S> __device__ __forceinline__ void inv_mid(c2* buf, const c2* tws, int tid) {
;     constexpr int lq = 9 - 3 * S, Q = 1 << lq; const c2* T = tws + (S == 1 ? 3584 : 4032);
;     const int k = tid & (Q - 1), base = ((tid >> lq) << (lq + 3)) + k;
;     c2 x[8];
;     c2* bp_ = buf + LP(base); constexpr int QP = Q + Q / 8;
; #pragma unroll
;     for (int r = 0; r < 8; ++r) { c2 v = bp_[r * QP]; if (r) v = cmulc(v, T[(r - 1) * Q + k]); x[r] = v; }
;     idft8(x);
; #pragma unroll
;     for (int q = 0; q < 8; ++q) bp_[q * QP] = x[q];
; }
; __device__ __forceinline__ void inv_s0(c2 (&x)[8], const c2* buf, const c2* tws, int tid) {
;     const c2* bp_ = buf + LP(tid);
; #pragma unroll
;     for (int r = 0; r < 8; ++r) { c2 v = bp_[576 * r]; if (r) v = cmulc(v, tws[(r - 1) * 512 + tid]); x[r] = v; }
;     idft8(x);
; }
	v_pk_mul_f32 v[198:199], v[92:93], v[196:197] op_sel:[1,1] op_sel_hi:[0,1]
	v_pk_fma_f32 v[200:201], v[92:93], v[196:197], v[198:199]
	v_pk_fma_f32 v[92:93], v[92:93], v[196:197], v[198:199] op_sel_hi:[1,0,1] neg_lo:[0,0,1] neg_hi:[0,0,1]
	s_nop 0
	v_mov_b32_e32 v201, v93
	v_pk_mul_f32 v[92:93], v[18:19], v[94:95] op_sel:[1,1] op_sel_hi:[0,1]
	v_pk_fma_f32 v[196:197], v[18:19], v[94:95], v[92:93]
	v_pk_fma_f32 v[18:19], v[18:19], v[94:95], v[92:93] op_sel_hi:[1,0,1] neg_lo:[0,0,1] neg_hi:[0,0,1]
	s_nop 0
	v_mov_b32_e32 v197, v19
	v_pk_mul_f32 v[18:19], v[20:21], v[96:97] op_sel:[1,1] op_sel_hi:[0,1]
	v_pk_fma_f32 v[92:93], v[20:21], v[96:97], v[18:19]
	v_pk_fma_f32 v[18:19], v[20:21], v[96:97], v[18:19] op_sel_hi:[1,0,1] neg_lo:[0,0,1] neg_hi:[0,0,1]
	s_nop 0
	v_mov_b32_e32 v93, v19
	v_pk_mul_f32 v[18:19], v[22:23], v[98:99] op_sel:[1,1] op_sel_hi:[0,1]
	v_pk_fma_f32 v[20:21], v[22:23], v[98:99], v[18:19]
	v_pk_fma_f32 v[18:19], v[22:23], v[98:99], v[18:19] op_sel_hi:[1,0,1] neg_lo:[0,0,1] neg_hi:[0,0,1]
	s_nop 0
	v_mov_b32_e32 v21, v19
	v_pk_mul_f32 v[18:19], v[86:87], v[100:101] op_sel:[1,1] op_sel_hi:[0,1]
	v_pk_fma_f32 v[22:23], v[86:87], v[100:101], v[18:19]
	v_pk_fma_f32 v[18:19], v[86:87], v[100:101], v[18:19] op_sel_hi:[1,0,1] neg_lo:[0,0,1] neg_hi:[0,0,1]
	s_nop 0
	v_mov_b32_e32 v23, v19
	v_pk_mul_f32 v[18:19], v[88:89], v[102:103] op_sel:[1,1] op_sel_hi:[0,1]
	v_pk_fma_f32 v[86:87], v[88:89], v[102:103], v[18:19]
	v_pk_fma_f32 v[18:19], v[88:89], v[102:103], v[18:19] op_sel_hi:[1,0,1] neg_lo:[0,0,1] neg_hi:[0,0,1]
	s_nop 0
	v_mov_b32_e32 v87, v19
	v_pk_mul_f32 v[18:19], v[90:91], v[194:195] op_sel:[1,1] op_sel_hi:[0,1]
	v_pk_fma_f32 v[88:89], v[90:91], v[194:195], v[18:19]
	v_pk_fma_f32 v[18:19], v[90:91], v[194:195], v[18:19] op_sel_hi:[1,0,1] neg_lo:[0,0,1] neg_hi:[0,0,1]
	s_nop 0
	v_mov_b32_e32 v89, v19
	v_pk_add_f32 v[18:19], v[16:17], v[22:23]
	v_pk_add_f32 v[16:17], v[16:17], v[22:23] neg_lo:[0,1] neg_hi:[0,1]
	v_pk_add_f32 v[22:23], v[196:197], v[86:87]
	v_pk_add_f32 v[86:87], v[196:197], v[86:87] neg_lo:[0,1] neg_hi:[0,1]
	v_pk_add_f32 v[90:91], v[92:93], v[88:89]
	v_pk_add_f32 v[88:89], v[92:93], v[88:89] neg_lo:[0,1] neg_hi:[0,1]
	v_pk_add_f32 v[92:93], v[20:21], v[200:201]
	v_pk_add_f32 v[20:21], v[20:21], v[200:201] neg_lo:[0,1] neg_hi:[0,1]
	v_pk_add_f32 v[94:95], v[86:87], v[86:87] op_sel:[0,1] neg_lo:[0,1] neg_hi:[0,1]
	v_pk_add_f32 v[86:87], v[86:87], v[86:87] op_sel_hi:[0,1]
	v_mov_b32_e32 v95, v87
	v_xor_b32_e32 v86, 0x80000000, v89
	v_mov_b32_e32 v87, v88
	v_pk_add_f32 v[88:89], v[20:21], v[20:21] op_sel:[0,1]
	v_pk_add_f32 v[20:21], v[20:21], v[20:21] op_sel_hi:[0,1] neg_lo:[0,1] neg_hi:[0,1]
	v_mov_b32_e32 v89, v21
	v_pk_mul_f32 v[20:21], v[88:89], s[84:85]
	v_pk_add_f32 v[88:89], v[18:19], v[90:91]
	v_pk_add_f32 v[18:19], v[18:19], v[90:91] neg_lo:[0,1] neg_hi:[0,1]
	v_pk_add_f32 v[90:91], v[22:23], v[92:93]
	v_pk_add_f32 v[22:23], v[22:23], v[92:93] neg_lo:[0,1] neg_hi:[0,1]
	s_nop 0
	v_xor_b32_e32 v92, 0x80000000, v23
	v_mov_b32_e32 v93, v22
	v_pk_add_f32 v[22:23], v[88:89], v[90:91]
	v_pk_add_f32 v[88:89], v[88:89], v[90:91] neg_lo:[0,1] neg_hi:[0,1]
	v_pk_add_f32 v[90:91], v[18:19], v[92:93]
	v_pk_add_f32 v[18:19], v[18:19], v[92:93] neg_lo:[0,1] neg_hi:[0,1]
	v_pk_add_f32 v[92:93], v[16:17], v[86:87]
	v_pk_add_f32 v[16:17], v[16:17], v[86:87] neg_lo:[0,1] neg_hi:[0,1]
	v_pk_fma_f32 v[86:87], v[94:95], s[20:21], v[20:21] op_sel_hi:[1,0,1]
	v_pk_fma_f32 v[20:21], v[94:95], s[20:21], v[20:21] op_sel_hi:[1,0,1] neg_lo:[0,0,1] neg_hi:[0,0,1]
	s_nop 0
	v_xor_b32_e32 v94, 0x80000000, v21
	v_mov_b32_e32 v95, v20
	v_pk_add_f32 v[20:21], v[92:93], v[86:87]
	v_pk_add_f32 v[86:87], v[92:93], v[86:87] neg_lo:[0,1] neg_hi:[0,1]
	v_pk_add_f32 v[92:93], v[16:17], v[94:95]
	v_pk_add_f32 v[16:17], v[16:17], v[94:95] neg_lo:[0,1] neg_hi:[0,1]
	ds_write2_b64 v191, v[22:23], v[20:21] offset1:72
	ds_write2_b64 v191, v[90:91], v[92:93] offset0:144 offset1:216
	ds_write2_b64 v192, v[88:89], v[86:87] offset0:32 offset1:104
	ds_write2_b64 v192, v[18:19], v[16:17] offset0:176 offset1:248
	s_waitcnt lgkmcnt(0)
	s_barrier
	ds_read2st64_b64 v[20:23], v115 offset1:9
	v_mov_b64_e32 v[98:99], v[210:211]
	v_mov_b64_e32 v[100:101], v[212:213]
	v_mov_b64_e32 v[194:195], v[214:215]
	v_mov_b64_e32 v[196:197], v[216:217]
	ds_read2st64_b64 v[86:89], v115 offset0:36 offset1:45
	s_waitcnt lgkmcnt(0)
	v_pk_mul_f32 v[16:17], v[22:23], v[98:99] op_sel:[0,1]
	s_nop 0
	v_pk_fma_f32 v[92:93], v[22:23], v[98:99], v[16:17] op_sel:[0,0,1] op_sel_hi:[1,1,0]
	v_pk_fma_f32 v[16:17], v[22:23], v[98:99], v[16:17] op_sel:[0,0,1] op_sel_hi:[1,0,0] neg_lo:[0,0,1] neg_hi:[0,0,1]
	s_nop 0
	v_mov_b32_e32 v93, v17
	ds_read2st64_b64 v[16:19], v115 offset0:18 offset1:27
	s_waitcnt lgkmcnt(0)
	v_pk_mul_f32 v[22:23], v[16:17], v[100:101] op_sel:[0,1]
	s_nop 0
	v_pk_fma_f32 v[94:95], v[16:17], v[100:101], v[22:23] op_sel:[0,0,1] op_sel_hi:[1,1,0]
	v_pk_fma_f32 v[16:17], v[16:17], v[100:101], v[22:23] op_sel:[0,0,1] op_sel_hi:[1,0,0] neg_lo:[0,0,1] neg_hi:[0,0,1]
	s_nop 0
	v_mov_b32_e32 v95, v17
	v_pk_mul_f32 v[16:17], v[18:19], v[194:195] op_sel:[0,1]
	s_nop 0
	v_pk_fma_f32 v[22:23], v[18:19], v[194:195], v[16:17] op_sel:[0,0,1] op_sel_hi:[1,1,0]
	v_pk_fma_f32 v[16:17], v[18:19], v[194:195], v[16:17] op_sel:[0,0,1] op_sel_hi:[1,0,0] neg_lo:[0,0,1] neg_hi:[0,0,1]
	s_nop 0
	v_mov_b32_e32 v23, v17
	v_pk_mul_f32 v[16:17], v[86:87], v[196:197] op_sel:[0,1]
	s_nop 0
	v_pk_fma_f32 v[96:97], v[86:87], v[196:197], v[16:17] op_sel:[0,0,1] op_sel_hi:[1,1,0]
	v_pk_fma_f32 v[16:17], v[86:87], v[196:197], v[16:17] op_sel:[0,0,1] op_sel_hi:[1,0,0] neg_lo:[0,0,1] neg_hi:[0,0,1]
	s_nop 0
	v_mov_b32_e32 v97, v17
	v_mov_b64_e32 v[16:17], v[218:219]
	v_mov_b64_e32 v[18:19], v[220:221]
	s_waitcnt lgkmcnt(0)
; __device__ __forceinline__ c2 cmulc(c2 a, c2 b) { return (c2){a.x * b.x + a.y * b.y, a.y * b.x - a.x * b.y}; }
; __device__ __forceinline__ c2 mpi(c2 a) { return (c2){-a.y, a.x}; }
; __device__ __forceinline__ void idft8(c2 (&x)[8]) {
;     const float s = 0.70710678118654752f;
;     const c2 a0 = x[0] + x[4], a4 = x[0] - x[4], a1 = x[1] + x[5], a5 = x[1] - x[5], a2 = x[2] + x[6], a6 = x[2] - x[6], a3 = x[3] + x[7], a7 = x[3] - x[7];
;     const c2 a5w = (c2){(a5.x - a5.y) * s, (a5.x + a5.y) * s};
;     const c2 a6w = mpi(a6);
;     const c2 a7w = (c2){-(a7.x + a7.y) * s, (a7.x - a7.y) * s};
;     const c2 b0 = a0 + a2, b1 = a0 - a2, b2 = a1 + a3, b3 = mpi(a1 - a3);
;     x[0] = b0 + b2; x[4] = b0 - b2; x[2] = b1 + b3; x[6] = b1 - b3;
;     const c2 c0 = a4 + a6w, c1 = a4 - a6w, c2_ = a5w + a7w, c3 = mpi(a5w - a7w);
;     x[1] = c0 + c2_; x[5] = c0 - c2_; x[3] = c1 + c3; x[7] = c1 - c3;
; }
; __device__ __forceinline__ void inv_s0(c2 (&x)[8], const c2* buf, const c2* tws, int tid) {
;     const c2* bp_ = buf + LP(tid);
; #pragma unroll
;     for (int r = 0; r < 8; ++r) { c2 v = bp_[576 * r]; if (r) v = cmulc(v, tws[(r - 1) * 512 + tid]); x[r] = v; }
;     idft8(x);
; }
	v_pk_mul_f32 v[86:87], v[88:89], v[16:17] op_sel:[0,1]
	s_nop 0
	v_pk_fma_f32 v[102:103], v[88:89], v[16:17], v[86:87] op_sel:[0,0,1] op_sel_hi:[1,1,0]
	v_pk_fma_f32 v[86:87], v[88:89], v[16:17], v[86:87] op_sel:[0,0,1] op_sel_hi:[1,0,0] neg_lo:[0,0,1] neg_hi:[0,0,1]
	ds_read2st64_b64 v[88:91], v115 offset0:54 offset1:63
	v_mov_b32_e32 v103, v87
	s_waitcnt lgkmcnt(0)
	v_pk_mul_f32 v[86:87], v[88:89], v[18:19] op_sel:[0,1]
	s_nop 0
	v_pk_fma_f32 v[198:199], v[88:89], v[18:19], v[86:87] op_sel:[0,0,1] op_sel_hi:[1,1,0]
	v_pk_fma_f32 v[86:87], v[88:89], v[18:19], v[86:87] op_sel:[0,0,1] op_sel_hi:[1,0,0] neg_lo:[0,0,1] neg_hi:[0,0,1]
	v_mov_b64_e32 v[88:89], v[222:223]
	v_mov_b32_e32 v199, v87
	s_waitcnt lgkmcnt(0)
	v_pk_mul_f32 v[86:87], v[90:91], v[88:89] op_sel:[0,1]
	s_nop 0
	v_pk_fma_f32 v[200:201], v[90:91], v[88:89], v[86:87] op_sel:[0,0,1] op_sel_hi:[1,1,0]
	v_pk_fma_f32 v[86:87], v[90:91], v[88:89], v[86:87] op_sel:[0,0,1] op_sel_hi:[1,0,0] neg_lo:[0,0,1] neg_hi:[0,0,1]
	v_pk_add_f32 v[90:91], v[92:93], v[102:103]
	v_mov_b32_e32 v201, v87
	v_pk_add_f32 v[92:93], v[92:93], v[102:103] neg_lo:[0,1] neg_hi:[0,1]
	v_pk_add_f32 v[86:87], v[20:21], v[96:97]
	v_pk_add_f32 v[20:21], v[20:21], v[96:97] neg_lo:[0,1] neg_hi:[0,1]
	v_pk_add_f32 v[96:97], v[94:95], v[198:199]
	v_pk_add_f32 v[94:95], v[94:95], v[198:199] neg_lo:[0,1] neg_hi:[0,1]
	v_pk_add_f32 v[102:103], v[22:23], v[200:201]
	v_pk_add_f32 v[22:23], v[22:23], v[200:201] neg_lo:[0,1] neg_hi:[0,1]
	v_pk_add_f32 v[198:199], v[92:93], v[92:93] op_sel:[0,1] neg_lo:[0,1] neg_hi:[0,1]
	v_pk_add_f32 v[92:93], v[92:93], v[92:93] op_sel_hi:[0,1]
	v_mov_b32_e32 v199, v93
	v_xor_b32_e32 v92, 0x80000000, v95
	v_mov_b32_e32 v93, v94
	v_pk_add_f32 v[94:95], v[22:23], v[22:23] op_sel:[0,1]
	v_pk_add_f32 v[22:23], v[22:23], v[22:23] op_sel_hi:[0,1] neg_lo:[0,1] neg_hi:[0,1]
	v_mov_b32_e32 v95, v23
	v_pk_mul_f32 v[22:23], v[94:95], s[84:85]
	v_pk_add_f32 v[94:95], v[86:87], v[96:97]
	v_pk_add_f32 v[86:87], v[86:87], v[96:97] neg_lo:[0,1] neg_hi:[0,1]
	v_pk_add_f32 v[96:97], v[90:91], v[102:103]
	v_pk_add_f32 v[90:91], v[90:91], v[102:103] neg_lo:[0,1] neg_hi:[0,1]
	v_pk_add_f32 v[94:95], v[94:95], v[96:97]
	v_xor_b32_e32 v102, 0x80000000, v91
	v_mov_b32_e32 v103, v90
	v_pk_add_f32 v[90:91], v[86:87], v[102:103]
	v_pk_add_f32 v[86:87], v[20:21], v[92:93]
	v_pk_add_f32 v[20:21], v[20:21], v[92:93] neg_lo:[0,1] neg_hi:[0,1]
	v_pk_fma_f32 v[92:93], v[198:199], s[20:21], v[22:23] op_sel_hi:[1,0,1]
	v_pk_fma_f32 v[22:23], v[198:199], s[20:21], v[22:23] op_sel_hi:[1,0,1] neg_lo:[0,0,1] neg_hi:[0,0,1]
	v_pk_add_f32 v[92:93], v[86:87], v[92:93]
	v_xor_b32_e32 v96, 0x80000000, v23
	v_mov_b32_e32 v97, v22
	v_pk_add_f32 v[86:87], v[20:21], v[96:97]
	ds_read2st64_b64 v[20:23], v115 offset0:72 offset1:81
	ds_read2st64_b64 v[198:201], v115 offset0:90 offset1:99
	s_waitcnt lgkmcnt(0)
	v_pk_mul_f32 v[102:103], v[98:99], v[22:23] op_sel:[1,0]
	s_nop 0
	v_pk_fma_f32 v[96:97], v[98:99], v[22:23], v[102:103] op_sel:[0,0,1] op_sel_hi:[1,1,0]
	v_pk_fma_f32 v[22:23], v[98:99], v[22:23], v[102:103] op_sel:[0,0,1] op_sel_hi:[0,1,0] neg_lo:[0,0,1] neg_hi:[0,0,1]
	s_waitcnt lgkmcnt(0)
	v_pk_mul_f32 v[98:99], v[100:101], v[198:199] op_sel:[1,0]
	v_mov_b32_e32 v97, v23
	v_pk_fma_f32 v[22:23], v[100:101], v[198:199], v[98:99] op_sel:[0,0,1] op_sel_hi:[1,1,0]
	v_pk_fma_f32 v[98:99], v[100:101], v[198:199], v[98:99] op_sel:[0,0,1] op_sel_hi:[0,1,0] neg_lo:[0,0,1] neg_hi:[0,0,1]
	v_pk_mul_f32 v[100:101], v[194:195], v[200:201] op_sel:[1,0]
	v_mov_b32_e32 v23, v99
	v_pk_fma_f32 v[98:99], v[194:195], v[200:201], v[100:101] op_sel:[0,0,1] op_sel_hi:[1,1,0]
	v_pk_fma_f32 v[100:101], v[194:195], v[200:201], v[100:101] op_sel:[0,0,1] op_sel_hi:[0,1,0] neg_lo:[0,0,1] neg_hi:[0,0,1]
	ds_read2st64_b64 v[198:201], v115 offset0:108 offset1:117
	v_mov_b32_e32 v99, v101
	s_waitcnt lgkmcnt(0)
	v_pk_mul_f32 v[102:103], v[196:197], v[198:199] op_sel:[1,0]
	s_nop 0
	v_pk_fma_f32 v[100:101], v[196:197], v[198:199], v[102:103] op_sel:[0,0,1] op_sel_hi:[1,1,0]
	v_pk_fma_f32 v[102:103], v[196:197], v[198:199], v[102:103] op_sel:[0,0,1] op_sel_hi:[0,1,0] neg_lo:[0,0,1] neg_hi:[0,0,1]
	v_pk_mul_f32 v[194:195], v[16:17], v[200:201] op_sel:[1,0]
	v_mov_b32_e32 v101, v103
	v_pk_fma_f32 v[102:103], v[16:17], v[200:201], v[194:195] op_sel:[0,0,1] op_sel_hi:[1,1,0]
	v_pk_fma_f32 v[16:17], v[16:17], v[200:201], v[194:195] op_sel:[0,0,1] op_sel_hi:[0,1,0] neg_lo:[0,0,1] neg_hi:[0,0,1]
	v_mov_b32_e32 v103, v17
	ds_read_b64 v[16:17], v115 offset:64512
	s_waitcnt lgkmcnt(0)
	v_pk_mul_f32 v[194:195], v[18:19], v[16:17] op_sel:[1,0]
	s_nop 0
	v_pk_fma_f32 v[196:197], v[18:19], v[16:17], v[194:195] op_sel:[0,0,1] op_sel_hi:[1,1,0]
	v_pk_fma_f32 v[16:17], v[18:19], v[16:17], v[194:195] op_sel:[0,0,1] op_sel_hi:[0,1,0] neg_lo:[0,0,1] neg_hi:[0,0,1]
	v_mov_b32_e32 v197, v17
	ds_read_b64 v[16:17], v116 offset:32256
	s_waitcnt lgkmcnt(0)
; __device__ __forceinline__ float bf2f(bf16_t b) { return __uint_as_float(((unsigned)b) << 16); }
; __device__ __forceinline__ float dwl(const bf16_t* r, int t, float w0, float w1, float w2, float b) { return w0 * bf2f(r[7 + t]) + w1 * bf2f(r[8 + t]) + w2 * bf2f(r[9 + t]) + b; }
	v_pk_mul_f32 v[18:19], v[88:89], v[16:17] op_sel:[1,0]
	s_nop 0
	v_pk_fma_f32 v[194:195], v[88:89], v[16:17], v[18:19] op_sel:[0,0,1] op_sel_hi:[1,1,0]
	v_pk_fma_f32 v[16:17], v[88:89], v[16:17], v[18:19] op_sel:[0,0,1] op_sel_hi:[0,1,0] neg_lo:[0,0,1] neg_hi:[0,0,1]
	v_mov_b32_e32 v195, v17
	v_pk_add_f32 v[88:89], v[96:97], v[102:103] neg_lo:[0,1] neg_hi:[0,1]
	v_pk_add_f32 v[16:17], v[20:21], v[100:101]
	v_pk_add_f32 v[20:21], v[20:21], v[100:101] neg_lo:[0,1] neg_hi:[0,1]
	v_pk_add_f32 v[18:19], v[96:97], v[102:103]
	v_pk_add_f32 v[96:97], v[22:23], v[196:197]
	v_pk_add_f32 v[22:23], v[22:23], v[196:197] neg_lo:[0,1] neg_hi:[0,1]
	v_pk_add_f32 v[100:101], v[98:99], v[194:195]
	v_pk_add_f32 v[98:99], v[98:99], v[194:195] neg_lo:[0,1] neg_hi:[0,1]
	v_pk_add_f32 v[102:103], v[88:89], v[88:89] op_sel:[0,1] neg_lo:[0,1] neg_hi:[0,1]
	v_pk_add_f32 v[88:89], v[88:89], v[88:89] op_sel_hi:[0,1]
	v_mov_b32_e32 v103, v89
	v_xor_b32_e32 v194, 0x80000000, v23
	v_mov_b32_e32 v195, v22
	v_pk_add_f32 v[22:23], v[98:99], v[98:99] op_sel:[0,1]
	v_pk_add_f32 v[88:89], v[98:99], v[98:99] op_sel_hi:[0,1] neg_lo:[0,1] neg_hi:[0,1]
	v_mov_b32_e32 v23, v89
	v_pk_mul_f32 v[22:23], v[22:23], s[84:85]
	v_pk_add_f32 v[88:89], v[16:17], v[96:97]
	v_pk_add_f32 v[16:17], v[16:17], v[96:97] neg_lo:[0,1] neg_hi:[0,1]
	v_pk_add_f32 v[96:97], v[18:19], v[100:101]
	v_pk_add_f32 v[18:19], v[18:19], v[100:101] neg_lo:[0,1] neg_hi:[0,1]
	v_pk_add_f32 v[88:89], v[88:89], v[96:97]
	v_xor_b32_e32 v98, 0x80000000, v19
	v_mov_b32_e32 v99, v18
	v_pk_fma_f32 v[96:97], v[102:103], s[20:21], v[22:23] op_sel_hi:[1,0,1]
	v_pk_fma_f32 v[22:23], v[102:103], s[20:21], v[22:23] op_sel_hi:[1,0,1] neg_lo:[0,0,1] neg_hi:[0,0,1]
	v_pk_add_f32 v[18:19], v[16:17], v[98:99]
	v_pk_add_f32 v[16:17], v[20:21], v[194:195]
	v_pk_add_f32 v[20:21], v[20:21], v[194:195] neg_lo:[0,1] neg_hi:[0,1]
	v_xor_b32_e32 v98, 0x80000000, v23
	v_mov_b32_e32 v99, v22
	v_pk_add_f32 v[22:23], v[16:17], v[96:97]
	v_pk_add_f32 v[16:17], v[20:21], v[98:99]
	ds_read_u16 v20, v160 offset:14
	ds_read_u16 v21, v160 offset:16
	ds_read_u16 v63, v160 offset:18
	v_pk_mul_f32 v[96:97], v[66:67], v[94:95]
	v_pk_mul_f32 v[22:23], v[66:67], v[22:23]
	s_waitcnt lgkmcnt(0)
	v_lshlrev_b32_e32 v20, 16, v20
	s_waitcnt lgkmcnt(0)
	v_lshlrev_b32_e32 v21, 16, v21
	v_mul_f32_e32 v21, v190, v21
	v_fmac_f32_e32 v21, v187, v20
	s_waitcnt lgkmcnt(0)
	v_lshlrev_b32_e32 v20, 16, v63
	v_fmac_f32_e32 v21, v189, v20
	v_add_f32_e32 v20, v188, v21
	ds_read_u16 v21, v161 offset:14
	ds_read_u16 v63, v161 offset:16
	ds_read_u16 v94, v161 offset:18
	v_fmac_f32_e32 v97, v184, v85
	v_fma_f32 v22, v184, v74, v22
	s_waitcnt lgkmcnt(0)
	v_lshlrev_b32_e32 v21, 16, v21
	s_waitcnt lgkmcnt(0)
	v_lshlrev_b32_e32 v63, 16, v63
	v_mul_f32_e32 v63, v190, v63
	v_fmac_f32_e32 v63, v187, v21
	s_waitcnt lgkmcnt(0)
	v_lshlrev_b32_e32 v21, 16, v94
	v_fmac_f32_e32 v63, v189, v21
	v_fma_f32 v21, v184, v84, v96
	v_mul_f32_e32 v20, v21, v20
	v_cvt_pk_bf16_f32 v84, v20, s0
	v_add_u32_e32 v20, s92, v113
	v_ashrrev_i32_e32 v21, 31, v20
	v_lshl_add_u64 v[94:95], v[20:21], 1, s[50:51]
	v_add_f32_e32 v63, v188, v63
	global_store_short v[94:95], v84, off
	v_add_u32_e32 v84, 0x800, v20
	v_mul_f32_e32 v21, v97, v63
	v_ashrrev_i32_e32 v85, 31, v84
	v_cvt_pk_bf16_f32 v21, v21, s0
	v_lshl_add_u64 v[84:85], v[84:85], 1, s[50:51]
	global_store_short v[84:85], v21, off
	v_pk_mul_f32 v[84:85], v[66:67], v[92:93]
	ds_read_u16 v21, v162 offset:14
	ds_read_u16 v63, v162 offset:16
	ds_read_u16 v92, v162 offset:18
	v_fma_f32 v82, v184, v82, v84
	v_fmac_f32_e32 v85, v184, v83
	s_waitcnt lgkmcnt(0)
	v_lshlrev_b32_e32 v21, 16, v21
	s_waitcnt lgkmcnt(0)
	v_lshlrev_b32_e32 v63, 16, v63
	v_mul_f32_e32 v63, v190, v63
	v_fmac_f32_e32 v63, v187, v21
	s_waitcnt lgkmcnt(0)
	v_lshlrev_b32_e32 v21, 16, v92
	v_fmac_f32_e32 v63, v189, v21
	v_add_f32_e32 v21, v188, v63
	ds_read_u16 v63, v163 offset:14
	ds_read_u16 v92, v163 offset:16
	ds_read_u16 v93, v163 offset:18
	v_mul_f32_e32 v21, v82, v21
	v_cvt_pk_bf16_f32 v21, v21, s0
	s_waitcnt lgkmcnt(0)
	v_lshlrev_b32_e32 v63, 16, v63
	s_waitcnt lgkmcnt(0)
	v_lshlrev_b32_e32 v92, 16, v92
	v_mul_f32_e32 v92, v190, v92
	v_fmac_f32_e32 v92, v187, v63
	s_waitcnt lgkmcnt(0)
	v_lshlrev_b32_e32 v63, 16, v93
	v_fmac_f32_e32 v92, v189, v63
	v_add_f32_e32 v63, v188, v92
	v_add_u32_e32 v82, 0xa00, v20
	global_store_short v[94:95], v21, off offset:1024
	v_mul_f32_e32 v21, v85, v63
	v_ashrrev_i32_e32 v83, 31, v82
	v_cvt_pk_bf16_f32 v21, v21, s0
	v_lshl_add_u64 v[82:83], v[82:83], 1, s[50:51]
	global_store_short v[82:83], v21, off
	ds_read_u16 v21, v164 offset:14
	ds_read_u16 v63, v164 offset:16
	ds_read_u16 v84, v164 offset:18
	v_pk_mul_f32 v[82:83], v[66:67], v[90:91]
	v_fmac_f32_e32 v23, v184, v75
	s_waitcnt lgkmcnt(0)
	v_lshlrev_b32_e32 v21, 16, v21
	s_waitcnt lgkmcnt(0)
	v_lshlrev_b32_e32 v63, 16, v63
	v_mul_f32_e32 v63, v190, v63
	v_fmac_f32_e32 v63, v187, v21
	s_waitcnt lgkmcnt(0)
	v_lshlrev_b32_e32 v21, 16, v84
	v_fmac_f32_e32 v63, v189, v21
	v_add_f32_e32 v21, v188, v63
	ds_read_u16 v63, v165 offset:14
	ds_read_u16 v84, v165 offset:16
	ds_read_u16 v85, v165 offset:18
	v_fma_f32 v78, v184, v78, v82
	v_mul_f32_e32 v21, v78, v21
	s_waitcnt lgkmcnt(0)
	v_lshlrev_b32_e32 v63, 16, v63
	s_waitcnt lgkmcnt(0)
	v_lshlrev_b32_e32 v84, 16, v84
	v_mul_f32_e32 v84, v190, v84
	v_fmac_f32_e32 v84, v187, v63
	s_waitcnt lgkmcnt(0)
; __device__ __forceinline__ void phase_conv(const Params& p, int o, unsigned char* smem, int wave) {
;     ...
;                 EPIZ(x0, zk0, 0, gq); EPIZ(x1, zk1, 2, gq);
	v_lshlrev_b32_e32 v63, 16, v85
	v_fmac_f32_e32 v84, v189, v63
	v_add_f32_e32 v63, v188, v84
	v_cvt_pk_bf16_f32 v21, v21, s0
	v_fmac_f32_e32 v83, v184, v79
	v_add_u32_e32 v78, 0xc00, v20
	global_store_short v[94:95], v21, off offset:2048
	v_mul_f32_e32 v21, v83, v63
	v_ashrrev_i32_e32 v79, 31, v78
	v_cvt_pk_bf16_f32 v21, v21, s0
	v_lshl_add_u64 v[78:79], v[78:79], 1, s[50:51]
	global_store_short v[78:79], v21, off
	ds_read_u16 v21, v166 offset:14
	ds_read_u16 v63, v166 offset:16
	ds_read_u16 v82, v166 offset:18
	v_pk_mul_f32 v[78:79], v[66:67], v[86:87]
	v_pk_mul_f32 v[18:19], v[66:67], v[18:19]
	s_waitcnt lgkmcnt(0)
	v_lshlrev_b32_e32 v21, 16, v21
	s_waitcnt lgkmcnt(0)
	v_lshlrev_b32_e32 v63, 16, v63
	v_mul_f32_e32 v63, v190, v63
	v_fmac_f32_e32 v63, v187, v21
	s_waitcnt lgkmcnt(0)
	v_lshlrev_b32_e32 v21, 16, v82
	v_fmac_f32_e32 v63, v189, v21
	v_add_f32_e32 v21, v188, v63
	ds_read_u16 v63, v167 offset:14
	ds_read_u16 v82, v167 offset:16
	ds_read_u16 v83, v167 offset:18
	v_fma_f32 v78, v184, v80, v78
	v_mul_f32_e32 v21, v78, v21
	s_waitcnt lgkmcnt(0)
	v_lshlrev_b32_e32 v63, 16, v63
	s_waitcnt lgkmcnt(0)
	v_lshlrev_b32_e32 v82, 16, v82
	v_mul_f32_e32 v82, v190, v82
	v_fmac_f32_e32 v82, v187, v63
	s_waitcnt lgkmcnt(0)
	v_lshlrev_b32_e32 v63, 16, v83
	v_fmac_f32_e32 v82, v189, v63
	v_add_f32_e32 v63, v188, v82
	v_cvt_pk_bf16_f32 v21, v21, s0
	v_fmac_f32_e32 v79, v184, v81
	v_add_u32_e32 v78, 0xe00, v20
	global_store_short v[94:95], v21, off offset:3072
	v_mul_f32_e32 v21, v79, v63
	v_ashrrev_i32_e32 v79, 31, v78
	v_cvt_pk_bf16_f32 v21, v21, s0
	v_lshl_add_u64 v[78:79], v[78:79], 1, s[50:51]
	global_store_short v[78:79], v21, off
	ds_read_u16 v21, v168 offset:14
	ds_read_u16 v63, v168 offset:16
	ds_read_u16 v80, v168 offset:18
	v_pk_mul_f32 v[78:79], v[66:67], v[88:89]
	v_fma_f32 v18, v184, v72, v18
	s_waitcnt lgkmcnt(0)
	v_lshlrev_b32_e32 v21, 16, v21
	s_waitcnt lgkmcnt(0)
	v_lshlrev_b32_e32 v63, 16, v63
	v_mul_f32_e32 v63, v190, v63
	v_fmac_f32_e32 v63, v187, v21
	s_waitcnt lgkmcnt(0)
	v_lshlrev_b32_e32 v21, 16, v80
	v_fmac_f32_e32 v63, v189, v21
	v_add_f32_e32 v21, v188, v63
	ds_read_u16 v63, v169 offset:14
	ds_read_u16 v80, v169 offset:16
	ds_read_u16 v81, v169 offset:18
	v_fma_f32 v76, v184, v76, v78
	v_mul_f32_e32 v21, v76, v21
	s_waitcnt lgkmcnt(0)
	v_lshlrev_b32_e32 v63, 16, v63
	s_waitcnt lgkmcnt(0)
	v_lshlrev_b32_e32 v80, 16, v80
	v_mul_f32_e32 v80, v190, v80
	v_fmac_f32_e32 v80, v187, v63
	s_waitcnt lgkmcnt(0)
	v_lshlrev_b32_e32 v63, 16, v81
	v_fmac_f32_e32 v80, v189, v63
	v_add_f32_e32 v63, v188, v80
	v_add_u32_e32 v80, 0x1000, v20
	v_ashrrev_i32_e32 v81, 31, v80
	v_cvt_pk_bf16_f32 v21, v21, s0
	v_lshl_add_u64 v[80:81], v[80:81], 1, s[50:51]
	v_fmac_f32_e32 v79, v184, v77
	v_add_u32_e32 v76, 0x1800, v20
	global_store_short v[80:81], v21, off
	v_mul_f32_e32 v21, v79, v63
	v_ashrrev_i32_e32 v77, 31, v76
	v_cvt_pk_bf16_f32 v21, v21, s0
	v_lshl_add_u64 v[76:77], v[76:77], 1, s[50:51]
	global_store_short v[76:77], v21, off
	ds_read_u16 v21, v170 offset:14
	ds_read_u16 v63, v170 offset:16
	ds_read_u16 v76, v170 offset:18
	v_fmac_f32_e32 v19, v184, v73
	v_pk_mul_f32 v[16:17], v[66:67], v[16:17]
	s_waitcnt lgkmcnt(0)
	v_lshlrev_b32_e32 v21, 16, v21
	s_waitcnt lgkmcnt(0)
	v_lshlrev_b32_e32 v63, 16, v63
	v_mul_f32_e32 v63, v190, v63
	v_fmac_f32_e32 v63, v187, v21
	s_waitcnt lgkmcnt(0)
	v_lshlrev_b32_e32 v21, 16, v76
	v_fmac_f32_e32 v63, v189, v21
	v_add_f32_e32 v21, v188, v63
	ds_read_u16 v63, v171 offset:14
	ds_read_u16 v76, v171 offset:16
	ds_read_u16 v77, v171 offset:18
	v_mul_f32_e32 v21, v22, v21
	v_cvt_pk_bf16_f32 v21, v21, s0
	s_waitcnt lgkmcnt(0)
	v_lshlrev_b32_e32 v63, 16, v63
	s_waitcnt lgkmcnt(0)
	v_lshlrev_b32_e32 v76, 16, v76
	v_mul_f32_e32 v76, v190, v76
	v_fmac_f32_e32 v76, v187, v63
	s_waitcnt lgkmcnt(0)
	v_lshlrev_b32_e32 v63, 16, v77
	v_fmac_f32_e32 v76, v189, v63
	v_add_f32_e32 v63, v188, v76
	v_add_u32_e32 v76, 0x1200, v20
	v_ashrrev_i32_e32 v77, 31, v76
	v_lshl_add_u64 v[76:77], v[76:77], 1, s[50:51]
	v_add_u32_e32 v22, 0x1a00, v20
	global_store_short v[76:77], v21, off
	v_mul_f32_e32 v21, v23, v63
	v_ashrrev_i32_e32 v23, 31, v22
	v_cvt_pk_bf16_f32 v21, v21, s0
	v_lshl_add_u64 v[22:23], v[22:23], 1, s[50:51]
	global_store_short v[22:23], v21, off
	ds_read_u16 v21, v172 offset:14
	ds_read_u16 v22, v172 offset:16
	ds_read_u16 v23, v172 offset:18
	v_fma_f32 v16, v184, v70, v16
	v_fmac_f32_e32 v17, v184, v71
	s_waitcnt lgkmcnt(0)
	v_lshlrev_b32_e32 v21, 16, v21
	s_waitcnt lgkmcnt(0)
	v_lshlrev_b32_e32 v22, 16, v22
	v_mul_f32_e32 v22, v190, v22
	v_fmac_f32_e32 v22, v187, v21
	s_waitcnt lgkmcnt(0)
	v_lshlrev_b32_e32 v21, 16, v23
	v_fmac_f32_e32 v22, v189, v21
	v_add_f32_e32 v21, v188, v22
	ds_read_u16 v22, v173 offset:14
	ds_read_u16 v23, v173 offset:16
	ds_read_u16 v63, v173 offset:18
	v_mul_f32_e32 v18, v18, v21
	v_cvt_pk_bf16_f32 v18, v18, s0
	s_waitcnt lgkmcnt(0)
	v_lshlrev_b32_e32 v22, 16, v22
	s_waitcnt lgkmcnt(0)
	v_lshlrev_b32_e32 v23, 16, v23
	v_mul_f32_e32 v23, v190, v23
	v_fmac_f32_e32 v23, v187, v22
	s_waitcnt lgkmcnt(0)
	v_lshlrev_b32_e32 v22, 16, v63
	v_fmac_f32_e32 v23, v189, v22
	v_add_u32_e32 v22, 0x1400, v20
	v_add_f32_e32 v63, v188, v23
	v_ashrrev_i32_e32 v23, 31, v22
	v_lshl_add_u64 v[22:23], v[22:23], 1, s[50:51]
	global_store_short v[22:23], v18, off
	v_mul_f32_e32 v18, v19, v63
	v_cvt_pk_bf16_f32 v21, v18, s0
	v_add_u32_e32 v18, 0x1c00, v20
	v_ashrrev_i32_e32 v19, 31, v18
	v_lshl_add_u64 v[18:19], v[18:19], 1, s[50:51]
	global_store_short v[18:19], v21, off
	ds_read_u16 v18, v174 offset:14
	ds_read_u16 v19, v174 offset:16
	ds_read_u16 v21, v174 offset:18
	s_addk_i32 s92, 0x2000
	s_cmp_eq_u32 s92, 0x10000
	s_waitcnt lgkmcnt(0)
	v_lshlrev_b32_e32 v18, 16, v18
	s_waitcnt lgkmcnt(0)
	v_lshlrev_b32_e32 v19, 16, v19
	v_mul_f32_e32 v19, v190, v19
	v_fmac_f32_e32 v19, v187, v18
	s_waitcnt lgkmcnt(0)
	v_lshlrev_b32_e32 v18, 16, v21
	v_fmac_f32_e32 v19, v189, v18
	v_add_f32_e32 v18, v188, v19
	ds_read_u16 v19, v175 offset:14
	ds_read_u16 v21, v175 offset:16
	ds_read_u16 v22, v175 offset:18
	v_mul_f32_e32 v16, v16, v18
	v_add_u32_e32 v18, 0x1600, v20
	s_waitcnt lgkmcnt(0)
	v_lshlrev_b32_e32 v19, 16, v19
	s_waitcnt lgkmcnt(0)
	v_lshlrev_b32_e32 v21, 16, v21
	v_mul_f32_e32 v21, v190, v21
	v_fmac_f32_e32 v21, v187, v19
	s_waitcnt lgkmcnt(0)
	v_lshlrev_b32_e32 v19, 16, v22
	v_fmac_f32_e32 v21, v189, v19
	v_ashrrev_i32_e32 v19, 31, v18
	v_add_f32_e32 v21, v188, v21
	v_cvt_pk_bf16_f32 v16, v16, s0
	v_lshl_add_u64 v[18:19], v[18:19], 1, s[50:51]
	global_store_short v[18:19], v16, off
	v_mul_f32_e32 v16, v17, v21
	v_cvt_pk_bf16_f32 v18, v16, s0
	v_add_u32_e32 v16, 0x1e00, v20
	v_ashrrev_i32_e32 v17, 31, v16
	v_lshl_add_u64 v[16:17], v[16:17], 1, s[50:51]
	global_store_short v[16:17], v18, off
	s_cbranch_scc1 .LBB0_379

; __device__ __forceinline__ float bf2f(bf16_t b) { return __uint_as_float(((unsigned)b) << 16); }
; #define ZVAL(r, t) ((o == 0) ? dwl((r), (t), zw0, zw1, zw2, zb) : bf2f((r)[8 + (t)]))
; __device__ __forceinline__ float dwl(const bf16_t* r, int t, float w0, float w1, float w2, float b) { return w0 * bf2f(r[7 + t]) + w1 * bf2f(r[8 + t]) + w2 * bf2f(r[9 + t]) + b; }
; __device__ __forceinline__ void phase_conv(const Params& p, int o, unsigned char* smem, int wave) {
;     ...
;                 for (int r = 0; r < 4; ++r) { const int t = tid + 512 * r;
;                     x0[r] = (c2){ZVAL(raw, t), ZVAL(raw + RAWROW, t)}; x1[r] = (c2){ZVAL(raw + 2 * RAWROW, t), ZVAL(raw + 3 * RAWROW, t)}; zk0[r] = x0[r]; zk1[r] = x1[r];
;                     x0[4 + r] = (c2){0.f, 0.f}; x1[4 + r] = (c2){0.f, 0.f}; }
.LBB0_320:
	ds_read_u16 v16, v147 offset:16
	ds_read_u16 v17, v147 offset:18
	ds_read_u16 v18, v147 offset:14
	s_waitcnt lgkmcnt(0)
	v_lshlrev_b32_e32 v19, 16, v16
	s_waitcnt lgkmcnt(0)
	v_lshlrev_b32_e32 v17, 16, v17
	s_waitcnt lgkmcnt(0)
	v_lshlrev_b32_e32 v16, 16, v18
	v_pk_mul_f32 v[16:17], v[64:65], v[16:17]
	s_nop 0
	v_fma_f32 v16, v186, v19, v16
	v_add_f32_e32 v16, v16, v17
	v_add_f32_e32 v77, v185, v16

; __device__ __forceinline__ float bf2f(bf16_t b) { return __uint_as_float(((unsigned)b) << 16); }
; #define ZVAL(r, t) ((o == 0) ? dwl((r), (t), zw0, zw1, zw2, zb) : bf2f((r)[8 + (t)]))
; __device__ __forceinline__ float dwl(const bf16_t* r, int t, float w0, float w1, float w2, float b) { return w0 * bf2f(r[7 + t]) + w1 * bf2f(r[8 + t]) + w2 * bf2f(r[9 + t]) + b; }
; __device__ __forceinline__ void phase_conv(const Params& p, int o, unsigned char* smem, int wave) {
;     ...
;                 for (int r = 0; r < 4; ++r) { const int t = tid + 512 * r;
;                     x0[r] = (c2){ZVAL(raw, t), ZVAL(raw + RAWROW, t)}; x1[r] = (c2){ZVAL(raw + 2 * RAWROW, t), ZVAL(raw + 3 * RAWROW, t)}; zk0[r] = x0[r]; zk1[r] = x1[r];
;                     x0[4 + r] = (c2){0.f, 0.f}; x1[4 + r] = (c2){0.f, 0.f}; }
.LBB0_349:
	ds_read_u16 v16, v144 offset:16
	ds_read_u16 v17, v144 offset:18
	ds_read_u16 v18, v144 offset:14
	s_waitcnt lgkmcnt(0)
	v_lshlrev_b32_e32 v19, 16, v16
	s_waitcnt lgkmcnt(0)
	v_lshlrev_b32_e32 v17, 16, v17
	s_waitcnt lgkmcnt(0)
	v_lshlrev_b32_e32 v16, 16, v18
	v_pk_mul_f32 v[16:17], v[64:65], v[16:17]
	s_nop 0
	v_fma_f32 v16, v186, v19, v16
	v_add_f32_e32 v16, v16, v17
	v_add_f32_e32 v84, v185, v16
	s_mov_b64 s[72:73], -1
	s_and_b64 vcc, exec, s[30:31]
	s_cbranch_vccz .LBB0_315

; __device__ __forceinline__ float bf2f(bf16_t b) { return __uint_as_float(((unsigned)b) << 16); }
; #define ZVAL(r, t) ((o == 0) ? dwl((r), (t), zw0, zw1, zw2, zb) : bf2f((r)[8 + (t)]))
; __device__ __forceinline__ float dwl(const bf16_t* r, int t, float w0, float w1, float w2, float b) { return w0 * bf2f(r[7 + t]) + w1 * bf2f(r[8 + t]) + w2 * bf2f(r[9 + t]) + b; }
; __device__ __forceinline__ void phase_conv(const Params& p, int o, unsigned char* smem, int wave) {
;     ...
;                 for (int r = 0; r < 4; ++r) { const int t = tid + 512 * r;
;                     x0[r] = (c2){ZVAL(raw, t), ZVAL(raw + RAWROW, t)}; x1[r] = (c2){ZVAL(raw + 2 * RAWROW, t), ZVAL(raw + 3 * RAWROW, t)}; zk0[r] = x0[r]; zk1[r] = x1[r];
;                     x0[4 + r] = (c2){0.f, 0.f}; x1[4 + r] = (c2){0.f, 0.f}; }
.LBB0_351:
	ds_read_u16 v16, v145 offset:16
	ds_read_u16 v17, v145 offset:18
	ds_read_u16 v18, v145 offset:14
	s_waitcnt lgkmcnt(0)
	v_lshlrev_b32_e32 v19, 16, v16
	s_waitcnt lgkmcnt(0)
	v_lshlrev_b32_e32 v17, 16, v17
	s_waitcnt lgkmcnt(0)
	v_lshlrev_b32_e32 v16, 16, v18
	v_pk_mul_f32 v[16:17], v[64:65], v[16:17]
	s_nop 0
	v_fma_f32 v16, v186, v19, v16
	v_add_f32_e32 v16, v16, v17
	v_add_f32_e32 v85, v185, v16
	s_mov_b64 s[72:73], -1
	s_and_b64 vcc, exec, s[30:31]
	s_cbranch_vccz .LBB0_317

; __device__ __forceinline__ float bf2f(bf16_t b) { return __uint_as_float(((unsigned)b) << 16); }
; #define ZVAL(r, t) ((o == 0) ? dwl((r), (t), zw0, zw1, zw2, zb) : bf2f((r)[8 + (t)]))
; __device__ __forceinline__ float dwl(const bf16_t* r, int t, float w0, float w1, float w2, float b) { return w0 * bf2f(r[7 + t]) + w1 * bf2f(r[8 + t]) + w2 * bf2f(r[9 + t]) + b; }
; __device__ __forceinline__ void phase_conv(const Params& p, int o, unsigned char* smem, int wave) {
;     ...
;                 for (int r = 0; r < 4; ++r) { const int t = tid + 512 * r;
;                     x0[r] = (c2){ZVAL(raw, t), ZVAL(raw + RAWROW, t)}; x1[r] = (c2){ZVAL(raw + 2 * RAWROW, t), ZVAL(raw + 3 * RAWROW, t)}; zk0[r] = x0[r]; zk1[r] = x1[r];
;                     x0[4 + r] = (c2){0.f, 0.f}; x1[4 + r] = (c2){0.f, 0.f}; }
.LBB0_353:
	ds_read_u16 v16, v146 offset:16
	ds_read_u16 v17, v146 offset:18
	ds_read_u16 v18, v146 offset:14
	s_waitcnt lgkmcnt(0)
	v_lshlrev_b32_e32 v19, 16, v16
	s_waitcnt lgkmcnt(0)
	v_lshlrev_b32_e32 v17, 16, v17
	s_waitcnt lgkmcnt(0)
	v_lshlrev_b32_e32 v16, 16, v18
	v_pk_mul_f32 v[16:17], v[64:65], v[16:17]
	s_nop 0
	v_fma_f32 v16, v186, v19, v16
	v_add_f32_e32 v16, v16, v17
	v_add_f32_e32 v76, v185, v16
	s_mov_b64 s[72:73], -1
	s_and_b64 vcc, exec, s[30:31]
	s_cbranch_vccz .LBB0_319

; __device__ __forceinline__ float bf2f(bf16_t b) { return __uint_as_float(((unsigned)b) << 16); }
; #define ZVAL(r, t) ((o == 0) ? dwl((r), (t), zw0, zw1, zw2, zb) : bf2f((r)[8 + (t)]))
; __device__ __forceinline__ float dwl(const bf16_t* r, int t, float w0, float w1, float w2, float b) { return w0 * bf2f(r[7 + t]) + w1 * bf2f(r[8 + t]) + w2 * bf2f(r[9 + t]) + b; }
; __device__ __forceinline__ void phase_conv(const Params& p, int o, unsigned char* smem, int wave) {
;     ...
;                 for (int r = 0; r < 4; ++r) { const int t = tid + 512 * r;
;                     x0[r] = (c2){ZVAL(raw, t), ZVAL(raw + RAWROW, t)}; x1[r] = (c2){ZVAL(raw + 2 * RAWROW, t), ZVAL(raw + 3 * RAWROW, t)}; zk0[r] = x0[r]; zk1[r] = x1[r];
;                     x0[4 + r] = (c2){0.f, 0.f}; x1[4 + r] = (c2){0.f, 0.f}; }
.LBB0_356:
	ds_read_u16 v16, v148 offset:16
	ds_read_u16 v17, v148 offset:18
	ds_read_u16 v18, v148 offset:14
	s_waitcnt lgkmcnt(0)
	v_lshlrev_b32_e32 v19, 16, v16
	s_waitcnt lgkmcnt(0)
	v_lshlrev_b32_e32 v17, 16, v17
	s_waitcnt lgkmcnt(0)
	v_lshlrev_b32_e32 v16, 16, v18
	v_pk_mul_f32 v[16:17], v[64:65], v[16:17]
	s_nop 0
	v_fma_f32 v16, v186, v19, v16
	v_add_f32_e32 v16, v16, v17
	v_add_f32_e32 v82, v185, v16
	s_and_b64 vcc, exec, s[84:85]
	s_mov_b64 s[72:73], -1
	s_cbranch_vccnz .LBB0_324

; __device__ __forceinline__ float bf2f(bf16_t b) { return __uint_as_float(((unsigned)b) << 16); }
; #define ZVAL(r, t) ((o == 0) ? dwl((r), (t), zw0, zw1, zw2, zb) : bf2f((r)[8 + (t)]))
; __device__ __forceinline__ float dwl(const bf16_t* r, int t, float w0, float w1, float w2, float b) { return w0 * bf2f(r[7 + t]) + w1 * bf2f(r[8 + t]) + w2 * bf2f(r[9 + t]) + b; }
; __device__ __forceinline__ void phase_conv(const Params& p, int o, unsigned char* smem, int wave) {
;     ...
;                 for (int r = 0; r < 4; ++r) { const int t = tid + 512 * r;
;                     x0[r] = (c2){ZVAL(raw, t), ZVAL(raw + RAWROW, t)}; x1[r] = (c2){ZVAL(raw + 2 * RAWROW, t), ZVAL(raw + 3 * RAWROW, t)}; zk0[r] = x0[r]; zk1[r] = x1[r];
;                     x0[4 + r] = (c2){0.f, 0.f}; x1[4 + r] = (c2){0.f, 0.f}; }
.LBB0_358:
	ds_read_u16 v16, v149 offset:16
	ds_read_u16 v17, v149 offset:18
	ds_read_u16 v18, v149 offset:14
	s_waitcnt lgkmcnt(0)
	v_lshlrev_b32_e32 v19, 16, v16
	s_waitcnt lgkmcnt(0)
	v_lshlrev_b32_e32 v17, 16, v17
	s_waitcnt lgkmcnt(0)
	v_lshlrev_b32_e32 v16, 16, v18
	v_pk_mul_f32 v[16:17], v[64:65], v[16:17]
	s_nop 0
	v_fma_f32 v16, v186, v19, v16
	v_add_f32_e32 v16, v16, v17
	v_add_f32_e32 v83, v185, v16
	s_and_b64 vcc, exec, s[84:85]
	s_mov_b64 s[72:73], -1
	s_cbranch_vccnz .LBB0_326

; __device__ __forceinline__ float bf2f(bf16_t b) { return __uint_as_float(((unsigned)b) << 16); }
; #define ZVAL(r, t) ((o == 0) ? dwl((r), (t), zw0, zw1, zw2, zb) : bf2f((r)[8 + (t)]))
; __device__ __forceinline__ float dwl(const bf16_t* r, int t, float w0, float w1, float w2, float b) { return w0 * bf2f(r[7 + t]) + w1 * bf2f(r[8 + t]) + w2 * bf2f(r[9 + t]) + b; }
; __device__ __forceinline__ void phase_conv(const Params& p, int o, unsigned char* smem, int wave) {
;     ...
;                 for (int r = 0; r < 4; ++r) { const int t = tid + 512 * r;
;                     x0[r] = (c2){ZVAL(raw, t), ZVAL(raw + RAWROW, t)}; x1[r] = (c2){ZVAL(raw + 2 * RAWROW, t), ZVAL(raw + 3 * RAWROW, t)}; zk0[r] = x0[r]; zk1[r] = x1[r];
;                     x0[4 + r] = (c2){0.f, 0.f}; x1[4 + r] = (c2){0.f, 0.f}; }
.LBB0_360:
	ds_read_u16 v16, v150 offset:16
	ds_read_u16 v17, v150 offset:18
	ds_read_u16 v18, v150 offset:14
	s_waitcnt lgkmcnt(0)
	v_lshlrev_b32_e32 v19, 16, v16
	s_waitcnt lgkmcnt(0)
	v_lshlrev_b32_e32 v17, 16, v17
	s_waitcnt lgkmcnt(0)
	v_lshlrev_b32_e32 v16, 16, v18
	v_pk_mul_f32 v[16:17], v[64:65], v[16:17]
	s_nop 0
	v_fma_f32 v16, v186, v19, v16
	v_add_f32_e32 v16, v16, v17
	v_add_f32_e32 v74, v185, v16
	s_and_b64 vcc, exec, s[84:85]
	s_mov_b64 s[72:73], -1
	s_cbranch_vccnz .LBB0_328

; __device__ __forceinline__ float bf2f(bf16_t b) { return __uint_as_float(((unsigned)b) << 16); }
; #define ZVAL(r, t) ((o == 0) ? dwl((r), (t), zw0, zw1, zw2, zb) : bf2f((r)[8 + (t)]))
; __device__ __forceinline__ float dwl(const bf16_t* r, int t, float w0, float w1, float w2, float b) { return w0 * bf2f(r[7 + t]) + w1 * bf2f(r[8 + t]) + w2 * bf2f(r[9 + t]) + b; }
; __device__ __forceinline__ void phase_conv(const Params& p, int o, unsigned char* smem, int wave) {
;     ...
;                 for (int r = 0; r < 4; ++r) { const int t = tid + 512 * r;
;                     x0[r] = (c2){ZVAL(raw, t), ZVAL(raw + RAWROW, t)}; x1[r] = (c2){ZVAL(raw + 2 * RAWROW, t), ZVAL(raw + 3 * RAWROW, t)}; zk0[r] = x0[r]; zk1[r] = x1[r];
;                     x0[4 + r] = (c2){0.f, 0.f}; x1[4 + r] = (c2){0.f, 0.f}; }
.LBB0_362:
	ds_read_u16 v16, v151 offset:16
	ds_read_u16 v17, v151 offset:18
	ds_read_u16 v18, v151 offset:14
	s_waitcnt lgkmcnt(0)
	v_lshlrev_b32_e32 v19, 16, v16
	s_waitcnt lgkmcnt(0)
	v_lshlrev_b32_e32 v17, 16, v17
	s_waitcnt lgkmcnt(0)
	v_lshlrev_b32_e32 v16, 16, v18
	v_pk_mul_f32 v[16:17], v[64:65], v[16:17]
	s_nop 0
	v_fma_f32 v16, v186, v19, v16
	v_add_f32_e32 v16, v16, v17
	v_add_f32_e32 v75, v185, v16
	s_and_b64 vcc, exec, s[84:85]
	s_mov_b64 s[72:73], -1
	s_cbranch_vccnz .LBB0_330

; __device__ __forceinline__ float bf2f(bf16_t b) { return __uint_as_float(((unsigned)b) << 16); }
; #define ZVAL(r, t) ((o == 0) ? dwl((r), (t), zw0, zw1, zw2, zb) : bf2f((r)[8 + (t)]))
; __device__ __forceinline__ float dwl(const bf16_t* r, int t, float w0, float w1, float w2, float b) { return w0 * bf2f(r[7 + t]) + w1 * bf2f(r[8 + t]) + w2 * bf2f(r[9 + t]) + b; }
; __device__ __forceinline__ void phase_conv(const Params& p, int o, unsigned char* smem, int wave) {
;     ...
;                 for (int r = 0; r < 4; ++r) { const int t = tid + 512 * r;
;                     x0[r] = (c2){ZVAL(raw, t), ZVAL(raw + RAWROW, t)}; x1[r] = (c2){ZVAL(raw + 2 * RAWROW, t), ZVAL(raw + 3 * RAWROW, t)}; zk0[r] = x0[r]; zk1[r] = x1[r];
;                     x0[4 + r] = (c2){0.f, 0.f}; x1[4 + r] = (c2){0.f, 0.f}; }
.LBB0_364:
	ds_read_u16 v16, v152 offset:16
	ds_read_u16 v17, v152 offset:18
	ds_read_u16 v18, v152 offset:14
	s_waitcnt lgkmcnt(0)
	v_lshlrev_b32_e32 v19, 16, v16
	s_waitcnt lgkmcnt(0)
	v_lshlrev_b32_e32 v17, 16, v17
	s_waitcnt lgkmcnt(0)
	v_lshlrev_b32_e32 v16, 16, v18
	v_pk_mul_f32 v[16:17], v[64:65], v[16:17]
	s_nop 0
	v_fma_f32 v16, v186, v19, v16
	v_add_f32_e32 v16, v16, v17
	v_add_f32_e32 v78, v185, v16
	s_and_b64 vcc, exec, s[84:85]
	s_mov_b64 s[72:73], -1
	s_cbranch_vccnz .LBB0_332

; __device__ __forceinline__ float bf2f(bf16_t b) { return __uint_as_float(((unsigned)b) << 16); }
; #define ZVAL(r, t) ((o == 0) ? dwl((r), (t), zw0, zw1, zw2, zb) : bf2f((r)[8 + (t)]))
; __device__ __forceinline__ float dwl(const bf16_t* r, int t, float w0, float w1, float w2, float b) { return w0 * bf2f(r[7 + t]) + w1 * bf2f(r[8 + t]) + w2 * bf2f(r[9 + t]) + b; }
; __device__ __forceinline__ void phase_conv(const Params& p, int o, unsigned char* smem, int wave) {
;     ...
;                 for (int r = 0; r < 4; ++r) { const int t = tid + 512 * r;
;                     x0[r] = (c2){ZVAL(raw, t), ZVAL(raw + RAWROW, t)}; x1[r] = (c2){ZVAL(raw + 2 * RAWROW, t), ZVAL(raw + 3 * RAWROW, t)}; zk0[r] = x0[r]; zk1[r] = x1[r];
;                     x0[4 + r] = (c2){0.f, 0.f}; x1[4 + r] = (c2){0.f, 0.f}; }
.LBB0_366:
	ds_read_u16 v16, v153 offset:16
	ds_read_u16 v17, v153 offset:18
	ds_read_u16 v18, v153 offset:14
	s_waitcnt lgkmcnt(0)
	v_lshlrev_b32_e32 v19, 16, v16
	s_waitcnt lgkmcnt(0)
	v_lshlrev_b32_e32 v17, 16, v17
	s_waitcnt lgkmcnt(0)
	v_lshlrev_b32_e32 v16, 16, v18
	v_pk_mul_f32 v[16:17], v[64:65], v[16:17]
	s_nop 0
	v_fma_f32 v16, v186, v19, v16
	v_add_f32_e32 v16, v16, v17
	v_add_f32_e32 v79, v185, v16
	s_and_b64 vcc, exec, s[84:85]
	s_mov_b64 s[72:73], -1
	s_cbranch_vccnz .LBB0_334

; __device__ __forceinline__ float bf2f(bf16_t b) { return __uint_as_float(((unsigned)b) << 16); }
; #define ZVAL(r, t) ((o == 0) ? dwl((r), (t), zw0, zw1, zw2, zb) : bf2f((r)[8 + (t)]))
; __device__ __forceinline__ float dwl(const bf16_t* r, int t, float w0, float w1, float w2, float b) { return w0 * bf2f(r[7 + t]) + w1 * bf2f(r[8 + t]) + w2 * bf2f(r[9 + t]) + b; }
; __device__ __forceinline__ void phase_conv(const Params& p, int o, unsigned char* smem, int wave) {
;     ...
;                 for (int r = 0; r < 4; ++r) { const int t = tid + 512 * r;
;                     x0[r] = (c2){ZVAL(raw, t), ZVAL(raw + RAWROW, t)}; x1[r] = (c2){ZVAL(raw + 2 * RAWROW, t), ZVAL(raw + 3 * RAWROW, t)}; zk0[r] = x0[r]; zk1[r] = x1[r];
;                     x0[4 + r] = (c2){0.f, 0.f}; x1[4 + r] = (c2){0.f, 0.f}; }
.LBB0_368:
	ds_read_u16 v16, v154 offset:16
	ds_read_u16 v17, v154 offset:18
	ds_read_u16 v18, v154 offset:14
	s_waitcnt lgkmcnt(0)
	v_lshlrev_b32_e32 v19, 16, v16
	s_waitcnt lgkmcnt(0)
	v_lshlrev_b32_e32 v17, 16, v17
	s_waitcnt lgkmcnt(0)
	v_lshlrev_b32_e32 v16, 16, v18
	v_pk_mul_f32 v[16:17], v[64:65], v[16:17]
	s_nop 0
	v_fma_f32 v16, v186, v19, v16
	v_add_f32_e32 v16, v16, v17
	v_add_f32_e32 v72, v185, v16
	s_and_b64 vcc, exec, s[84:85]
	s_mov_b64 s[72:73], -1
	s_cbranch_vccnz .LBB0_336

; __device__ __forceinline__ float bf2f(bf16_t b) { return __uint_as_float(((unsigned)b) << 16); }
; #define ZVAL(r, t) ((o == 0) ? dwl((r), (t), zw0, zw1, zw2, zb) : bf2f((r)[8 + (t)]))
; __device__ __forceinline__ float dwl(const bf16_t* r, int t, float w0, float w1, float w2, float b) { return w0 * bf2f(r[7 + t]) + w1 * bf2f(r[8 + t]) + w2 * bf2f(r[9 + t]) + b; }
; __device__ __forceinline__ void phase_conv(const Params& p, int o, unsigned char* smem, int wave) {
;     ...
;                 for (int r = 0; r < 4; ++r) { const int t = tid + 512 * r;
;                     x0[r] = (c2){ZVAL(raw, t), ZVAL(raw + RAWROW, t)}; x1[r] = (c2){ZVAL(raw + 2 * RAWROW, t), ZVAL(raw + 3 * RAWROW, t)}; zk0[r] = x0[r]; zk1[r] = x1[r];
;                     x0[4 + r] = (c2){0.f, 0.f}; x1[4 + r] = (c2){0.f, 0.f}; }
.LBB0_370:
	ds_read_u16 v16, v155 offset:16
	ds_read_u16 v17, v155 offset:18
	ds_read_u16 v18, v155 offset:14
	s_waitcnt lgkmcnt(0)
	v_lshlrev_b32_e32 v19, 16, v16
	s_waitcnt lgkmcnt(0)
	v_lshlrev_b32_e32 v17, 16, v17
	s_waitcnt lgkmcnt(0)
	v_lshlrev_b32_e32 v16, 16, v18
	v_pk_mul_f32 v[16:17], v[64:65], v[16:17]
	s_nop 0
	v_fma_f32 v16, v186, v19, v16
	v_add_f32_e32 v16, v16, v17
	v_add_f32_e32 v73, v185, v16
	s_and_b64 vcc, exec, s[84:85]
	s_mov_b64 s[72:73], -1
	s_cbranch_vccnz .LBB0_338

; __device__ __forceinline__ float bf2f(bf16_t b) { return __uint_as_float(((unsigned)b) << 16); }
; #define ZVAL(r, t) ((o == 0) ? dwl((r), (t), zw0, zw1, zw2, zb) : bf2f((r)[8 + (t)]))
; __device__ __forceinline__ float dwl(const bf16_t* r, int t, float w0, float w1, float w2, float b) { return w0 * bf2f(r[7 + t]) + w1 * bf2f(r[8 + t]) + w2 * bf2f(r[9 + t]) + b; }
; __device__ __forceinline__ void phase_conv(const Params& p, int o, unsigned char* smem, int wave) {
;     ...
;                 for (int r = 0; r < 4; ++r) { const int t = tid + 512 * r;
;                     x0[r] = (c2){ZVAL(raw, t), ZVAL(raw + RAWROW, t)}; x1[r] = (c2){ZVAL(raw + 2 * RAWROW, t), ZVAL(raw + 3 * RAWROW, t)}; zk0[r] = x0[r]; zk1[r] = x1[r];
;                     x0[4 + r] = (c2){0.f, 0.f}; x1[4 + r] = (c2){0.f, 0.f}; }
.LBB0_372:
	ds_read_u16 v16, v156 offset:16
	ds_read_u16 v17, v156 offset:18
	ds_read_u16 v18, v156 offset:14
	s_waitcnt lgkmcnt(0)
	v_lshlrev_b32_e32 v19, 16, v16
	s_waitcnt lgkmcnt(0)
	v_lshlrev_b32_e32 v17, 16, v17
	s_waitcnt lgkmcnt(0)
	v_lshlrev_b32_e32 v16, 16, v18
	v_pk_mul_f32 v[16:17], v[64:65], v[16:17]
	s_nop 0
	v_fma_f32 v16, v186, v19, v16
	v_add_f32_e32 v16, v16, v17
	v_add_f32_e32 v80, v185, v16
	s_and_b64 vcc, exec, s[84:85]
	s_mov_b64 s[72:73], -1
	s_cbranch_vccnz .LBB0_340

; __device__ __forceinline__ float bf2f(bf16_t b) { return __uint_as_float(((unsigned)b) << 16); }
; #define ZVAL(r, t) ((o == 0) ? dwl((r), (t), zw0, zw1, zw2, zb) : bf2f((r)[8 + (t)]))
; __device__ __forceinline__ float dwl(const bf16_t* r, int t, float w0, float w1, float w2, float b) { return w0 * bf2f(r[7 + t]) + w1 * bf2f(r[8 + t]) + w2 * bf2f(r[9 + t]) + b; }
; __device__ __forceinline__ void phase_conv(const Params& p, int o, unsigned char* smem, int wave) {
;     ...
;                 for (int r = 0; r < 4; ++r) { const int t = tid + 512 * r;
;                     x0[r] = (c2){ZVAL(raw, t), ZVAL(raw + RAWROW, t)}; x1[r] = (c2){ZVAL(raw + 2 * RAWROW, t), ZVAL(raw + 3 * RAWROW, t)}; zk0[r] = x0[r]; zk1[r] = x1[r];
;                     x0[4 + r] = (c2){0.f, 0.f}; x1[4 + r] = (c2){0.f, 0.f}; }
.LBB0_374:
	ds_read_u16 v16, v157 offset:16
	ds_read_u16 v17, v157 offset:18
	ds_read_u16 v18, v157 offset:14
	s_waitcnt lgkmcnt(0)
	v_lshlrev_b32_e32 v19, 16, v16
	s_waitcnt lgkmcnt(0)
	v_lshlrev_b32_e32 v17, 16, v17
	s_waitcnt lgkmcnt(0)
	v_lshlrev_b32_e32 v16, 16, v18
	v_pk_mul_f32 v[16:17], v[64:65], v[16:17]
	s_nop 0
	v_fma_f32 v16, v186, v19, v16
	v_add_f32_e32 v16, v16, v17
	v_add_f32_e32 v81, v185, v16
	s_and_b64 vcc, exec, s[84:85]
	s_mov_b64 s[72:73], -1
	s_cbranch_vccnz .LBB0_342

; __device__ __forceinline__ float bf2f(bf16_t b) { return __uint_as_float(((unsigned)b) << 16); }
; #define ZVAL(r, t) ((o == 0) ? dwl((r), (t), zw0, zw1, zw2, zb) : bf2f((r)[8 + (t)]))
; __device__ __forceinline__ float dwl(const bf16_t* r, int t, float w0, float w1, float w2, float b) { return w0 * bf2f(r[7 + t]) + w1 * bf2f(r[8 + t]) + w2 * bf2f(r[9 + t]) + b; }
; __device__ __forceinline__ void phase_conv(const Params& p, int o, unsigned char* smem, int wave) {
;     ...
;                 for (int r = 0; r < 4; ++r) { const int t = tid + 512 * r;
;                     x0[r] = (c2){ZVAL(raw, t), ZVAL(raw + RAWROW, t)}; x1[r] = (c2){ZVAL(raw + 2 * RAWROW, t), ZVAL(raw + 3 * RAWROW, t)}; zk0[r] = x0[r]; zk1[r] = x1[r];
;                     x0[4 + r] = (c2){0.f, 0.f}; x1[4 + r] = (c2){0.f, 0.f}; }
.LBB0_376:
	ds_read_u16 v16, v158 offset:16
	ds_read_u16 v17, v158 offset:18
	ds_read_u16 v18, v158 offset:14
	s_waitcnt lgkmcnt(0)
	v_lshlrev_b32_e32 v19, 16, v16
	s_waitcnt lgkmcnt(0)
	v_lshlrev_b32_e32 v17, 16, v17
	s_waitcnt lgkmcnt(0)
	v_lshlrev_b32_e32 v16, 16, v18
	v_pk_mul_f32 v[16:17], v[64:65], v[16:17]
	s_nop 0
	v_fma_f32 v16, v186, v19, v16
	v_add_f32_e32 v16, v16, v17
	v_add_f32_e32 v70, v185, v16
	s_and_b64 vcc, exec, s[84:85]
	s_mov_b64 s[72:73], -1
	s_cbranch_vccnz .LBB0_344

; __device__ __forceinline__ float bf2f(bf16_t b) { return __uint_as_float(((unsigned)b) << 16); }
; #define ZVAL(r, t) ((o == 0) ? dwl((r), (t), zw0, zw1, zw2, zb) : bf2f((r)[8 + (t)]))
; __device__ __forceinline__ float dwl(const bf16_t* r, int t, float w0, float w1, float w2, float b) { return w0 * bf2f(r[7 + t]) + w1 * bf2f(r[8 + t]) + w2 * bf2f(r[9 + t]) + b; }
; __device__ __forceinline__ void phase_conv(const Params& p, int o, unsigned char* smem, int wave) {
;     ...
;                 for (int r = 0; r < 4; ++r) { const int t = tid + 512 * r;
;                     x0[r] = (c2){ZVAL(raw, t), ZVAL(raw + RAWROW, t)}; x1[r] = (c2){ZVAL(raw + 2 * RAWROW, t), ZVAL(raw + 3 * RAWROW, t)}; zk0[r] = x0[r]; zk1[r] = x1[r];
;                     x0[4 + r] = (c2){0.f, 0.f}; x1[4 + r] = (c2){0.f, 0.f}; }
.LBB0_378:
	ds_read_u16 v16, v159 offset:16
	ds_read_u16 v17, v159 offset:18
	ds_read_u16 v18, v159 offset:14
	s_waitcnt lgkmcnt(0)
	v_lshlrev_b32_e32 v19, 16, v16
	s_waitcnt lgkmcnt(0)
	v_lshlrev_b32_e32 v17, 16, v17
	s_waitcnt lgkmcnt(0)
	v_lshlrev_b32_e32 v16, 16, v18
	v_pk_mul_f32 v[16:17], v[64:65], v[16:17]
	s_nop 0
	v_fma_f32 v16, v186, v19, v16
	v_add_f32_e32 v16, v16, v17
	v_add_f32_e32 v71, v185, v16
	s_branch .LBB0_288

; __device__ __forceinline__ c2 cmul(c2 a, c2 b) { return (c2){a.x * b.x - a.y * b.y, a.x * b.y + a.y * b.x}; }
; __device__ __forceinline__ c2 mni(c2 a) { return (c2){a.y, -a.x}; }
; __device__ __forceinline__ void dft8(c2 (&x)[8]) {
;     const float s = 0.70710678118654752f;
;     const c2 a0 = x[0] + x[4], a4 = x[0] - x[4], a1 = x[1] + x[5], a5 = x[1] - x[5], a2 = x[2] + x[6], a6 = x[2] - x[6], a3 = x[3] + x[7], a7 = x[3] - x[7];
;     const c2 a5w = (c2){(a5.x + a5.y) * s, (a5.y - a5.x) * s};
;     const c2 a6w = mni(a6);
;     const c2 a7w = (c2){(a7.y - a7.x) * s, -(a7.x + a7.y) * s};
;     const c2 b0 = a0 + a2, b1 = a0 - a2, b2 = a1 + a3, b3 = mni(a1 - a3);
;     x[0] = b0 + b2; x[4] = b0 - b2; x[2] = b1 + b3; x[6] = b1 - b3;
;     const c2 c0 = a4 + a6w, c1 = a4 - a6w, c2_ = a5w + a7w, c3 = mni(a5w - a7w);
;     x[1] = c0 + c2_; x[5] = c0 - c2_; x[3] = c1 + c3; x[7] = c1 - c3;
; }
; __device__ __forceinline__ void fwd_s0(c2 (&x)[8], c2* buf, const c2* tws, int tid) {
;     dft8(x);
; #pragma unroll
;     for (int q = 1; q < 8; ++q) x[q] = cmul(x[q], tws[(q - 1) * 512 + tid]);
;     { c2* bp_ = buf + LP(tid);
; #pragma unroll
;     for (int q = 0; q < 8; ++q) bp_[576 * q] = x[q]; }
; }
.LBB0_480:
	s_or_b64 exec, exec, s[72:73]
	s_waitcnt vmcnt(0)
	v_pk_add_f32 v[16:17], v[2:3], v[10:11]
	v_sub_f32_e32 v56, v2, v10
	v_sub_f32_e32 v10, v3, v11
	v_pk_add_f32 v[2:3], v[6:7], v[14:15]
	v_sub_f32_e32 v15, v7, v15
	s_barrier
	v_sub_f32_e32 v11, v6, v14
	v_sub_f32_e32 v14, 0, v15
	v_add_f32_e32 v15, 0, v15
	v_pk_add_f32 v[18:19], v[16:17], v[2:3] neg_lo:[0,1] neg_hi:[0,1]
	v_mov_b64_e32 v[26:27], v[210:211]
	v_add_f32_e32 v6, 0, v10
	v_sub_f32_e32 v7, 0, v10
	v_pk_mul_f32 v[14:15], v[14:15], s[20:21]
	v_pk_add_f32 v[2:3], v[16:17], v[2:3]
	v_pk_add_f32 v[16:17], v[18:19], 0 neg_lo:[1,1] neg_hi:[1,1]
	v_xor_b32_e32 v11, 0x80000000, v11
	v_mov_b32_e32 v10, v57
	v_mov_b32_e32 v20, v18
	v_mov_b32_e32 v21, v57
	v_mov_b32_e32 v16, v57
	v_pk_fma_f32 v[24:25], v[6:7], s[20:21], v[14:15] op_sel_hi:[1,0,1]
	v_pk_fma_f32 v[6:7], v[6:7], s[20:21], v[14:15] op_sel_hi:[1,0,1] neg_lo:[0,0,1] neg_hi:[0,0,1]
	v_pk_add_f32 v[22:23], v[20:21], v[16:17]
	v_pk_add_f32 v[16:17], v[20:21], v[16:17] neg_lo:[0,1] neg_hi:[0,1]
	v_pk_add_f32 v[20:21], v[56:57], v[10:11]
	v_pk_add_f32 v[10:11], v[56:57], v[10:11] neg_lo:[0,1] neg_hi:[0,1]
	v_xor_b32_e32 v15, 0x80000000, v6
	v_mov_b32_e32 v14, v7
	v_pk_add_f32 v[6:7], v[20:21], v[24:25]
	v_pk_add_f32 v[20:21], v[20:21], v[24:25] neg_lo:[0,1] neg_hi:[0,1]
	v_pk_add_f32 v[24:25], v[10:11], v[14:15]
	v_pk_add_f32 v[10:11], v[10:11], v[14:15] neg_lo:[0,1] neg_hi:[0,1]
	v_mov_b64_e32 v[14:15], v[212:213]
	v_mov_b64_e32 v[28:29], v[214:215]
	v_mov_b64_e32 v[30:31], v[216:217]
	s_waitcnt lgkmcnt(0)
	v_pk_mul_f32 v[32:33], v[6:7], v[26:27] op_sel:[1,1] op_sel_hi:[1,0]
	v_pk_add_f32 v[18:19], v[2:3], v[2:3] op_sel:[0,1] op_sel_hi:[1,0]
	v_pk_fma_f32 v[34:35], v[6:7], v[26:27], v[32:33] neg_lo:[0,0,1] neg_hi:[0,0,1]
	v_pk_fma_f32 v[6:7], v[6:7], v[26:27], v[32:33] op_sel_hi:[0,1,1]
	v_mov_b32_e32 v35, v7
	s_waitcnt lgkmcnt(0)
	v_pk_mul_f32 v[6:7], v[22:23], v[14:15] op_sel:[1,1] op_sel_hi:[1,0]
	v_pk_add_f32 v[2:3], v[2:3], v[2:3] op_sel:[0,1] op_sel_hi:[0,1] neg_lo:[0,1] neg_hi:[0,1]
	v_pk_fma_f32 v[26:27], v[22:23], v[14:15], v[6:7] neg_lo:[0,0,1] neg_hi:[0,0,1]
	v_pk_fma_f32 v[6:7], v[22:23], v[14:15], v[6:7] op_sel_hi:[0,1,1]
	v_mov_b32_e32 v27, v7
	s_waitcnt lgkmcnt(0)
	v_pk_mul_f32 v[6:7], v[24:25], v[28:29] op_sel:[1,1] op_sel_hi:[1,0]
	v_mov_b32_e32 v19, v57
	v_pk_fma_f32 v[14:15], v[24:25], v[28:29], v[6:7] neg_lo:[0,0,1] neg_hi:[0,0,1]
	v_pk_fma_f32 v[6:7], v[24:25], v[28:29], v[6:7] op_sel_hi:[0,1,1]
	v_mov_b64_e32 v[24:25], v[218:219]
	v_mov_b32_e32 v15, v7
	s_waitcnt lgkmcnt(0)
	v_pk_mul_f32 v[6:7], v[30:31], 0 op_sel_hi:[1,0]
	v_sub_f32_e32 v56, v0, v8
	v_pk_fma_f32 v[22:23], v[2:3], v[30:31], v[6:7] op_sel:[0,0,1] op_sel_hi:[1,1,0] neg_lo:[0,0,1] neg_hi:[0,0,1]
	v_pk_fma_f32 v[2:3], v[2:3], v[30:31], v[6:7] op_sel:[0,0,1] op_sel_hi:[1,1,0]
	s_waitcnt lgkmcnt(0)
	v_pk_mul_f32 v[28:29], v[20:21], v[24:25] op_sel:[1,1] op_sel_hi:[1,0]
	v_mov_b32_e32 v23, v3
	v_mov_b64_e32 v[2:3], v[220:221]
	v_mov_b64_e32 v[6:7], v[222:223]
	v_pk_fma_f32 v[30:31], v[20:21], v[24:25], v[28:29] neg_lo:[0,0,1] neg_hi:[0,0,1]
	v_pk_fma_f32 v[20:21], v[20:21], v[24:25], v[28:29] op_sel_hi:[0,1,1]
	v_mov_b32_e32 v31, v21
	s_waitcnt lgkmcnt(0)
	v_pk_mul_f32 v[20:21], v[16:17], v[2:3] op_sel:[1,1] op_sel_hi:[1,0]
	v_add_u32_e32 v63, 0x800, v117
	v_pk_fma_f32 v[24:25], v[16:17], v[2:3], v[20:21] neg_lo:[0,0,1] neg_hi:[0,0,1]
	v_pk_fma_f32 v[2:3], v[16:17], v[2:3], v[20:21] op_sel_hi:[0,1,1]
	v_mov_b32_e32 v25, v3
	s_waitcnt lgkmcnt(0)
	v_pk_mul_f32 v[2:3], v[10:11], v[6:7] op_sel:[1,1] op_sel_hi:[1,0]
	v_add_u32_e32 v191, 0x9000, v117
	v_pk_fma_f32 v[16:17], v[10:11], v[6:7], v[2:3] neg_lo:[0,0,1] neg_hi:[0,0,1]
	v_pk_fma_f32 v[2:3], v[10:11], v[6:7], v[2:3] op_sel_hi:[0,1,1]
	v_mov_b32_e32 v17, v3
	ds_write2st64_b64 v115, v[18:19], v[34:35] offset1:9
	ds_write2st64_b64 v115, v[26:27], v[14:15] offset0:18 offset1:27
	ds_write2st64_b64 v115, v[22:23], v[30:31] offset0:36 offset1:45
	ds_write2st64_b64 v115, v[24:25], v[16:17] offset0:54 offset1:63
	v_pk_add_f32 v[2:3], v[0:1], v[8:9]
	v_sub_f32_e32 v6, v1, v9
	v_pk_add_f32 v[0:1], v[4:5], v[12:13]
	v_sub_f32_e32 v9, v5, v13
	v_sub_f32_e32 v8, 0, v9
	v_add_f32_e32 v9, 0, v9
	v_pk_add_f32 v[10:11], v[2:3], v[0:1] neg_lo:[0,1] neg_hi:[0,1]
	v_mov_b64_e32 v[18:19], v[210:211]
	v_sub_f32_e32 v7, v4, v12
	v_add_f32_e32 v4, 0, v6
	v_sub_f32_e32 v5, 0, v6
	v_pk_mul_f32 v[8:9], v[8:9], s[20:21]
	v_pk_add_f32 v[0:1], v[2:3], v[0:1]
	v_pk_add_f32 v[2:3], v[10:11], 0 neg_lo:[1,1] neg_hi:[1,1]
	v_xor_b32_e32 v7, 0x80000000, v7
	v_mov_b32_e32 v6, v57
	v_mov_b32_e32 v12, v10
	v_mov_b32_e32 v13, v57
	v_mov_b32_e32 v2, v57
	v_pk_fma_f32 v[16:17], v[4:5], s[20:21], v[8:9] op_sel_hi:[1,0,1]
	v_pk_fma_f32 v[4:5], v[4:5], s[20:21], v[8:9] op_sel_hi:[1,0,1] neg_lo:[0,0,1] neg_hi:[0,0,1]
	v_pk_add_f32 v[14:15], v[12:13], v[2:3]
	v_pk_add_f32 v[2:3], v[12:13], v[2:3] neg_lo:[0,1] neg_hi:[0,1]
	v_pk_add_f32 v[12:13], v[56:57], v[6:7]
	v_pk_add_f32 v[6:7], v[56:57], v[6:7] neg_lo:[0,1] neg_hi:[0,1]
	v_xor_b32_e32 v9, 0x80000000, v4
	v_mov_b32_e32 v8, v5
	v_pk_add_f32 v[4:5], v[12:13], v[16:17]
	v_pk_add_f32 v[12:13], v[12:13], v[16:17] neg_lo:[0,1] neg_hi:[0,1]
	v_pk_add_f32 v[16:17], v[6:7], v[8:9]
	v_pk_add_f32 v[6:7], v[6:7], v[8:9] neg_lo:[0,1] neg_hi:[0,1]
	v_mov_b64_e32 v[8:9], v[212:213]
	v_mov_b64_e32 v[20:21], v[214:215]
	v_mov_b64_e32 v[22:23], v[216:217]
	s_waitcnt lgkmcnt(0)
	v_pk_mul_f32 v[24:25], v[4:5], v[18:19] op_sel:[1,1] op_sel_hi:[1,0]
	v_pk_add_f32 v[10:11], v[0:1], v[0:1] op_sel:[0,1] op_sel_hi:[1,0]
	v_pk_fma_f32 v[26:27], v[4:5], v[18:19], v[24:25] neg_lo:[0,0,1] neg_hi:[0,0,1]
	v_pk_fma_f32 v[4:5], v[4:5], v[18:19], v[24:25] op_sel_hi:[0,1,1]
	v_mov_b32_e32 v27, v5
	s_waitcnt lgkmcnt(0)
; __device__ __forceinline__ c2 cmul(c2 a, c2 b) { return (c2){a.x * b.x - a.y * b.y, a.x * b.y + a.y * b.x}; }
; __device__ __forceinline__ void fwd_s0(c2 (&x)[8], c2* buf, const c2* tws, int tid) {
;     dft8(x);
; #pragma unroll
;     for (int q = 1; q < 8; ++q) x[q] = cmul(x[q], tws[(q - 1) * 512 + tid]);
;     { c2* bp_ = buf + LP(tid);
; #pragma unroll
;     for (int q = 0; q < 8; ++q) bp_[576 * q] = x[q]; }
; }
; template <int S> __device__ __forceinline__ void fwd_mid(c2* buf, const c2* tws, int tid) {
;     constexpr int lq = 9 - 3 * S, Q = 1 << lq; const c2* T = tws + (S == 1 ? 3584 : 4032);
;     const int k = tid & (Q - 1), base = ((tid >> lq) << (lq + 3)) + k;
;     c2 x[8];
;     c2* bp_ = buf + LP(base); constexpr int QP = Q + Q / 8;
; #pragma unroll
;     for (int r = 0; r < 8; ++r) x[r] = bp_[r * QP];
;     dft8(x);
; #pragma unroll
;     for (int q = 1; q < 8; ++q) x[q] = cmul(x[q], T[(q - 1) * Q + k]);
; #pragma unroll
;     for (int q = 0; q < 8; ++q) bp_[q * QP] = x[q];
; }
	v_pk_mul_f32 v[4:5], v[14:15], v[8:9] op_sel:[1,1] op_sel_hi:[1,0]
	v_pk_add_f32 v[0:1], v[0:1], v[0:1] op_sel:[0,1] op_sel_hi:[0,1] neg_lo:[0,1] neg_hi:[0,1]
	v_pk_fma_f32 v[18:19], v[14:15], v[8:9], v[4:5] neg_lo:[0,0,1] neg_hi:[0,0,1]
	v_pk_fma_f32 v[4:5], v[14:15], v[8:9], v[4:5] op_sel_hi:[0,1,1]
	v_mov_b32_e32 v19, v5
	s_waitcnt lgkmcnt(0)
	v_pk_mul_f32 v[4:5], v[16:17], v[20:21] op_sel:[1,1] op_sel_hi:[1,0]
	v_mov_b32_e32 v11, v57
	v_pk_fma_f32 v[8:9], v[16:17], v[20:21], v[4:5] neg_lo:[0,0,1] neg_hi:[0,0,1]
	v_pk_fma_f32 v[4:5], v[16:17], v[20:21], v[4:5] op_sel_hi:[0,1,1]
	v_mov_b64_e32 v[16:17], v[218:219]
	v_mov_b32_e32 v9, v5
	s_waitcnt lgkmcnt(0)
	v_pk_mul_f32 v[4:5], v[22:23], 0 op_sel_hi:[1,0]
	v_add_u32_e32 v192, 0x9800, v117
	v_pk_fma_f32 v[14:15], v[0:1], v[22:23], v[4:5] op_sel:[0,0,1] op_sel_hi:[1,1,0] neg_lo:[0,0,1] neg_hi:[0,0,1]
	v_pk_fma_f32 v[0:1], v[0:1], v[22:23], v[4:5] op_sel:[0,0,1] op_sel_hi:[1,1,0]
	s_waitcnt lgkmcnt(0)
	v_pk_mul_f32 v[20:21], v[12:13], v[16:17] op_sel:[1,1] op_sel_hi:[1,0]
	v_mov_b32_e32 v15, v1
	v_mov_b64_e32 v[0:1], v[220:221]
	v_mov_b64_e32 v[4:5], v[222:223]
	v_pk_fma_f32 v[22:23], v[12:13], v[16:17], v[20:21] neg_lo:[0,0,1] neg_hi:[0,0,1]
	v_pk_fma_f32 v[12:13], v[12:13], v[16:17], v[20:21] op_sel_hi:[0,1,1]
	v_mov_b32_e32 v23, v13
	s_waitcnt lgkmcnt(0)
	v_pk_mul_f32 v[12:13], v[2:3], v[0:1] op_sel:[1,1] op_sel_hi:[1,0]
	v_add_u32_e32 v193, 0x9000, v119
	v_pk_fma_f32 v[16:17], v[2:3], v[0:1], v[12:13] neg_lo:[0,0,1] neg_hi:[0,0,1]
	v_pk_fma_f32 v[0:1], v[2:3], v[0:1], v[12:13] op_sel_hi:[0,1,1]
	v_mov_b32_e32 v17, v1
	s_waitcnt lgkmcnt(0)
	v_pk_mul_f32 v[0:1], v[6:7], v[4:5] op_sel:[1,1] op_sel_hi:[1,0]
	v_add_u32_e32 v194, 0x9000, v121
	v_pk_fma_f32 v[2:3], v[6:7], v[4:5], v[0:1] neg_lo:[0,0,1] neg_hi:[0,0,1]
	v_pk_fma_f32 v[0:1], v[6:7], v[4:5], v[0:1] op_sel_hi:[0,1,1]
	v_mov_b32_e32 v3, v1
	ds_write2st64_b64 v115, v[10:11], v[26:27] offset0:72 offset1:81
	ds_write2st64_b64 v115, v[18:19], v[8:9] offset0:90 offset1:99
	ds_write2st64_b64 v115, v[14:15], v[22:23] offset0:108 offset1:117
	ds_write_b64 v115, v[16:17] offset:64512
	ds_write_b64 v116, v[2:3] offset:32256
	s_waitcnt lgkmcnt(0)
	s_barrier
	ds_read2_b64 v[0:3], v117 offset1:72
	ds_read2_b64 v[4:7], v63 offset0:32 offset1:104
	ds_read2_b64 v[8:11], v117 offset0:144 offset1:216
	ds_read2_b64 v[12:15], v63 offset0:176 offset1:248
	v_mov_b64_e32 v[18:19], v[224:225]
	v_add_u32_e32 v195, 0x9020, v121
	v_add_u32_e32 v196, 0x9010, v121
	s_waitcnt lgkmcnt(0)
	v_pk_add_f32 v[16:17], v[0:1], v[4:5]
	v_pk_add_f32 v[0:1], v[0:1], v[4:5] neg_lo:[0,1] neg_hi:[0,1]
	v_pk_add_f32 v[4:5], v[2:3], v[6:7]
	v_pk_add_f32 v[2:3], v[2:3], v[6:7] neg_lo:[0,1] neg_hi:[0,1]
	s_waitcnt lgkmcnt(0)
	v_pk_add_f32 v[6:7], v[8:9], v[12:13]
	v_pk_add_f32 v[8:9], v[8:9], v[12:13] neg_lo:[0,1] neg_hi:[0,1]
	v_pk_add_f32 v[12:13], v[10:11], v[14:15]
	v_pk_add_f32 v[10:11], v[10:11], v[14:15] neg_lo:[0,1] neg_hi:[0,1]
	v_pk_add_f32 v[14:15], v[2:3], v[2:3] op_sel:[1,0]
	v_pk_add_f32 v[2:3], v[2:3], v[2:3] op_sel_hi:[1,0] neg_lo:[0,1] neg_hi:[0,1]
	v_add_u32_e32 v197, 0x9030, v121
	v_mov_b32_e32 v15, v3
	v_xor_b32_e32 v3, 0x80000000, v8
	v_mov_b32_e32 v2, v9
	v_pk_add_f32 v[8:9], v[10:11], v[10:11] op_sel:[1,0] neg_lo:[0,1] neg_hi:[0,1]
	v_pk_add_f32 v[10:11], v[10:11], v[10:11] op_sel_hi:[1,0]
	s_andn2_b64 vcc, exec, s[70:71]
	v_mov_b32_e32 v9, v11
	v_pk_add_f32 v[10:11], v[16:17], v[6:7]
	v_pk_add_f32 v[6:7], v[16:17], v[6:7] neg_lo:[0,1] neg_hi:[0,1]
	v_pk_add_f32 v[16:17], v[4:5], v[12:13]
	v_pk_add_f32 v[4:5], v[4:5], v[12:13] neg_lo:[0,1] neg_hi:[0,1]
	v_pk_mul_f32 v[8:9], v[8:9], s[20:21]
	v_xor_b32_e32 v13, 0x80000000, v4
	v_mov_b32_e32 v12, v5
	v_pk_add_f32 v[4:5], v[10:11], v[16:17]
	v_pk_add_f32 v[10:11], v[10:11], v[16:17] neg_lo:[0,1] neg_hi:[0,1]
	v_pk_add_f32 v[16:17], v[6:7], v[12:13]
	v_pk_add_f32 v[6:7], v[6:7], v[12:13] neg_lo:[0,1] neg_hi:[0,1]
	v_pk_add_f32 v[12:13], v[0:1], v[2:3]
	v_pk_add_f32 v[0:1], v[0:1], v[2:3] neg_lo:[0,1] neg_hi:[0,1]
	v_pk_fma_f32 v[2:3], v[14:15], s[20:21], v[8:9] op_sel_hi:[1,0,1]
	v_pk_fma_f32 v[8:9], v[14:15], s[20:21], v[8:9] op_sel_hi:[1,0,1] neg_lo:[0,0,1] neg_hi:[0,0,1]
	s_nop 0
	v_xor_b32_e32 v15, 0x80000000, v8
	v_mov_b32_e32 v14, v9
	v_pk_add_f32 v[8:9], v[12:13], v[2:3]
	v_pk_add_f32 v[2:3], v[12:13], v[2:3] neg_lo:[0,1] neg_hi:[0,1]
	v_pk_add_f32 v[12:13], v[0:1], v[14:15]
	v_pk_add_f32 v[0:1], v[0:1], v[14:15] neg_lo:[0,1] neg_hi:[0,1]
	v_mov_b64_e32 v[14:15], v[226:227]
	v_mov_b64_e32 v[20:21], v[228:229]
	v_mov_b64_e32 v[22:23], v[230:231]
	s_waitcnt lgkmcnt(0)
	v_pk_mul_f32 v[24:25], v[18:19], v[8:9] op_sel:[1,1] op_sel_hi:[0,1]
	v_pk_fma_f32 v[26:27], v[18:19], v[8:9], v[24:25] neg_lo:[0,0,1] neg_hi:[0,0,1]
	v_pk_fma_f32 v[8:9], v[18:19], v[8:9], v[24:25] op_sel_hi:[1,0,1]
	s_nop 0
	v_mov_b32_e32 v27, v9
	s_waitcnt lgkmcnt(0)
	v_pk_mul_f32 v[8:9], v[14:15], v[16:17] op_sel:[1,1] op_sel_hi:[0,1]
	v_pk_fma_f32 v[18:19], v[14:15], v[16:17], v[8:9] neg_lo:[0,0,1] neg_hi:[0,0,1]
	v_pk_fma_f32 v[8:9], v[14:15], v[16:17], v[8:9] op_sel_hi:[1,0,1]
	v_mov_b64_e32 v[16:17], v[232:233]
	v_mov_b32_e32 v19, v9
	s_waitcnt lgkmcnt(0)
	v_pk_mul_f32 v[8:9], v[20:21], v[12:13] op_sel:[1,1] op_sel_hi:[0,1]
	v_pk_fma_f32 v[14:15], v[20:21], v[12:13], v[8:9] neg_lo:[0,0,1] neg_hi:[0,0,1]
	v_pk_fma_f32 v[8:9], v[20:21], v[12:13], v[8:9] op_sel_hi:[1,0,1]
	s_waitcnt lgkmcnt(0)
; __device__ __forceinline__ c2 cmul(c2 a, c2 b) { return (c2){a.x * b.x - a.y * b.y, a.x * b.y + a.y * b.x}; }
; template <int S> __device__ __forceinline__ void fwd_mid(c2* buf, const c2* tws, int tid) {
;     constexpr int lq = 9 - 3 * S, Q = 1 << lq; const c2* T = tws + (S == 1 ? 3584 : 4032);
;     const int k = tid & (Q - 1), base = ((tid >> lq) << (lq + 3)) + k;
;     c2 x[8];
;     c2* bp_ = buf + LP(base); constexpr int QP = Q + Q / 8;
; #pragma unroll
;     for (int r = 0; r < 8; ++r) x[r] = bp_[r * QP];
;     dft8(x);
; #pragma unroll
;     for (int q = 1; q < 8; ++q) x[q] = cmul(x[q], T[(q - 1) * Q + k]);
; #pragma unroll
;     for (int q = 0; q < 8; ++q) bp_[q * QP] = x[q];
; }
	v_pk_mul_f32 v[20:21], v[16:17], v[2:3] op_sel:[1,1] op_sel_hi:[0,1]
	v_mov_b32_e32 v15, v9
	v_pk_mul_f32 v[8:9], v[10:11], v[22:23] op_sel:[1,1] op_sel_hi:[1,0]
	s_nop 0
	v_pk_fma_f32 v[12:13], v[10:11], v[22:23], v[8:9] neg_lo:[0,0,1] neg_hi:[0,0,1]
	v_pk_fma_f32 v[8:9], v[10:11], v[22:23], v[8:9] op_sel_hi:[0,1,1]
	v_mov_b32_e32 v13, v9
	v_mov_b64_e32 v[8:9], v[234:235]
	v_mov_b64_e32 v[10:11], v[236:237]
	v_pk_fma_f32 v[22:23], v[16:17], v[2:3], v[20:21] neg_lo:[0,0,1] neg_hi:[0,0,1]
	v_pk_fma_f32 v[2:3], v[16:17], v[2:3], v[20:21] op_sel_hi:[1,0,1]
	ds_write2_b64 v117, v[4:5], v[26:27] offset1:72
	ds_write2_b64 v117, v[18:19], v[14:15] offset0:144 offset1:216
	v_mov_b32_e32 v23, v3
	s_waitcnt lgkmcnt(0)
	v_pk_mul_f32 v[2:3], v[6:7], v[8:9] op_sel:[1,1] op_sel_hi:[1,0]
	s_nop 0
	v_pk_fma_f32 v[16:17], v[6:7], v[8:9], v[2:3] neg_lo:[0,0,1] neg_hi:[0,0,1]
	v_pk_fma_f32 v[2:3], v[6:7], v[8:9], v[2:3] op_sel_hi:[0,1,1]
	v_mov_b32_e32 v17, v3
	s_waitcnt lgkmcnt(0)
	v_pk_mul_f32 v[2:3], v[10:11], v[0:1] op_sel:[1,1] op_sel_hi:[0,1]
	v_pk_fma_f32 v[8:9], v[10:11], v[0:1], v[2:3] neg_lo:[0,0,1] neg_hi:[0,0,1]
	v_pk_fma_f32 v[0:1], v[10:11], v[0:1], v[2:3] op_sel_hi:[1,0,1]
	ds_read2_b64 v[4:7], v192 offset0:32 offset1:104
	v_mov_b32_e32 v9, v1
	ds_read2_b64 v[0:3], v191 offset1:72
	ds_write2_b64 v63, v[12:13], v[22:23] offset0:32 offset1:104
	ds_write2_b64 v63, v[16:17], v[8:9] offset0:176 offset1:248
	ds_read2_b64 v[8:11], v191 offset0:144 offset1:216
	ds_read2_b64 v[12:15], v192 offset0:176 offset1:248
	v_mov_b64_e32 v[18:19], v[224:225]
	s_waitcnt lgkmcnt(0)
	v_pk_add_f32 v[16:17], v[0:1], v[4:5]
	v_pk_add_f32 v[0:1], v[0:1], v[4:5] neg_lo:[0,1] neg_hi:[0,1]
	v_pk_add_f32 v[4:5], v[2:3], v[6:7]
	v_pk_add_f32 v[2:3], v[2:3], v[6:7] neg_lo:[0,1] neg_hi:[0,1]
	s_waitcnt lgkmcnt(0)
	v_pk_add_f32 v[6:7], v[8:9], v[12:13]
	v_pk_add_f32 v[8:9], v[8:9], v[12:13] neg_lo:[0,1] neg_hi:[0,1]
	v_pk_add_f32 v[12:13], v[10:11], v[14:15]
	v_pk_add_f32 v[10:11], v[10:11], v[14:15] neg_lo:[0,1] neg_hi:[0,1]
	v_pk_add_f32 v[14:15], v[2:3], v[2:3] op_sel:[1,0]
	v_pk_add_f32 v[2:3], v[2:3], v[2:3] op_sel_hi:[1,0] neg_lo:[0,1] neg_hi:[0,1]
	s_nop 0
	v_mov_b32_e32 v15, v3
	v_xor_b32_e32 v3, 0x80000000, v8
	v_mov_b32_e32 v2, v9
	v_pk_add_f32 v[8:9], v[10:11], v[10:11] op_sel:[1,0] neg_lo:[0,1] neg_hi:[0,1]
	v_pk_add_f32 v[10:11], v[10:11], v[10:11] op_sel_hi:[1,0]
	s_nop 0
	v_mov_b32_e32 v9, v11
	v_pk_add_f32 v[10:11], v[16:17], v[6:7]
	v_pk_add_f32 v[6:7], v[16:17], v[6:7] neg_lo:[0,1] neg_hi:[0,1]
	v_pk_add_f32 v[16:17], v[4:5], v[12:13]
	v_pk_add_f32 v[4:5], v[4:5], v[12:13] neg_lo:[0,1] neg_hi:[0,1]
	v_pk_mul_f32 v[8:9], v[8:9], s[20:21]
	v_xor_b32_e32 v13, 0x80000000, v4
	v_mov_b32_e32 v12, v5
	v_pk_add_f32 v[4:5], v[10:11], v[16:17]
	v_pk_add_f32 v[10:11], v[10:11], v[16:17] neg_lo:[0,1] neg_hi:[0,1]
	v_pk_add_f32 v[16:17], v[6:7], v[12:13]
	v_pk_add_f32 v[6:7], v[6:7], v[12:13] neg_lo:[0,1] neg_hi:[0,1]
	v_pk_add_f32 v[12:13], v[0:1], v[2:3]
	v_pk_add_f32 v[0:1], v[0:1], v[2:3] neg_lo:[0,1] neg_hi:[0,1]
	v_pk_fma_f32 v[2:3], v[14:15], s[20:21], v[8:9] op_sel_hi:[1,0,1]
	v_pk_fma_f32 v[8:9], v[14:15], s[20:21], v[8:9] op_sel_hi:[1,0,1] neg_lo:[0,0,1] neg_hi:[0,0,1]
	s_nop 0
	v_xor_b32_e32 v15, 0x80000000, v8
	v_mov_b32_e32 v14, v9
	v_pk_add_f32 v[8:9], v[12:13], v[2:3]
	v_pk_add_f32 v[2:3], v[12:13], v[2:3] neg_lo:[0,1] neg_hi:[0,1]
	v_pk_add_f32 v[12:13], v[0:1], v[14:15]
	v_pk_add_f32 v[0:1], v[0:1], v[14:15] neg_lo:[0,1] neg_hi:[0,1]
	v_mov_b64_e32 v[14:15], v[226:227]
	v_mov_b64_e32 v[20:21], v[228:229]
	v_mov_b64_e32 v[22:23], v[230:231]
	s_waitcnt lgkmcnt(0)
	v_pk_mul_f32 v[24:25], v[18:19], v[8:9] op_sel:[1,1] op_sel_hi:[0,1]
	v_pk_fma_f32 v[26:27], v[18:19], v[8:9], v[24:25] neg_lo:[0,0,1] neg_hi:[0,0,1]
	v_pk_fma_f32 v[8:9], v[18:19], v[8:9], v[24:25] op_sel_hi:[1,0,1]
	s_nop 0
	v_mov_b32_e32 v27, v9
	s_waitcnt lgkmcnt(0)
	v_pk_mul_f32 v[8:9], v[14:15], v[16:17] op_sel:[1,1] op_sel_hi:[0,1]
	v_pk_fma_f32 v[18:19], v[14:15], v[16:17], v[8:9] neg_lo:[0,0,1] neg_hi:[0,0,1]
	v_pk_fma_f32 v[8:9], v[14:15], v[16:17], v[8:9] op_sel_hi:[1,0,1]
	v_mov_b64_e32 v[16:17], v[232:233]
	v_mov_b32_e32 v19, v9
	s_waitcnt lgkmcnt(0)
	v_pk_mul_f32 v[8:9], v[20:21], v[12:13] op_sel:[1,1] op_sel_hi:[0,1]
	v_pk_fma_f32 v[14:15], v[20:21], v[12:13], v[8:9] neg_lo:[0,0,1] neg_hi:[0,0,1]
	v_pk_fma_f32 v[8:9], v[20:21], v[12:13], v[8:9] op_sel_hi:[1,0,1]
	s_waitcnt lgkmcnt(0)
	v_pk_mul_f32 v[20:21], v[16:17], v[2:3] op_sel:[1,1] op_sel_hi:[0,1]
	v_mov_b32_e32 v15, v9
	v_pk_mul_f32 v[8:9], v[10:11], v[22:23] op_sel:[1,1] op_sel_hi:[1,0]
	s_nop 0
	v_pk_fma_f32 v[12:13], v[10:11], v[22:23], v[8:9] neg_lo:[0,0,1] neg_hi:[0,0,1]
	v_pk_fma_f32 v[8:9], v[10:11], v[22:23], v[8:9] op_sel_hi:[0,1,1]
	v_mov_b32_e32 v13, v9
	v_mov_b64_e32 v[8:9], v[234:235]
	v_mov_b64_e32 v[10:11], v[236:237]
	v_pk_fma_f32 v[22:23], v[16:17], v[2:3], v[20:21] neg_lo:[0,0,1] neg_hi:[0,0,1]
	v_pk_fma_f32 v[2:3], v[16:17], v[2:3], v[20:21] op_sel_hi:[1,0,1]
	s_nop 0
	v_mov_b32_e32 v23, v3
	s_waitcnt lgkmcnt(0)
	v_pk_mul_f32 v[2:3], v[6:7], v[8:9] op_sel:[1,1] op_sel_hi:[1,0]
	s_nop 0
	v_pk_fma_f32 v[16:17], v[6:7], v[8:9], v[2:3] neg_lo:[0,0,1] neg_hi:[0,0,1]
	v_pk_fma_f32 v[2:3], v[6:7], v[8:9], v[2:3] op_sel_hi:[0,1,1]
	v_mov_b32_e32 v17, v3
	s_waitcnt lgkmcnt(0)
	v_pk_mul_f32 v[2:3], v[10:11], v[0:1] op_sel:[1,1] op_sel_hi:[0,1]
	v_pk_fma_f32 v[6:7], v[10:11], v[0:1], v[2:3] neg_lo:[0,0,1] neg_hi:[0,0,1]
	v_pk_fma_f32 v[0:1], v[10:11], v[0:1], v[2:3] op_sel_hi:[1,0,1]
	s_nop 0
	v_mov_b32_e32 v7, v1
	ds_write2_b64 v191, v[4:5], v[26:27] offset1:72
	ds_write2_b64 v191, v[18:19], v[14:15] offset0:144 offset1:216
	ds_write2_b64 v192, v[12:13], v[22:23] offset0:32 offset1:104
	ds_write2_b64 v192, v[16:17], v[6:7] offset0:176 offset1:248
	s_waitcnt lgkmcnt(0)
	s_barrier
; __device__ __forceinline__ c2 cmul(c2 a, c2 b) { return (c2){a.x * b.x - a.y * b.y, a.x * b.y + a.y * b.x}; }
; template <int S> __device__ __forceinline__ void fwd_mid(c2* buf, const c2* tws, int tid) {
;     constexpr int lq = 9 - 3 * S, Q = 1 << lq; const c2* T = tws + (S == 1 ? 3584 : 4032);
;     const int k = tid & (Q - 1), base = ((tid >> lq) << (lq + 3)) + k;
;     c2 x[8];
;     c2* bp_ = buf + LP(base); constexpr int QP = Q + Q / 8;
; #pragma unroll
;     for (int r = 0; r < 8; ++r) x[r] = bp_[r * QP];
;     dft8(x);
; #pragma unroll
;     for (int q = 1; q < 8; ++q) x[q] = cmul(x[q], T[(q - 1) * Q + k]);
; #pragma unroll
;     for (int q = 0; q < 8; ++q) bp_[q * QP] = x[q];
; }
	ds_read2_b64 v[0:3], v119 offset1:9
	ds_read2_b64 v[4:7], v119 offset0:36 offset1:45
	ds_read2_b64 v[8:11], v119 offset0:18 offset1:27
	ds_read2_b64 v[12:15], v119 offset0:54 offset1:63
	v_mov_b64_e32 v[18:19], v[238:239]
	s_waitcnt lgkmcnt(0)
	v_pk_add_f32 v[16:17], v[0:1], v[4:5]
	v_pk_add_f32 v[0:1], v[0:1], v[4:5] neg_lo:[0,1] neg_hi:[0,1]
	v_pk_add_f32 v[4:5], v[2:3], v[6:7]
	v_pk_add_f32 v[2:3], v[2:3], v[6:7] neg_lo:[0,1] neg_hi:[0,1]
	s_waitcnt lgkmcnt(0)
	v_pk_add_f32 v[6:7], v[8:9], v[12:13]
	v_pk_add_f32 v[8:9], v[8:9], v[12:13] neg_lo:[0,1] neg_hi:[0,1]
	v_pk_add_f32 v[12:13], v[10:11], v[14:15]
	v_pk_add_f32 v[10:11], v[10:11], v[14:15] neg_lo:[0,1] neg_hi:[0,1]
	v_pk_add_f32 v[14:15], v[2:3], v[2:3] op_sel:[1,0]
	v_pk_add_f32 v[2:3], v[2:3], v[2:3] op_sel_hi:[1,0] neg_lo:[0,1] neg_hi:[0,1]
	s_nop 0
	v_mov_b32_e32 v15, v3
	v_xor_b32_e32 v3, 0x80000000, v8
	v_mov_b32_e32 v2, v9
	v_pk_add_f32 v[8:9], v[10:11], v[10:11] op_sel:[1,0] neg_lo:[0,1] neg_hi:[0,1]
	v_pk_add_f32 v[10:11], v[10:11], v[10:11] op_sel_hi:[1,0]
	s_nop 0
	v_mov_b32_e32 v9, v11
	v_pk_add_f32 v[10:11], v[16:17], v[6:7]
	v_pk_add_f32 v[6:7], v[16:17], v[6:7] neg_lo:[0,1] neg_hi:[0,1]
	v_pk_add_f32 v[16:17], v[4:5], v[12:13]
	v_pk_add_f32 v[4:5], v[4:5], v[12:13] neg_lo:[0,1] neg_hi:[0,1]
	v_pk_mul_f32 v[8:9], v[8:9], s[20:21]
	v_xor_b32_e32 v13, 0x80000000, v4
	v_mov_b32_e32 v12, v5
	v_pk_add_f32 v[4:5], v[10:11], v[16:17]
	v_pk_add_f32 v[10:11], v[10:11], v[16:17] neg_lo:[0,1] neg_hi:[0,1]
	v_pk_add_f32 v[16:17], v[6:7], v[12:13]
	v_pk_add_f32 v[6:7], v[6:7], v[12:13] neg_lo:[0,1] neg_hi:[0,1]
	v_pk_add_f32 v[12:13], v[0:1], v[2:3]
	v_pk_add_f32 v[0:1], v[0:1], v[2:3] neg_lo:[0,1] neg_hi:[0,1]
	v_pk_fma_f32 v[2:3], v[14:15], s[20:21], v[8:9] op_sel_hi:[1,0,1]
	v_pk_fma_f32 v[8:9], v[14:15], s[20:21], v[8:9] op_sel_hi:[1,0,1] neg_lo:[0,0,1] neg_hi:[0,0,1]
	s_nop 0
	v_xor_b32_e32 v15, 0x80000000, v8
	v_mov_b32_e32 v14, v9
	v_pk_add_f32 v[8:9], v[12:13], v[2:3]
	v_pk_add_f32 v[2:3], v[12:13], v[2:3] neg_lo:[0,1] neg_hi:[0,1]
	v_pk_add_f32 v[12:13], v[0:1], v[14:15]
	v_pk_add_f32 v[0:1], v[0:1], v[14:15] neg_lo:[0,1] neg_hi:[0,1]
	v_mov_b64_e32 v[14:15], v[240:241]
	v_mov_b64_e32 v[20:21], v[242:243]
	v_mov_b64_e32 v[22:23], v[244:245]
	s_waitcnt lgkmcnt(0)
	v_pk_mul_f32 v[24:25], v[18:19], v[8:9] op_sel:[1,1] op_sel_hi:[0,1]
	v_pk_fma_f32 v[26:27], v[18:19], v[8:9], v[24:25] neg_lo:[0,0,1] neg_hi:[0,0,1]
	v_pk_fma_f32 v[8:9], v[18:19], v[8:9], v[24:25] op_sel_hi:[1,0,1]
	s_nop 0
	v_mov_b32_e32 v27, v9
	s_waitcnt lgkmcnt(0)
	v_pk_mul_f32 v[8:9], v[14:15], v[16:17] op_sel:[1,1] op_sel_hi:[0,1]
	v_pk_fma_f32 v[18:19], v[14:15], v[16:17], v[8:9] neg_lo:[0,0,1] neg_hi:[0,0,1]
	v_pk_fma_f32 v[8:9], v[14:15], v[16:17], v[8:9] op_sel_hi:[1,0,1]
	v_mov_b64_e32 v[16:17], v[246:247]
	v_mov_b32_e32 v19, v9
	s_waitcnt lgkmcnt(0)
	v_pk_mul_f32 v[8:9], v[20:21], v[12:13] op_sel:[1,1] op_sel_hi:[0,1]
	v_pk_fma_f32 v[14:15], v[20:21], v[12:13], v[8:9] neg_lo:[0,0,1] neg_hi:[0,0,1]
	v_pk_fma_f32 v[8:9], v[20:21], v[12:13], v[8:9] op_sel_hi:[1,0,1]
	s_waitcnt lgkmcnt(0)
	v_pk_mul_f32 v[20:21], v[16:17], v[2:3] op_sel:[1,1] op_sel_hi:[0,1]
	v_mov_b32_e32 v15, v9
	v_pk_mul_f32 v[8:9], v[10:11], v[22:23] op_sel:[1,1] op_sel_hi:[1,0]
	s_nop 0
	v_pk_fma_f32 v[12:13], v[10:11], v[22:23], v[8:9] neg_lo:[0,0,1] neg_hi:[0,0,1]
	v_pk_fma_f32 v[8:9], v[10:11], v[22:23], v[8:9] op_sel_hi:[0,1,1]
	v_mov_b32_e32 v13, v9
	v_mov_b64_e32 v[8:9], v[248:249]
	v_mov_b64_e32 v[10:11], v[250:251]
	v_pk_fma_f32 v[22:23], v[16:17], v[2:3], v[20:21] neg_lo:[0,0,1] neg_hi:[0,0,1]
	v_pk_fma_f32 v[2:3], v[16:17], v[2:3], v[20:21] op_sel_hi:[1,0,1]
	ds_write2_b64 v119, v[4:5], v[26:27] offset1:9
	ds_write2_b64 v119, v[18:19], v[14:15] offset0:18 offset1:27
	v_mov_b32_e32 v23, v3
	s_waitcnt lgkmcnt(0)
	v_pk_mul_f32 v[2:3], v[6:7], v[8:9] op_sel:[1,1] op_sel_hi:[1,0]
	s_nop 0
	v_pk_fma_f32 v[16:17], v[6:7], v[8:9], v[2:3] neg_lo:[0,0,1] neg_hi:[0,0,1]
	v_pk_fma_f32 v[2:3], v[6:7], v[8:9], v[2:3] op_sel_hi:[0,1,1]
	v_mov_b32_e32 v17, v3
	s_waitcnt lgkmcnt(0)
	v_pk_mul_f32 v[2:3], v[10:11], v[0:1] op_sel:[1,1] op_sel_hi:[0,1]
	v_pk_fma_f32 v[8:9], v[10:11], v[0:1], v[2:3] neg_lo:[0,0,1] neg_hi:[0,0,1]
	v_pk_fma_f32 v[0:1], v[10:11], v[0:1], v[2:3] op_sel_hi:[1,0,1]
	s_nop 0
	v_mov_b32_e32 v9, v1
	ds_read2_b64 v[0:3], v193 offset1:9
	ds_read2_b64 v[4:7], v193 offset0:36 offset1:45
	ds_write2_b64 v119, v[12:13], v[22:23] offset0:36 offset1:45
	ds_write2_b64 v119, v[16:17], v[8:9] offset0:54 offset1:63
	ds_read2_b64 v[8:11], v193 offset0:18 offset1:27
	ds_read2_b64 v[12:15], v193 offset0:54 offset1:63
	v_mov_b64_e32 v[18:19], v[238:239]
	s_waitcnt lgkmcnt(0)
	v_pk_add_f32 v[16:17], v[0:1], v[4:5]
	v_pk_add_f32 v[0:1], v[0:1], v[4:5] neg_lo:[0,1] neg_hi:[0,1]
	v_pk_add_f32 v[4:5], v[2:3], v[6:7]
	v_pk_add_f32 v[2:3], v[2:3], v[6:7] neg_lo:[0,1] neg_hi:[0,1]
	s_waitcnt lgkmcnt(0)
; __device__ __forceinline__ c2 cmul(c2 a, c2 b) { return (c2){a.x * b.x - a.y * b.y, a.x * b.y + a.y * b.x}; }
; template <int S> __device__ __forceinline__ void fwd_mid(c2* buf, const c2* tws, int tid) {
;     constexpr int lq = 9 - 3 * S, Q = 1 << lq; const c2* T = tws + (S == 1 ? 3584 : 4032);
;     const int k = tid & (Q - 1), base = ((tid >> lq) << (lq + 3)) + k;
;     c2 x[8];
;     c2* bp_ = buf + LP(base); constexpr int QP = Q + Q / 8;
; #pragma unroll
;     for (int r = 0; r < 8; ++r) x[r] = bp_[r * QP];
;     dft8(x);
; #pragma unroll
;     for (int q = 1; q < 8; ++q) x[q] = cmul(x[q], T[(q - 1) * Q + k]);
; #pragma unroll
;     for (int q = 0; q < 8; ++q) bp_[q * QP] = x[q];
; }
	v_pk_add_f32 v[6:7], v[8:9], v[12:13]
	v_pk_add_f32 v[8:9], v[8:9], v[12:13] neg_lo:[0,1] neg_hi:[0,1]
	v_pk_add_f32 v[12:13], v[10:11], v[14:15]
	v_pk_add_f32 v[10:11], v[10:11], v[14:15] neg_lo:[0,1] neg_hi:[0,1]
	v_pk_add_f32 v[14:15], v[2:3], v[2:3] op_sel:[1,0]
	v_pk_add_f32 v[2:3], v[2:3], v[2:3] op_sel_hi:[1,0] neg_lo:[0,1] neg_hi:[0,1]
	s_nop 0
	v_mov_b32_e32 v15, v3
	v_xor_b32_e32 v3, 0x80000000, v8
	v_mov_b32_e32 v2, v9
	v_pk_add_f32 v[8:9], v[10:11], v[10:11] op_sel:[1,0] neg_lo:[0,1] neg_hi:[0,1]
	v_pk_add_f32 v[10:11], v[10:11], v[10:11] op_sel_hi:[1,0]
	s_nop 0
	v_mov_b32_e32 v9, v11
	v_pk_add_f32 v[10:11], v[16:17], v[6:7]
	v_pk_add_f32 v[6:7], v[16:17], v[6:7] neg_lo:[0,1] neg_hi:[0,1]
	v_pk_add_f32 v[16:17], v[4:5], v[12:13]
	v_pk_add_f32 v[4:5], v[4:5], v[12:13] neg_lo:[0,1] neg_hi:[0,1]
	v_pk_mul_f32 v[8:9], v[8:9], s[20:21]
	v_xor_b32_e32 v13, 0x80000000, v4
	v_mov_b32_e32 v12, v5
	v_pk_add_f32 v[4:5], v[10:11], v[16:17]
	v_pk_add_f32 v[10:11], v[10:11], v[16:17] neg_lo:[0,1] neg_hi:[0,1]
	v_pk_add_f32 v[16:17], v[6:7], v[12:13]
	v_pk_add_f32 v[6:7], v[6:7], v[12:13] neg_lo:[0,1] neg_hi:[0,1]
	v_pk_add_f32 v[12:13], v[0:1], v[2:3]
	v_pk_add_f32 v[0:1], v[0:1], v[2:3] neg_lo:[0,1] neg_hi:[0,1]
	v_pk_fma_f32 v[2:3], v[14:15], s[20:21], v[8:9] op_sel_hi:[1,0,1]
	v_pk_fma_f32 v[8:9], v[14:15], s[20:21], v[8:9] op_sel_hi:[1,0,1] neg_lo:[0,0,1] neg_hi:[0,0,1]
	s_nop 0
	v_xor_b32_e32 v15, 0x80000000, v8
	v_mov_b32_e32 v14, v9
	v_pk_add_f32 v[8:9], v[12:13], v[2:3]
	v_pk_add_f32 v[2:3], v[12:13], v[2:3] neg_lo:[0,1] neg_hi:[0,1]
	v_pk_add_f32 v[12:13], v[0:1], v[14:15]
	v_pk_add_f32 v[0:1], v[0:1], v[14:15] neg_lo:[0,1] neg_hi:[0,1]
	v_mov_b64_e32 v[14:15], v[240:241]
	v_mov_b64_e32 v[20:21], v[242:243]
	v_mov_b64_e32 v[22:23], v[244:245]
	s_waitcnt lgkmcnt(0)
	v_pk_mul_f32 v[24:25], v[18:19], v[8:9] op_sel:[1,1] op_sel_hi:[0,1]
	v_pk_fma_f32 v[26:27], v[18:19], v[8:9], v[24:25] neg_lo:[0,0,1] neg_hi:[0,0,1]
	v_pk_fma_f32 v[8:9], v[18:19], v[8:9], v[24:25] op_sel_hi:[1,0,1]
	s_nop 0
	v_mov_b32_e32 v27, v9
	s_waitcnt lgkmcnt(0)
	v_pk_mul_f32 v[8:9], v[14:15], v[16:17] op_sel:[1,1] op_sel_hi:[0,1]
	v_pk_fma_f32 v[18:19], v[14:15], v[16:17], v[8:9] neg_lo:[0,0,1] neg_hi:[0,0,1]
	v_pk_fma_f32 v[8:9], v[14:15], v[16:17], v[8:9] op_sel_hi:[1,0,1]
	v_mov_b64_e32 v[16:17], v[246:247]
	v_mov_b32_e32 v19, v9
	s_waitcnt lgkmcnt(0)
	v_pk_mul_f32 v[8:9], v[20:21], v[12:13] op_sel:[1,1] op_sel_hi:[0,1]
	v_pk_fma_f32 v[14:15], v[20:21], v[12:13], v[8:9] neg_lo:[0,0,1] neg_hi:[0,0,1]
	v_pk_fma_f32 v[8:9], v[20:21], v[12:13], v[8:9] op_sel_hi:[1,0,1]
	s_waitcnt lgkmcnt(0)
	v_pk_mul_f32 v[20:21], v[16:17], v[2:3] op_sel:[1,1] op_sel_hi:[0,1]
	v_mov_b32_e32 v15, v9
	v_pk_mul_f32 v[8:9], v[10:11], v[22:23] op_sel:[1,1] op_sel_hi:[1,0]
	s_nop 0
	v_pk_fma_f32 v[12:13], v[10:11], v[22:23], v[8:9] neg_lo:[0,0,1] neg_hi:[0,0,1]
	v_pk_fma_f32 v[8:9], v[10:11], v[22:23], v[8:9] op_sel_hi:[0,1,1]
	v_mov_b32_e32 v13, v9
	v_mov_b64_e32 v[8:9], v[248:249]
	v_mov_b64_e32 v[10:11], v[250:251]
	v_pk_fma_f32 v[22:23], v[16:17], v[2:3], v[20:21] neg_lo:[0,0,1] neg_hi:[0,0,1]
	v_pk_fma_f32 v[2:3], v[16:17], v[2:3], v[20:21] op_sel_hi:[1,0,1]
	s_nop 0
	v_mov_b32_e32 v23, v3
	s_waitcnt lgkmcnt(0)
	v_pk_mul_f32 v[2:3], v[6:7], v[8:9] op_sel:[1,1] op_sel_hi:[1,0]
	s_nop 0
	v_pk_fma_f32 v[16:17], v[6:7], v[8:9], v[2:3] neg_lo:[0,0,1] neg_hi:[0,0,1]
	v_pk_fma_f32 v[2:3], v[6:7], v[8:9], v[2:3] op_sel_hi:[0,1,1]
	v_mov_b32_e32 v17, v3
	s_waitcnt lgkmcnt(0)
	v_pk_mul_f32 v[2:3], v[10:11], v[0:1] op_sel:[1,1] op_sel_hi:[0,1]
	v_pk_fma_f32 v[6:7], v[10:11], v[0:1], v[2:3] neg_lo:[0,0,1] neg_hi:[0,0,1]
	v_pk_fma_f32 v[0:1], v[10:11], v[0:1], v[2:3] op_sel_hi:[1,0,1]
	s_nop 0
	v_mov_b32_e32 v7, v1
	ds_write2_b64 v193, v[4:5], v[26:27] offset1:9
	ds_write2_b64 v193, v[18:19], v[14:15] offset0:18 offset1:27
	ds_write2_b64 v193, v[12:13], v[22:23] offset0:36 offset1:45
	ds_write2_b64 v193, v[16:17], v[6:7] offset0:54 offset1:63
	s_waitcnt lgkmcnt(0)
	s_barrier
; __device__ __forceinline__ void fwd_s3(c2 (&x)[8], const c2* buf, int tid) {
; #pragma unroll
;     for (int r = 0; r < 8; ++r) x[r] = buf[9 * tid + r];
;     dft8(x);
; }
; __device__ __forceinline__ void phase_conv(const Params& p, int o, unsigned char* smem, int wave) {
;     ...
;                 for (int q = 0; q < 8; ++q) { sK[((d + 7) * 8 + q) * 512 + tid] = x0[q]; if (d < 7) sK[((d + 8) * 8 + q) * 512 + tid] = x1[q]; }
	ds_read2_b64 v[0:3], v121 offset0:4 offset1:5
	ds_read2_b64 v[4:7], v121 offset1:1
	ds_read2_b64 v[8:11], v121 offset0:2 offset1:3
	ds_read2_b64 v[12:15], v121 offset0:6 offset1:7
	ds_read2_b64 v[26:29], v195 offset1:1
	ds_read2_b64 v[30:33], v196 offset1:1
	ds_read2_b64 v[38:41], v197 offset1:1
	s_waitcnt lgkmcnt(0)
	v_pk_add_f32 v[16:17], v[4:5], v[0:1]
	v_pk_add_f32 v[0:1], v[4:5], v[0:1] neg_lo:[0,1] neg_hi:[0,1]
	v_pk_add_f32 v[4:5], v[6:7], v[2:3]
	v_pk_add_f32 v[2:3], v[6:7], v[2:3] neg_lo:[0,1] neg_hi:[0,1]
	s_waitcnt lgkmcnt(0)
	v_pk_add_f32 v[6:7], v[8:9], v[12:13]
	v_pk_add_f32 v[8:9], v[8:9], v[12:13] neg_lo:[0,1] neg_hi:[0,1]
	v_pk_add_f32 v[18:19], v[10:11], v[14:15]
	v_pk_add_f32 v[10:11], v[10:11], v[14:15] neg_lo:[0,1] neg_hi:[0,1]
	v_pk_add_f32 v[22:23], v[2:3], v[2:3] op_sel:[1,0]
	v_pk_add_f32 v[2:3], v[2:3], v[2:3] op_sel_hi:[1,0] neg_lo:[0,1] neg_hi:[0,1]
	v_pk_add_f32 v[12:13], v[4:5], v[18:19]
	v_mov_b32_e32 v23, v3
	v_xor_b32_e32 v3, 0x80000000, v8
	v_mov_b32_e32 v2, v9
	v_pk_add_f32 v[8:9], v[10:11], v[10:11] op_sel:[1,0] neg_lo:[0,1] neg_hi:[0,1]
	v_pk_add_f32 v[10:11], v[10:11], v[10:11] op_sel_hi:[1,0]
	v_pk_add_f32 v[4:5], v[4:5], v[18:19] neg_lo:[0,1] neg_hi:[0,1]
	v_mov_b32_e32 v9, v11
	v_pk_mul_f32 v[24:25], v[8:9], s[20:21]
	v_pk_add_f32 v[8:9], v[16:17], v[6:7]
	v_pk_add_f32 v[10:11], v[16:17], v[6:7] neg_lo:[0,1] neg_hi:[0,1]
	v_pk_fma_f32 v[20:21], v[22:23], s[20:21], v[24:25] op_sel_hi:[1,0,1]
	v_pk_fma_f32 v[6:7], v[22:23], s[20:21], v[24:25] op_sel_hi:[1,0,1] neg_lo:[0,0,1] neg_hi:[0,0,1]
	ds_read2_b64 v[22:25], v194 offset1:1
	v_xor_b32_e32 v15, 0x80000000, v4
	v_mov_b32_e32 v14, v5
	v_pk_add_f32 v[16:17], v[0:1], v[2:3]
	v_pk_add_f32 v[0:1], v[0:1], v[2:3] neg_lo:[0,1] neg_hi:[0,1]
	s_waitcnt lgkmcnt(0)
	v_pk_add_f32 v[18:19], v[22:23], v[26:27]
	v_pk_add_f32 v[34:35], v[22:23], v[26:27] neg_lo:[0,1] neg_hi:[0,1]
	v_pk_add_f32 v[22:23], v[24:25], v[28:29] neg_lo:[0,1] neg_hi:[0,1]
	v_pk_add_f32 v[44:45], v[24:25], v[28:29]
	v_pk_add_f32 v[24:25], v[30:31], v[38:39]
	v_pk_add_f32 v[26:27], v[30:31], v[38:39] neg_lo:[0,1] neg_hi:[0,1]
	v_pk_add_f32 v[30:31], v[32:33], v[40:41] neg_lo:[0,1] neg_hi:[0,1]
	v_pk_add_f32 v[38:39], v[22:23], v[22:23] op_sel:[1,0]
	v_pk_add_f32 v[22:23], v[22:23], v[22:23] op_sel_hi:[1,0] neg_lo:[0,1] neg_hi:[0,1]
	v_pk_add_f32 v[28:29], v[32:33], v[40:41]
	v_mov_b32_e32 v39, v23
	v_xor_b32_e32 v33, 0x80000000, v26
	v_mov_b32_e32 v32, v27
	v_pk_add_f32 v[22:23], v[30:31], v[30:31] op_sel:[1,0] neg_lo:[0,1] neg_hi:[0,1]
	v_pk_add_f32 v[26:27], v[30:31], v[30:31] op_sel_hi:[1,0]
	v_pk_add_f32 v[30:31], v[34:35], v[32:33]
	v_mov_b32_e32 v23, v27
	v_pk_mul_f32 v[40:41], v[22:23], s[20:21]
	v_pk_add_f32 v[22:23], v[18:19], v[24:25]
	v_pk_add_f32 v[24:25], v[18:19], v[24:25] neg_lo:[0,1] neg_hi:[0,1]
	v_pk_add_f32 v[18:19], v[44:45], v[28:29] neg_lo:[0,1] neg_hi:[0,1]
	v_pk_add_f32 v[26:27], v[44:45], v[28:29]
	v_xor_b32_e32 v29, 0x80000000, v18
	v_mov_b32_e32 v28, v19
	v_pk_fma_f32 v[18:19], v[38:39], s[20:21], v[40:41] op_sel_hi:[1,0,1] neg_lo:[0,0,1] neg_hi:[0,0,1]
	v_pk_add_f32 v[32:33], v[34:35], v[32:33] neg_lo:[0,1] neg_hi:[0,1]
	v_pk_fma_f32 v[34:35], v[38:39], s[20:21], v[40:41] op_sel_hi:[1,0,1]
	v_xor_b32_e32 v39, 0x80000000, v18
	v_add_u32_e32 v18, s95, v113
	v_mov_b32_e32 v38, v19
	v_ashrrev_i32_e32 v19, 31, v18
	v_xor_b32_e32 v3, 0x80000000, v6
	v_mov_b32_e32 v2, v7
	v_lshl_add_u64 v[40:41], v[18:19], 3, s[8:9]
	v_cndmask_b32_e64 v19, 0, 1, s[70:71]
	v_pk_add_f32 v[42:43], v[8:9], v[12:13]
	v_pk_add_f32 v[4:5], v[10:11], v[14:15]
	v_pk_add_f32 v[36:37], v[16:17], v[20:21]
	v_pk_add_f32 v[6:7], v[0:1], v[2:3]
	v_cmp_ne_u32_e64 s[84:85], 1, v19
	global_store_dwordx2 v[40:41], v[42:43], off
	s_cbranch_vccnz .LBB0_482
	v_add_u32_e32 v48, 0x1000, v18
	v_ashrrev_i32_e32 v49, 31, v48
	v_pk_add_f32 v[46:47], v[22:23], v[26:27]
	v_lshl_add_u64 v[48:49], v[48:49], 3, s[8:9]
	global_store_dwordx2 v[48:49], v[46:47], off
	v_add_u32_e32 v46, 0x200, v18
	v_ashrrev_i32_e32 v47, 31, v46
	v_lshl_add_u64 v[46:47], v[46:47], 3, s[8:9]
	global_store_dwordx2 v[46:47], v[36:37], off
	v_add_u32_e32 v36, 0x1200, v18
	v_ashrrev_i32_e32 v37, 31, v36
	v_pk_add_f32 v[40:41], v[30:31], v[34:35]
	v_lshl_add_u64 v[36:37], v[36:37], 3, s[8:9]
	global_store_dwordx2 v[36:37], v[40:41], off
	v_add_u32_e32 v36, 0x400, v18
	v_ashrrev_i32_e32 v37, 31, v36
	v_pk_add_f32 v[42:43], v[32:33], v[38:39]
	v_pk_add_f32 v[44:45], v[24:25], v[28:29]
	v_lshl_add_u64 v[36:37], v[36:37], 3, s[8:9]
	global_store_dwordx2 v[36:37], v[4:5], off
	v_mov_b32_e32 v41, v178
	v_mov_b64_e32 v[36:37], v[44:45]
	v_mov_b32_e32 v40, v179
	v_mov_b64_e32 v[4:5], v[6:7]
	v_mov_b32_e32 v19, v180
	v_mov_b64_e32 v[6:7], v[42:43]
	s_branch .LBB0_483

; __device__ __forceinline__ c2 cmul(c2 a, c2 b) { return (c2){a.x * b.x - a.y * b.y, a.x * b.y + a.y * b.x}; }
; #define ZVAL(r, t) ((o == 0) ? dwl((r), (t), zw0, zw1, zw2, zb) : bf2f((r)[8 + (t)]))
; __device__ __forceinline__ void fwd_s0(c2 (&x)[8], c2* buf, const c2* tws, int tid) {
;     dft8(x);
; #pragma unroll
;     for (int q = 1; q < 8; ++q) x[q] = cmul(x[q], tws[(q - 1) * 512 + tid]);
;     { c2* bp_ = buf + LP(tid);
; #pragma unroll
;     for (int q = 0; q < 8; ++q) bp_[576 * q] = x[q]; }
; }
; __device__ __forceinline__ void phase_conv(const Params& p, int o, unsigned char* smem, int wave) {
;     ...
;                         for (int r = 0; r < 4; ++r) { const int t = tid + 512 * r; x0[r] = (c2){ZVAL(raw + (2 * hh) * RAWROW, t), 0.f}; x1[r] = (c2){ZVAL(raw + (2 * hh + 1) * RAWROW, t), 0.f}; x0[4 + r] = (c2){0.f, 0.f}; x1[4 + r] = (c2){0.f, 0.f}; }
;                         fft_fwd_regs2(x0, x1, buf0, buf1, tws, tid);
.LBB0_558:
	v_pk_add_f32 v[40:41], v[30:31], 0 op_sel_hi:[1,0]
	v_pk_add_f32 v[42:43], v[34:35], 0 op_sel_hi:[1,0]
	v_xor_b32_e32 v45, 0x80000000, v34
	v_sub_f32_e32 v34, 0, v35
	v_mov_b32_e32 v35, v43
	v_pk_add_f32 v[46:47], v[40:41], v[42:43] neg_lo:[0,1] neg_hi:[0,1]
	v_mov_b64_e32 v[54:55], v[210:211]
	v_mov_b32_e32 v56, v30
	v_sub_f32_e32 v31, 0, v31
	v_mov_b32_e32 v30, v41
	v_pk_mul_f32 v[34:35], v[34:35], s[20:21]
	v_pk_add_f32 v[40:41], v[40:41], v[42:43]
	v_pk_add_f32 v[42:43], v[46:47], 0 neg_lo:[1,1] neg_hi:[1,1]
	v_mov_b32_e32 v44, v57
	v_mov_b32_e32 v48, v46
	v_mov_b32_e32 v49, v57
	v_mov_b32_e32 v42, v57
	v_pk_fma_f32 v[52:53], v[30:31], s[20:21], v[34:35] op_sel_hi:[1,0,1]
	v_pk_fma_f32 v[30:31], v[30:31], s[20:21], v[34:35] op_sel_hi:[1,0,1] neg_lo:[0,0,1] neg_hi:[0,0,1]
	v_pk_add_f32 v[50:51], v[48:49], v[42:43]
	v_pk_add_f32 v[42:43], v[48:49], v[42:43] neg_lo:[0,1] neg_hi:[0,1]
	v_pk_add_f32 v[48:49], v[56:57], v[44:45]
	v_pk_add_f32 v[44:45], v[56:57], v[44:45] neg_lo:[0,1] neg_hi:[0,1]
	v_xor_b32_e32 v35, 0x80000000, v30
	v_mov_b32_e32 v34, v31
	v_pk_add_f32 v[30:31], v[48:49], v[52:53]
	v_pk_add_f32 v[48:49], v[48:49], v[52:53] neg_lo:[0,1] neg_hi:[0,1]
	v_pk_add_f32 v[52:53], v[44:45], v[34:35]
	v_pk_add_f32 v[34:35], v[44:45], v[34:35] neg_lo:[0,1] neg_hi:[0,1]
	v_mov_b64_e32 v[44:45], v[212:213]
	v_mov_b64_e32 v[90:91], v[214:215]
	v_mov_b64_e32 v[92:93], v[216:217]
	s_waitcnt lgkmcnt(0)
	v_pk_mul_f32 v[94:95], v[30:31], v[54:55] op_sel:[1,1] op_sel_hi:[1,0]
	v_pk_add_f32 v[46:47], v[40:41], v[40:41] op_sel:[0,1] op_sel_hi:[1,0]
	v_pk_fma_f32 v[96:97], v[30:31], v[54:55], v[94:95] neg_lo:[0,0,1] neg_hi:[0,0,1]
	v_pk_fma_f32 v[30:31], v[30:31], v[54:55], v[94:95] op_sel_hi:[0,1,1]
	v_mov_b32_e32 v97, v31
	s_waitcnt lgkmcnt(0)
	v_pk_mul_f32 v[30:31], v[50:51], v[44:45] op_sel:[1,1] op_sel_hi:[1,0]
	v_mov_b32_e32 v47, v57
	v_pk_fma_f32 v[54:55], v[50:51], v[44:45], v[30:31] neg_lo:[0,0,1] neg_hi:[0,0,1]
	v_pk_fma_f32 v[30:31], v[50:51], v[44:45], v[30:31] op_sel_hi:[0,1,1]
	v_mov_b32_e32 v55, v31
	s_waitcnt lgkmcnt(0)
	v_pk_mul_f32 v[30:31], v[52:53], v[90:91] op_sel:[1,1] op_sel_hi:[1,0]
	v_mov_b32_e32 v56, v28
	v_pk_fma_f32 v[44:45], v[52:53], v[90:91], v[30:31] neg_lo:[0,0,1] neg_hi:[0,0,1]
	v_pk_fma_f32 v[30:31], v[52:53], v[90:91], v[30:31] op_sel_hi:[0,1,1]
	v_mov_b64_e32 v[52:53], v[218:219]
	v_mov_b32_e32 v45, v31
	v_pk_add_f32 v[30:31], v[40:41], v[40:41] op_sel:[0,1] op_sel_hi:[0,1] neg_lo:[0,1] neg_hi:[0,1]
	s_waitcnt lgkmcnt(0)
	v_pk_mul_f32 v[40:41], v[92:93], 0 op_sel_hi:[1,0]
	s_lshl_b32 s7, s40, 13
	v_pk_fma_f32 v[50:51], v[30:31], v[92:93], v[40:41] op_sel:[0,0,1] op_sel_hi:[1,1,0] neg_lo:[0,0,1] neg_hi:[0,0,1]
	v_pk_fma_f32 v[30:31], v[30:31], v[92:93], v[40:41] op_sel:[0,0,1] op_sel_hi:[1,1,0]
	s_waitcnt lgkmcnt(0)
	v_pk_mul_f32 v[90:91], v[48:49], v[52:53] op_sel:[1,1] op_sel_hi:[1,0]
	v_mov_b32_e32 v51, v31
	v_mov_b64_e32 v[30:31], v[220:221]
	v_mov_b64_e32 v[40:41], v[222:223]
	v_pk_fma_f32 v[92:93], v[48:49], v[52:53], v[90:91] neg_lo:[0,0,1] neg_hi:[0,0,1]
	v_pk_fma_f32 v[48:49], v[48:49], v[52:53], v[90:91] op_sel_hi:[0,1,1]
	v_mov_b32_e32 v93, v49
	s_waitcnt lgkmcnt(0)
	v_pk_mul_f32 v[48:49], v[42:43], v[30:31] op_sel:[1,1] op_sel_hi:[1,0]
	s_or_b32 s7, s7, s3
	v_pk_fma_f32 v[52:53], v[42:43], v[30:31], v[48:49] neg_lo:[0,0,1] neg_hi:[0,0,1]
	v_pk_fma_f32 v[30:31], v[42:43], v[30:31], v[48:49] op_sel_hi:[0,1,1]
	v_mov_b32_e32 v53, v31
	s_waitcnt lgkmcnt(0)
	v_pk_mul_f32 v[30:31], v[34:35], v[40:41] op_sel:[1,1] op_sel_hi:[1,0]
	s_or_b32 s16, s7, 0x200
	v_pk_fma_f32 v[42:43], v[34:35], v[40:41], v[30:31] neg_lo:[0,0,1] neg_hi:[0,0,1]
	v_pk_fma_f32 v[30:31], v[34:35], v[40:41], v[30:31] op_sel_hi:[0,1,1]
	v_mov_b32_e32 v43, v31
	ds_write2st64_b64 v115, v[46:47], v[96:97] offset1:9
	ds_write2st64_b64 v115, v[54:55], v[44:45] offset0:18 offset1:27
	ds_write2st64_b64 v115, v[50:51], v[92:93] offset0:36 offset1:45
	ds_write2st64_b64 v115, v[52:53], v[42:43] offset0:54 offset1:63
	v_pk_add_f32 v[30:31], v[28:29], 0 op_sel_hi:[1,0]
	v_pk_add_f32 v[34:35], v[32:33], 0 op_sel_hi:[1,0]
	v_xor_b32_e32 v41, 0x80000000, v32
	v_sub_f32_e32 v32, 0, v33
	v_mov_b32_e32 v33, v35
	v_pk_add_f32 v[42:43], v[30:31], v[34:35] neg_lo:[0,1] neg_hi:[0,1]
	v_mov_b64_e32 v[50:51], v[210:211]
	v_sub_f32_e32 v29, 0, v29
	v_mov_b32_e32 v28, v31
	v_pk_mul_f32 v[32:33], v[32:33], s[20:21]
	v_pk_add_f32 v[30:31], v[30:31], v[34:35]
	v_pk_add_f32 v[34:35], v[42:43], 0 neg_lo:[1,1] neg_hi:[1,1]
	v_mov_b32_e32 v40, v57
	v_mov_b32_e32 v44, v42
	v_mov_b32_e32 v45, v57
	v_mov_b32_e32 v34, v57
	v_pk_fma_f32 v[48:49], v[28:29], s[20:21], v[32:33] op_sel_hi:[1,0,1]
	v_pk_fma_f32 v[28:29], v[28:29], s[20:21], v[32:33] op_sel_hi:[1,0,1] neg_lo:[0,0,1] neg_hi:[0,0,1]
	v_pk_add_f32 v[46:47], v[44:45], v[34:35]
	v_pk_add_f32 v[34:35], v[44:45], v[34:35] neg_lo:[0,1] neg_hi:[0,1]
	v_pk_add_f32 v[44:45], v[56:57], v[40:41]
	v_pk_add_f32 v[40:41], v[56:57], v[40:41] neg_lo:[0,1] neg_hi:[0,1]
	v_xor_b32_e32 v33, 0x80000000, v28
	v_mov_b32_e32 v32, v29
	v_pk_add_f32 v[28:29], v[44:45], v[48:49]
	v_pk_add_f32 v[44:45], v[44:45], v[48:49] neg_lo:[0,1] neg_hi:[0,1]
	v_pk_add_f32 v[48:49], v[40:41], v[32:33]
	v_pk_add_f32 v[32:33], v[40:41], v[32:33] neg_lo:[0,1] neg_hi:[0,1]
	v_mov_b64_e32 v[40:41], v[212:213]
	v_mov_b64_e32 v[52:53], v[214:215]
	v_mov_b64_e32 v[54:55], v[216:217]
	s_waitcnt lgkmcnt(0)
	v_pk_mul_f32 v[90:91], v[28:29], v[50:51] op_sel:[1,1] op_sel_hi:[1,0]
	v_pk_add_f32 v[42:43], v[30:31], v[30:31] op_sel:[0,1] op_sel_hi:[1,0]
	v_pk_fma_f32 v[92:93], v[28:29], v[50:51], v[90:91] neg_lo:[0,0,1] neg_hi:[0,0,1]
	v_pk_fma_f32 v[28:29], v[28:29], v[50:51], v[90:91] op_sel_hi:[0,1,1]
	v_mov_b32_e32 v93, v29
	s_waitcnt lgkmcnt(0)
; __device__ __forceinline__ c2 cmul(c2 a, c2 b) { return (c2){a.x * b.x - a.y * b.y, a.x * b.y + a.y * b.x}; }
; __device__ __forceinline__ void fwd_s0(c2 (&x)[8], c2* buf, const c2* tws, int tid) {
;     dft8(x);
; #pragma unroll
;     for (int q = 1; q < 8; ++q) x[q] = cmul(x[q], tws[(q - 1) * 512 + tid]);
;     { c2* bp_ = buf + LP(tid);
; #pragma unroll
;     for (int q = 0; q < 8; ++q) bp_[576 * q] = x[q]; }
; }
; template <int S> __device__ __forceinline__ void fwd_mid(c2* buf, const c2* tws, int tid) {
;     constexpr int lq = 9 - 3 * S, Q = 1 << lq; const c2* T = tws + (S == 1 ? 3584 : 4032);
;     const int k = tid & (Q - 1), base = ((tid >> lq) << (lq + 3)) + k;
;     c2 x[8];
;     c2* bp_ = buf + LP(base); constexpr int QP = Q + Q / 8;
; #pragma unroll
;     for (int r = 0; r < 8; ++r) x[r] = bp_[r * QP];
;     dft8(x);
; #pragma unroll
;     for (int q = 1; q < 8; ++q) x[q] = cmul(x[q], T[(q - 1) * Q + k]);
; #pragma unroll
;     for (int q = 0; q < 8; ++q) bp_[q * QP] = x[q];
; }
	v_pk_mul_f32 v[28:29], v[46:47], v[40:41] op_sel:[1,1] op_sel_hi:[1,0]
	v_mov_b32_e32 v43, v57
	v_pk_fma_f32 v[50:51], v[46:47], v[40:41], v[28:29] neg_lo:[0,0,1] neg_hi:[0,0,1]
	v_pk_fma_f32 v[28:29], v[46:47], v[40:41], v[28:29] op_sel_hi:[0,1,1]
	v_mov_b32_e32 v51, v29
	s_waitcnt lgkmcnt(0)
	v_pk_mul_f32 v[28:29], v[48:49], v[52:53] op_sel:[1,1] op_sel_hi:[1,0]
	s_xor_b64 s[70:71], s[62:63], -1
	v_pk_fma_f32 v[40:41], v[48:49], v[52:53], v[28:29] neg_lo:[0,0,1] neg_hi:[0,0,1]
	v_pk_fma_f32 v[28:29], v[48:49], v[52:53], v[28:29] op_sel_hi:[0,1,1]
	v_mov_b64_e32 v[48:49], v[218:219]
	v_mov_b32_e32 v41, v29
	v_pk_add_f32 v[28:29], v[30:31], v[30:31] op_sel:[0,1] op_sel_hi:[0,1] neg_lo:[0,1] neg_hi:[0,1]
	s_waitcnt lgkmcnt(0)
	v_pk_mul_f32 v[30:31], v[54:55], 0 op_sel_hi:[1,0]
	s_mov_b32 s40, 1
	v_pk_fma_f32 v[46:47], v[28:29], v[54:55], v[30:31] op_sel:[0,0,1] op_sel_hi:[1,1,0] neg_lo:[0,0,1] neg_hi:[0,0,1]
	v_pk_fma_f32 v[28:29], v[28:29], v[54:55], v[30:31] op_sel:[0,0,1] op_sel_hi:[1,1,0]
	s_waitcnt lgkmcnt(0)
	v_pk_mul_f32 v[52:53], v[44:45], v[48:49] op_sel:[1,1] op_sel_hi:[1,0]
	v_mov_b32_e32 v47, v29
	v_mov_b64_e32 v[28:29], v[220:221]
	v_mov_b64_e32 v[30:31], v[222:223]
	v_pk_fma_f32 v[54:55], v[44:45], v[48:49], v[52:53] neg_lo:[0,0,1] neg_hi:[0,0,1]
	v_pk_fma_f32 v[44:45], v[44:45], v[48:49], v[52:53] op_sel_hi:[0,1,1]
	v_mov_b32_e32 v55, v45
	s_waitcnt lgkmcnt(0)
	v_pk_mul_f32 v[44:45], v[34:35], v[28:29] op_sel:[1,1] op_sel_hi:[1,0]
	s_mov_b64 s[62:63], 0
	v_pk_fma_f32 v[48:49], v[34:35], v[28:29], v[44:45] neg_lo:[0,0,1] neg_hi:[0,0,1]
	v_pk_fma_f32 v[28:29], v[34:35], v[28:29], v[44:45] op_sel_hi:[0,1,1]
	v_mov_b32_e32 v49, v29
	s_waitcnt lgkmcnt(0)
	v_pk_mul_f32 v[28:29], v[32:33], v[30:31] op_sel:[1,1] op_sel_hi:[1,0]
	s_and_b64 vcc, exec, s[70:71]
	v_pk_fma_f32 v[34:35], v[32:33], v[30:31], v[28:29] neg_lo:[0,0,1] neg_hi:[0,0,1]
	v_pk_fma_f32 v[28:29], v[32:33], v[30:31], v[28:29] op_sel_hi:[0,1,1]
	v_mov_b32_e32 v35, v29
	ds_write2st64_b64 v115, v[42:43], v[92:93] offset0:72 offset1:81
	ds_write2st64_b64 v115, v[50:51], v[40:41] offset0:90 offset1:99
	ds_write2st64_b64 v115, v[46:47], v[54:55] offset0:108 offset1:117
	ds_write_b64 v115, v[48:49] offset:64512
	ds_write_b64 v116, v[34:35] offset:32256
	s_waitcnt lgkmcnt(0)
	s_barrier
	ds_read2_b64 v[28:31], v117 offset1:72
	ds_read2_b64 v[32:35], v63 offset0:32 offset1:104
	ds_read2_b64 v[40:43], v117 offset0:144 offset1:216
	ds_read2_b64 v[44:47], v63 offset0:176 offset1:248
	v_mov_b64_e32 v[50:51], v[224:225]
	s_waitcnt lgkmcnt(0)
	v_pk_add_f32 v[48:49], v[28:29], v[32:33]
	v_pk_add_f32 v[28:29], v[28:29], v[32:33] neg_lo:[0,1] neg_hi:[0,1]
	v_pk_add_f32 v[32:33], v[30:31], v[34:35]
	v_pk_add_f32 v[30:31], v[30:31], v[34:35] neg_lo:[0,1] neg_hi:[0,1]
	s_waitcnt lgkmcnt(0)
	v_pk_add_f32 v[34:35], v[40:41], v[44:45]
	v_pk_add_f32 v[40:41], v[40:41], v[44:45] neg_lo:[0,1] neg_hi:[0,1]
	v_pk_add_f32 v[44:45], v[42:43], v[46:47]
	v_pk_add_f32 v[42:43], v[42:43], v[46:47] neg_lo:[0,1] neg_hi:[0,1]
	v_pk_add_f32 v[46:47], v[30:31], v[30:31] op_sel:[1,0]
	v_pk_add_f32 v[30:31], v[30:31], v[30:31] op_sel_hi:[1,0] neg_lo:[0,1] neg_hi:[0,1]
	s_nop 0
	v_mov_b32_e32 v47, v31
	v_xor_b32_e32 v31, 0x80000000, v40
	v_mov_b32_e32 v30, v41
	v_pk_add_f32 v[40:41], v[42:43], v[42:43] op_sel:[1,0] neg_lo:[0,1] neg_hi:[0,1]
	v_pk_add_f32 v[42:43], v[42:43], v[42:43] op_sel_hi:[1,0]
	s_nop 0
	v_mov_b32_e32 v41, v43
	v_pk_add_f32 v[42:43], v[48:49], v[34:35]
	v_pk_add_f32 v[34:35], v[48:49], v[34:35] neg_lo:[0,1] neg_hi:[0,1]
	v_pk_add_f32 v[48:49], v[32:33], v[44:45]
	v_pk_add_f32 v[32:33], v[32:33], v[44:45] neg_lo:[0,1] neg_hi:[0,1]
	v_pk_mul_f32 v[40:41], v[40:41], s[20:21]
	v_xor_b32_e32 v45, 0x80000000, v32
	v_mov_b32_e32 v44, v33
	v_pk_add_f32 v[32:33], v[42:43], v[48:49]
	v_pk_add_f32 v[42:43], v[42:43], v[48:49] neg_lo:[0,1] neg_hi:[0,1]
	v_pk_add_f32 v[48:49], v[34:35], v[44:45]
	v_pk_add_f32 v[34:35], v[34:35], v[44:45] neg_lo:[0,1] neg_hi:[0,1]
	v_pk_add_f32 v[44:45], v[28:29], v[30:31]
	v_pk_add_f32 v[28:29], v[28:29], v[30:31] neg_lo:[0,1] neg_hi:[0,1]
	v_pk_fma_f32 v[30:31], v[46:47], s[20:21], v[40:41] op_sel_hi:[1,0,1]
	v_pk_fma_f32 v[40:41], v[46:47], s[20:21], v[40:41] op_sel_hi:[1,0,1] neg_lo:[0,0,1] neg_hi:[0,0,1]
	s_nop 0
	v_xor_b32_e32 v47, 0x80000000, v40
	v_mov_b32_e32 v46, v41
	v_pk_add_f32 v[40:41], v[44:45], v[30:31]
	v_pk_add_f32 v[30:31], v[44:45], v[30:31] neg_lo:[0,1] neg_hi:[0,1]
	v_pk_add_f32 v[44:45], v[28:29], v[46:47]
	v_pk_add_f32 v[28:29], v[28:29], v[46:47] neg_lo:[0,1] neg_hi:[0,1]
	v_mov_b64_e32 v[46:47], v[226:227]
	v_mov_b64_e32 v[52:53], v[228:229]
	v_mov_b64_e32 v[54:55], v[230:231]
	s_waitcnt lgkmcnt(0)
	v_pk_mul_f32 v[90:91], v[50:51], v[40:41] op_sel:[1,1] op_sel_hi:[0,1]
	v_pk_fma_f32 v[92:93], v[50:51], v[40:41], v[90:91] neg_lo:[0,0,1] neg_hi:[0,0,1]
	v_pk_fma_f32 v[40:41], v[50:51], v[40:41], v[90:91] op_sel_hi:[1,0,1]
	s_nop 0
	v_mov_b32_e32 v93, v41
	s_waitcnt lgkmcnt(0)
	v_pk_mul_f32 v[40:41], v[46:47], v[48:49] op_sel:[1,1] op_sel_hi:[0,1]
	v_pk_fma_f32 v[50:51], v[46:47], v[48:49], v[40:41] neg_lo:[0,0,1] neg_hi:[0,0,1]
	v_pk_fma_f32 v[40:41], v[46:47], v[48:49], v[40:41] op_sel_hi:[1,0,1]
	v_mov_b64_e32 v[48:49], v[232:233]
	v_mov_b32_e32 v51, v41
	s_waitcnt lgkmcnt(0)
	v_pk_mul_f32 v[40:41], v[52:53], v[44:45] op_sel:[1,1] op_sel_hi:[0,1]
	v_pk_fma_f32 v[46:47], v[52:53], v[44:45], v[40:41] neg_lo:[0,0,1] neg_hi:[0,0,1]
	v_pk_fma_f32 v[40:41], v[52:53], v[44:45], v[40:41] op_sel_hi:[1,0,1]
	s_waitcnt lgkmcnt(0)
; __device__ __forceinline__ c2 cmul(c2 a, c2 b) { return (c2){a.x * b.x - a.y * b.y, a.x * b.y + a.y * b.x}; }
; template <int S> __device__ __forceinline__ void fwd_mid(c2* buf, const c2* tws, int tid) {
;     constexpr int lq = 9 - 3 * S, Q = 1 << lq; const c2* T = tws + (S == 1 ? 3584 : 4032);
;     const int k = tid & (Q - 1), base = ((tid >> lq) << (lq + 3)) + k;
;     c2 x[8];
;     c2* bp_ = buf + LP(base); constexpr int QP = Q + Q / 8;
; #pragma unroll
;     for (int r = 0; r < 8; ++r) x[r] = bp_[r * QP];
;     dft8(x);
; #pragma unroll
;     for (int q = 1; q < 8; ++q) x[q] = cmul(x[q], T[(q - 1) * Q + k]);
; #pragma unroll
;     for (int q = 0; q < 8; ++q) bp_[q * QP] = x[q];
; }
	v_pk_mul_f32 v[52:53], v[48:49], v[30:31] op_sel:[1,1] op_sel_hi:[0,1]
	v_mov_b32_e32 v47, v41
	v_pk_mul_f32 v[40:41], v[42:43], v[54:55] op_sel:[1,1] op_sel_hi:[1,0]
	s_nop 0
	v_pk_fma_f32 v[44:45], v[42:43], v[54:55], v[40:41] neg_lo:[0,0,1] neg_hi:[0,0,1]
	v_pk_fma_f32 v[40:41], v[42:43], v[54:55], v[40:41] op_sel_hi:[0,1,1]
	v_mov_b32_e32 v45, v41
	v_mov_b64_e32 v[40:41], v[234:235]
	v_mov_b64_e32 v[42:43], v[236:237]
	v_pk_fma_f32 v[54:55], v[48:49], v[30:31], v[52:53] neg_lo:[0,0,1] neg_hi:[0,0,1]
	v_pk_fma_f32 v[30:31], v[48:49], v[30:31], v[52:53] op_sel_hi:[1,0,1]
	ds_write2_b64 v117, v[32:33], v[92:93] offset1:72
	ds_write2_b64 v117, v[50:51], v[46:47] offset0:144 offset1:216
	v_mov_b32_e32 v55, v31
	s_waitcnt lgkmcnt(0)
	v_pk_mul_f32 v[30:31], v[34:35], v[40:41] op_sel:[1,1] op_sel_hi:[1,0]
	s_nop 0
	v_pk_fma_f32 v[48:49], v[34:35], v[40:41], v[30:31] neg_lo:[0,0,1] neg_hi:[0,0,1]
	v_pk_fma_f32 v[30:31], v[34:35], v[40:41], v[30:31] op_sel_hi:[0,1,1]
	v_mov_b32_e32 v49, v31
	s_waitcnt lgkmcnt(0)
	v_pk_mul_f32 v[30:31], v[42:43], v[28:29] op_sel:[1,1] op_sel_hi:[0,1]
	v_pk_fma_f32 v[40:41], v[42:43], v[28:29], v[30:31] neg_lo:[0,0,1] neg_hi:[0,0,1]
	v_pk_fma_f32 v[28:29], v[42:43], v[28:29], v[30:31] op_sel_hi:[1,0,1]
	s_nop 0
	v_mov_b32_e32 v41, v29
	ds_read2_b64 v[28:31], v191 offset1:72
	ds_read2_b64 v[32:35], v192 offset0:32 offset1:104
	ds_write2_b64 v63, v[44:45], v[54:55] offset0:32 offset1:104
	ds_write2_b64 v63, v[48:49], v[40:41] offset0:176 offset1:248
	ds_read2_b64 v[40:43], v191 offset0:144 offset1:216
	ds_read2_b64 v[44:47], v192 offset0:176 offset1:248
	v_mov_b64_e32 v[50:51], v[224:225]
	s_waitcnt lgkmcnt(0)
	v_pk_add_f32 v[48:49], v[28:29], v[32:33]
	v_pk_add_f32 v[28:29], v[28:29], v[32:33] neg_lo:[0,1] neg_hi:[0,1]
	v_pk_add_f32 v[32:33], v[30:31], v[34:35]
	v_pk_add_f32 v[30:31], v[30:31], v[34:35] neg_lo:[0,1] neg_hi:[0,1]
	s_waitcnt lgkmcnt(0)
	v_pk_add_f32 v[34:35], v[40:41], v[44:45]
	v_pk_add_f32 v[40:41], v[40:41], v[44:45] neg_lo:[0,1] neg_hi:[0,1]
	v_pk_add_f32 v[44:45], v[42:43], v[46:47]
	v_pk_add_f32 v[42:43], v[42:43], v[46:47] neg_lo:[0,1] neg_hi:[0,1]
	v_pk_add_f32 v[46:47], v[30:31], v[30:31] op_sel:[1,0]
	v_pk_add_f32 v[30:31], v[30:31], v[30:31] op_sel_hi:[1,0] neg_lo:[0,1] neg_hi:[0,1]
	s_nop 0
	v_mov_b32_e32 v47, v31
	v_xor_b32_e32 v31, 0x80000000, v40
	v_mov_b32_e32 v30, v41
	v_pk_add_f32 v[40:41], v[42:43], v[42:43] op_sel:[1,0] neg_lo:[0,1] neg_hi:[0,1]
	v_pk_add_f32 v[42:43], v[42:43], v[42:43] op_sel_hi:[1,0]
	s_nop 0
	v_mov_b32_e32 v41, v43
	v_pk_add_f32 v[42:43], v[48:49], v[34:35]
	v_pk_add_f32 v[34:35], v[48:49], v[34:35] neg_lo:[0,1] neg_hi:[0,1]
	v_pk_add_f32 v[48:49], v[32:33], v[44:45]
	v_pk_add_f32 v[32:33], v[32:33], v[44:45] neg_lo:[0,1] neg_hi:[0,1]
	v_pk_mul_f32 v[40:41], v[40:41], s[20:21]
	v_xor_b32_e32 v45, 0x80000000, v32
	v_mov_b32_e32 v44, v33
	v_pk_add_f32 v[32:33], v[42:43], v[48:49]
	v_pk_add_f32 v[42:43], v[42:43], v[48:49] neg_lo:[0,1] neg_hi:[0,1]
	v_pk_add_f32 v[48:49], v[34:35], v[44:45]
	v_pk_add_f32 v[34:35], v[34:35], v[44:45] neg_lo:[0,1] neg_hi:[0,1]
	v_pk_add_f32 v[44:45], v[28:29], v[30:31]
	v_pk_add_f32 v[28:29], v[28:29], v[30:31] neg_lo:[0,1] neg_hi:[0,1]
	v_pk_fma_f32 v[30:31], v[46:47], s[20:21], v[40:41] op_sel_hi:[1,0,1]
	v_pk_fma_f32 v[40:41], v[46:47], s[20:21], v[40:41] op_sel_hi:[1,0,1] neg_lo:[0,0,1] neg_hi:[0,0,1]
	s_nop 0
	v_xor_b32_e32 v47, 0x80000000, v40
	v_mov_b32_e32 v46, v41
	v_pk_add_f32 v[40:41], v[44:45], v[30:31]
	v_pk_add_f32 v[30:31], v[44:45], v[30:31] neg_lo:[0,1] neg_hi:[0,1]
	v_pk_add_f32 v[44:45], v[28:29], v[46:47]
	v_pk_add_f32 v[28:29], v[28:29], v[46:47] neg_lo:[0,1] neg_hi:[0,1]
	v_mov_b64_e32 v[46:47], v[226:227]
	v_mov_b64_e32 v[52:53], v[228:229]
	v_mov_b64_e32 v[54:55], v[230:231]
	s_waitcnt lgkmcnt(0)
	v_pk_mul_f32 v[90:91], v[50:51], v[40:41] op_sel:[1,1] op_sel_hi:[0,1]
	v_pk_fma_f32 v[92:93], v[50:51], v[40:41], v[90:91] neg_lo:[0,0,1] neg_hi:[0,0,1]
	v_pk_fma_f32 v[40:41], v[50:51], v[40:41], v[90:91] op_sel_hi:[1,0,1]
	s_nop 0
	v_mov_b32_e32 v93, v41
	s_waitcnt lgkmcnt(0)
	v_pk_mul_f32 v[40:41], v[46:47], v[48:49] op_sel:[1,1] op_sel_hi:[0,1]
	v_pk_fma_f32 v[50:51], v[46:47], v[48:49], v[40:41] neg_lo:[0,0,1] neg_hi:[0,0,1]
	v_pk_fma_f32 v[40:41], v[46:47], v[48:49], v[40:41] op_sel_hi:[1,0,1]
	v_mov_b64_e32 v[48:49], v[232:233]
	v_mov_b32_e32 v51, v41
	s_waitcnt lgkmcnt(0)
	v_pk_mul_f32 v[40:41], v[52:53], v[44:45] op_sel:[1,1] op_sel_hi:[0,1]
	v_pk_fma_f32 v[46:47], v[52:53], v[44:45], v[40:41] neg_lo:[0,0,1] neg_hi:[0,0,1]
	v_pk_fma_f32 v[40:41], v[52:53], v[44:45], v[40:41] op_sel_hi:[1,0,1]
	s_waitcnt lgkmcnt(0)
	v_pk_mul_f32 v[52:53], v[48:49], v[30:31] op_sel:[1,1] op_sel_hi:[0,1]
	v_mov_b32_e32 v47, v41
	v_pk_mul_f32 v[40:41], v[42:43], v[54:55] op_sel:[1,1] op_sel_hi:[1,0]
	s_nop 0
	v_pk_fma_f32 v[44:45], v[42:43], v[54:55], v[40:41] neg_lo:[0,0,1] neg_hi:[0,0,1]
	v_pk_fma_f32 v[40:41], v[42:43], v[54:55], v[40:41] op_sel_hi:[0,1,1]
	v_mov_b32_e32 v45, v41
	v_mov_b64_e32 v[40:41], v[234:235]
	v_mov_b64_e32 v[42:43], v[236:237]
	v_pk_fma_f32 v[54:55], v[48:49], v[30:31], v[52:53] neg_lo:[0,0,1] neg_hi:[0,0,1]
	v_pk_fma_f32 v[30:31], v[48:49], v[30:31], v[52:53] op_sel_hi:[1,0,1]
	s_nop 0
	v_mov_b32_e32 v55, v31
	s_waitcnt lgkmcnt(0)
	v_pk_mul_f32 v[30:31], v[34:35], v[40:41] op_sel:[1,1] op_sel_hi:[1,0]
	s_nop 0
	v_pk_fma_f32 v[48:49], v[34:35], v[40:41], v[30:31] neg_lo:[0,0,1] neg_hi:[0,0,1]
	v_pk_fma_f32 v[30:31], v[34:35], v[40:41], v[30:31] op_sel_hi:[0,1,1]
	v_mov_b32_e32 v49, v31
	s_waitcnt lgkmcnt(0)
	v_pk_mul_f32 v[30:31], v[42:43], v[28:29] op_sel:[1,1] op_sel_hi:[0,1]
	v_pk_fma_f32 v[34:35], v[42:43], v[28:29], v[30:31] neg_lo:[0,0,1] neg_hi:[0,0,1]
	v_pk_fma_f32 v[28:29], v[42:43], v[28:29], v[30:31] op_sel_hi:[1,0,1]
	s_nop 0
	v_mov_b32_e32 v35, v29
	ds_write2_b64 v191, v[32:33], v[92:93] offset1:72
	ds_write2_b64 v191, v[50:51], v[46:47] offset0:144 offset1:216
	ds_write2_b64 v192, v[44:45], v[54:55] offset0:32 offset1:104
	ds_write2_b64 v192, v[48:49], v[34:35] offset0:176 offset1:248
	s_waitcnt lgkmcnt(0)
	s_barrier
; __device__ __forceinline__ c2 cmul(c2 a, c2 b) { return (c2){a.x * b.x - a.y * b.y, a.x * b.y + a.y * b.x}; }
; template <int S> __device__ __forceinline__ void fwd_mid(c2* buf, const c2* tws, int tid) {
;     constexpr int lq = 9 - 3 * S, Q = 1 << lq; const c2* T = tws + (S == 1 ? 3584 : 4032);
;     const int k = tid & (Q - 1), base = ((tid >> lq) << (lq + 3)) + k;
;     c2 x[8];
;     c2* bp_ = buf + LP(base); constexpr int QP = Q + Q / 8;
; #pragma unroll
;     for (int r = 0; r < 8; ++r) x[r] = bp_[r * QP];
;     dft8(x);
; #pragma unroll
;     for (int q = 1; q < 8; ++q) x[q] = cmul(x[q], T[(q - 1) * Q + k]);
; #pragma unroll
;     for (int q = 0; q < 8; ++q) bp_[q * QP] = x[q];
; }
	ds_read2_b64 v[28:31], v119 offset1:9
	ds_read2_b64 v[32:35], v119 offset0:36 offset1:45
	ds_read2_b64 v[40:43], v119 offset0:18 offset1:27
	ds_read2_b64 v[44:47], v119 offset0:54 offset1:63
	v_mov_b64_e32 v[50:51], v[238:239]
	s_waitcnt lgkmcnt(0)
	v_pk_add_f32 v[48:49], v[28:29], v[32:33]
	v_pk_add_f32 v[28:29], v[28:29], v[32:33] neg_lo:[0,1] neg_hi:[0,1]
	v_pk_add_f32 v[32:33], v[30:31], v[34:35]
	v_pk_add_f32 v[30:31], v[30:31], v[34:35] neg_lo:[0,1] neg_hi:[0,1]
	s_waitcnt lgkmcnt(0)
	v_pk_add_f32 v[34:35], v[40:41], v[44:45]
	v_pk_add_f32 v[40:41], v[40:41], v[44:45] neg_lo:[0,1] neg_hi:[0,1]
	v_pk_add_f32 v[44:45], v[42:43], v[46:47]
	v_pk_add_f32 v[42:43], v[42:43], v[46:47] neg_lo:[0,1] neg_hi:[0,1]
	v_pk_add_f32 v[46:47], v[30:31], v[30:31] op_sel:[1,0]
	v_pk_add_f32 v[30:31], v[30:31], v[30:31] op_sel_hi:[1,0] neg_lo:[0,1] neg_hi:[0,1]
	s_nop 0
	v_mov_b32_e32 v47, v31
	v_xor_b32_e32 v31, 0x80000000, v40
	v_mov_b32_e32 v30, v41
	v_pk_add_f32 v[40:41], v[42:43], v[42:43] op_sel:[1,0] neg_lo:[0,1] neg_hi:[0,1]
	v_pk_add_f32 v[42:43], v[42:43], v[42:43] op_sel_hi:[1,0]
	s_nop 0
	v_mov_b32_e32 v41, v43
	v_pk_add_f32 v[42:43], v[48:49], v[34:35]
	v_pk_add_f32 v[34:35], v[48:49], v[34:35] neg_lo:[0,1] neg_hi:[0,1]
	v_pk_add_f32 v[48:49], v[32:33], v[44:45]
	v_pk_add_f32 v[32:33], v[32:33], v[44:45] neg_lo:[0,1] neg_hi:[0,1]
	v_pk_mul_f32 v[40:41], v[40:41], s[20:21]
	v_xor_b32_e32 v45, 0x80000000, v32
	v_mov_b32_e32 v44, v33
	v_pk_add_f32 v[32:33], v[42:43], v[48:49]
	v_pk_add_f32 v[42:43], v[42:43], v[48:49] neg_lo:[0,1] neg_hi:[0,1]
	v_pk_add_f32 v[48:49], v[34:35], v[44:45]
	v_pk_add_f32 v[34:35], v[34:35], v[44:45] neg_lo:[0,1] neg_hi:[0,1]
	v_pk_add_f32 v[44:45], v[28:29], v[30:31]
	v_pk_add_f32 v[28:29], v[28:29], v[30:31] neg_lo:[0,1] neg_hi:[0,1]
	v_pk_fma_f32 v[30:31], v[46:47], s[20:21], v[40:41] op_sel_hi:[1,0,1]
	v_pk_fma_f32 v[40:41], v[46:47], s[20:21], v[40:41] op_sel_hi:[1,0,1] neg_lo:[0,0,1] neg_hi:[0,0,1]
	s_nop 0
	v_xor_b32_e32 v47, 0x80000000, v40
	v_mov_b32_e32 v46, v41
	v_pk_add_f32 v[40:41], v[44:45], v[30:31]
	v_pk_add_f32 v[30:31], v[44:45], v[30:31] neg_lo:[0,1] neg_hi:[0,1]
	v_pk_add_f32 v[44:45], v[28:29], v[46:47]
	v_pk_add_f32 v[28:29], v[28:29], v[46:47] neg_lo:[0,1] neg_hi:[0,1]
	v_mov_b64_e32 v[46:47], v[240:241]
	v_mov_b64_e32 v[52:53], v[242:243]
	v_mov_b64_e32 v[54:55], v[244:245]
	s_waitcnt lgkmcnt(0)
	v_pk_mul_f32 v[90:91], v[50:51], v[40:41] op_sel:[1,1] op_sel_hi:[0,1]
	v_pk_fma_f32 v[92:93], v[50:51], v[40:41], v[90:91] neg_lo:[0,0,1] neg_hi:[0,0,1]
	v_pk_fma_f32 v[40:41], v[50:51], v[40:41], v[90:91] op_sel_hi:[1,0,1]
	s_nop 0
	v_mov_b32_e32 v93, v41
	s_waitcnt lgkmcnt(0)
	v_pk_mul_f32 v[40:41], v[46:47], v[48:49] op_sel:[1,1] op_sel_hi:[0,1]
	v_pk_fma_f32 v[50:51], v[46:47], v[48:49], v[40:41] neg_lo:[0,0,1] neg_hi:[0,0,1]
	v_pk_fma_f32 v[40:41], v[46:47], v[48:49], v[40:41] op_sel_hi:[1,0,1]
	v_mov_b64_e32 v[48:49], v[246:247]
	v_mov_b32_e32 v51, v41
	s_waitcnt lgkmcnt(0)
	v_pk_mul_f32 v[40:41], v[52:53], v[44:45] op_sel:[1,1] op_sel_hi:[0,1]
	v_pk_fma_f32 v[46:47], v[52:53], v[44:45], v[40:41] neg_lo:[0,0,1] neg_hi:[0,0,1]
	v_pk_fma_f32 v[40:41], v[52:53], v[44:45], v[40:41] op_sel_hi:[1,0,1]
	s_waitcnt lgkmcnt(0)
	v_pk_mul_f32 v[52:53], v[48:49], v[30:31] op_sel:[1,1] op_sel_hi:[0,1]
	v_mov_b32_e32 v47, v41
	v_pk_mul_f32 v[40:41], v[42:43], v[54:55] op_sel:[1,1] op_sel_hi:[1,0]
	s_nop 0
	v_pk_fma_f32 v[44:45], v[42:43], v[54:55], v[40:41] neg_lo:[0,0,1] neg_hi:[0,0,1]
	v_pk_fma_f32 v[40:41], v[42:43], v[54:55], v[40:41] op_sel_hi:[0,1,1]
	v_mov_b32_e32 v45, v41
	v_mov_b64_e32 v[40:41], v[248:249]
	v_mov_b64_e32 v[42:43], v[250:251]
	v_pk_fma_f32 v[54:55], v[48:49], v[30:31], v[52:53] neg_lo:[0,0,1] neg_hi:[0,0,1]
	v_pk_fma_f32 v[30:31], v[48:49], v[30:31], v[52:53] op_sel_hi:[1,0,1]
	ds_write2_b64 v119, v[32:33], v[92:93] offset1:9
	ds_write2_b64 v119, v[50:51], v[46:47] offset0:18 offset1:27
	v_mov_b32_e32 v55, v31
	s_waitcnt lgkmcnt(0)
	v_pk_mul_f32 v[30:31], v[34:35], v[40:41] op_sel:[1,1] op_sel_hi:[1,0]
	s_nop 0
	v_pk_fma_f32 v[48:49], v[34:35], v[40:41], v[30:31] neg_lo:[0,0,1] neg_hi:[0,0,1]
	v_pk_fma_f32 v[30:31], v[34:35], v[40:41], v[30:31] op_sel_hi:[0,1,1]
	v_mov_b32_e32 v49, v31
	s_waitcnt lgkmcnt(0)
	v_pk_mul_f32 v[30:31], v[42:43], v[28:29] op_sel:[1,1] op_sel_hi:[0,1]
	v_pk_fma_f32 v[40:41], v[42:43], v[28:29], v[30:31] neg_lo:[0,0,1] neg_hi:[0,0,1]
	v_pk_fma_f32 v[28:29], v[42:43], v[28:29], v[30:31] op_sel_hi:[1,0,1]
	s_nop 0
	v_mov_b32_e32 v41, v29
	ds_read2_b64 v[28:31], v193 offset1:9
	ds_read2_b64 v[32:35], v193 offset0:36 offset1:45
	ds_write2_b64 v119, v[44:45], v[54:55] offset0:36 offset1:45
	ds_write2_b64 v119, v[48:49], v[40:41] offset0:54 offset1:63
	ds_read2_b64 v[40:43], v193 offset0:18 offset1:27
	ds_read2_b64 v[44:47], v193 offset0:54 offset1:63
	v_mov_b64_e32 v[50:51], v[238:239]
	s_waitcnt lgkmcnt(0)
	v_pk_add_f32 v[48:49], v[28:29], v[32:33]
	v_pk_add_f32 v[28:29], v[28:29], v[32:33] neg_lo:[0,1] neg_hi:[0,1]
	v_pk_add_f32 v[32:33], v[30:31], v[34:35]
	v_pk_add_f32 v[30:31], v[30:31], v[34:35] neg_lo:[0,1] neg_hi:[0,1]
	s_waitcnt lgkmcnt(0)
; __device__ __forceinline__ c2 cmul(c2 a, c2 b) { return (c2){a.x * b.x - a.y * b.y, a.x * b.y + a.y * b.x}; }
; template <int S> __device__ __forceinline__ void fwd_mid(c2* buf, const c2* tws, int tid) {
;     constexpr int lq = 9 - 3 * S, Q = 1 << lq; const c2* T = tws + (S == 1 ? 3584 : 4032);
;     const int k = tid & (Q - 1), base = ((tid >> lq) << (lq + 3)) + k;
;     c2 x[8];
;     c2* bp_ = buf + LP(base); constexpr int QP = Q + Q / 8;
; #pragma unroll
;     for (int r = 0; r < 8; ++r) x[r] = bp_[r * QP];
;     dft8(x);
; #pragma unroll
;     for (int q = 1; q < 8; ++q) x[q] = cmul(x[q], T[(q - 1) * Q + k]);
; #pragma unroll
;     for (int q = 0; q < 8; ++q) bp_[q * QP] = x[q];
; }
; __device__ __forceinline__ void fwd_s3(c2 (&x)[8], const c2* buf, int tid) {
; #pragma unroll
;     for (int r = 0; r < 8; ++r) x[r] = buf[9 * tid + r];
;     dft8(x);
; }
	v_pk_add_f32 v[34:35], v[40:41], v[44:45]
	v_pk_add_f32 v[40:41], v[40:41], v[44:45] neg_lo:[0,1] neg_hi:[0,1]
	v_pk_add_f32 v[44:45], v[42:43], v[46:47]
	v_pk_add_f32 v[42:43], v[42:43], v[46:47] neg_lo:[0,1] neg_hi:[0,1]
	v_pk_add_f32 v[46:47], v[30:31], v[30:31] op_sel:[1,0]
	v_pk_add_f32 v[30:31], v[30:31], v[30:31] op_sel_hi:[1,0] neg_lo:[0,1] neg_hi:[0,1]
	s_nop 0
	v_mov_b32_e32 v47, v31
	v_xor_b32_e32 v31, 0x80000000, v40
	v_mov_b32_e32 v30, v41
	v_pk_add_f32 v[40:41], v[42:43], v[42:43] op_sel:[1,0] neg_lo:[0,1] neg_hi:[0,1]
	v_pk_add_f32 v[42:43], v[42:43], v[42:43] op_sel_hi:[1,0]
	s_nop 0
	v_mov_b32_e32 v41, v43
	v_pk_add_f32 v[42:43], v[48:49], v[34:35]
	v_pk_add_f32 v[34:35], v[48:49], v[34:35] neg_lo:[0,1] neg_hi:[0,1]
	v_pk_add_f32 v[48:49], v[32:33], v[44:45]
	v_pk_add_f32 v[32:33], v[32:33], v[44:45] neg_lo:[0,1] neg_hi:[0,1]
	v_pk_mul_f32 v[40:41], v[40:41], s[20:21]
	v_xor_b32_e32 v45, 0x80000000, v32
	v_mov_b32_e32 v44, v33
	v_pk_add_f32 v[32:33], v[42:43], v[48:49]
	v_pk_add_f32 v[42:43], v[42:43], v[48:49] neg_lo:[0,1] neg_hi:[0,1]
	v_pk_add_f32 v[48:49], v[34:35], v[44:45]
	v_pk_add_f32 v[34:35], v[34:35], v[44:45] neg_lo:[0,1] neg_hi:[0,1]
	v_pk_add_f32 v[44:45], v[28:29], v[30:31]
	v_pk_add_f32 v[28:29], v[28:29], v[30:31] neg_lo:[0,1] neg_hi:[0,1]
	v_pk_fma_f32 v[30:31], v[46:47], s[20:21], v[40:41] op_sel_hi:[1,0,1]
	v_pk_fma_f32 v[40:41], v[46:47], s[20:21], v[40:41] op_sel_hi:[1,0,1] neg_lo:[0,0,1] neg_hi:[0,0,1]
	s_nop 0
	v_xor_b32_e32 v47, 0x80000000, v40
	v_mov_b32_e32 v46, v41
	v_pk_add_f32 v[40:41], v[44:45], v[30:31]
	v_pk_add_f32 v[30:31], v[44:45], v[30:31] neg_lo:[0,1] neg_hi:[0,1]
	v_pk_add_f32 v[44:45], v[28:29], v[46:47]
	v_pk_add_f32 v[28:29], v[28:29], v[46:47] neg_lo:[0,1] neg_hi:[0,1]
	v_mov_b64_e32 v[46:47], v[240:241]
	v_mov_b64_e32 v[52:53], v[242:243]
	v_mov_b64_e32 v[54:55], v[244:245]
	s_waitcnt lgkmcnt(0)
	v_pk_mul_f32 v[90:91], v[50:51], v[40:41] op_sel:[1,1] op_sel_hi:[0,1]
	v_pk_fma_f32 v[92:93], v[50:51], v[40:41], v[90:91] neg_lo:[0,0,1] neg_hi:[0,0,1]
	v_pk_fma_f32 v[40:41], v[50:51], v[40:41], v[90:91] op_sel_hi:[1,0,1]
	s_nop 0
	v_mov_b32_e32 v93, v41
	s_waitcnt lgkmcnt(0)
	v_pk_mul_f32 v[40:41], v[46:47], v[48:49] op_sel:[1,1] op_sel_hi:[0,1]
	v_pk_fma_f32 v[50:51], v[46:47], v[48:49], v[40:41] neg_lo:[0,0,1] neg_hi:[0,0,1]
	v_pk_fma_f32 v[40:41], v[46:47], v[48:49], v[40:41] op_sel_hi:[1,0,1]
	v_mov_b64_e32 v[48:49], v[246:247]
	v_mov_b32_e32 v51, v41
	s_waitcnt lgkmcnt(0)
	v_pk_mul_f32 v[40:41], v[52:53], v[44:45] op_sel:[1,1] op_sel_hi:[0,1]
	v_pk_fma_f32 v[46:47], v[52:53], v[44:45], v[40:41] neg_lo:[0,0,1] neg_hi:[0,0,1]
	v_pk_fma_f32 v[40:41], v[52:53], v[44:45], v[40:41] op_sel_hi:[1,0,1]
	s_waitcnt lgkmcnt(0)
	v_pk_mul_f32 v[52:53], v[48:49], v[30:31] op_sel:[1,1] op_sel_hi:[0,1]
	v_mov_b32_e32 v47, v41
	v_pk_mul_f32 v[40:41], v[42:43], v[54:55] op_sel:[1,1] op_sel_hi:[1,0]
	s_nop 0
	v_pk_fma_f32 v[44:45], v[42:43], v[54:55], v[40:41] neg_lo:[0,0,1] neg_hi:[0,0,1]
	v_pk_fma_f32 v[40:41], v[42:43], v[54:55], v[40:41] op_sel_hi:[0,1,1]
	v_mov_b32_e32 v45, v41
	v_mov_b64_e32 v[40:41], v[248:249]
	v_mov_b64_e32 v[42:43], v[250:251]
	v_pk_fma_f32 v[54:55], v[48:49], v[30:31], v[52:53] neg_lo:[0,0,1] neg_hi:[0,0,1]
	v_pk_fma_f32 v[30:31], v[48:49], v[30:31], v[52:53] op_sel_hi:[1,0,1]
	s_nop 0
	v_mov_b32_e32 v55, v31
	s_waitcnt lgkmcnt(0)
	v_pk_mul_f32 v[30:31], v[34:35], v[40:41] op_sel:[1,1] op_sel_hi:[1,0]
	s_nop 0
	v_pk_fma_f32 v[48:49], v[34:35], v[40:41], v[30:31] neg_lo:[0,0,1] neg_hi:[0,0,1]
	v_pk_fma_f32 v[30:31], v[34:35], v[40:41], v[30:31] op_sel_hi:[0,1,1]
	v_mov_b32_e32 v49, v31
	s_waitcnt lgkmcnt(0)
	v_pk_mul_f32 v[30:31], v[42:43], v[28:29] op_sel:[1,1] op_sel_hi:[0,1]
	v_pk_fma_f32 v[34:35], v[42:43], v[28:29], v[30:31] neg_lo:[0,0,1] neg_hi:[0,0,1]
	v_pk_fma_f32 v[28:29], v[42:43], v[28:29], v[30:31] op_sel_hi:[1,0,1]
	s_nop 0
	v_mov_b32_e32 v35, v29
	ds_write2_b64 v193, v[32:33], v[92:93] offset1:9
	ds_write2_b64 v193, v[50:51], v[46:47] offset0:18 offset1:27
	ds_write2_b64 v193, v[44:45], v[54:55] offset0:36 offset1:45
	ds_write2_b64 v193, v[48:49], v[34:35] offset0:54 offset1:63
	s_waitcnt lgkmcnt(0)
	s_barrier
	ds_read2_b64 v[28:31], v121 offset1:1
	ds_read2_b64 v[32:35], v121 offset0:4 offset1:5
	ds_read2_b64 v[40:43], v121 offset0:2 offset1:3
	ds_read2_b64 v[44:47], v121 offset0:6 offset1:7
	s_waitcnt lgkmcnt(0)
	v_pk_add_f32 v[48:49], v[28:29], v[32:33]
	v_pk_add_f32 v[28:29], v[28:29], v[32:33] neg_lo:[0,1] neg_hi:[0,1]
	v_pk_add_f32 v[32:33], v[30:31], v[34:35]
	v_pk_add_f32 v[30:31], v[30:31], v[34:35] neg_lo:[0,1] neg_hi:[0,1]
	s_waitcnt lgkmcnt(0)
	v_pk_add_f32 v[34:35], v[40:41], v[44:45]
	v_pk_add_f32 v[40:41], v[40:41], v[44:45] neg_lo:[0,1] neg_hi:[0,1]
	v_pk_add_f32 v[44:45], v[42:43], v[46:47]
	v_pk_add_f32 v[42:43], v[42:43], v[46:47] neg_lo:[0,1] neg_hi:[0,1]
	v_pk_add_f32 v[46:47], v[30:31], v[30:31] op_sel:[1,0]
	v_pk_add_f32 v[30:31], v[30:31], v[30:31] op_sel_hi:[1,0] neg_lo:[0,1] neg_hi:[0,1]
	s_nop 0
	v_mov_b32_e32 v47, v31
	v_xor_b32_e32 v31, 0x80000000, v40
	v_mov_b32_e32 v30, v41
	v_pk_add_f32 v[40:41], v[42:43], v[42:43] op_sel:[1,0] neg_lo:[0,1] neg_hi:[0,1]
	v_pk_add_f32 v[42:43], v[42:43], v[42:43] op_sel_hi:[1,0]
	s_nop 0
	v_mov_b32_e32 v41, v43
	v_pk_mul_f32 v[40:41], v[40:41], s[20:21]
	v_pk_add_f32 v[42:43], v[48:49], v[34:35]
	v_pk_add_f32 v[34:35], v[48:49], v[34:35] neg_lo:[0,1] neg_hi:[0,1]
	v_pk_add_f32 v[48:49], v[32:33], v[44:45]
	v_pk_add_f32 v[32:33], v[32:33], v[44:45] neg_lo:[0,1] neg_hi:[0,1]
	v_pk_add_f32 v[50:51], v[42:43], v[48:49]
	v_xor_b32_e32 v45, 0x80000000, v32
	v_mov_b32_e32 v44, v33
	v_pk_add_f32 v[48:49], v[42:43], v[48:49] neg_lo:[0,1] neg_hi:[0,1]
	v_pk_add_f32 v[32:33], v[28:29], v[30:31]
	v_pk_add_f32 v[42:43], v[28:29], v[30:31] neg_lo:[0,1] neg_hi:[0,1]
	v_pk_fma_f32 v[28:29], v[46:47], s[20:21], v[40:41] op_sel_hi:[1,0,1]
	v_pk_fma_f32 v[30:31], v[46:47], s[20:21], v[40:41] op_sel_hi:[1,0,1] neg_lo:[0,0,1] neg_hi:[0,0,1]
	v_pk_add_f32 v[52:53], v[34:35], v[44:45]
	v_pk_add_f32 v[54:55], v[34:35], v[44:45] neg_lo:[0,1] neg_hi:[0,1]
	v_xor_b32_e32 v41, 0x80000000, v30
	v_mov_b32_e32 v40, v31
	v_pk_add_f32 v[90:91], v[32:33], v[28:29]
	v_pk_add_f32 v[92:93], v[32:33], v[28:29] neg_lo:[0,1] neg_hi:[0,1]
	ds_read2_b64 v[28:31], v194 offset1:1
	ds_read2_b64 v[32:35], v195 offset1:1
	v_pk_add_f32 v[94:95], v[42:43], v[40:41]
	v_pk_add_f32 v[96:97], v[42:43], v[40:41] neg_lo:[0,1] neg_hi:[0,1]
	ds_read2_b64 v[40:43], v196 offset1:1
	ds_read2_b64 v[44:47], v197 offset1:1
	s_waitcnt lgkmcnt(0)
; __device__ __forceinline__ void fwd_s3(c2 (&x)[8], const c2* buf, int tid) {
; #pragma unroll
;     for (int r = 0; r < 8; ++r) x[r] = buf[9 * tid + r];
;     dft8(x);
; }
; __device__ __forceinline__ void phase_conv(const Params& p, int o, unsigned char* smem, int wave) {
;     ...
;                         for (int q = 0; q < 8; ++q) { sZ[((4 * a + 2 * hh) * 8 + q) * 512 + tid] = x0[q]; sZ[((4 * a + 2 * hh + 1) * 8 + q) * 512 + tid] = x1[q]; }
;                         __syncthreads();
	v_pk_add_f32 v[98:99], v[28:29], v[32:33]
	v_pk_add_f32 v[28:29], v[28:29], v[32:33] neg_lo:[0,1] neg_hi:[0,1]
	v_pk_add_f32 v[32:33], v[30:31], v[34:35]
	v_pk_add_f32 v[30:31], v[30:31], v[34:35] neg_lo:[0,1] neg_hi:[0,1]
	s_waitcnt lgkmcnt(0)
	v_pk_add_f32 v[34:35], v[40:41], v[44:45]
	v_pk_add_f32 v[40:41], v[40:41], v[44:45] neg_lo:[0,1] neg_hi:[0,1]
	v_pk_add_f32 v[44:45], v[42:43], v[46:47]
	v_pk_add_f32 v[42:43], v[42:43], v[46:47] neg_lo:[0,1] neg_hi:[0,1]
	v_pk_add_f32 v[46:47], v[30:31], v[30:31] op_sel:[1,0]
	v_pk_add_f32 v[30:31], v[30:31], v[30:31] op_sel_hi:[1,0] neg_lo:[0,1] neg_hi:[0,1]
	s_nop 0
	v_mov_b32_e32 v47, v31
	v_xor_b32_e32 v31, 0x80000000, v40
	v_mov_b32_e32 v30, v41
	v_pk_add_f32 v[40:41], v[42:43], v[42:43] op_sel:[1,0] neg_lo:[0,1] neg_hi:[0,1]
	v_pk_add_f32 v[42:43], v[42:43], v[42:43] op_sel_hi:[1,0]
	s_nop 0
	v_mov_b32_e32 v41, v43
	v_pk_add_f32 v[42:43], v[98:99], v[34:35]
	v_pk_add_f32 v[34:35], v[98:99], v[34:35] neg_lo:[0,1] neg_hi:[0,1]
	v_pk_add_f32 v[98:99], v[32:33], v[44:45]
	v_pk_add_f32 v[32:33], v[32:33], v[44:45] neg_lo:[0,1] neg_hi:[0,1]
	v_pk_mul_f32 v[40:41], v[40:41], s[20:21]
	v_xor_b32_e32 v45, 0x80000000, v32
	v_mov_b32_e32 v44, v33
	v_pk_add_f32 v[32:33], v[42:43], v[98:99]
	v_pk_add_f32 v[42:43], v[42:43], v[98:99] neg_lo:[0,1] neg_hi:[0,1]
	v_pk_add_f32 v[98:99], v[34:35], v[44:45]
	v_pk_add_f32 v[34:35], v[34:35], v[44:45] neg_lo:[0,1] neg_hi:[0,1]
	v_pk_add_f32 v[44:45], v[28:29], v[30:31]
	v_pk_add_f32 v[28:29], v[28:29], v[30:31] neg_lo:[0,1] neg_hi:[0,1]
	v_pk_fma_f32 v[30:31], v[46:47], s[20:21], v[40:41] op_sel_hi:[1,0,1]
	v_pk_fma_f32 v[40:41], v[46:47], s[20:21], v[40:41] op_sel_hi:[1,0,1] neg_lo:[0,0,1] neg_hi:[0,0,1]
	s_nop 0
	v_xor_b32_e32 v47, 0x80000000, v40
	v_mov_b32_e32 v46, v41
	v_pk_add_f32 v[40:41], v[44:45], v[30:31]
	v_pk_add_f32 v[30:31], v[44:45], v[30:31] neg_lo:[0,1] neg_hi:[0,1]
	v_pk_add_f32 v[44:45], v[28:29], v[46:47]
	v_pk_add_f32 v[28:29], v[28:29], v[46:47] neg_lo:[0,1] neg_hi:[0,1]
	v_add_u32_e32 v46, s7, v113
	v_ashrrev_i32_e32 v47, 31, v46
	v_lshl_add_u64 v[46:47], v[46:47], 3, s[18:19]
	global_store_dwordx2 v[46:47], v[50:51], off
	v_add_u32_e32 v46, s7, v124
	v_ashrrev_i32_e32 v47, 31, v46
	v_lshl_add_u64 v[46:47], v[46:47], 3, s[18:19]
	global_store_dwordx2 v[46:47], v[32:33], off
	v_add_u32_e32 v32, s16, v113
	v_ashrrev_i32_e32 v33, 31, v32
	v_lshl_add_u64 v[32:33], v[32:33], 3, s[18:19]
	global_store_dwordx2 v[32:33], v[90:91], off
	v_add_u32_e32 v32, s16, v124
	v_ashrrev_i32_e32 v33, 31, v32
	v_lshl_add_u64 v[32:33], v[32:33], 3, s[18:19]
	s_or_b32 s16, s7, 0x400
	global_store_dwordx2 v[32:33], v[40:41], off
	v_add_u32_e32 v32, s16, v113
	v_ashrrev_i32_e32 v33, 31, v32
	v_lshl_add_u64 v[32:33], v[32:33], 3, s[18:19]
	global_store_dwordx2 v[32:33], v[52:53], off
	v_add_u32_e32 v32, s16, v124
	v_ashrrev_i32_e32 v33, 31, v32
	v_lshl_add_u64 v[32:33], v[32:33], 3, s[18:19]
	s_or_b32 s16, s7, 0x600
	global_store_dwordx2 v[32:33], v[98:99], off
	v_add_u32_e32 v32, s16, v113
	v_ashrrev_i32_e32 v33, 31, v32
	v_lshl_add_u64 v[32:33], v[32:33], 3, s[18:19]
	global_store_dwordx2 v[32:33], v[94:95], off
	v_add_u32_e32 v32, s16, v124
	v_ashrrev_i32_e32 v33, 31, v32
	v_lshl_add_u64 v[32:33], v[32:33], 3, s[18:19]
	s_or_b32 s16, s7, 0x800
	global_store_dwordx2 v[32:33], v[44:45], off
	v_add_u32_e32 v32, s16, v113
	v_ashrrev_i32_e32 v33, 31, v32
	v_lshl_add_u64 v[32:33], v[32:33], 3, s[18:19]
	global_store_dwordx2 v[32:33], v[48:49], off
	v_add_u32_e32 v32, s16, v124
	v_ashrrev_i32_e32 v33, 31, v32
	v_lshl_add_u64 v[32:33], v[32:33], 3, s[18:19]
	s_or_b32 s16, s7, 0xa00
	global_store_dwordx2 v[32:33], v[42:43], off
	v_add_u32_e32 v32, s16, v113
	v_ashrrev_i32_e32 v33, 31, v32
	v_lshl_add_u64 v[32:33], v[32:33], 3, s[18:19]
	global_store_dwordx2 v[32:33], v[92:93], off
	v_add_u32_e32 v32, s16, v124
	v_ashrrev_i32_e32 v33, 31, v32
	v_lshl_add_u64 v[32:33], v[32:33], 3, s[18:19]
	s_or_b32 s16, s7, 0xc00
	global_store_dwordx2 v[32:33], v[30:31], off
	v_add_u32_e32 v30, s16, v113
	v_ashrrev_i32_e32 v31, 31, v30
	v_lshl_add_u64 v[30:31], v[30:31], 3, s[18:19]
	global_store_dwordx2 v[30:31], v[54:55], off
	v_add_u32_e32 v30, s16, v124
	v_ashrrev_i32_e32 v31, 31, v30
	v_lshl_add_u64 v[30:31], v[30:31], 3, s[18:19]
	s_or_b32 s7, s7, 0xe00
	global_store_dwordx2 v[30:31], v[34:35], off
	v_add_u32_e32 v30, s7, v113
	v_ashrrev_i32_e32 v31, 31, v30
	v_lshl_add_u64 v[30:31], v[30:31], 3, s[18:19]
	global_store_dwordx2 v[30:31], v[96:97], off
	v_add_u32_e32 v30, s7, v124
	v_ashrrev_i32_e32 v31, 31, v30
	v_lshl_add_u64 v[30:31], v[30:31], 3, s[18:19]
	global_store_dwordx2 v[30:31], v[28:29], off
	s_barrier
	s_cbranch_vccnz .LBB0_526

; __device__ __forceinline__ float bf2f(bf16_t b) { return __uint_as_float(((unsigned)b) << 16); }
; #define ZVAL(r, t) ((o == 0) ? dwl((r), (t), zw0, zw1, zw2, zb) : bf2f((r)[8 + (t)]))
; __device__ __forceinline__ float dwl(const bf16_t* r, int t, float w0, float w1, float w2, float b) { return w0 * bf2f(r[7 + t]) + w1 * bf2f(r[8 + t]) + w2 * bf2f(r[9 + t]) + b; }
; __device__ __forceinline__ void phase_conv(const Params& p, int o, unsigned char* smem, int wave) {
;     ...
;                         for (int r = 0; r < 4; ++r) { const int t = tid + 512 * r; x0[r] = (c2){ZVAL(raw + (2 * hh) * RAWROW, t), 0.f}; x1[r] = (c2){ZVAL(raw + (2 * hh + 1) * RAWROW, t), 0.f}; x0[4 + r] = (c2){0.f, 0.f}; x1[4 + r] = (c2){0.f, 0.f}; }
.LBB0_563:
	ds_read_u16 v28, v40 offset:4144
	ds_read_u16 v29, v40 offset:4146
	ds_read_u16 v31, v40 offset:4142
	s_waitcnt lgkmcnt(0)
	v_lshlrev_b32_e32 v32, 16, v28
	s_waitcnt lgkmcnt(0)
	v_lshlrev_b32_e32 v29, 16, v29
	s_waitcnt lgkmcnt(0)
	v_lshlrev_b32_e32 v28, 16, v31
	v_pk_mul_f32 v[28:29], v[64:65], v[28:29]
	s_nop 0
	v_fma_f32 v28, v186, v32, v28
	v_add_f32_e32 v28, v28, v29
	v_add_f32_e32 v28, v185, v28

; __device__ __forceinline__ float bf2f(bf16_t b) { return __uint_as_float(((unsigned)b) << 16); }
; #define ZVAL(r, t) ((o == 0) ? dwl((r), (t), zw0, zw1, zw2, zb) : bf2f((r)[8 + (t)]))
; __device__ __forceinline__ float dwl(const bf16_t* r, int t, float w0, float w1, float w2, float b) { return w0 * bf2f(r[7 + t]) + w1 * bf2f(r[8 + t]) + w2 * bf2f(r[9 + t]) + b; }
; __device__ __forceinline__ void phase_conv(const Params& p, int o, unsigned char* smem, int wave) {
;     ...
;                         for (int r = 0; r < 4; ++r) { const int t = tid + 512 * r; x0[r] = (c2){ZVAL(raw + (2 * hh) * RAWROW, t), 0.f}; x1[r] = (c2){ZVAL(raw + (2 * hh + 1) * RAWROW, t), 0.f}; x0[4 + r] = (c2){0.f, 0.f}; x1[4 + r] = (c2){0.f, 0.f}; }
.LBB0_577:
	ds_read_u16 v28, v40 offset:16
	ds_read_u16 v29, v40 offset:18
	ds_read_u16 v30, v40 offset:14
	s_waitcnt lgkmcnt(0)
	v_lshlrev_b32_e32 v31, 16, v28
	s_waitcnt lgkmcnt(0)
	v_lshlrev_b32_e32 v29, 16, v29
	s_waitcnt lgkmcnt(0)
	v_lshlrev_b32_e32 v28, 16, v30
	v_pk_mul_f32 v[28:29], v[64:65], v[28:29]
	s_nop 0
	v_fma_f32 v28, v186, v31, v28
	v_add_f32_e32 v28, v28, v29
	v_add_f32_e32 v30, v185, v28
	s_mov_b64 s[70:71], -1
	s_and_b64 vcc, exec, s[30:31]
	s_cbranch_vccz .LBB0_562

; __device__ __forceinline__ float bf2f(bf16_t b) { return __uint_as_float(((unsigned)b) << 16); }
; #define ZVAL(r, t) ((o == 0) ? dwl((r), (t), zw0, zw1, zw2, zb) : bf2f((r)[8 + (t)]))
; __device__ __forceinline__ float dwl(const bf16_t* r, int t, float w0, float w1, float w2, float b) { return w0 * bf2f(r[7 + t]) + w1 * bf2f(r[8 + t]) + w2 * bf2f(r[9 + t]) + b; }
; __device__ __forceinline__ void phase_conv(const Params& p, int o, unsigned char* smem, int wave) {
;     ...
;                         for (int r = 0; r < 4; ++r) { const int t = tid + 512 * r; x0[r] = (c2){ZVAL(raw + (2 * hh) * RAWROW, t), 0.f}; x1[r] = (c2){ZVAL(raw + (2 * hh + 1) * RAWROW, t), 0.f}; x0[4 + r] = (c2){0.f, 0.f}; x1[4 + r] = (c2){0.f, 0.f}; }
.LBB0_580:
	ds_read_u16 v29, v40 offset:1040
	ds_read_u16 v31, v40 offset:1042
	ds_read_u16 v32, v40 offset:1038
	s_waitcnt lgkmcnt(0)
	v_lshlrev_b32_e32 v29, 16, v29
	s_waitcnt lgkmcnt(0)
	v_lshlrev_b32_e32 v33, 16, v31
	s_waitcnt lgkmcnt(0)
	v_lshlrev_b32_e32 v32, 16, v32
	v_pk_mul_f32 v[32:33], v[64:65], v[32:33]
	s_nop 0
	v_fma_f32 v29, v186, v29, v32
	v_add_f32_e32 v29, v29, v33
	v_add_f32_e32 v31, v185, v29
	s_and_b64 vcc, exec, s[84:85]
	s_mov_b64 s[70:71], -1
	s_cbranch_vccnz .LBB0_567

; __device__ __forceinline__ float bf2f(bf16_t b) { return __uint_as_float(((unsigned)b) << 16); }
; #define ZVAL(r, t) ((o == 0) ? dwl((r), (t), zw0, zw1, zw2, zb) : bf2f((r)[8 + (t)]))
; __device__ __forceinline__ float dwl(const bf16_t* r, int t, float w0, float w1, float w2, float b) { return w0 * bf2f(r[7 + t]) + w1 * bf2f(r[8 + t]) + w2 * bf2f(r[9 + t]) + b; }
; __device__ __forceinline__ void phase_conv(const Params& p, int o, unsigned char* smem, int wave) {
;     ...
;                         for (int r = 0; r < 4; ++r) { const int t = tid + 512 * r; x0[r] = (c2){ZVAL(raw + (2 * hh) * RAWROW, t), 0.f}; x1[r] = (c2){ZVAL(raw + (2 * hh + 1) * RAWROW, t), 0.f}; x0[4 + r] = (c2){0.f, 0.f}; x1[4 + r] = (c2){0.f, 0.f}; }
.LBB0_582:
	ds_read_u16 v29, v40 offset:5168
	ds_read_u16 v32, v40 offset:5170
	ds_read_u16 v34, v40 offset:5166
	s_waitcnt lgkmcnt(0)
	v_lshlrev_b32_e32 v29, 16, v29
	s_waitcnt lgkmcnt(0)
	v_lshlrev_b32_e32 v33, 16, v32
	s_waitcnt lgkmcnt(0)
	v_lshlrev_b32_e32 v32, 16, v34
	v_pk_mul_f32 v[32:33], v[64:65], v[32:33]
	s_nop 0
	v_fma_f32 v29, v186, v29, v32
	v_add_f32_e32 v29, v29, v33
	v_add_f32_e32 v29, v185, v29
	s_and_b64 vcc, exec, s[84:85]
	s_mov_b64 s[70:71], -1
	s_cbranch_vccnz .LBB0_569

; __device__ __forceinline__ float bf2f(bf16_t b) { return __uint_as_float(((unsigned)b) << 16); }
; #define ZVAL(r, t) ((o == 0) ? dwl((r), (t), zw0, zw1, zw2, zb) : bf2f((r)[8 + (t)]))
; __device__ __forceinline__ float dwl(const bf16_t* r, int t, float w0, float w1, float w2, float b) { return w0 * bf2f(r[7 + t]) + w1 * bf2f(r[8 + t]) + w2 * bf2f(r[9 + t]) + b; }
; __device__ __forceinline__ void phase_conv(const Params& p, int o, unsigned char* smem, int wave) {
;     ...
;                         for (int r = 0; r < 4; ++r) { const int t = tid + 512 * r; x0[r] = (c2){ZVAL(raw + (2 * hh) * RAWROW, t), 0.f}; x1[r] = (c2){ZVAL(raw + (2 * hh + 1) * RAWROW, t), 0.f}; x0[4 + r] = (c2){0.f, 0.f}; x1[4 + r] = (c2){0.f, 0.f}; }
.LBB0_584:
	ds_read_u16 v32, v40 offset:2064
	ds_read_u16 v33, v40 offset:2066
	ds_read_u16 v34, v40 offset:2062
	s_waitcnt lgkmcnt(0)
	v_lshlrev_b32_e32 v35, 16, v32
	s_waitcnt lgkmcnt(0)
	v_lshlrev_b32_e32 v33, 16, v33
	s_waitcnt lgkmcnt(0)
	v_lshlrev_b32_e32 v32, 16, v34
	v_pk_mul_f32 v[32:33], v[64:65], v[32:33]
	s_nop 0
	v_fma_f32 v32, v186, v35, v32
	v_add_f32_e32 v32, v32, v33
	v_add_f32_e32 v34, v185, v32
	s_and_b64 vcc, exec, s[84:85]
	s_mov_b64 s[70:71], -1
	s_cbranch_vccnz .LBB0_571

; __device__ __forceinline__ float bf2f(bf16_t b) { return __uint_as_float(((unsigned)b) << 16); }
; #define ZVAL(r, t) ((o == 0) ? dwl((r), (t), zw0, zw1, zw2, zb) : bf2f((r)[8 + (t)]))
; __device__ __forceinline__ float dwl(const bf16_t* r, int t, float w0, float w1, float w2, float b) { return w0 * bf2f(r[7 + t]) + w1 * bf2f(r[8 + t]) + w2 * bf2f(r[9 + t]) + b; }
; __device__ __forceinline__ void phase_conv(const Params& p, int o, unsigned char* smem, int wave) {
;     ...
;                         for (int r = 0; r < 4; ++r) { const int t = tid + 512 * r; x0[r] = (c2){ZVAL(raw + (2 * hh) * RAWROW, t), 0.f}; x1[r] = (c2){ZVAL(raw + (2 * hh + 1) * RAWROW, t), 0.f}; x0[4 + r] = (c2){0.f, 0.f}; x1[4 + r] = (c2){0.f, 0.f}; }
.LBB0_586:
	ds_read_u16 v32, v40 offset:6192
	ds_read_u16 v33, v40 offset:6194
	ds_read_u16 v35, v40 offset:6190
	s_waitcnt lgkmcnt(0)
	v_lshlrev_b32_e32 v41, 16, v32
	s_waitcnt lgkmcnt(0)
	v_lshlrev_b32_e32 v33, 16, v33
	s_waitcnt lgkmcnt(0)
	v_lshlrev_b32_e32 v32, 16, v35
	v_pk_mul_f32 v[32:33], v[64:65], v[32:33]
	s_nop 0
	v_fma_f32 v32, v186, v41, v32
	v_add_f32_e32 v32, v32, v33
	v_add_f32_e32 v32, v185, v32
	s_and_b64 vcc, exec, s[84:85]
	s_mov_b64 s[70:71], -1
	s_cbranch_vccnz .LBB0_573

; __device__ __forceinline__ float bf2f(bf16_t b) { return __uint_as_float(((unsigned)b) << 16); }
; #define ZVAL(r, t) ((o == 0) ? dwl((r), (t), zw0, zw1, zw2, zb) : bf2f((r)[8 + (t)]))
; __device__ __forceinline__ float dwl(const bf16_t* r, int t, float w0, float w1, float w2, float b) { return w0 * bf2f(r[7 + t]) + w1 * bf2f(r[8 + t]) + w2 * bf2f(r[9 + t]) + b; }
; __device__ __forceinline__ void phase_conv(const Params& p, int o, unsigned char* smem, int wave) {
;     ...
;                         for (int r = 0; r < 4; ++r) { const int t = tid + 512 * r; x0[r] = (c2){ZVAL(raw + (2 * hh) * RAWROW, t), 0.f}; x1[r] = (c2){ZVAL(raw + (2 * hh + 1) * RAWROW, t), 0.f}; x0[4 + r] = (c2){0.f, 0.f}; x1[4 + r] = (c2){0.f, 0.f}; }
.LBB0_588:
	ds_read_u16 v33, v40 offset:3088
	ds_read_u16 v35, v40 offset:3090
	ds_read_u16 v41, v40 offset:3086
	s_waitcnt lgkmcnt(0)
	v_lshlrev_b32_e32 v33, 16, v33
	s_waitcnt lgkmcnt(0)
	v_lshlrev_b32_e32 v43, 16, v35
	s_waitcnt lgkmcnt(0)
	v_lshlrev_b32_e32 v42, 16, v41
	v_pk_mul_f32 v[42:43], v[64:65], v[42:43]
	s_nop 0
	v_fma_f32 v33, v186, v33, v42
	v_add_f32_e32 v33, v33, v43
	v_add_f32_e32 v35, v185, v33
	s_and_b64 vcc, exec, s[84:85]
	s_mov_b64 s[70:71], -1
	s_cbranch_vccnz .LBB0_575

; __device__ __forceinline__ float bf2f(bf16_t b) { return __uint_as_float(((unsigned)b) << 16); }
; #define ZVAL(r, t) ((o == 0) ? dwl((r), (t), zw0, zw1, zw2, zb) : bf2f((r)[8 + (t)]))
; __device__ __forceinline__ float dwl(const bf16_t* r, int t, float w0, float w1, float w2, float b) { return w0 * bf2f(r[7 + t]) + w1 * bf2f(r[8 + t]) + w2 * bf2f(r[9 + t]) + b; }
; __device__ __forceinline__ void phase_conv(const Params& p, int o, unsigned char* smem, int wave) {
;     ...
;                         for (int r = 0; r < 4; ++r) { const int t = tid + 512 * r; x0[r] = (c2){ZVAL(raw + (2 * hh) * RAWROW, t), 0.f}; x1[r] = (c2){ZVAL(raw + (2 * hh + 1) * RAWROW, t), 0.f}; x0[4 + r] = (c2){0.f, 0.f}; x1[4 + r] = (c2){0.f, 0.f}; }
.LBB0_590:
	ds_read_u16 v33, v40 offset:7216
	ds_read_u16 v41, v40 offset:7218
	ds_read_u16 v40, v40 offset:7214
	s_waitcnt lgkmcnt(0)
	v_lshlrev_b32_e32 v33, 16, v33
	s_waitcnt lgkmcnt(0)
	v_lshlrev_b32_e32 v41, 16, v41
	s_waitcnt lgkmcnt(0)
	v_lshlrev_b32_e32 v40, 16, v40
	v_pk_mul_f32 v[40:41], v[64:65], v[40:41]
	s_nop 0
	v_fma_f32 v33, v186, v33, v40
	v_add_f32_e32 v33, v33, v41
	v_add_f32_e32 v33, v185, v33
	s_branch .LBB0_558

; __device__ __forceinline__ c2 cmul(c2 a, c2 b) { return (c2){a.x * b.x - a.y * b.y, a.x * b.y + a.y * b.x}; }
; __device__ __forceinline__ void phase_conv(const Params& p, int o, unsigned char* smem, int wave) {
;     ...
;             for (int q = 0; q < 8; ++q) {
;                 c2 Z[8], Y[8];
; #pragma unroll
;                 for (int j = 0; j < 8; ++j) { Z[j] = sZ[(j * 8 + q) * 512 + tid]; Y[j] = (c2){0.f, 0.f}; }
; #pragma unroll
;                 for (int d = -7; d <= 7; ++d) { const c2 kd = sK[((d + 7) * 8 + q) * 512 + tid];
; #pragma unroll
;                     for (int i = 0; i < 8; ++i) if (i - d >= 0 && i - d < 8) Y[i] += cmul(Z[i - d], kd); }
; #pragma unroll
;                 for (int a = 0; a < 4; ++a) sZ[(a * 8 + q) * 512 + tid] = (c2){Y[2 * a].x - Y[2 * a + 1].y, Y[2 * a].y + Y[2 * a + 1].x};
;             }
.LBB0_594:
	s_waitcnt vmcnt(16)
	v_add_u32_e32 v234, s60, v113
	v_lshlrev_b32_e32 v234, 3, v234
	v_add_u32_e32 v235, 0x8000, v234
	v_add_u32_e32 v236, 0x10000, v234
	v_add_u32_e32 v237, 0x18000, v234
	v_add_u32_e32 v238, 0x20000, v234
	v_add_u32_e32 v239, 0x28000, v234
	v_add_u32_e32 v240, 0x30000, v234
	v_add_u32_e32 v241, 0x38000, v234
	v_add_u32_e32 v242, 0x40000, v234
	v_add_u32_e32 v243, 0x48000, v234
	v_add_u32_e32 v244, 0x50000, v234
	v_add_u32_e32 v245, 0x58000, v234
	v_add_u32_e32 v246, 0x60000, v234
	v_add_u32_e32 v247, 0x68000, v234
	v_add_u32_e32 v248, 0x70000, v234
	global_load_dwordx2 v[210:211], v234, s[18:19]
	global_load_dwordx2 v[212:213], v235, s[18:19]
	global_load_dwordx2 v[214:215], v236, s[18:19]
	global_load_dwordx2 v[216:217], v237, s[18:19]
	global_load_dwordx2 v[218:219], v238, s[18:19]
	global_load_dwordx2 v[220:221], v239, s[18:19]
	global_load_dwordx2 v[222:223], v240, s[18:19]
	global_load_dwordx2 v[224:225], v241, s[18:19]
	global_load_dwordx2 v[28:29], v234, s[8:9]
	global_load_dwordx2 v[30:31], v235, s[8:9]
	global_load_dwordx2 v[32:33], v236, s[8:9]
	global_load_dwordx2 v[34:35], v237, s[8:9]
	global_load_dwordx2 v[36:37], v238, s[8:9]
	global_load_dwordx2 v[38:39], v239, s[8:9]
	global_load_dwordx2 v[40:41], v240, s[8:9]
	global_load_dwordx2 v[42:43], v241, s[8:9]
	global_load_dwordx2 v[44:45], v242, s[8:9]
	global_load_dwordx2 v[46:47], v243, s[8:9]
	global_load_dwordx2 v[48:49], v244, s[8:9]
	global_load_dwordx2 v[50:51], v245, s[8:9]
	global_load_dwordx2 v[52:53], v246, s[8:9]
	global_load_dwordx2 v[54:55], v247, s[8:9]
	global_load_dwordx2 v[90:91], v248, s[8:9]
	v_mov_b32_e32 v0, 0
	v_mov_b32_e32 v1, 0
	v_mov_b32_e32 v2, 0
	v_mov_b32_e32 v3, 0
	v_mov_b32_e32 v4, 0
	v_mov_b32_e32 v5, 0
	v_mov_b32_e32 v6, 0
	v_mov_b32_e32 v7, 0
	v_mov_b32_e32 v8, 0
	v_mov_b32_e32 v9, 0
	v_mov_b32_e32 v10, 0
	v_mov_b32_e32 v11, 0
	v_mov_b32_e32 v12, 0
	v_mov_b32_e32 v13, 0
	v_mov_b32_e32 v14, 0
	v_mov_b32_e32 v15, 0
	s_waitcnt vmcnt(14)
	v_fmac_f32_e32 v0, v224, v28
	v_fmac_f32_e32 v1, v224, v29
	v_fma_f32 v0, -v225, v29, v0
	v_fmac_f32_e32 v1, v225, v28
	s_waitcnt vmcnt(13)
	v_fmac_f32_e32 v0, v222, v30
	v_fmac_f32_e32 v2, v224, v30
	v_fmac_f32_e32 v1, v222, v31
	v_fmac_f32_e32 v3, v224, v31
	v_fma_f32 v0, -v223, v31, v0
	v_fma_f32 v2, -v225, v31, v2
	v_fmac_f32_e32 v1, v223, v30
	v_fmac_f32_e32 v3, v225, v30
	s_waitcnt vmcnt(12)
	v_fmac_f32_e32 v0, v220, v32
	v_fmac_f32_e32 v2, v222, v32
	v_fmac_f32_e32 v4, v224, v32
	v_fmac_f32_e32 v1, v220, v33
	v_fmac_f32_e32 v3, v222, v33
	v_fmac_f32_e32 v5, v224, v33
	v_fma_f32 v0, -v221, v33, v0
	v_fma_f32 v2, -v223, v33, v2
	v_fma_f32 v4, -v225, v33, v4
	v_fmac_f32_e32 v1, v221, v32
	v_fmac_f32_e32 v3, v223, v32
	v_fmac_f32_e32 v5, v225, v32
	s_waitcnt vmcnt(11)
	v_fmac_f32_e32 v0, v218, v34
	v_fmac_f32_e32 v2, v220, v34
	v_fmac_f32_e32 v4, v222, v34
	v_fmac_f32_e32 v6, v224, v34
	v_fmac_f32_e32 v1, v218, v35
	v_fmac_f32_e32 v3, v220, v35
	v_fmac_f32_e32 v5, v222, v35
	v_fmac_f32_e32 v7, v224, v35
	v_fma_f32 v0, -v219, v35, v0
	v_fma_f32 v2, -v221, v35, v2
	v_fma_f32 v4, -v223, v35, v4
	v_fma_f32 v6, -v225, v35, v6
	v_fmac_f32_e32 v1, v219, v34
	v_fmac_f32_e32 v3, v221, v34
	v_fmac_f32_e32 v5, v223, v34
	v_fmac_f32_e32 v7, v225, v34
	s_waitcnt vmcnt(10)
	v_fmac_f32_e32 v0, v216, v36
	v_fmac_f32_e32 v2, v218, v36
	v_fmac_f32_e32 v4, v220, v36
	v_fmac_f32_e32 v6, v222, v36
	v_fmac_f32_e32 v8, v224, v36
	v_fmac_f32_e32 v1, v216, v37
	v_fmac_f32_e32 v3, v218, v37
	v_fmac_f32_e32 v5, v220, v37
	v_fmac_f32_e32 v7, v222, v37
	v_fmac_f32_e32 v9, v224, v37
	v_fma_f32 v0, -v217, v37, v0
	v_fma_f32 v2, -v219, v37, v2
	v_fma_f32 v4, -v221, v37, v4
	v_fma_f32 v6, -v223, v37, v6
	v_fma_f32 v8, -v225, v37, v8
	v_fmac_f32_e32 v1, v217, v36
	v_fmac_f32_e32 v3, v219, v36
	v_fmac_f32_e32 v5, v221, v36
	v_fmac_f32_e32 v7, v223, v36
	v_fmac_f32_e32 v9, v225, v36
	s_waitcnt vmcnt(9)
	v_fmac_f32_e32 v0, v214, v38
	v_fmac_f32_e32 v2, v216, v38
	v_fmac_f32_e32 v4, v218, v38
	v_fmac_f32_e32 v6, v220, v38
	v_fmac_f32_e32 v8, v222, v38
	v_fmac_f32_e32 v10, v224, v38
	v_fmac_f32_e32 v1, v214, v39
	v_fmac_f32_e32 v3, v216, v39
	v_fmac_f32_e32 v5, v218, v39
	v_fmac_f32_e32 v7, v220, v39
	v_fmac_f32_e32 v9, v222, v39
	v_fmac_f32_e32 v11, v224, v39
	v_fma_f32 v0, -v215, v39, v0
	v_fma_f32 v2, -v217, v39, v2
	v_fma_f32 v4, -v219, v39, v4
	v_fma_f32 v6, -v221, v39, v6
	v_fma_f32 v8, -v223, v39, v8
	v_fma_f32 v10, -v225, v39, v10
	v_fmac_f32_e32 v1, v215, v38
	v_fmac_f32_e32 v3, v217, v38
	v_fmac_f32_e32 v5, v219, v38
	v_fmac_f32_e32 v7, v221, v38
	v_fmac_f32_e32 v9, v223, v38
	v_fmac_f32_e32 v11, v225, v38
	s_waitcnt vmcnt(8)
	v_fmac_f32_e32 v0, v212, v40
	v_fmac_f32_e32 v2, v214, v40
	v_fmac_f32_e32 v4, v216, v40
	v_fmac_f32_e32 v6, v218, v40
	v_fmac_f32_e32 v8, v220, v40
	v_fmac_f32_e32 v10, v222, v40
	v_fmac_f32_e32 v12, v224, v40
	v_fmac_f32_e32 v1, v212, v41
	v_fmac_f32_e32 v3, v214, v41
	v_fmac_f32_e32 v5, v216, v41
	v_fmac_f32_e32 v7, v218, v41
	v_fmac_f32_e32 v9, v220, v41
	v_fmac_f32_e32 v11, v222, v41
	v_fmac_f32_e32 v13, v224, v41
	v_fma_f32 v0, -v213, v41, v0
	v_fma_f32 v2, -v215, v41, v2
	v_fma_f32 v4, -v217, v41, v4
	v_fma_f32 v6, -v219, v41, v6
	v_fma_f32 v8, -v221, v41, v8
	v_fma_f32 v10, -v223, v41, v10
	v_fma_f32 v12, -v225, v41, v12
	v_fmac_f32_e32 v1, v213, v40
	v_fmac_f32_e32 v3, v215, v40
	v_fmac_f32_e32 v5, v217, v40
	v_fmac_f32_e32 v7, v219, v40
	v_fmac_f32_e32 v9, v221, v40
	v_fmac_f32_e32 v11, v223, v40
	v_fmac_f32_e32 v13, v225, v40
	s_waitcnt vmcnt(7)
; __device__ __forceinline__ c2 cmul(c2 a, c2 b) { return (c2){a.x * b.x - a.y * b.y, a.x * b.y + a.y * b.x}; }
; __device__ __forceinline__ QuadRegs quad_load(const bf16_t* zsrc, const bf16_t* gsrc, int gstart, bool joined, bool first, bool last, int tid) {
;     const bf16_t* src = ((tid >> 8) ? gsrc : zsrc) + gstart; const int ci = tid & 255;
;     QuadRegs R;
; #pragma unroll
;     for (int k = 0; k < 4; ++k) { R.v[k] = *(const u32x4*)(src + 2048 * k + 8 * ci); R.h[k] = 0u; }
;     if (joined) {
;         if (ci == 0) {
; #pragma unroll
;             for (int k = 0; k < 4; ++k) if (k > 0 || !first) R.h[k] = src[2048 * k - 1]; }
;         if (ci == 255) {
; #pragma unroll
;             for (int k = 0; k < 4; ++k) if (k < 3 || !last) R.h[k] = src[2048 * (k + 1)]; }
;     }
;     return R;
; }
; __device__ __forceinline__ void phase_conv(const Params& p, int o, unsigned char* smem, int wave) {
;     ...
;             for (int q = 0; q < 8; ++q) {
;                 c2 Z[8], Y[8];
; #pragma unroll
;                 for (int j = 0; j < 8; ++j) { Z[j] = sZ[(j * 8 + q) * 512 + tid]; Y[j] = (c2){0.f, 0.f}; }
; #pragma unroll
;                 for (int d = -7; d <= 7; ++d) { const c2 kd = sK[((d + 7) * 8 + q) * 512 + tid];
; #pragma unroll
;                     for (int i = 0; i < 8; ++i) if (i - d >= 0 && i - d < 8) Y[i] += cmul(Z[i - d], kd); }
; #pragma unroll
;                 for (int a = 0; a < 4; ++a) sZ[(a * 8 + q) * 512 + tid] = (c2){Y[2 * a].x - Y[2 * a + 1].y, Y[2 * a].y + Y[2 * a + 1].x};
;             }
	v_fmac_f32_e32 v0, v210, v42
	v_fmac_f32_e32 v2, v212, v42
	v_fmac_f32_e32 v4, v214, v42
	v_fmac_f32_e32 v6, v216, v42
	v_fmac_f32_e32 v8, v218, v42
	v_fmac_f32_e32 v10, v220, v42
	v_fmac_f32_e32 v12, v222, v42
	v_fmac_f32_e32 v14, v224, v42
	v_fmac_f32_e32 v1, v210, v43
	v_fmac_f32_e32 v3, v212, v43
	v_fmac_f32_e32 v5, v214, v43
	v_fmac_f32_e32 v7, v216, v43
	v_fmac_f32_e32 v9, v218, v43
	v_fmac_f32_e32 v11, v220, v43
	v_fmac_f32_e32 v13, v222, v43
	v_fmac_f32_e32 v15, v224, v43
	v_fma_f32 v0, -v211, v43, v0
	v_fma_f32 v2, -v213, v43, v2
	v_fma_f32 v4, -v215, v43, v4
	v_fma_f32 v6, -v217, v43, v6
	v_fma_f32 v8, -v219, v43, v8
	v_fma_f32 v10, -v221, v43, v10
	v_fma_f32 v12, -v223, v43, v12
	v_fma_f32 v14, -v225, v43, v14
	v_fmac_f32_e32 v1, v211, v42
	v_fmac_f32_e32 v3, v213, v42
	v_fmac_f32_e32 v5, v215, v42
	v_fmac_f32_e32 v7, v217, v42
	v_fmac_f32_e32 v9, v219, v42
	v_fmac_f32_e32 v11, v221, v42
	v_fmac_f32_e32 v13, v223, v42
	v_fmac_f32_e32 v15, v225, v42
	s_waitcnt vmcnt(6)
	v_fmac_f32_e32 v2, v210, v44
	v_fmac_f32_e32 v4, v212, v44
	v_fmac_f32_e32 v6, v214, v44
	v_fmac_f32_e32 v8, v216, v44
	v_fmac_f32_e32 v10, v218, v44
	v_fmac_f32_e32 v12, v220, v44
	v_fmac_f32_e32 v14, v222, v44
	v_fmac_f32_e32 v3, v210, v45
	v_fmac_f32_e32 v5, v212, v45
	v_fmac_f32_e32 v7, v214, v45
	v_fmac_f32_e32 v9, v216, v45
	v_fmac_f32_e32 v11, v218, v45
	v_fmac_f32_e32 v13, v220, v45
	v_fmac_f32_e32 v15, v222, v45
	v_fma_f32 v2, -v211, v45, v2
	v_fma_f32 v4, -v213, v45, v4
	v_fma_f32 v6, -v215, v45, v6
	v_fma_f32 v8, -v217, v45, v8
	v_fma_f32 v10, -v219, v45, v10
	v_fma_f32 v12, -v221, v45, v12
	v_fma_f32 v14, -v223, v45, v14
	v_fmac_f32_e32 v3, v211, v44
	v_fmac_f32_e32 v5, v213, v44
	v_fmac_f32_e32 v7, v215, v44
	v_fmac_f32_e32 v9, v217, v44
	v_fmac_f32_e32 v11, v219, v44
	v_fmac_f32_e32 v13, v221, v44
	v_fmac_f32_e32 v15, v223, v44
	s_waitcnt vmcnt(5)
	v_fmac_f32_e32 v4, v210, v46
	v_fmac_f32_e32 v6, v212, v46
	v_fmac_f32_e32 v8, v214, v46
	v_fmac_f32_e32 v10, v216, v46
	v_fmac_f32_e32 v12, v218, v46
	v_fmac_f32_e32 v14, v220, v46
	v_fmac_f32_e32 v5, v210, v47
	v_fmac_f32_e32 v7, v212, v47
	v_fmac_f32_e32 v9, v214, v47
	v_fmac_f32_e32 v11, v216, v47
	v_fmac_f32_e32 v13, v218, v47
	v_fmac_f32_e32 v15, v220, v47
	v_fma_f32 v4, -v211, v47, v4
	v_fma_f32 v6, -v213, v47, v6
	v_fma_f32 v8, -v215, v47, v8
	v_fma_f32 v10, -v217, v47, v10
	v_fma_f32 v12, -v219, v47, v12
	v_fma_f32 v14, -v221, v47, v14
	v_fmac_f32_e32 v5, v211, v46
	v_fmac_f32_e32 v7, v213, v46
	v_fmac_f32_e32 v9, v215, v46
	v_fmac_f32_e32 v11, v217, v46
	v_fmac_f32_e32 v13, v219, v46
	v_fmac_f32_e32 v15, v221, v46
	s_waitcnt vmcnt(4)
	v_fmac_f32_e32 v6, v210, v48
	v_fmac_f32_e32 v8, v212, v48
	v_fmac_f32_e32 v10, v214, v48
	v_fmac_f32_e32 v12, v216, v48
	v_fmac_f32_e32 v14, v218, v48
	v_fmac_f32_e32 v7, v210, v49
	v_fmac_f32_e32 v9, v212, v49
	v_fmac_f32_e32 v11, v214, v49
	v_fmac_f32_e32 v13, v216, v49
	v_fmac_f32_e32 v15, v218, v49
	v_fma_f32 v6, -v211, v49, v6
	v_fma_f32 v8, -v213, v49, v8
	v_fma_f32 v10, -v215, v49, v10
	v_fma_f32 v12, -v217, v49, v12
	v_fma_f32 v14, -v219, v49, v14
	v_fmac_f32_e32 v7, v211, v48
	v_fmac_f32_e32 v9, v213, v48
	v_fmac_f32_e32 v11, v215, v48
	v_fmac_f32_e32 v13, v217, v48
	v_fmac_f32_e32 v15, v219, v48
	s_waitcnt vmcnt(3)
	v_fmac_f32_e32 v8, v210, v50
	v_fmac_f32_e32 v10, v212, v50
	v_fmac_f32_e32 v12, v214, v50
	v_fmac_f32_e32 v14, v216, v50
	v_fmac_f32_e32 v9, v210, v51
	v_fmac_f32_e32 v11, v212, v51
	v_fmac_f32_e32 v13, v214, v51
	v_fmac_f32_e32 v15, v216, v51
	v_fma_f32 v8, -v211, v51, v8
	v_fma_f32 v10, -v213, v51, v10
	v_fma_f32 v12, -v215, v51, v12
	v_fma_f32 v14, -v217, v51, v14
	v_fmac_f32_e32 v9, v211, v50
	v_fmac_f32_e32 v11, v213, v50
	v_fmac_f32_e32 v13, v215, v50
	v_fmac_f32_e32 v15, v217, v50
	s_waitcnt vmcnt(2)
	v_fmac_f32_e32 v10, v210, v52
	v_fmac_f32_e32 v12, v212, v52
	v_fmac_f32_e32 v14, v214, v52
	v_fmac_f32_e32 v11, v210, v53
	v_fmac_f32_e32 v13, v212, v53
	v_fmac_f32_e32 v15, v214, v53
	v_fma_f32 v10, -v211, v53, v10
	v_fma_f32 v12, -v213, v53, v12
	v_fma_f32 v14, -v215, v53, v14
	v_fmac_f32_e32 v11, v211, v52
	v_fmac_f32_e32 v13, v213, v52
	v_fmac_f32_e32 v15, v215, v52
	s_waitcnt vmcnt(1)
	v_fmac_f32_e32 v12, v210, v54
	v_fmac_f32_e32 v14, v212, v54
	v_fmac_f32_e32 v13, v210, v55
	v_fmac_f32_e32 v15, v212, v55
	v_fma_f32 v12, -v211, v55, v12
	v_fma_f32 v14, -v213, v55, v14
	v_fmac_f32_e32 v13, v211, v54
	v_fmac_f32_e32 v15, v213, v54
	s_waitcnt vmcnt(0)
	v_fmac_f32_e32 v14, v210, v90
	v_fmac_f32_e32 v15, v210, v91
	v_fma_f32 v14, -v211, v91, v14
	v_fmac_f32_e32 v15, v211, v90
	v_sub_f32_e32 v0, v0, v3
	v_add_f32_e32 v1, v1, v2
	v_sub_f32_e32 v4, v4, v7
	v_add_f32_e32 v5, v5, v6
	v_sub_f32_e32 v8, v8, v11
	v_add_f32_e32 v9, v9, v10
	v_sub_f32_e32 v12, v12, v15
	v_add_f32_e32 v13, v13, v14
	global_store_dwordx2 v234, v[0:1], s[18:19]
	global_store_dwordx2 v235, v[4:5], s[18:19]
	global_store_dwordx2 v236, v[8:9], s[18:19]
	global_store_dwordx2 v237, v[12:13], s[18:19]
	s_addk_i32 s60, 0x200
	s_cmpk_eq_i32 s60, 0x1000
	s_cbranch_scc0 .LBB0_594
	ds_read_b64 v[210:211], v114 offset:4096
	ds_read_b64 v[212:213], v114 offset:8192
	ds_read_b64 v[214:215], v114 offset:12288
	ds_read_b64 v[216:217], v114 offset:16384
	ds_read_b64 v[218:219], v114 offset:20480
	ds_read_b64 v[220:221], v114 offset:24576
	ds_read_b64 v[222:223], v114 offset:28672
	ds_read_b64 v[224:225], v118 offset:512
	ds_read_b64 v[226:227], v118 offset:1024
	ds_read_b64 v[228:229], v118 offset:1536
	ds_read_b64 v[230:231], v118 offset:2048
	ds_read_b64 v[232:233], v118 offset:2560
	ds_read_b64 v[234:235], v118 offset:3072
	ds_read_b64 v[236:237], v118 offset:3584
	ds_read_b64 v[238:239], v120 offset:64
	ds_read_b64 v[240:241], v120 offset:128
	ds_read_b64 v[242:243], v120 offset:192
	ds_read_b64 v[244:245], v120 offset:256
	ds_read_b64 v[246:247], v120 offset:320
	ds_read_b64 v[248:249], v120 offset:384
	ds_read_b64 v[250:251], v120 offset:448
	s_waitcnt lgkmcnt(0)
	global_load_dwordx4 v[0:3], v[20:21], off
	global_load_dwordx4 v[4:7], v[22:23], off
	global_load_dwordx4 v[8:11], v[24:25], off
	global_load_dwordx4 v[12:15], v[26:27], off
	v_cmp_lt_i16_sdwa s[40:41], v113, s94 src0_sel:BYTE_0 src1_sel:DWORD
	s_mov_b64 s[62:63], -1
	s_and_saveexec_b64 s[60:61], s[40:41]
	s_cbranch_execz .LBB0_599
	v_mov_b32_e32 v20, 0
	v_cmp_eq_u16_sdwa s[40:41], v113, v57 src0_sel:BYTE_0 src1_sel:DWORD
	s_mov_b64 s[70:71], 0
	v_mov_b32_e32 v21, 0
	v_mov_b32_e32 v22, 0
	s_and_saveexec_b64 s[62:63], s[40:41]
	s_cbranch_execz .LBB0_598
	v_add_co_u32_e32 v20, vcc, 0x20000, v16
	s_and_b64 s[70:71], s[42:43], exec
	s_nop 0
	v_addc_co_u32_e32 v21, vcc, 0, v17, vcc
	v_add_co_u32_e32 v22, vcc, 0x21000, v16
	global_load_ushort v20, v[20:21], off offset:4094
	s_nop 0
	v_addc_co_u32_e32 v23, vcc, 0, v17, vcc
	global_load_ushort v21, v[22:23], off offset:4094
	v_add_co_u32_e32 v22, vcc, 0x22000, v16
	s_nop 1
	v_addc_co_u32_e32 v23, vcc, 0, v17, vcc
	global_load_ushort v22, v[22:23], off offset:4094

; __device__ __forceinline__ void phase_conv(const Params& p, int o, unsigned char* smem, int wave) {
;     ...
;                     EPI(x0, 0, gq); EPI(x1, 2, gq);
.LBB0_602:
	v_pk_mul_f32 v[20:21], v[26:27], s[20:21] op_sel_hi:[1,0]
	v_pk_add_f32 v[16:17], v[16:17], v[28:29] neg_lo:[0,1] neg_hi:[0,1]
	v_pk_add_f32 v[20:21], v[20:21], v[30:31] neg_lo:[0,1] neg_hi:[0,1]
	s_mov_b64 s[62:63], 0
	v_xor_b32_e32 v22, 0x80000000, v21
	v_mov_b32_e32 v23, v20
	v_pk_add_f32 v[16:17], v[16:17], v[22:23]
	ds_read_u16 v20, v174 offset:14
	ds_read_u16 v21, v174 offset:16
	ds_read_u16 v22, v174 offset:18
	ds_read_u16 v23, v175 offset:14
	ds_read_u16 v24, v175 offset:16
	ds_read_u16 v25, v175 offset:18
	s_waitcnt lgkmcnt(0)
	v_lshlrev_b32_e32 v21, 16, v21
	v_lshlrev_b32_e32 v20, 16, v20
	v_mul_f32_e32 v21, v190, v21
	v_fmac_f32_e32 v21, v187, v20
	s_waitcnt lgkmcnt(0)
	v_lshlrev_b32_e32 v20, 16, v22
	v_pk_mul_f32 v[16:17], v[66:67], v[16:17]
	v_fmac_f32_e32 v21, v189, v20
	s_waitcnt lgkmcnt(0)
	v_lshlrev_b32_e32 v22, 16, v24
	v_add_f32_e32 v20, v188, v21
	v_lshlrev_b32_e32 v21, 16, v23
	v_mul_f32_e32 v22, v190, v22
	v_fma_f32 v16, v184, v18, v16
	v_fmac_f32_e32 v22, v187, v21
	s_waitcnt lgkmcnt(0)
	v_lshlrev_b32_e32 v21, 16, v25
	v_mul_f32_e32 v16, v16, v20
	v_add_u32_e32 v20, s7, v133
	v_fmac_f32_e32 v22, v189, v21
	v_ashrrev_i32_e32 v21, 31, v20
	v_add_f32_e32 v22, v188, v22
	v_cvt_pk_bf16_f32 v16, v16, s0
	v_lshl_add_u64 v[20:21], v[20:21], 1, s[50:51]
	v_fmac_f32_e32 v17, v184, v19
	global_store_short v[20:21], v16, off
	v_mul_f32_e32 v16, v17, v22
	v_cvt_pk_bf16_f32 v18, v16, s0
	v_add_u32_e32 v16, s3, v133
	v_ashrrev_i32_e32 v17, 31, v16
	v_lshl_add_u64 v[16:17], v[16:17], 1, s[50:51]
	s_movk_i32 s3, 0x2000
	s_and_b64 vcc, exec, s[60:61]
	global_store_short v[16:17], v18, off
	s_cbranch_vccnz .LBB0_215

; __device__ __forceinline__ c2 mpi(c2 a) { return (c2){-a.y, a.x}; }
; __device__ __forceinline__ void idft8(c2 (&x)[8]) {
;     const float s = 0.70710678118654752f;
;     const c2 a0 = x[0] + x[4], a4 = x[0] - x[4], a1 = x[1] + x[5], a5 = x[1] - x[5], a2 = x[2] + x[6], a6 = x[2] - x[6], a3 = x[3] + x[7], a7 = x[3] - x[7];
;     const c2 a5w = (c2){(a5.x - a5.y) * s, (a5.x + a5.y) * s};
;     const c2 a6w = mpi(a6);
;     const c2 a7w = (c2){-(a7.x + a7.y) * s, (a7.x - a7.y) * s};
;     const c2 b0 = a0 + a2, b1 = a0 - a2, b2 = a1 + a3, b3 = mpi(a1 - a3);
;     x[0] = b0 + b2; x[4] = b0 - b2; x[2] = b1 + b3; x[6] = b1 - b3;
;     const c2 c0 = a4 + a6w, c1 = a4 - a6w, c2_ = a5w + a7w, c3 = mpi(a5w - a7w);
;     x[1] = c0 + c2_; x[5] = c0 - c2_; x[3] = c1 + c3; x[7] = c1 - c3;
; }
; __device__ __forceinline__ void inv_s3(c2 (&x)[8], c2* buf, int tid) {
;     idft8(x);
; #pragma unroll
;     for (int q = 0; q < 8; ++q) buf[9 * tid + q] = x[q];
; }
.LBB0_633:
	s_or_b32 s7, s3, 0x200
	v_add_u32_e32 v16, s3, v113
	v_add_u32_e32 v18, s7, v113
	v_ashrrev_i32_e32 v17, 31, v16
	v_ashrrev_i32_e32 v19, 31, v18
	v_lshl_add_u64 v[16:17], v[16:17], 3, s[18:19]
	v_lshl_add_u64 v[18:19], v[18:19], 3, s[18:19]
	global_load_dwordx2 v[22:23], v[16:17], off
	global_load_dwordx2 v[26:27], v[18:19], off
	v_add_u32_e32 v18, s7, v124
	s_or_b32 s7, s3, 0x400
	v_add_u32_e32 v16, s3, v124
	v_add_u32_e32 v20, s7, v113
	v_ashrrev_i32_e32 v17, 31, v16
	v_ashrrev_i32_e32 v19, 31, v18
	v_ashrrev_i32_e32 v21, 31, v20
	v_lshl_add_u64 v[16:17], v[16:17], 3, s[18:19]
	v_lshl_add_u64 v[18:19], v[18:19], 3, s[18:19]
	v_lshl_add_u64 v[20:21], v[20:21], 3, s[18:19]
	global_load_dwordx2 v[16:17], v[16:17], off
	s_mov_b32 s62, s21
	global_load_dwordx2 v[18:19], v[18:19], off
	s_mov_b32 s63, s20
	global_load_dwordx2 v[30:31], v[20:21], off
	v_add_u32_e32 v20, s7, v124
	s_or_b32 s7, s3, 0x600
	v_add_u32_e32 v24, s7, v113
	v_ashrrev_i32_e32 v21, 31, v20
	v_ashrrev_i32_e32 v25, 31, v24
	v_lshl_add_u64 v[20:21], v[20:21], 3, s[18:19]
	v_lshl_add_u64 v[24:25], v[24:25], 3, s[18:19]
	global_load_dwordx2 v[20:21], v[20:21], off
	s_and_b64 vcc, exec, s[30:31]
	global_load_dwordx2 v[32:33], v[24:25], off
	v_add_u32_e32 v24, s7, v124
	s_or_b32 s7, s3, 0x800
	v_add_u32_e32 v28, s7, v113
	v_ashrrev_i32_e32 v25, 31, v24
	v_ashrrev_i32_e32 v29, 31, v28
	v_lshl_add_u64 v[24:25], v[24:25], 3, s[18:19]
	v_lshl_add_u64 v[28:29], v[28:29], 3, s[18:19]
	global_load_dwordx2 v[24:25], v[24:25], off
	s_nop 0
	global_load_dwordx2 v[34:35], v[28:29], off
	v_add_u32_e32 v28, s7, v124
	s_or_b32 s7, s3, 0xa00
	v_add_u32_e32 v36, s7, v113
	v_add_u32_e32 v38, s7, v124
	s_or_b32 s7, s3, 0xc00
	v_add_u32_e32 v40, s7, v113
	v_add_u32_e32 v42, s7, v124
	s_or_b32 s7, s3, 0xe00
	v_ashrrev_i32_e32 v29, 31, v28
	v_ashrrev_i32_e32 v37, 31, v36
	v_add_u32_e32 v44, s7, v113
	v_lshl_add_u64 v[28:29], v[28:29], 3, s[18:19]
	v_lshl_add_u64 v[36:37], v[36:37], 3, s[18:19]
	v_ashrrev_i32_e32 v39, 31, v38
	v_ashrrev_i32_e32 v41, 31, v40
	v_ashrrev_i32_e32 v43, 31, v42
	v_ashrrev_i32_e32 v45, 31, v44
	global_load_dwordx2 v[28:29], v[28:29], off
	v_lshl_add_u64 v[38:39], v[38:39], 3, s[18:19]
	global_load_dwordx2 v[36:37], v[36:37], off
	v_lshl_add_u64 v[40:41], v[40:41], 3, s[18:19]
	v_lshl_add_u64 v[42:43], v[42:43], 3, s[18:19]
	v_lshl_add_u64 v[44:45], v[44:45], 3, s[18:19]
	global_load_dwordx2 v[38:39], v[38:39], off
	v_add_u32_e32 v46, s7, v124
	global_load_dwordx2 v[40:41], v[40:41], off
	v_ashrrev_i32_e32 v47, 31, v46
	global_load_dwordx2 v[42:43], v[42:43], off
	v_lshl_add_u64 v[46:47], v[46:47], 3, s[18:19]
	global_load_dwordx2 v[44:45], v[44:45], off
	s_waitcnt vmcnt(6)
	v_pk_add_f32 v[48:49], v[22:23], v[34:35]
	global_load_dwordx2 v[46:47], v[46:47], off
	v_pk_add_f32 v[22:23], v[22:23], v[34:35] neg_lo:[0,1] neg_hi:[0,1]
	s_waitcnt vmcnt(5)
	v_pk_add_f32 v[34:35], v[26:27], v[36:37]
	v_pk_add_f32 v[26:27], v[26:27], v[36:37] neg_lo:[0,1] neg_hi:[0,1]
	s_waitcnt vmcnt(3)
	v_pk_add_f32 v[36:37], v[30:31], v[40:41]
	v_pk_add_f32 v[30:31], v[30:31], v[40:41] neg_lo:[0,1] neg_hi:[0,1]
	s_waitcnt vmcnt(1)
	v_pk_add_f32 v[40:41], v[32:33], v[44:45]
	v_pk_add_f32 v[32:33], v[32:33], v[44:45] neg_lo:[0,1] neg_hi:[0,1]
	v_pk_add_f32 v[44:45], v[26:27], v[26:27] op_sel:[0,1] neg_lo:[0,1] neg_hi:[0,1]
	v_pk_add_f32 v[26:27], v[26:27], v[26:27] op_sel_hi:[0,1]
	v_mov_b32_e32 v45, v27
	v_xor_b32_e32 v26, 0x80000000, v31
	v_mov_b32_e32 v27, v30
	v_pk_add_f32 v[30:31], v[32:33], v[32:33] op_sel:[0,1]
	v_pk_add_f32 v[32:33], v[32:33], v[32:33] op_sel_hi:[0,1] neg_lo:[0,1] neg_hi:[0,1]
	v_mov_b32_e32 v31, v33
	v_pk_add_f32 v[32:33], v[48:49], v[36:37]
	v_pk_add_f32 v[36:37], v[48:49], v[36:37] neg_lo:[0,1] neg_hi:[0,1]
	v_pk_add_f32 v[48:49], v[34:35], v[40:41]
	v_pk_add_f32 v[34:35], v[34:35], v[40:41] neg_lo:[0,1] neg_hi:[0,1]
	v_pk_mul_f32 v[30:31], v[30:31], s[62:63]
	v_xor_b32_e32 v40, 0x80000000, v35
	v_mov_b32_e32 v41, v34
	v_pk_add_f32 v[34:35], v[32:33], v[48:49]
	v_pk_add_f32 v[32:33], v[32:33], v[48:49] neg_lo:[0,1] neg_hi:[0,1]
	v_pk_add_f32 v[48:49], v[36:37], v[40:41]
	v_pk_add_f32 v[36:37], v[36:37], v[40:41] neg_lo:[0,1] neg_hi:[0,1]
	v_pk_add_f32 v[40:41], v[22:23], v[26:27]
	v_pk_add_f32 v[22:23], v[22:23], v[26:27] neg_lo:[0,1] neg_hi:[0,1]
	v_pk_fma_f32 v[26:27], v[44:45], s[20:21], v[30:31] op_sel_hi:[1,0,1]
	v_pk_fma_f32 v[30:31], v[44:45], s[20:21], v[30:31] op_sel_hi:[1,0,1] neg_lo:[0,0,1] neg_hi:[0,0,1]
	s_nop 0
	v_xor_b32_e32 v44, 0x80000000, v31
	v_mov_b32_e32 v45, v30
	v_pk_add_f32 v[30:31], v[40:41], v[26:27]
	v_pk_add_f32 v[26:27], v[40:41], v[26:27] neg_lo:[0,1] neg_hi:[0,1]
	v_pk_add_f32 v[40:41], v[22:23], v[44:45]
	v_pk_add_f32 v[22:23], v[22:23], v[44:45] neg_lo:[0,1] neg_hi:[0,1]
	ds_write2_b64 v121, v[34:35], v[30:31] offset1:1
	ds_write2_b64 v121, v[48:49], v[40:41] offset0:2 offset1:3
	ds_write2_b64 v121, v[32:33], v[26:27] offset0:4 offset1:5
	ds_write2_b64 v121, v[36:37], v[22:23] offset0:6 offset1:7
	v_pk_add_f32 v[26:27], v[18:19], v[38:39]
	v_pk_add_f32 v[18:19], v[18:19], v[38:39] neg_lo:[0,1] neg_hi:[0,1]
	v_pk_add_f32 v[22:23], v[16:17], v[28:29]
	v_pk_add_f32 v[16:17], v[16:17], v[28:29] neg_lo:[0,1] neg_hi:[0,1]
	v_pk_add_f32 v[28:29], v[20:21], v[42:43]
	v_pk_add_f32 v[20:21], v[20:21], v[42:43] neg_lo:[0,1] neg_hi:[0,1]
	v_pk_add_f32 v[32:33], v[18:19], v[18:19] op_sel:[0,1] neg_lo:[0,1] neg_hi:[0,1]
	v_pk_add_f32 v[18:19], v[18:19], v[18:19] op_sel_hi:[0,1]
	v_mov_b32_e32 v33, v19
	v_xor_b32_e32 v18, 0x80000000, v21
	v_mov_b32_e32 v19, v20
	s_waitcnt vmcnt(0)
; __device__ __forceinline__ c2 cmulc(c2 a, c2 b) { return (c2){a.x * b.x + a.y * b.y, a.y * b.x - a.x * b.y}; }
; __device__ __forceinline__ c2 mpi(c2 a) { return (c2){-a.y, a.x}; }
; __device__ __forceinline__ void idft8(c2 (&x)[8]) {
;     const float s = 0.70710678118654752f;
;     const c2 a0 = x[0] + x[4], a4 = x[0] - x[4], a1 = x[1] + x[5], a5 = x[1] - x[5], a2 = x[2] + x[6], a6 = x[2] - x[6], a3 = x[3] + x[7], a7 = x[3] - x[7];
;     const c2 a5w = (c2){(a5.x - a5.y) * s, (a5.x + a5.y) * s};
;     const c2 a6w = mpi(a6);
;     const c2 a7w = (c2){-(a7.x + a7.y) * s, (a7.x - a7.y) * s};
;     const c2 b0 = a0 + a2, b1 = a0 - a2, b2 = a1 + a3, b3 = mpi(a1 - a3);
;     x[0] = b0 + b2; x[4] = b0 - b2; x[2] = b1 + b3; x[6] = b1 - b3;
;     const c2 c0 = a4 + a6w, c1 = a4 - a6w, c2_ = a5w + a7w, c3 = mpi(a5w - a7w);
;     x[1] = c0 + c2_; x[5] = c0 - c2_; x[3] = c1 + c3; x[7] = c1 - c3;
; }
; template <int S> __device__ __forceinline__ void inv_mid(c2* buf, const c2* tws, int tid) {
;     constexpr int lq = 9 - 3 * S, Q = 1 << lq; const c2* T = tws + (S == 1 ? 3584 : 4032);
;     const int k = tid & (Q - 1), base = ((tid >> lq) << (lq + 3)) + k;
;     c2 x[8];
;     c2* bp_ = buf + LP(base); constexpr int QP = Q + Q / 8;
; #pragma unroll
;     for (int r = 0; r < 8; ++r) { c2 v = bp_[r * QP]; if (r) v = cmulc(v, T[(r - 1) * Q + k]); x[r] = v; }
;     idft8(x);
; #pragma unroll
;     for (int q = 0; q < 8; ++q) bp_[q * QP] = x[q];
; }
; __device__ __forceinline__ void inv_s0(c2 (&x)[8], const c2* buf, const c2* tws, int tid) {
;     const c2* bp_ = buf + LP(tid);
; #pragma unroll
;     for (int r = 0; r < 8; ++r) { c2 v = bp_[576 * r]; if (r) v = cmulc(v, tws[(r - 1) * 512 + tid]); x[r] = v; }
;     idft8(x);
; }
	v_pk_add_f32 v[30:31], v[24:25], v[46:47]
	v_pk_add_f32 v[24:25], v[24:25], v[46:47] neg_lo:[0,1] neg_hi:[0,1]
	s_nop 0
	v_pk_add_f32 v[20:21], v[24:25], v[24:25] op_sel:[0,1]
	v_pk_add_f32 v[24:25], v[24:25], v[24:25] op_sel_hi:[0,1] neg_lo:[0,1] neg_hi:[0,1]
	v_mov_b32_e32 v21, v25
	v_pk_add_f32 v[24:25], v[22:23], v[28:29]
	v_pk_add_f32 v[22:23], v[22:23], v[28:29] neg_lo:[0,1] neg_hi:[0,1]
	v_pk_add_f32 v[28:29], v[26:27], v[30:31]
	v_pk_add_f32 v[26:27], v[26:27], v[30:31] neg_lo:[0,1] neg_hi:[0,1]
	v_pk_mul_f32 v[20:21], v[20:21], s[62:63]
	v_xor_b32_e32 v30, 0x80000000, v27
	v_mov_b32_e32 v31, v26
	v_pk_add_f32 v[26:27], v[24:25], v[28:29]
	v_pk_add_f32 v[24:25], v[24:25], v[28:29] neg_lo:[0,1] neg_hi:[0,1]
	v_pk_add_f32 v[28:29], v[22:23], v[30:31]
	v_pk_add_f32 v[22:23], v[22:23], v[30:31] neg_lo:[0,1] neg_hi:[0,1]
	v_pk_add_f32 v[30:31], v[16:17], v[18:19]
	v_pk_add_f32 v[16:17], v[16:17], v[18:19] neg_lo:[0,1] neg_hi:[0,1]
	v_pk_fma_f32 v[18:19], v[32:33], s[20:21], v[20:21] op_sel_hi:[1,0,1]
	v_pk_fma_f32 v[20:21], v[32:33], s[20:21], v[20:21] op_sel_hi:[1,0,1] neg_lo:[0,0,1] neg_hi:[0,0,1]
	s_nop 0
	v_xor_b32_e32 v32, 0x80000000, v21
	v_mov_b32_e32 v33, v20
	v_pk_add_f32 v[20:21], v[30:31], v[18:19]
	v_pk_add_f32 v[18:19], v[30:31], v[18:19] neg_lo:[0,1] neg_hi:[0,1]
	v_pk_add_f32 v[30:31], v[16:17], v[32:33]
	v_pk_add_f32 v[16:17], v[16:17], v[32:33] neg_lo:[0,1] neg_hi:[0,1]
	ds_write2_b64 v194, v[26:27], v[20:21] offset1:1
	ds_write2_b64 v196, v[28:29], v[30:31] offset1:1
	ds_write2_b64 v195, v[24:25], v[18:19] offset1:1
	ds_write2_b64 v197, v[22:23], v[16:17] offset1:1
	s_waitcnt lgkmcnt(0)
	s_barrier
	ds_read2_b64 v[16:19], v119 offset1:9
	v_mov_b64_e32 v[32:33], v[238:239]
	ds_read2_b64 v[20:23], v119 offset0:18 offset1:27
	v_mov_b64_e32 v[34:35], v[240:241]
	v_mov_b64_e32 v[36:37], v[242:243]
	ds_read2_b64 v[24:27], v119 offset0:36 offset1:45
	v_mov_b64_e32 v[38:39], v[244:245]
	v_mov_b64_e32 v[40:41], v[246:247]
	ds_read2_b64 v[28:31], v119 offset0:54 offset1:63
	v_mov_b64_e32 v[42:43], v[248:249]
	v_mov_b64_e32 v[44:45], v[250:251]
	s_waitcnt lgkmcnt(0)
	v_pk_mul_f32 v[46:47], v[30:31], v[44:45] op_sel:[1,1] op_sel_hi:[0,1]
	v_pk_fma_f32 v[48:49], v[30:31], v[44:45], v[46:47]
	v_pk_fma_f32 v[30:31], v[30:31], v[44:45], v[46:47] op_sel_hi:[1,0,1] neg_lo:[0,0,1] neg_hi:[0,0,1]
	s_nop 0
	v_mov_b32_e32 v49, v31
	v_pk_mul_f32 v[30:31], v[18:19], v[32:33] op_sel:[1,1] op_sel_hi:[0,1]
	v_pk_fma_f32 v[44:45], v[18:19], v[32:33], v[30:31]
	v_pk_fma_f32 v[18:19], v[18:19], v[32:33], v[30:31] op_sel_hi:[1,0,1] neg_lo:[0,0,1] neg_hi:[0,0,1]
	s_nop 0
	v_mov_b32_e32 v45, v19
	v_pk_mul_f32 v[18:19], v[20:21], v[34:35] op_sel:[1,1] op_sel_hi:[0,1]
	v_pk_fma_f32 v[30:31], v[20:21], v[34:35], v[18:19]
	v_pk_fma_f32 v[18:19], v[20:21], v[34:35], v[18:19] op_sel_hi:[1,0,1] neg_lo:[0,0,1] neg_hi:[0,0,1]
	s_nop 0
	v_mov_b32_e32 v31, v19
	v_pk_mul_f32 v[18:19], v[22:23], v[36:37] op_sel:[1,1] op_sel_hi:[0,1]
	v_pk_fma_f32 v[20:21], v[22:23], v[36:37], v[18:19]
	v_pk_fma_f32 v[18:19], v[22:23], v[36:37], v[18:19] op_sel_hi:[1,0,1] neg_lo:[0,0,1] neg_hi:[0,0,1]
	s_nop 0
	v_mov_b32_e32 v21, v19
	v_pk_mul_f32 v[18:19], v[24:25], v[38:39] op_sel:[1,1] op_sel_hi:[0,1]
	v_pk_fma_f32 v[22:23], v[24:25], v[38:39], v[18:19]
	v_pk_fma_f32 v[18:19], v[24:25], v[38:39], v[18:19] op_sel_hi:[1,0,1] neg_lo:[0,0,1] neg_hi:[0,0,1]
	s_nop 0
	v_mov_b32_e32 v23, v19
	v_pk_mul_f32 v[18:19], v[26:27], v[40:41] op_sel:[1,1] op_sel_hi:[0,1]
	v_pk_fma_f32 v[24:25], v[26:27], v[40:41], v[18:19]
	v_pk_fma_f32 v[18:19], v[26:27], v[40:41], v[18:19] op_sel_hi:[1,0,1] neg_lo:[0,0,1] neg_hi:[0,0,1]
	s_nop 0
	v_mov_b32_e32 v25, v19
	v_pk_mul_f32 v[18:19], v[28:29], v[42:43] op_sel:[1,1] op_sel_hi:[0,1]
	v_pk_fma_f32 v[26:27], v[28:29], v[42:43], v[18:19]
	v_pk_fma_f32 v[18:19], v[28:29], v[42:43], v[18:19] op_sel_hi:[1,0,1] neg_lo:[0,0,1] neg_hi:[0,0,1]
	s_nop 0
	v_mov_b32_e32 v27, v19
	v_pk_add_f32 v[18:19], v[16:17], v[22:23]
	v_pk_add_f32 v[16:17], v[16:17], v[22:23] neg_lo:[0,1] neg_hi:[0,1]
	v_pk_add_f32 v[22:23], v[44:45], v[24:25]
	v_pk_add_f32 v[24:25], v[44:45], v[24:25] neg_lo:[0,1] neg_hi:[0,1]
	v_pk_add_f32 v[28:29], v[30:31], v[26:27]
	v_pk_add_f32 v[26:27], v[30:31], v[26:27] neg_lo:[0,1] neg_hi:[0,1]
	v_pk_add_f32 v[30:31], v[20:21], v[48:49]
	v_pk_add_f32 v[20:21], v[20:21], v[48:49] neg_lo:[0,1] neg_hi:[0,1]
	v_pk_add_f32 v[32:33], v[24:25], v[24:25] op_sel:[0,1] neg_lo:[0,1] neg_hi:[0,1]
	v_pk_add_f32 v[24:25], v[24:25], v[24:25] op_sel_hi:[0,1]
	v_mov_b32_e32 v33, v25
	v_xor_b32_e32 v24, 0x80000000, v27
	v_mov_b32_e32 v25, v26
	v_pk_add_f32 v[26:27], v[20:21], v[20:21] op_sel:[0,1]
	v_pk_add_f32 v[20:21], v[20:21], v[20:21] op_sel_hi:[0,1] neg_lo:[0,1] neg_hi:[0,1]
	v_mov_b32_e32 v27, v21
	v_pk_mul_f32 v[20:21], v[26:27], s[62:63]
	v_pk_add_f32 v[26:27], v[18:19], v[28:29]
	v_pk_add_f32 v[18:19], v[18:19], v[28:29] neg_lo:[0,1] neg_hi:[0,1]
	v_pk_add_f32 v[28:29], v[22:23], v[30:31]
	v_pk_add_f32 v[22:23], v[22:23], v[30:31] neg_lo:[0,1] neg_hi:[0,1]
	s_nop 0
	v_xor_b32_e32 v30, 0x80000000, v23
	v_mov_b32_e32 v31, v22
	v_pk_add_f32 v[22:23], v[26:27], v[28:29]
	v_pk_add_f32 v[26:27], v[26:27], v[28:29] neg_lo:[0,1] neg_hi:[0,1]
	v_pk_add_f32 v[28:29], v[18:19], v[30:31]
	v_pk_add_f32 v[18:19], v[18:19], v[30:31] neg_lo:[0,1] neg_hi:[0,1]
	v_pk_add_f32 v[30:31], v[16:17], v[24:25]
	v_pk_add_f32 v[16:17], v[16:17], v[24:25] neg_lo:[0,1] neg_hi:[0,1]
	v_pk_fma_f32 v[24:25], v[32:33], s[20:21], v[20:21] op_sel_hi:[1,0,1]
	v_pk_fma_f32 v[20:21], v[32:33], s[20:21], v[20:21] op_sel_hi:[1,0,1] neg_lo:[0,0,1] neg_hi:[0,0,1]
	s_nop 0
	v_xor_b32_e32 v32, 0x80000000, v21
	v_mov_b32_e32 v33, v20
	v_pk_add_f32 v[20:21], v[30:31], v[24:25]
	v_pk_add_f32 v[24:25], v[30:31], v[24:25] neg_lo:[0,1] neg_hi:[0,1]
	v_pk_add_f32 v[30:31], v[16:17], v[32:33]
	v_pk_add_f32 v[16:17], v[16:17], v[32:33] neg_lo:[0,1] neg_hi:[0,1]
	ds_write2_b64 v119, v[22:23], v[20:21] offset1:9
	ds_write2_b64 v119, v[28:29], v[30:31] offset0:18 offset1:27
	ds_write2_b64 v119, v[26:27], v[24:25] offset0:36 offset1:45
	ds_write2_b64 v119, v[18:19], v[16:17] offset0:54 offset1:63
	ds_read2_b64 v[16:19], v193 offset1:9
	v_mov_b64_e32 v[32:33], v[238:239]
	ds_read2_b64 v[20:23], v193 offset0:18 offset1:27
	v_mov_b64_e32 v[34:35], v[240:241]
	v_mov_b64_e32 v[36:37], v[242:243]
	ds_read2_b64 v[24:27], v193 offset0:36 offset1:45
	v_mov_b64_e32 v[38:39], v[244:245]
	v_mov_b64_e32 v[40:41], v[246:247]
	ds_read2_b64 v[28:31], v193 offset0:54 offset1:63
	v_mov_b64_e32 v[42:43], v[248:249]
	v_mov_b64_e32 v[44:45], v[250:251]
	s_waitcnt lgkmcnt(0)
; __device__ __forceinline__ c2 cmulc(c2 a, c2 b) { return (c2){a.x * b.x + a.y * b.y, a.y * b.x - a.x * b.y}; }
; __device__ __forceinline__ c2 mpi(c2 a) { return (c2){-a.y, a.x}; }
; __device__ __forceinline__ void idft8(c2 (&x)[8]) {
;     const float s = 0.70710678118654752f;
;     const c2 a0 = x[0] + x[4], a4 = x[0] - x[4], a1 = x[1] + x[5], a5 = x[1] - x[5], a2 = x[2] + x[6], a6 = x[2] - x[6], a3 = x[3] + x[7], a7 = x[3] - x[7];
;     const c2 a5w = (c2){(a5.x - a5.y) * s, (a5.x + a5.y) * s};
;     const c2 a6w = mpi(a6);
;     const c2 a7w = (c2){-(a7.x + a7.y) * s, (a7.x - a7.y) * s};
;     const c2 b0 = a0 + a2, b1 = a0 - a2, b2 = a1 + a3, b3 = mpi(a1 - a3);
;     x[0] = b0 + b2; x[4] = b0 - b2; x[2] = b1 + b3; x[6] = b1 - b3;
;     const c2 c0 = a4 + a6w, c1 = a4 - a6w, c2_ = a5w + a7w, c3 = mpi(a5w - a7w);
;     x[1] = c0 + c2_; x[5] = c0 - c2_; x[3] = c1 + c3; x[7] = c1 - c3;
; }
; template <int S> __device__ __forceinline__ void inv_mid(c2* buf, const c2* tws, int tid) {
;     constexpr int lq = 9 - 3 * S, Q = 1 << lq; const c2* T = tws + (S == 1 ? 3584 : 4032);
;     const int k = tid & (Q - 1), base = ((tid >> lq) << (lq + 3)) + k;
;     c2 x[8];
;     c2* bp_ = buf + LP(base); constexpr int QP = Q + Q / 8;
; #pragma unroll
;     for (int r = 0; r < 8; ++r) { c2 v = bp_[r * QP]; if (r) v = cmulc(v, T[(r - 1) * Q + k]); x[r] = v; }
;     idft8(x);
; #pragma unroll
;     for (int q = 0; q < 8; ++q) bp_[q * QP] = x[q];
; }
	v_pk_mul_f32 v[46:47], v[30:31], v[44:45] op_sel:[1,1] op_sel_hi:[0,1]
	v_pk_fma_f32 v[48:49], v[30:31], v[44:45], v[46:47]
	v_pk_fma_f32 v[30:31], v[30:31], v[44:45], v[46:47] op_sel_hi:[1,0,1] neg_lo:[0,0,1] neg_hi:[0,0,1]
	s_nop 0
	v_mov_b32_e32 v49, v31
	v_pk_mul_f32 v[30:31], v[18:19], v[32:33] op_sel:[1,1] op_sel_hi:[0,1]
	v_pk_fma_f32 v[44:45], v[18:19], v[32:33], v[30:31]
	v_pk_fma_f32 v[18:19], v[18:19], v[32:33], v[30:31] op_sel_hi:[1,0,1] neg_lo:[0,0,1] neg_hi:[0,0,1]
	s_nop 0
	v_mov_b32_e32 v45, v19
	v_pk_mul_f32 v[18:19], v[20:21], v[34:35] op_sel:[1,1] op_sel_hi:[0,1]
	v_pk_fma_f32 v[30:31], v[20:21], v[34:35], v[18:19]
	v_pk_fma_f32 v[18:19], v[20:21], v[34:35], v[18:19] op_sel_hi:[1,0,1] neg_lo:[0,0,1] neg_hi:[0,0,1]
	s_nop 0
	v_mov_b32_e32 v31, v19
	v_pk_mul_f32 v[18:19], v[22:23], v[36:37] op_sel:[1,1] op_sel_hi:[0,1]
	v_pk_fma_f32 v[20:21], v[22:23], v[36:37], v[18:19]
	v_pk_fma_f32 v[18:19], v[22:23], v[36:37], v[18:19] op_sel_hi:[1,0,1] neg_lo:[0,0,1] neg_hi:[0,0,1]
	s_nop 0
	v_mov_b32_e32 v21, v19
	v_pk_mul_f32 v[18:19], v[24:25], v[38:39] op_sel:[1,1] op_sel_hi:[0,1]
	v_pk_fma_f32 v[22:23], v[24:25], v[38:39], v[18:19]
	v_pk_fma_f32 v[18:19], v[24:25], v[38:39], v[18:19] op_sel_hi:[1,0,1] neg_lo:[0,0,1] neg_hi:[0,0,1]
	s_nop 0
	v_mov_b32_e32 v23, v19
	v_pk_mul_f32 v[18:19], v[26:27], v[40:41] op_sel:[1,1] op_sel_hi:[0,1]
	v_pk_fma_f32 v[24:25], v[26:27], v[40:41], v[18:19]
	v_pk_fma_f32 v[18:19], v[26:27], v[40:41], v[18:19] op_sel_hi:[1,0,1] neg_lo:[0,0,1] neg_hi:[0,0,1]
	s_nop 0
	v_mov_b32_e32 v25, v19
	v_pk_mul_f32 v[18:19], v[28:29], v[42:43] op_sel:[1,1] op_sel_hi:[0,1]
	v_pk_fma_f32 v[26:27], v[28:29], v[42:43], v[18:19]
	v_pk_fma_f32 v[18:19], v[28:29], v[42:43], v[18:19] op_sel_hi:[1,0,1] neg_lo:[0,0,1] neg_hi:[0,0,1]
	s_nop 0
	v_mov_b32_e32 v27, v19
	v_pk_add_f32 v[18:19], v[16:17], v[22:23]
	v_pk_add_f32 v[16:17], v[16:17], v[22:23] neg_lo:[0,1] neg_hi:[0,1]
	v_pk_add_f32 v[22:23], v[44:45], v[24:25]
	v_pk_add_f32 v[24:25], v[44:45], v[24:25] neg_lo:[0,1] neg_hi:[0,1]
	v_pk_add_f32 v[28:29], v[30:31], v[26:27]
	v_pk_add_f32 v[26:27], v[30:31], v[26:27] neg_lo:[0,1] neg_hi:[0,1]
	v_pk_add_f32 v[30:31], v[20:21], v[48:49]
	v_pk_add_f32 v[20:21], v[20:21], v[48:49] neg_lo:[0,1] neg_hi:[0,1]
	v_pk_add_f32 v[32:33], v[24:25], v[24:25] op_sel:[0,1] neg_lo:[0,1] neg_hi:[0,1]
	v_pk_add_f32 v[24:25], v[24:25], v[24:25] op_sel_hi:[0,1]
	v_mov_b32_e32 v33, v25
	v_xor_b32_e32 v24, 0x80000000, v27
	v_mov_b32_e32 v25, v26
	v_pk_add_f32 v[26:27], v[20:21], v[20:21] op_sel:[0,1]
	v_pk_add_f32 v[20:21], v[20:21], v[20:21] op_sel_hi:[0,1] neg_lo:[0,1] neg_hi:[0,1]
	v_mov_b32_e32 v27, v21
	v_pk_mul_f32 v[20:21], v[26:27], s[62:63]
	v_pk_add_f32 v[26:27], v[18:19], v[28:29]
	v_pk_add_f32 v[18:19], v[18:19], v[28:29] neg_lo:[0,1] neg_hi:[0,1]
	v_pk_add_f32 v[28:29], v[22:23], v[30:31]
	v_pk_add_f32 v[22:23], v[22:23], v[30:31] neg_lo:[0,1] neg_hi:[0,1]
	s_nop 0
	v_xor_b32_e32 v30, 0x80000000, v23
	v_mov_b32_e32 v31, v22
	v_pk_add_f32 v[22:23], v[26:27], v[28:29]
	v_pk_add_f32 v[26:27], v[26:27], v[28:29] neg_lo:[0,1] neg_hi:[0,1]
	v_pk_add_f32 v[28:29], v[18:19], v[30:31]
	v_pk_add_f32 v[18:19], v[18:19], v[30:31] neg_lo:[0,1] neg_hi:[0,1]
	v_pk_add_f32 v[30:31], v[16:17], v[24:25]
	v_pk_add_f32 v[16:17], v[16:17], v[24:25] neg_lo:[0,1] neg_hi:[0,1]
	v_pk_fma_f32 v[24:25], v[32:33], s[20:21], v[20:21] op_sel_hi:[1,0,1]
	v_pk_fma_f32 v[20:21], v[32:33], s[20:21], v[20:21] op_sel_hi:[1,0,1] neg_lo:[0,0,1] neg_hi:[0,0,1]
	s_nop 0
	v_xor_b32_e32 v32, 0x80000000, v21
	v_mov_b32_e32 v33, v20
	v_pk_add_f32 v[20:21], v[30:31], v[24:25]
	v_pk_add_f32 v[24:25], v[30:31], v[24:25] neg_lo:[0,1] neg_hi:[0,1]
	v_pk_add_f32 v[30:31], v[16:17], v[32:33]
	v_pk_add_f32 v[16:17], v[16:17], v[32:33] neg_lo:[0,1] neg_hi:[0,1]
	ds_write2_b64 v193, v[22:23], v[20:21] offset1:9
	ds_write2_b64 v193, v[28:29], v[30:31] offset0:18 offset1:27
	ds_write2_b64 v193, v[26:27], v[24:25] offset0:36 offset1:45
	ds_write2_b64 v193, v[18:19], v[16:17] offset0:54 offset1:63
	s_waitcnt lgkmcnt(0)
	s_barrier
	ds_read2_b64 v[16:19], v117 offset1:72
	v_mov_b64_e32 v[32:33], v[224:225]
	ds_read2_b64 v[20:23], v117 offset0:144 offset1:216
	v_mov_b64_e32 v[34:35], v[226:227]
	v_mov_b64_e32 v[36:37], v[228:229]
	ds_read2_b64 v[24:27], v63 offset0:32 offset1:104
	v_mov_b64_e32 v[38:39], v[230:231]
	v_mov_b64_e32 v[40:41], v[232:233]
	ds_read2_b64 v[28:31], v63 offset0:176 offset1:248
	v_mov_b64_e32 v[42:43], v[234:235]
	v_mov_b64_e32 v[44:45], v[236:237]
	s_waitcnt lgkmcnt(0)
; __device__ __forceinline__ c2 cmulc(c2 a, c2 b) { return (c2){a.x * b.x + a.y * b.y, a.y * b.x - a.x * b.y}; }
; __device__ __forceinline__ c2 mpi(c2 a) { return (c2){-a.y, a.x}; }
; __device__ __forceinline__ void idft8(c2 (&x)[8]) {
;     const float s = 0.70710678118654752f;
;     const c2 a0 = x[0] + x[4], a4 = x[0] - x[4], a1 = x[1] + x[5], a5 = x[1] - x[5], a2 = x[2] + x[6], a6 = x[2] - x[6], a3 = x[3] + x[7], a7 = x[3] - x[7];
;     const c2 a5w = (c2){(a5.x - a5.y) * s, (a5.x + a5.y) * s};
;     const c2 a6w = mpi(a6);
;     const c2 a7w = (c2){-(a7.x + a7.y) * s, (a7.x - a7.y) * s};
;     const c2 b0 = a0 + a2, b1 = a0 - a2, b2 = a1 + a3, b3 = mpi(a1 - a3);
;     x[0] = b0 + b2; x[4] = b0 - b2; x[2] = b1 + b3; x[6] = b1 - b3;
;     const c2 c0 = a4 + a6w, c1 = a4 - a6w, c2_ = a5w + a7w, c3 = mpi(a5w - a7w);
;     x[1] = c0 + c2_; x[5] = c0 - c2_; x[3] = c1 + c3; x[7] = c1 - c3;
; }
; template <int S> __device__ __forceinline__ void inv_mid(c2* buf, const c2* tws, int tid) {
;     constexpr int lq = 9 - 3 * S, Q = 1 << lq; const c2* T = tws + (S == 1 ? 3584 : 4032);
;     const int k = tid & (Q - 1), base = ((tid >> lq) << (lq + 3)) + k;
;     c2 x[8];
;     c2* bp_ = buf + LP(base); constexpr int QP = Q + Q / 8;
; #pragma unroll
;     for (int r = 0; r < 8; ++r) { c2 v = bp_[r * QP]; if (r) v = cmulc(v, T[(r - 1) * Q + k]); x[r] = v; }
;     idft8(x);
; #pragma unroll
;     for (int q = 0; q < 8; ++q) bp_[q * QP] = x[q];
; }
	v_pk_mul_f32 v[46:47], v[30:31], v[44:45] op_sel:[1,1] op_sel_hi:[0,1]
	v_pk_fma_f32 v[48:49], v[30:31], v[44:45], v[46:47]
	v_pk_fma_f32 v[30:31], v[30:31], v[44:45], v[46:47] op_sel_hi:[1,0,1] neg_lo:[0,0,1] neg_hi:[0,0,1]
	s_nop 0
	v_mov_b32_e32 v49, v31
	v_pk_mul_f32 v[30:31], v[18:19], v[32:33] op_sel:[1,1] op_sel_hi:[0,1]
	v_pk_fma_f32 v[44:45], v[18:19], v[32:33], v[30:31]
	v_pk_fma_f32 v[18:19], v[18:19], v[32:33], v[30:31] op_sel_hi:[1,0,1] neg_lo:[0,0,1] neg_hi:[0,0,1]
	s_nop 0
	v_mov_b32_e32 v45, v19
	v_pk_mul_f32 v[18:19], v[20:21], v[34:35] op_sel:[1,1] op_sel_hi:[0,1]
	v_pk_fma_f32 v[30:31], v[20:21], v[34:35], v[18:19]
	v_pk_fma_f32 v[18:19], v[20:21], v[34:35], v[18:19] op_sel_hi:[1,0,1] neg_lo:[0,0,1] neg_hi:[0,0,1]
	s_nop 0
	v_mov_b32_e32 v31, v19
	v_pk_mul_f32 v[18:19], v[22:23], v[36:37] op_sel:[1,1] op_sel_hi:[0,1]
	v_pk_fma_f32 v[20:21], v[22:23], v[36:37], v[18:19]
	v_pk_fma_f32 v[18:19], v[22:23], v[36:37], v[18:19] op_sel_hi:[1,0,1] neg_lo:[0,0,1] neg_hi:[0,0,1]
	s_nop 0
	v_mov_b32_e32 v21, v19
	v_pk_mul_f32 v[18:19], v[24:25], v[38:39] op_sel:[1,1] op_sel_hi:[0,1]
	v_pk_fma_f32 v[22:23], v[24:25], v[38:39], v[18:19]
	v_pk_fma_f32 v[18:19], v[24:25], v[38:39], v[18:19] op_sel_hi:[1,0,1] neg_lo:[0,0,1] neg_hi:[0,0,1]
	s_nop 0
	v_mov_b32_e32 v23, v19
	v_pk_mul_f32 v[18:19], v[26:27], v[40:41] op_sel:[1,1] op_sel_hi:[0,1]
	v_pk_fma_f32 v[24:25], v[26:27], v[40:41], v[18:19]
	v_pk_fma_f32 v[18:19], v[26:27], v[40:41], v[18:19] op_sel_hi:[1,0,1] neg_lo:[0,0,1] neg_hi:[0,0,1]
	s_nop 0
	v_mov_b32_e32 v25, v19
	v_pk_mul_f32 v[18:19], v[28:29], v[42:43] op_sel:[1,1] op_sel_hi:[0,1]
	v_pk_fma_f32 v[26:27], v[28:29], v[42:43], v[18:19]
	v_pk_fma_f32 v[18:19], v[28:29], v[42:43], v[18:19] op_sel_hi:[1,0,1] neg_lo:[0,0,1] neg_hi:[0,0,1]
	s_nop 0
	v_mov_b32_e32 v27, v19
	v_pk_add_f32 v[18:19], v[16:17], v[22:23]
	v_pk_add_f32 v[16:17], v[16:17], v[22:23] neg_lo:[0,1] neg_hi:[0,1]
	v_pk_add_f32 v[22:23], v[44:45], v[24:25]
	v_pk_add_f32 v[24:25], v[44:45], v[24:25] neg_lo:[0,1] neg_hi:[0,1]
	v_pk_add_f32 v[28:29], v[30:31], v[26:27]
	v_pk_add_f32 v[26:27], v[30:31], v[26:27] neg_lo:[0,1] neg_hi:[0,1]
	v_pk_add_f32 v[30:31], v[20:21], v[48:49]
	v_pk_add_f32 v[20:21], v[20:21], v[48:49] neg_lo:[0,1] neg_hi:[0,1]
	v_pk_add_f32 v[32:33], v[24:25], v[24:25] op_sel:[0,1] neg_lo:[0,1] neg_hi:[0,1]
	v_pk_add_f32 v[24:25], v[24:25], v[24:25] op_sel_hi:[0,1]
	v_mov_b32_e32 v33, v25
	v_xor_b32_e32 v24, 0x80000000, v27
	v_mov_b32_e32 v25, v26
	v_pk_add_f32 v[26:27], v[20:21], v[20:21] op_sel:[0,1]
	v_pk_add_f32 v[20:21], v[20:21], v[20:21] op_sel_hi:[0,1] neg_lo:[0,1] neg_hi:[0,1]
	v_mov_b32_e32 v27, v21
	v_pk_mul_f32 v[20:21], v[26:27], s[62:63]
	v_pk_add_f32 v[26:27], v[18:19], v[28:29]
	v_pk_add_f32 v[18:19], v[18:19], v[28:29] neg_lo:[0,1] neg_hi:[0,1]
	v_pk_add_f32 v[28:29], v[22:23], v[30:31]
	v_pk_add_f32 v[22:23], v[22:23], v[30:31] neg_lo:[0,1] neg_hi:[0,1]
	s_nop 0
	v_xor_b32_e32 v30, 0x80000000, v23
	v_mov_b32_e32 v31, v22
	v_pk_add_f32 v[22:23], v[26:27], v[28:29]
	v_pk_add_f32 v[26:27], v[26:27], v[28:29] neg_lo:[0,1] neg_hi:[0,1]
	v_pk_add_f32 v[28:29], v[18:19], v[30:31]
	v_pk_add_f32 v[18:19], v[18:19], v[30:31] neg_lo:[0,1] neg_hi:[0,1]
	v_pk_add_f32 v[30:31], v[16:17], v[24:25]
	v_pk_add_f32 v[16:17], v[16:17], v[24:25] neg_lo:[0,1] neg_hi:[0,1]
	v_pk_fma_f32 v[24:25], v[32:33], s[20:21], v[20:21] op_sel_hi:[1,0,1]
	v_pk_fma_f32 v[20:21], v[32:33], s[20:21], v[20:21] op_sel_hi:[1,0,1] neg_lo:[0,0,1] neg_hi:[0,0,1]
	s_nop 0
	v_xor_b32_e32 v32, 0x80000000, v21
	v_mov_b32_e32 v33, v20
	v_pk_add_f32 v[20:21], v[30:31], v[24:25]
	v_pk_add_f32 v[24:25], v[30:31], v[24:25] neg_lo:[0,1] neg_hi:[0,1]
	v_pk_add_f32 v[30:31], v[16:17], v[32:33]
	v_pk_add_f32 v[16:17], v[16:17], v[32:33] neg_lo:[0,1] neg_hi:[0,1]
	ds_write2_b64 v117, v[22:23], v[20:21] offset1:72
	ds_write2_b64 v117, v[28:29], v[30:31] offset0:144 offset1:216
	ds_write2_b64 v63, v[26:27], v[24:25] offset0:32 offset1:104
	ds_write2_b64 v63, v[18:19], v[16:17] offset0:176 offset1:248
	ds_read2_b64 v[16:19], v191 offset1:72
	v_mov_b64_e32 v[32:33], v[224:225]
	ds_read2_b64 v[20:23], v191 offset0:144 offset1:216
	v_mov_b64_e32 v[34:35], v[226:227]
	v_mov_b64_e32 v[36:37], v[228:229]
	ds_read2_b64 v[24:27], v192 offset0:32 offset1:104
	v_mov_b64_e32 v[38:39], v[230:231]
	v_mov_b64_e32 v[40:41], v[232:233]
	ds_read2_b64 v[28:31], v192 offset0:176 offset1:248
	v_mov_b64_e32 v[42:43], v[234:235]
	v_mov_b64_e32 v[44:45], v[236:237]
	s_waitcnt lgkmcnt(0)
; __device__ __forceinline__ c2 cmulc(c2 a, c2 b) { return (c2){a.x * b.x + a.y * b.y, a.y * b.x - a.x * b.y}; }
; template <int S> __device__ __forceinline__ void inv_mid(c2* buf, const c2* tws, int tid) {
;     constexpr int lq = 9 - 3 * S, Q = 1 << lq; const c2* T = tws + (S == 1 ? 3584 : 4032);
;     const int k = tid & (Q - 1), base = ((tid >> lq) << (lq + 3)) + k;
;     c2 x[8];
;     c2* bp_ = buf + LP(base); constexpr int QP = Q + Q / 8;
; #pragma unroll
;     for (int r = 0; r < 8; ++r) { c2 v = bp_[r * QP]; if (r) v = cmulc(v, T[(r - 1) * Q + k]); x[r] = v; }
;     idft8(x);
; #pragma unroll
;     for (int q = 0; q < 8; ++q) bp_[q * QP] = x[q];
; }
; __device__ __forceinline__ void inv_s0(c2 (&x)[8], const c2* buf, const c2* tws, int tid) {
;     const c2* bp_ = buf + LP(tid);
; #pragma unroll
;     for (int r = 0; r < 8; ++r) { c2 v = bp_[576 * r]; if (r) v = cmulc(v, tws[(r - 1) * 512 + tid]); x[r] = v; }
;     idft8(x);
; }
	v_pk_mul_f32 v[46:47], v[30:31], v[44:45] op_sel:[1,1] op_sel_hi:[0,1]
	v_pk_fma_f32 v[48:49], v[30:31], v[44:45], v[46:47]
	v_pk_fma_f32 v[30:31], v[30:31], v[44:45], v[46:47] op_sel_hi:[1,0,1] neg_lo:[0,0,1] neg_hi:[0,0,1]
	s_nop 0
	v_mov_b32_e32 v49, v31
	v_pk_mul_f32 v[30:31], v[18:19], v[32:33] op_sel:[1,1] op_sel_hi:[0,1]
	v_pk_fma_f32 v[44:45], v[18:19], v[32:33], v[30:31]
	v_pk_fma_f32 v[18:19], v[18:19], v[32:33], v[30:31] op_sel_hi:[1,0,1] neg_lo:[0,0,1] neg_hi:[0,0,1]
	s_nop 0
	v_mov_b32_e32 v45, v19
	v_pk_mul_f32 v[18:19], v[20:21], v[34:35] op_sel:[1,1] op_sel_hi:[0,1]
	v_pk_fma_f32 v[30:31], v[20:21], v[34:35], v[18:19]
	v_pk_fma_f32 v[18:19], v[20:21], v[34:35], v[18:19] op_sel_hi:[1,0,1] neg_lo:[0,0,1] neg_hi:[0,0,1]
	s_nop 0
	v_mov_b32_e32 v31, v19
	v_pk_mul_f32 v[18:19], v[22:23], v[36:37] op_sel:[1,1] op_sel_hi:[0,1]
	v_pk_fma_f32 v[20:21], v[22:23], v[36:37], v[18:19]
	v_pk_fma_f32 v[18:19], v[22:23], v[36:37], v[18:19] op_sel_hi:[1,0,1] neg_lo:[0,0,1] neg_hi:[0,0,1]
	s_nop 0
	v_mov_b32_e32 v21, v19
	v_pk_mul_f32 v[18:19], v[24:25], v[38:39] op_sel:[1,1] op_sel_hi:[0,1]
	v_pk_fma_f32 v[22:23], v[24:25], v[38:39], v[18:19]
	v_pk_fma_f32 v[18:19], v[24:25], v[38:39], v[18:19] op_sel_hi:[1,0,1] neg_lo:[0,0,1] neg_hi:[0,0,1]
	s_nop 0
	v_mov_b32_e32 v23, v19
	v_pk_mul_f32 v[18:19], v[26:27], v[40:41] op_sel:[1,1] op_sel_hi:[0,1]
	v_pk_fma_f32 v[24:25], v[26:27], v[40:41], v[18:19]
	v_pk_fma_f32 v[18:19], v[26:27], v[40:41], v[18:19] op_sel_hi:[1,0,1] neg_lo:[0,0,1] neg_hi:[0,0,1]
	s_nop 0
	v_mov_b32_e32 v25, v19
	v_pk_mul_f32 v[18:19], v[28:29], v[42:43] op_sel:[1,1] op_sel_hi:[0,1]
	v_pk_fma_f32 v[26:27], v[28:29], v[42:43], v[18:19]
	v_pk_fma_f32 v[18:19], v[28:29], v[42:43], v[18:19] op_sel_hi:[1,0,1] neg_lo:[0,0,1] neg_hi:[0,0,1]
	s_nop 0
	v_mov_b32_e32 v27, v19
	v_pk_add_f32 v[18:19], v[16:17], v[22:23]
	v_pk_add_f32 v[16:17], v[16:17], v[22:23] neg_lo:[0,1] neg_hi:[0,1]
	v_pk_add_f32 v[22:23], v[44:45], v[24:25]
	v_pk_add_f32 v[24:25], v[44:45], v[24:25] neg_lo:[0,1] neg_hi:[0,1]
	v_pk_add_f32 v[28:29], v[30:31], v[26:27]
	v_pk_add_f32 v[26:27], v[30:31], v[26:27] neg_lo:[0,1] neg_hi:[0,1]
	v_pk_add_f32 v[30:31], v[20:21], v[48:49]
	v_pk_add_f32 v[20:21], v[20:21], v[48:49] neg_lo:[0,1] neg_hi:[0,1]
	v_pk_add_f32 v[32:33], v[24:25], v[24:25] op_sel:[0,1] neg_lo:[0,1] neg_hi:[0,1]
	v_pk_add_f32 v[24:25], v[24:25], v[24:25] op_sel_hi:[0,1]
	v_mov_b32_e32 v33, v25
	v_xor_b32_e32 v24, 0x80000000, v27
	v_mov_b32_e32 v25, v26
	v_pk_add_f32 v[26:27], v[20:21], v[20:21] op_sel:[0,1]
	v_pk_add_f32 v[20:21], v[20:21], v[20:21] op_sel_hi:[0,1] neg_lo:[0,1] neg_hi:[0,1]
	v_mov_b32_e32 v27, v21
	v_pk_mul_f32 v[20:21], v[26:27], s[62:63]
	v_pk_add_f32 v[26:27], v[18:19], v[28:29]
	v_pk_add_f32 v[18:19], v[18:19], v[28:29] neg_lo:[0,1] neg_hi:[0,1]
	v_pk_add_f32 v[28:29], v[22:23], v[30:31]
	v_pk_add_f32 v[22:23], v[22:23], v[30:31] neg_lo:[0,1] neg_hi:[0,1]
	s_mov_b64 s[62:63], -1
	v_xor_b32_e32 v30, 0x80000000, v23
	v_mov_b32_e32 v31, v22
	v_pk_add_f32 v[22:23], v[26:27], v[28:29]
	v_pk_add_f32 v[26:27], v[26:27], v[28:29] neg_lo:[0,1] neg_hi:[0,1]
	v_pk_add_f32 v[28:29], v[18:19], v[30:31]
	v_pk_add_f32 v[18:19], v[18:19], v[30:31] neg_lo:[0,1] neg_hi:[0,1]
	v_pk_add_f32 v[30:31], v[16:17], v[24:25]
	v_pk_add_f32 v[16:17], v[16:17], v[24:25] neg_lo:[0,1] neg_hi:[0,1]
	v_pk_fma_f32 v[24:25], v[32:33], s[20:21], v[20:21] op_sel_hi:[1,0,1]
	v_pk_fma_f32 v[20:21], v[32:33], s[20:21], v[20:21] op_sel_hi:[1,0,1] neg_lo:[0,0,1] neg_hi:[0,0,1]
	s_nop 0
	v_xor_b32_e32 v32, 0x80000000, v21
	v_mov_b32_e32 v33, v20
	v_pk_add_f32 v[20:21], v[30:31], v[24:25]
	v_pk_add_f32 v[24:25], v[30:31], v[24:25] neg_lo:[0,1] neg_hi:[0,1]
	v_pk_add_f32 v[30:31], v[16:17], v[32:33]
	v_pk_add_f32 v[16:17], v[16:17], v[32:33] neg_lo:[0,1] neg_hi:[0,1]
	ds_write2_b64 v191, v[22:23], v[20:21] offset1:72
	ds_write2_b64 v191, v[28:29], v[30:31] offset0:144 offset1:216
	ds_write2_b64 v192, v[26:27], v[24:25] offset0:32 offset1:104
	ds_write2_b64 v192, v[18:19], v[16:17] offset0:176 offset1:248
	s_waitcnt lgkmcnt(0)
	s_barrier
	ds_read2st64_b64 v[40:43], v115 offset1:9
	v_mov_b64_e32 v[28:29], v[210:211]
	v_mov_b64_e32 v[30:31], v[212:213]
	ds_read2st64_b64 v[52:55], v115 offset0:18 offset1:27
	v_mov_b64_e32 v[24:25], v[214:215]
	v_mov_b64_e32 v[26:27], v[216:217]
	ds_read2st64_b64 v[48:51], v115 offset0:36 offset1:45
	v_mov_b64_e32 v[20:21], v[218:219]
	v_mov_b64_e32 v[22:23], v[220:221]
	ds_read2st64_b64 v[44:47], v115 offset0:54 offset1:63
	v_mov_b64_e32 v[90:91], v[222:223]
	ds_read2st64_b64 v[16:19], v115 offset0:72 offset1:81
	ds_read2st64_b64 v[36:39], v115 offset0:90 offset1:99
	ds_read2st64_b64 v[32:35], v115 offset0:108 offset1:117
	ds_read_b64 v[94:95], v115 offset:64512
	ds_read_b64 v[92:93], v116 offset:32256
	s_cbranch_vccnz .LBB0_674
	s_andn2_b64 vcc, exec, s[62:63]
	s_cbranch_vccz .LBB0_675

; __device__ __forceinline__ c2 cmulc(c2 a, c2 b) { return (c2){a.x * b.x + a.y * b.y, a.y * b.x - a.x * b.y}; }
; __device__ __forceinline__ void inv_s0(c2 (&x)[8], const c2* buf, const c2* tws, int tid) {
;     const c2* bp_ = buf + LP(tid);
; #pragma unroll
;     for (int r = 0; r < 8; ++r) { c2 v = bp_[576 * r]; if (r) v = cmulc(v, tws[(r - 1) * 512 + tid]); x[r] = v; }
;     idft8(x);
; }
.LBB0_637:
	ds_read_u16 v96, v145 offset:16
	ds_read_u16 v97, v145 offset:18
	ds_read_u16 v98, v145 offset:14
	s_waitcnt lgkmcnt(0)
	v_lshlrev_b32_e32 v99, 16, v96
	s_waitcnt lgkmcnt(0)
	v_lshlrev_b32_e32 v97, 16, v97
	s_waitcnt lgkmcnt(0)
	v_lshlrev_b32_e32 v96, 16, v98
	v_pk_mul_f32 v[96:97], v[64:65], v[96:97]
	s_nop 0
	v_fma_f32 v96, v186, v99, v96
	v_add_f32_e32 v96, v96, v97
	v_add_f32_e32 v203, v185, v96
.LBB0_638:
	s_waitcnt lgkmcnt(0)
	v_pk_mul_f32 v[98:99], v[42:43], v[28:29] op_sel:[0,1]
	s_or_b32 s16, s3, 0x10000
	v_pk_fma_f32 v[96:97], v[42:43], v[28:29], v[98:99] op_sel:[0,0,1] op_sel_hi:[1,1,0]
	v_pk_fma_f32 v[42:43], v[42:43], v[28:29], v[98:99] op_sel:[0,0,1] op_sel_hi:[1,0,0] neg_lo:[0,0,1] neg_hi:[0,0,1]
	s_or_b32 s7, s3, 0x10800
	v_mov_b32_e32 v97, v43
	s_waitcnt lgkmcnt(0)
	v_pk_mul_f32 v[42:43], v[52:53], v[30:31] op_sel:[0,1]
	s_mov_b64 s[62:63], -1
	v_pk_fma_f32 v[98:99], v[52:53], v[30:31], v[42:43] op_sel:[0,0,1] op_sel_hi:[1,1,0]
	v_pk_fma_f32 v[42:43], v[52:53], v[30:31], v[42:43] op_sel:[0,0,1] op_sel_hi:[1,0,0] neg_lo:[0,0,1] neg_hi:[0,0,1]
	s_and_b64 vcc, exec, s[84:85]
	v_mov_b32_e32 v99, v43
	s_waitcnt lgkmcnt(0)
	v_pk_mul_f32 v[42:43], v[54:55], v[24:25] op_sel:[0,1]
	s_nop 0
	v_pk_fma_f32 v[52:53], v[54:55], v[24:25], v[42:43] op_sel:[0,0,1] op_sel_hi:[1,1,0]
	v_pk_fma_f32 v[42:43], v[54:55], v[24:25], v[42:43] op_sel:[0,0,1] op_sel_hi:[1,0,0] neg_lo:[0,0,1] neg_hi:[0,0,1]
	s_nop 0
	v_mov_b32_e32 v53, v43
	s_waitcnt lgkmcnt(0)
	v_pk_mul_f32 v[42:43], v[48:49], v[26:27] op_sel:[0,1]
	s_nop 0
	v_pk_fma_f32 v[54:55], v[48:49], v[26:27], v[42:43] op_sel:[0,0,1] op_sel_hi:[1,1,0]
	v_pk_fma_f32 v[42:43], v[48:49], v[26:27], v[42:43] op_sel:[0,0,1] op_sel_hi:[1,0,0] neg_lo:[0,0,1] neg_hi:[0,0,1]
	s_nop 0
	v_mov_b32_e32 v55, v43
	s_waitcnt lgkmcnt(0)
	v_pk_mul_f32 v[42:43], v[50:51], v[20:21] op_sel:[0,1]
	s_nop 0
	v_pk_fma_f32 v[100:101], v[50:51], v[20:21], v[42:43] op_sel:[0,0,1] op_sel_hi:[1,1,0]
	v_pk_fma_f32 v[42:43], v[50:51], v[20:21], v[42:43] op_sel:[0,0,1] op_sel_hi:[1,0,0] neg_lo:[0,0,1] neg_hi:[0,0,1]
	s_nop 0
	v_mov_b32_e32 v101, v43
	s_waitcnt lgkmcnt(0)
	v_pk_mul_f32 v[42:43], v[44:45], v[22:23] op_sel:[0,1]
	s_nop 0
	v_pk_fma_f32 v[50:51], v[44:45], v[22:23], v[42:43] op_sel:[0,0,1] op_sel_hi:[1,1,0]
	v_pk_fma_f32 v[42:43], v[44:45], v[22:23], v[42:43] op_sel:[0,0,1] op_sel_hi:[1,0,0] neg_lo:[0,0,1] neg_hi:[0,0,1]
	v_pk_add_f32 v[44:45], v[96:97], v[100:101]
	v_mov_b32_e32 v51, v43
	s_waitcnt lgkmcnt(0)
	v_pk_mul_f32 v[42:43], v[46:47], v[90:91] op_sel:[0,1]
	s_nop 0
	v_pk_fma_f32 v[102:103], v[46:47], v[90:91], v[42:43] op_sel:[0,0,1] op_sel_hi:[1,1,0]
	v_pk_fma_f32 v[42:43], v[46:47], v[90:91], v[42:43] op_sel:[0,0,1] op_sel_hi:[1,0,0] neg_lo:[0,0,1] neg_hi:[0,0,1]
	v_pk_add_f32 v[46:47], v[98:99], v[50:51]
	v_mov_b32_e32 v103, v43
	v_pk_add_f32 v[42:43], v[40:41], v[54:55]
	v_pk_add_f32 v[48:49], v[52:53], v[102:103]
	v_pk_add_f32 v[204:205], v[42:43], v[46:47]
	v_pk_add_f32 v[206:207], v[44:45], v[48:49]
	s_nop 0
	v_pk_add_f32 v[204:205], v[204:205], v[206:207]
	ds_read_u16 v206, v160 offset:14
	ds_read_u16 v207, v160 offset:16
	ds_read_u16 v208, v160 offset:18
	v_pk_mul_f32 v[204:205], v[66:67], v[204:205]
	s_waitcnt lgkmcnt(0)
	v_lshlrev_b32_e32 v206, 16, v206
	s_waitcnt lgkmcnt(0)
	v_lshlrev_b32_e32 v207, 16, v207
	v_mul_f32_e32 v207, v190, v207
	v_fmac_f32_e32 v207, v187, v206
	s_waitcnt lgkmcnt(0)
	v_lshlrev_b32_e32 v206, 16, v208
	v_fmac_f32_e32 v207, v189, v206
	v_add_f32_e32 v206, v188, v207
	ds_read_u16 v207, v161 offset:14
	ds_read_u16 v208, v161 offset:16
	ds_read_u16 v209, v161 offset:18
	v_fma_f32 v202, v184, v202, v204
	v_mul_f32_e32 v202, v202, v206
	s_waitcnt lgkmcnt(0)
	v_lshlrev_b32_e32 v207, 16, v207
	s_waitcnt lgkmcnt(0)
	v_lshlrev_b32_e32 v208, 16, v208
	v_mul_f32_e32 v208, v190, v208
	v_fmac_f32_e32 v208, v187, v207
	s_waitcnt lgkmcnt(0)
	v_lshlrev_b32_e32 v207, 16, v209
	v_add_u32_e32 v206, s16, v113
	v_fmac_f32_e32 v208, v189, v207
	v_ashrrev_i32_e32 v207, 31, v206
	v_add_f32_e32 v208, v188, v208
	v_cvt_pk_bf16_f32 v202, v202, s0
	v_lshl_add_u64 v[206:207], v[206:207], 1, s[50:51]
	v_fmac_f32_e32 v205, v184, v203
	global_store_short v[206:207], v202, off
	v_mul_f32_e32 v202, v205, v208
	v_cvt_pk_bf16_f32 v204, v202, s0
	v_add_u32_e32 v202, s7, v113
	v_ashrrev_i32_e32 v203, 31, v202
	v_lshl_add_u64 v[202:203], v[202:203], 1, s[50:51]
	global_store_short v[202:203], v204, off
	s_cbranch_vccz .LBB0_677
	s_andn2_b64 vcc, exec, s[62:63]
	s_cbranch_vccz .LBB0_678

; __device__ __forceinline__ c2 mpi(c2 a) { return (c2){-a.y, a.x}; }
; __device__ __forceinline__ void idft8(c2 (&x)[8]) {
;     const float s = 0.70710678118654752f;
;     const c2 a0 = x[0] + x[4], a4 = x[0] - x[4], a1 = x[1] + x[5], a5 = x[1] - x[5], a2 = x[2] + x[6], a6 = x[2] - x[6], a3 = x[3] + x[7], a7 = x[3] - x[7];
;     const c2 a5w = (c2){(a5.x - a5.y) * s, (a5.x + a5.y) * s};
;     const c2 a6w = mpi(a6);
;     const c2 a7w = (c2){-(a7.x + a7.y) * s, (a7.x - a7.y) * s};
;     const c2 b0 = a0 + a2, b1 = a0 - a2, b2 = a1 + a3, b3 = mpi(a1 - a3);
;     x[0] = b0 + b2; x[4] = b0 - b2; x[2] = b1 + b3; x[6] = b1 - b3;
;     const c2 c0 = a4 + a6w, c1 = a4 - a6w, c2_ = a5w + a7w, c3 = mpi(a5w - a7w);
;     x[1] = c0 + c2_; x[5] = c0 - c2_; x[3] = c1 + c3; x[7] = c1 - c3;
; }
.LBB0_642:
	ds_read_u16 v203, v149 offset:16
	ds_read_u16 v204, v149 offset:18
	ds_read_u16 v206, v149 offset:14
	s_waitcnt lgkmcnt(0)
	v_lshlrev_b32_e32 v203, 16, v203
	s_waitcnt lgkmcnt(0)
	v_lshlrev_b32_e32 v205, 16, v204
	s_waitcnt lgkmcnt(0)
	v_lshlrev_b32_e32 v204, 16, v206
	v_pk_mul_f32 v[204:205], v[64:65], v[204:205]
	s_nop 0
	v_fma_f32 v203, v186, v203, v204
	v_add_f32_e32 v203, v203, v205
	v_add_f32_e32 v203, v185, v203
.LBB0_643:
	v_pk_add_f32 v[40:41], v[40:41], v[54:55] neg_lo:[0,1] neg_hi:[0,1]
	v_pk_add_f32 v[54:55], v[96:97], v[100:101] neg_lo:[0,1] neg_hi:[0,1]
	v_pk_add_f32 v[96:97], v[98:99], v[50:51] neg_lo:[0,1] neg_hi:[0,1]
	v_pk_add_f32 v[98:99], v[52:53], v[102:103] neg_lo:[0,1] neg_hi:[0,1]
	v_pk_add_f32 v[50:51], v[54:55], v[54:55] op_sel:[0,1] neg_lo:[0,1] neg_hi:[0,1]
	v_pk_add_f32 v[52:53], v[54:55], v[54:55] op_sel_hi:[0,1]
	v_mov_b32_e32 v51, v53
	v_xor_b32_e32 v52, 0x80000000, v97
	v_mov_b32_e32 v53, v96
	v_pk_add_f32 v[54:55], v[98:99], v[98:99] op_sel:[0,1]
	v_pk_add_f32 v[96:97], v[98:99], v[98:99] op_sel_hi:[0,1] neg_lo:[0,1] neg_hi:[0,1]
	v_mov_b32_e32 v55, v97
	s_mov_b32 s40, s21
	s_mov_b32 s41, s20
	v_pk_mul_f32 v[54:55], v[54:55], s[40:41]
	v_pk_add_f32 v[96:97], v[40:41], v[52:53]
	v_pk_fma_f32 v[98:99], v[50:51], s[20:21], v[54:55] op_sel_hi:[1,0,1]
	s_and_b64 vcc, exec, s[84:85]
	v_pk_add_f32 v[96:97], v[96:97], v[98:99]
	ds_read_u16 v98, v162 offset:14
	ds_read_u16 v99, v162 offset:16
	ds_read_u16 v100, v162 offset:18
	ds_read_u16 v101, v163 offset:14
	ds_read_u16 v102, v163 offset:16
	ds_read_u16 v103, v163 offset:18
	s_waitcnt lgkmcnt(0)
	v_lshlrev_b32_e32 v99, 16, v99
	v_lshlrev_b32_e32 v98, 16, v98
	v_mul_f32_e32 v99, v190, v99
	v_fmac_f32_e32 v99, v187, v98
	s_waitcnt lgkmcnt(0)
	v_lshlrev_b32_e32 v98, 16, v100
	v_pk_mul_f32 v[96:97], v[66:67], v[96:97]
	v_fmac_f32_e32 v99, v189, v98
	s_waitcnt lgkmcnt(0)
	v_lshlrev_b32_e32 v100, 16, v102
	v_add_f32_e32 v98, v188, v99
	v_lshlrev_b32_e32 v99, 16, v101
	v_mul_f32_e32 v100, v190, v100
	v_fma_f32 v96, v184, v202, v96
	v_fmac_f32_e32 v100, v187, v99
	s_waitcnt lgkmcnt(0)
	v_lshlrev_b32_e32 v99, 16, v103
	v_mul_f32_e32 v96, v96, v98
	v_add_u32_e32 v98, s16, v127
	v_fmac_f32_e32 v100, v189, v99
	v_ashrrev_i32_e32 v99, 31, v98
	v_add_f32_e32 v100, v188, v100
	v_cvt_pk_bf16_f32 v96, v96, s0
	v_lshl_add_u64 v[98:99], v[98:99], 1, s[50:51]
	v_fmac_f32_e32 v97, v184, v203
	global_store_short v[98:99], v96, off
	v_mul_f32_e32 v96, v97, v100
	v_cvt_pk_bf16_f32 v98, v96, s0
	v_add_u32_e32 v96, s7, v127
	v_ashrrev_i32_e32 v97, 31, v96
	v_lshl_add_u64 v[96:97], v[96:97], 1, s[50:51]
	s_mov_b64 s[62:63], -1
	global_store_short v[96:97], v98, off
	s_cbranch_vccz .LBB0_680
	s_andn2_b64 vcc, exec, s[62:63]
	s_cbranch_vccz .LBB0_681

; __device__ __forceinline__ c2 mpi(c2 a) { return (c2){-a.y, a.x}; }
; __device__ __forceinline__ void idft8(c2 (&x)[8]) {
;     const float s = 0.70710678118654752f;
;     const c2 a0 = x[0] + x[4], a4 = x[0] - x[4], a1 = x[1] + x[5], a5 = x[1] - x[5], a2 = x[2] + x[6], a6 = x[2] - x[6], a3 = x[3] + x[7], a7 = x[3] - x[7];
;     const c2 a5w = (c2){(a5.x - a5.y) * s, (a5.x + a5.y) * s};
;     const c2 a6w = mpi(a6);
;     const c2 a7w = (c2){-(a7.x + a7.y) * s, (a7.x - a7.y) * s};
;     const c2 b0 = a0 + a2, b1 = a0 - a2, b2 = a1 + a3, b3 = mpi(a1 - a3);
;     x[0] = b0 + b2; x[4] = b0 - b2; x[2] = b1 + b3; x[6] = b1 - b3;
;     const c2 c0 = a4 + a6w, c1 = a4 - a6w, c2_ = a5w + a7w, c3 = mpi(a5w - a7w);
;     x[1] = c0 + c2_; x[5] = c0 - c2_; x[3] = c1 + c3; x[7] = c1 - c3;
; }
.LBB0_647:
	ds_read_u16 v97, v153 offset:16
	ds_read_u16 v98, v153 offset:18
	ds_read_u16 v100, v153 offset:14
	s_waitcnt lgkmcnt(0)
	v_lshlrev_b32_e32 v97, 16, v97
	s_waitcnt lgkmcnt(0)
	v_lshlrev_b32_e32 v99, 16, v98
	s_waitcnt lgkmcnt(0)
	v_lshlrev_b32_e32 v98, 16, v100
	v_pk_mul_f32 v[98:99], v[64:65], v[98:99]
	s_nop 0
	v_fma_f32 v97, v186, v97, v98
	v_add_f32_e32 v97, v97, v99
	v_add_f32_e32 v97, v185, v97
.LBB0_648:
	v_pk_add_f32 v[44:45], v[44:45], v[48:49] neg_lo:[0,1] neg_hi:[0,1]
	v_pk_add_f32 v[42:43], v[42:43], v[46:47] neg_lo:[0,1] neg_hi:[0,1]
	v_xor_b32_e32 v46, 0x80000000, v45
	v_mov_b32_e32 v47, v44
	v_pk_add_f32 v[42:43], v[42:43], v[46:47]
	ds_read_u16 v44, v164 offset:14
	ds_read_u16 v45, v164 offset:16
	ds_read_u16 v46, v164 offset:18
	ds_read_u16 v47, v165 offset:14
	ds_read_u16 v48, v165 offset:16
	ds_read_u16 v49, v165 offset:18
	s_waitcnt lgkmcnt(0)
	v_lshlrev_b32_e32 v45, 16, v45
	v_lshlrev_b32_e32 v44, 16, v44
	v_mul_f32_e32 v45, v190, v45
	v_fmac_f32_e32 v45, v187, v44
	s_waitcnt lgkmcnt(0)
	v_lshlrev_b32_e32 v44, 16, v46
	v_pk_mul_f32 v[42:43], v[66:67], v[42:43]
	v_fmac_f32_e32 v45, v189, v44
	s_waitcnt lgkmcnt(0)
	v_lshlrev_b32_e32 v46, 16, v48
	v_add_f32_e32 v44, v188, v45
	v_lshlrev_b32_e32 v45, 16, v47
	v_mul_f32_e32 v46, v190, v46
	v_fma_f32 v42, v184, v96, v42
	v_fmac_f32_e32 v46, v187, v45
	s_waitcnt lgkmcnt(0)
	v_lshlrev_b32_e32 v45, 16, v49
	v_mul_f32_e32 v42, v42, v44
	v_add_u32_e32 v44, s16, v130
	v_fmac_f32_e32 v46, v189, v45
	v_ashrrev_i32_e32 v45, 31, v44
	v_add_f32_e32 v46, v188, v46
	v_cvt_pk_bf16_f32 v42, v42, s0
	v_lshl_add_u64 v[44:45], v[44:45], 1, s[50:51]
	v_fmac_f32_e32 v43, v184, v97
	global_store_short v[44:45], v42, off
	v_mul_f32_e32 v42, v43, v46
	v_cvt_pk_bf16_f32 v44, v42, s0
	v_add_u32_e32 v42, s7, v130
	v_ashrrev_i32_e32 v43, 31, v42
	v_lshl_add_u64 v[42:43], v[42:43], 1, s[50:51]
	s_and_b64 vcc, exec, s[84:85]
	s_mov_b64 s[62:63], -1
	global_store_short v[42:43], v44, off
	s_cbranch_vccz .LBB0_683
	s_andn2_b64 vcc, exec, s[62:63]
	s_cbranch_vccz .LBB0_684

; __device__ __forceinline__ c2 mpi(c2 a) { return (c2){-a.y, a.x}; }
; __device__ __forceinline__ void idft8(c2 (&x)[8]) {
;     const float s = 0.70710678118654752f;
;     const c2 a0 = x[0] + x[4], a4 = x[0] - x[4], a1 = x[1] + x[5], a5 = x[1] - x[5], a2 = x[2] + x[6], a6 = x[2] - x[6], a3 = x[3] + x[7], a7 = x[3] - x[7];
;     const c2 a5w = (c2){(a5.x - a5.y) * s, (a5.x + a5.y) * s};
;     const c2 a6w = mpi(a6);
;     const c2 a7w = (c2){-(a7.x + a7.y) * s, (a7.x - a7.y) * s};
;     const c2 b0 = a0 + a2, b1 = a0 - a2, b2 = a1 + a3, b3 = mpi(a1 - a3);
;     x[0] = b0 + b2; x[4] = b0 - b2; x[2] = b1 + b3; x[6] = b1 - b3;
;     const c2 c0 = a4 + a6w, c1 = a4 - a6w, c2_ = a5w + a7w, c3 = mpi(a5w - a7w);
;     x[1] = c0 + c2_; x[5] = c0 - c2_; x[3] = c1 + c3; x[7] = c1 - c3;
; }
.LBB0_652:
	ds_read_u16 v43, v157 offset:16
	ds_read_u16 v44, v157 offset:18
	ds_read_u16 v46, v157 offset:14
	s_waitcnt lgkmcnt(0)
	v_lshlrev_b32_e32 v43, 16, v43
	s_waitcnt lgkmcnt(0)
	v_lshlrev_b32_e32 v45, 16, v44
	s_waitcnt lgkmcnt(0)
	v_lshlrev_b32_e32 v44, 16, v46
	v_pk_mul_f32 v[44:45], v[64:65], v[44:45]
	s_nop 0
	v_fma_f32 v43, v186, v43, v44
	v_add_f32_e32 v43, v43, v45
	v_add_f32_e32 v43, v185, v43
.LBB0_653:
	v_pk_mul_f32 v[44:45], v[50:51], s[20:21] op_sel_hi:[1,0]
	v_pk_add_f32 v[40:41], v[40:41], v[52:53] neg_lo:[0,1] neg_hi:[0,1]
	v_pk_add_f32 v[44:45], v[44:45], v[54:55] neg_lo:[0,1] neg_hi:[0,1]
	s_mov_b64 s[62:63], -1
	v_xor_b32_e32 v46, 0x80000000, v45
	v_mov_b32_e32 v47, v44
	v_pk_add_f32 v[40:41], v[40:41], v[46:47]
	ds_read_u16 v44, v166 offset:14
	ds_read_u16 v45, v166 offset:16
	ds_read_u16 v46, v166 offset:18
	ds_read_u16 v47, v167 offset:14
	ds_read_u16 v48, v167 offset:16
	ds_read_u16 v49, v167 offset:18
	s_waitcnt lgkmcnt(0)
	v_lshlrev_b32_e32 v45, 16, v45
	v_lshlrev_b32_e32 v44, 16, v44
	v_mul_f32_e32 v45, v190, v45
	v_fmac_f32_e32 v45, v187, v44
	s_waitcnt lgkmcnt(0)
	v_lshlrev_b32_e32 v44, 16, v46
	v_pk_mul_f32 v[40:41], v[66:67], v[40:41]
	v_fmac_f32_e32 v45, v189, v44
	s_waitcnt lgkmcnt(0)
	v_lshlrev_b32_e32 v46, 16, v48
	v_add_f32_e32 v44, v188, v45
	v_lshlrev_b32_e32 v45, 16, v47
	v_mul_f32_e32 v46, v190, v46
	v_fma_f32 v40, v184, v42, v40
	v_fmac_f32_e32 v46, v187, v45
	s_waitcnt lgkmcnt(0)
	v_lshlrev_b32_e32 v45, 16, v49
	v_mul_f32_e32 v40, v40, v44
	v_add_u32_e32 v44, s16, v133
	v_fmac_f32_e32 v46, v189, v45
	v_ashrrev_i32_e32 v45, 31, v44
	v_add_f32_e32 v46, v188, v46
	v_cvt_pk_bf16_f32 v40, v40, s0
	v_lshl_add_u64 v[44:45], v[44:45], 1, s[50:51]
	v_fmac_f32_e32 v41, v184, v43
	global_store_short v[44:45], v40, off
	v_mul_f32_e32 v40, v41, v46
	v_cvt_pk_bf16_f32 v42, v40, s0
	v_add_u32_e32 v40, s7, v133
	v_ashrrev_i32_e32 v41, 31, v40
	v_lshl_add_u64 v[40:41], v[40:41], 1, s[50:51]
	s_and_b64 vcc, exec, s[30:31]
	global_store_short v[40:41], v42, off
	s_cbranch_vccnz .LBB0_686
	s_andn2_b64 vcc, exec, s[62:63]
	s_cbranch_vccz .LBB0_687

; __device__ __forceinline__ c2 cmulc(c2 a, c2 b) { return (c2){a.x * b.x + a.y * b.y, a.y * b.x - a.x * b.y}; }
; __device__ __forceinline__ void inv_s0(c2 (&x)[8], const c2* buf, const c2* tws, int tid) {
;     const c2* bp_ = buf + LP(tid);
; #pragma unroll
;     for (int r = 0; r < 8; ++r) { c2 v = bp_[576 * r]; if (r) v = cmulc(v, tws[(r - 1) * 512 + tid]); x[r] = v; }
;     idft8(x);
; }
.LBB0_657:
	ds_read_u16 v41, v147 offset:16
	ds_read_u16 v42, v147 offset:18
	ds_read_u16 v44, v147 offset:14
	s_waitcnt lgkmcnt(0)
	v_lshlrev_b32_e32 v41, 16, v41
	s_waitcnt lgkmcnt(0)
	v_lshlrev_b32_e32 v43, 16, v42
	s_waitcnt lgkmcnt(0)
	v_lshlrev_b32_e32 v42, 16, v44
	v_pk_mul_f32 v[42:43], v[64:65], v[42:43]
	s_nop 0
	v_fma_f32 v41, v186, v41, v42
	v_add_f32_e32 v41, v41, v43
	v_add_f32_e32 v41, v185, v41
.LBB0_658:
	v_mov_b32_e32 v42, v28
	v_mov_b32_e32 v43, v28
	v_mov_b32_e32 v28, v29
	v_pk_mul_f32 v[96:97], v[28:29], v[18:19]
	v_mov_b32_e32 v44, v30
	v_mov_b32_e32 v45, v30
	v_mov_b32_e32 v30, v31
	v_pk_fma_f32 v[28:29], v[42:43], v[18:19], v[96:97] op_sel:[0,0,1] op_sel_hi:[1,1,0]
	v_pk_fma_f32 v[18:19], v[42:43], v[18:19], v[96:97] op_sel:[0,0,1] op_sel_hi:[1,1,0] neg_lo:[0,0,1] neg_hi:[0,0,1]
	v_mov_b32_e32 v46, v24
	v_mov_b32_e32 v29, v19
	v_pk_mul_f32 v[18:19], v[30:31], v[36:37]
	v_mov_b32_e32 v47, v24
	v_mov_b32_e32 v24, v25
	v_pk_fma_f32 v[30:31], v[44:45], v[36:37], v[18:19] op_sel:[0,0,1] op_sel_hi:[1,1,0]
	v_pk_fma_f32 v[18:19], v[44:45], v[36:37], v[18:19] op_sel:[0,0,1] op_sel_hi:[1,1,0] neg_lo:[0,0,1] neg_hi:[0,0,1]
	v_mov_b32_e32 v48, v26
	v_mov_b32_e32 v31, v19
	v_pk_mul_f32 v[18:19], v[24:25], v[38:39]
	v_mov_b32_e32 v49, v26
	v_mov_b32_e32 v26, v27
	v_pk_fma_f32 v[36:37], v[46:47], v[38:39], v[18:19] op_sel:[0,0,1] op_sel_hi:[1,1,0]
	v_pk_fma_f32 v[18:19], v[46:47], v[38:39], v[18:19] op_sel:[0,0,1] op_sel_hi:[1,1,0] neg_lo:[0,0,1] neg_hi:[0,0,1]
	v_mov_b32_e32 v50, v20
	v_mov_b32_e32 v37, v19
	v_pk_mul_f32 v[18:19], v[26:27], v[32:33]
	v_mov_b32_e32 v51, v20
	v_mov_b32_e32 v20, v21
	v_pk_fma_f32 v[26:27], v[48:49], v[32:33], v[18:19] op_sel:[0,0,1] op_sel_hi:[1,1,0]
	v_pk_fma_f32 v[18:19], v[48:49], v[32:33], v[18:19] op_sel:[0,0,1] op_sel_hi:[1,1,0] neg_lo:[0,0,1] neg_hi:[0,0,1]
	v_mov_b32_e32 v52, v22
	v_mov_b32_e32 v27, v19
	v_pk_mul_f32 v[18:19], v[20:21], v[34:35]
	v_mov_b32_e32 v53, v22
	v_mov_b32_e32 v22, v23
	v_pk_fma_f32 v[32:33], v[50:51], v[34:35], v[18:19] op_sel:[0,0,1] op_sel_hi:[1,1,0]
	v_pk_fma_f32 v[18:19], v[50:51], v[34:35], v[18:19] op_sel:[0,0,1] op_sel_hi:[1,1,0] neg_lo:[0,0,1] neg_hi:[0,0,1]
	v_mov_b32_e32 v54, v90
	v_mov_b32_e32 v33, v19
	v_pk_mul_f32 v[18:19], v[22:23], v[94:95]
	v_mov_b32_e32 v55, v90
	v_mov_b32_e32 v90, v91
	v_pk_fma_f32 v[34:35], v[52:53], v[94:95], v[18:19] op_sel:[0,0,1] op_sel_hi:[1,1,0]
	v_pk_fma_f32 v[18:19], v[52:53], v[94:95], v[18:19] op_sel:[0,0,1] op_sel_hi:[1,1,0] neg_lo:[0,0,1] neg_hi:[0,0,1]
	v_pk_add_f32 v[20:21], v[28:29], v[32:33]
	v_mov_b32_e32 v35, v19
	v_pk_mul_f32 v[18:19], v[90:91], v[92:93]
	v_pk_add_f32 v[22:23], v[30:31], v[34:35]
	v_pk_fma_f32 v[38:39], v[54:55], v[92:93], v[18:19] op_sel:[0,0,1] op_sel_hi:[1,1,0]
	v_pk_fma_f32 v[18:19], v[54:55], v[92:93], v[18:19] op_sel:[0,0,1] op_sel_hi:[1,1,0] neg_lo:[0,0,1] neg_hi:[0,0,1]
	s_or_b32 s7, s3, 0x11000
	v_mov_b32_e32 v39, v19
	v_pk_add_f32 v[18:19], v[16:17], v[26:27]
	v_pk_add_f32 v[24:25], v[36:37], v[38:39]
	v_pk_add_f32 v[42:43], v[18:19], v[22:23]
	v_pk_add_f32 v[44:45], v[20:21], v[24:25]
	s_or_b32 s3, s3, 0x11800
	v_pk_add_f32 v[42:43], v[42:43], v[44:45]
	ds_read_u16 v44, v168 offset:14
	ds_read_u16 v45, v168 offset:16
	ds_read_u16 v46, v168 offset:18
	ds_read_u16 v47, v169 offset:14
	ds_read_u16 v48, v169 offset:16
	ds_read_u16 v49, v169 offset:18
	s_waitcnt lgkmcnt(0)
	v_lshlrev_b32_e32 v45, 16, v45
	v_lshlrev_b32_e32 v44, 16, v44
	v_mul_f32_e32 v45, v190, v45
	v_fmac_f32_e32 v45, v187, v44
	s_waitcnt lgkmcnt(0)
	v_lshlrev_b32_e32 v44, 16, v46
	v_pk_mul_f32 v[42:43], v[66:67], v[42:43]
	v_fmac_f32_e32 v45, v189, v44
	s_waitcnt lgkmcnt(0)
	v_lshlrev_b32_e32 v46, 16, v48
	v_add_f32_e32 v44, v188, v45
	v_lshlrev_b32_e32 v45, 16, v47
	v_mul_f32_e32 v46, v190, v46
	v_fma_f32 v40, v184, v40, v42
	v_fmac_f32_e32 v46, v187, v45
	s_waitcnt lgkmcnt(0)
	v_lshlrev_b32_e32 v45, 16, v49
	v_mul_f32_e32 v40, v40, v44
	v_add_u32_e32 v44, s7, v113
	v_fmac_f32_e32 v46, v189, v45
	v_ashrrev_i32_e32 v45, 31, v44
	v_add_f32_e32 v46, v188, v46
	v_cvt_pk_bf16_f32 v40, v40, s0
	v_lshl_add_u64 v[44:45], v[44:45], 1, s[50:51]
	v_fmac_f32_e32 v43, v184, v41
	global_store_short v[44:45], v40, off
	v_mul_f32_e32 v40, v43, v46
	v_cvt_pk_bf16_f32 v42, v40, s0
	v_add_u32_e32 v40, s3, v113
	v_ashrrev_i32_e32 v41, 31, v40
	v_lshl_add_u64 v[40:41], v[40:41], 1, s[50:51]
	s_and_b64 vcc, exec, s[84:85]
	s_mov_b64 s[62:63], -1
	global_store_short v[40:41], v42, off
	s_cbranch_vccz .LBB0_689
	s_andn2_b64 vcc, exec, s[62:63]
	s_cbranch_vccz .LBB0_690

; __device__ __forceinline__ c2 mpi(c2 a) { return (c2){-a.y, a.x}; }
; __device__ __forceinline__ void idft8(c2 (&x)[8]) {
;     const float s = 0.70710678118654752f;
;     const c2 a0 = x[0] + x[4], a4 = x[0] - x[4], a1 = x[1] + x[5], a5 = x[1] - x[5], a2 = x[2] + x[6], a6 = x[2] - x[6], a3 = x[3] + x[7], a7 = x[3] - x[7];
;     const c2 a5w = (c2){(a5.x - a5.y) * s, (a5.x + a5.y) * s};
;     const c2 a6w = mpi(a6);
;     const c2 a7w = (c2){-(a7.x + a7.y) * s, (a7.x - a7.y) * s};
;     const c2 b0 = a0 + a2, b1 = a0 - a2, b2 = a1 + a3, b3 = mpi(a1 - a3);
;     x[0] = b0 + b2; x[4] = b0 - b2; x[2] = b1 + b3; x[6] = b1 - b3;
;     const c2 c0 = a4 + a6w, c1 = a4 - a6w, c2_ = a5w + a7w, c3 = mpi(a5w - a7w);
;     x[1] = c0 + c2_; x[5] = c0 - c2_; x[3] = c1 + c3; x[7] = c1 - c3;
; }
.LBB0_662:
	ds_read_u16 v41, v151 offset:16
	ds_read_u16 v42, v151 offset:18
	ds_read_u16 v44, v151 offset:14
	s_waitcnt lgkmcnt(0)
	v_lshlrev_b32_e32 v41, 16, v41
	s_waitcnt lgkmcnt(0)
	v_lshlrev_b32_e32 v43, 16, v42
	s_waitcnt lgkmcnt(0)
	v_lshlrev_b32_e32 v42, 16, v44
	v_pk_mul_f32 v[42:43], v[64:65], v[42:43]
	s_nop 0
	v_fma_f32 v41, v186, v41, v42
	v_add_f32_e32 v41, v41, v43
	v_add_f32_e32 v41, v185, v41
.LBB0_663:
	v_pk_add_f32 v[28:29], v[28:29], v[32:33] neg_lo:[0,1] neg_hi:[0,1]
	v_pk_add_f32 v[16:17], v[16:17], v[26:27] neg_lo:[0,1] neg_hi:[0,1]
	v_pk_add_f32 v[30:31], v[30:31], v[34:35] neg_lo:[0,1] neg_hi:[0,1]
	v_pk_add_f32 v[32:33], v[36:37], v[38:39] neg_lo:[0,1] neg_hi:[0,1]
	v_pk_add_f32 v[26:27], v[28:29], v[28:29] op_sel:[0,1] neg_lo:[0,1] neg_hi:[0,1]
	v_pk_add_f32 v[28:29], v[28:29], v[28:29] op_sel_hi:[0,1]
	v_mov_b32_e32 v27, v29
	v_xor_b32_e32 v28, 0x80000000, v31
	v_mov_b32_e32 v29, v30
	v_pk_add_f32 v[30:31], v[32:33], v[32:33] op_sel:[0,1]
	v_pk_add_f32 v[32:33], v[32:33], v[32:33] op_sel_hi:[0,1] neg_lo:[0,1] neg_hi:[0,1]
	v_mov_b32_e32 v31, v33
	s_mov_b32 s40, s21
	s_mov_b32 s41, s20
	v_pk_mul_f32 v[30:31], v[30:31], s[40:41]
	v_pk_add_f32 v[32:33], v[16:17], v[28:29]
	v_pk_fma_f32 v[34:35], v[26:27], s[20:21], v[30:31] op_sel_hi:[1,0,1]
	s_and_b64 vcc, exec, s[84:85]
	v_pk_add_f32 v[32:33], v[32:33], v[34:35]
	ds_read_u16 v34, v170 offset:14
	ds_read_u16 v35, v170 offset:16
	ds_read_u16 v36, v170 offset:18
	ds_read_u16 v37, v171 offset:14
	ds_read_u16 v38, v171 offset:16
	ds_read_u16 v39, v171 offset:18
	s_waitcnt lgkmcnt(0)
	v_lshlrev_b32_e32 v35, 16, v35
	v_lshlrev_b32_e32 v34, 16, v34
	v_mul_f32_e32 v35, v190, v35
	v_fmac_f32_e32 v35, v187, v34
	s_waitcnt lgkmcnt(0)
	v_lshlrev_b32_e32 v34, 16, v36
	v_pk_mul_f32 v[32:33], v[66:67], v[32:33]
	v_fmac_f32_e32 v35, v189, v34
	s_waitcnt lgkmcnt(0)
	v_lshlrev_b32_e32 v36, 16, v38
	v_add_f32_e32 v34, v188, v35
	v_lshlrev_b32_e32 v35, 16, v37
	v_mul_f32_e32 v36, v190, v36
	v_fma_f32 v32, v184, v40, v32
	v_fmac_f32_e32 v36, v187, v35
	s_waitcnt lgkmcnt(0)
	v_lshlrev_b32_e32 v35, 16, v39
	v_mul_f32_e32 v32, v32, v34
	v_add_u32_e32 v34, s7, v127
	v_fmac_f32_e32 v36, v189, v35
	v_ashrrev_i32_e32 v35, 31, v34
	v_add_f32_e32 v36, v188, v36
	v_cvt_pk_bf16_f32 v32, v32, s0
	v_lshl_add_u64 v[34:35], v[34:35], 1, s[50:51]
	v_fmac_f32_e32 v33, v184, v41
	global_store_short v[34:35], v32, off
	v_mul_f32_e32 v32, v33, v36
	v_cvt_pk_bf16_f32 v34, v32, s0
	v_add_u32_e32 v32, s3, v127
	v_ashrrev_i32_e32 v33, 31, v32
	v_lshl_add_u64 v[32:33], v[32:33], 1, s[50:51]
	s_mov_b64 s[62:63], -1
	global_store_short v[32:33], v34, off
	s_cbranch_vccz .LBB0_692
	s_andn2_b64 vcc, exec, s[62:63]
	s_cbranch_vccz .LBB0_693

; __device__ __forceinline__ c2 mpi(c2 a) { return (c2){-a.y, a.x}; }
; __device__ __forceinline__ void idft8(c2 (&x)[8]) {
;     const float s = 0.70710678118654752f;
;     const c2 a0 = x[0] + x[4], a4 = x[0] - x[4], a1 = x[1] + x[5], a5 = x[1] - x[5], a2 = x[2] + x[6], a6 = x[2] - x[6], a3 = x[3] + x[7], a7 = x[3] - x[7];
;     const c2 a5w = (c2){(a5.x - a5.y) * s, (a5.x + a5.y) * s};
;     const c2 a6w = mpi(a6);
;     const c2 a7w = (c2){-(a7.x + a7.y) * s, (a7.x - a7.y) * s};
;     const c2 b0 = a0 + a2, b1 = a0 - a2, b2 = a1 + a3, b3 = mpi(a1 - a3);
;     x[0] = b0 + b2; x[4] = b0 - b2; x[2] = b1 + b3; x[6] = b1 - b3;
;     const c2 c0 = a4 + a6w, c1 = a4 - a6w, c2_ = a5w + a7w, c3 = mpi(a5w - a7w);
;     x[1] = c0 + c2_; x[5] = c0 - c2_; x[3] = c1 + c3; x[7] = c1 - c3;
; }
.LBB0_667:
	ds_read_u16 v33, v155 offset:16
	ds_read_u16 v34, v155 offset:18
	ds_read_u16 v36, v155 offset:14
	s_waitcnt lgkmcnt(0)
	v_lshlrev_b32_e32 v33, 16, v33
	s_waitcnt lgkmcnt(0)
	v_lshlrev_b32_e32 v35, 16, v34
	s_waitcnt lgkmcnt(0)
	v_lshlrev_b32_e32 v34, 16, v36
	v_pk_mul_f32 v[34:35], v[64:65], v[34:35]
	s_nop 0
	v_fma_f32 v33, v186, v33, v34
	v_add_f32_e32 v33, v33, v35
	v_add_f32_e32 v33, v185, v33
.LBB0_668:
	v_pk_add_f32 v[20:21], v[20:21], v[24:25] neg_lo:[0,1] neg_hi:[0,1]
	v_pk_add_f32 v[18:19], v[18:19], v[22:23] neg_lo:[0,1] neg_hi:[0,1]
	v_xor_b32_e32 v22, 0x80000000, v21
	v_mov_b32_e32 v23, v20
	v_pk_add_f32 v[18:19], v[18:19], v[22:23]
	ds_read_u16 v20, v172 offset:14
	ds_read_u16 v21, v172 offset:16
	ds_read_u16 v22, v172 offset:18
	ds_read_u16 v23, v173 offset:14
	ds_read_u16 v24, v173 offset:16
	ds_read_u16 v25, v173 offset:18
	s_waitcnt lgkmcnt(0)
	v_lshlrev_b32_e32 v21, 16, v21
	v_lshlrev_b32_e32 v20, 16, v20
	v_mul_f32_e32 v21, v190, v21
	v_fmac_f32_e32 v21, v187, v20
	s_waitcnt lgkmcnt(0)
	v_lshlrev_b32_e32 v20, 16, v22
	v_pk_mul_f32 v[18:19], v[66:67], v[18:19]
	v_fmac_f32_e32 v21, v189, v20
	s_waitcnt lgkmcnt(0)
	v_lshlrev_b32_e32 v22, 16, v24
	v_add_f32_e32 v20, v188, v21
	v_lshlrev_b32_e32 v21, 16, v23
	v_mul_f32_e32 v22, v190, v22
	v_fma_f32 v18, v184, v32, v18
	v_fmac_f32_e32 v22, v187, v21
	s_waitcnt lgkmcnt(0)
	v_lshlrev_b32_e32 v21, 16, v25
	v_mul_f32_e32 v18, v18, v20
	v_add_u32_e32 v20, s7, v130
	v_fmac_f32_e32 v22, v189, v21
	v_ashrrev_i32_e32 v21, 31, v20
	v_add_f32_e32 v22, v188, v22
	v_cvt_pk_bf16_f32 v18, v18, s0
	v_lshl_add_u64 v[20:21], v[20:21], 1, s[50:51]
	v_fmac_f32_e32 v19, v184, v33
	global_store_short v[20:21], v18, off
	v_mul_f32_e32 v18, v19, v22
	v_cvt_pk_bf16_f32 v20, v18, s0
	v_add_u32_e32 v18, s3, v130
	v_ashrrev_i32_e32 v19, 31, v18
	v_lshl_add_u64 v[18:19], v[18:19], 1, s[50:51]
	s_and_b64 vcc, exec, s[84:85]
	s_mov_b64 s[62:63], -1
	global_store_short v[18:19], v20, off
	s_cbranch_vccz .LBB0_695
	s_andn2_b64 vcc, exec, s[62:63]
	s_cbranch_vccz .LBB0_696

; __device__ __forceinline__ float bf2f(bf16_t b) { return __uint_as_float(((unsigned)b) << 16); }
; __device__ __forceinline__ float dwl(const bf16_t* r, int t, float w0, float w1, float w2, float b) { return w0 * bf2f(r[7 + t]) + w1 * bf2f(r[8 + t]) + w2 * bf2f(r[9 + t]) + b; }
.LBB0_675:
	ds_read_u16 v96, v144 offset:16
	ds_read_u16 v97, v144 offset:18
	ds_read_u16 v98, v144 offset:14
	s_waitcnt lgkmcnt(0)
	v_lshlrev_b32_e32 v99, 16, v96
	s_waitcnt lgkmcnt(0)
	v_lshlrev_b32_e32 v97, 16, v97
	s_waitcnt lgkmcnt(0)
	v_lshlrev_b32_e32 v96, 16, v98
	v_pk_mul_f32 v[96:97], v[64:65], v[96:97]
	s_nop 0
	v_fma_f32 v96, v186, v99, v96
	v_add_f32_e32 v96, v96, v97
	v_add_f32_e32 v202, v185, v96
	s_mov_b64 s[62:63], -1
	s_and_b64 vcc, exec, s[30:31]
	s_cbranch_vccz .LBB0_636

; __device__ __forceinline__ float bf2f(bf16_t b) { return __uint_as_float(((unsigned)b) << 16); }
; __device__ __forceinline__ float dwl(const bf16_t* r, int t, float w0, float w1, float w2, float b) { return w0 * bf2f(r[7 + t]) + w1 * bf2f(r[8 + t]) + w2 * bf2f(r[9 + t]) + b; }
.LBB0_678:
	ds_read_u16 v202, v148 offset:16
	ds_read_u16 v203, v148 offset:18
	ds_read_u16 v204, v148 offset:14
	s_waitcnt lgkmcnt(0)
	v_lshlrev_b32_e32 v205, 16, v202
	s_waitcnt lgkmcnt(0)
	v_lshlrev_b32_e32 v203, 16, v203
	s_waitcnt lgkmcnt(0)
	v_lshlrev_b32_e32 v202, 16, v204
	v_pk_mul_f32 v[202:203], v[64:65], v[202:203]
	s_nop 0
	v_fma_f32 v202, v186, v205, v202
	v_add_f32_e32 v202, v202, v203
	v_add_f32_e32 v202, v185, v202
	s_and_b64 vcc, exec, s[84:85]
	s_mov_b64 s[62:63], -1
	s_cbranch_vccnz .LBB0_641

; __device__ __forceinline__ float bf2f(bf16_t b) { return __uint_as_float(((unsigned)b) << 16); }
; __device__ __forceinline__ float dwl(const bf16_t* r, int t, float w0, float w1, float w2, float b) { return w0 * bf2f(r[7 + t]) + w1 * bf2f(r[8 + t]) + w2 * bf2f(r[9 + t]) + b; }
.LBB0_681:
	ds_read_u16 v96, v152 offset:16
	ds_read_u16 v97, v152 offset:18
	ds_read_u16 v98, v152 offset:14
	s_waitcnt lgkmcnt(0)
	v_lshlrev_b32_e32 v99, 16, v96
	s_waitcnt lgkmcnt(0)
	v_lshlrev_b32_e32 v97, 16, v97
	s_waitcnt lgkmcnt(0)
	v_lshlrev_b32_e32 v96, 16, v98
	v_pk_mul_f32 v[96:97], v[64:65], v[96:97]
	s_nop 0
	v_fma_f32 v96, v186, v99, v96
	v_add_f32_e32 v96, v96, v97
	v_add_f32_e32 v96, v185, v96
	s_and_b64 vcc, exec, s[84:85]
	s_mov_b64 s[62:63], -1
	s_cbranch_vccnz .LBB0_646

; __device__ __forceinline__ float bf2f(bf16_t b) { return __uint_as_float(((unsigned)b) << 16); }
; __device__ __forceinline__ float dwl(const bf16_t* r, int t, float w0, float w1, float w2, float b) { return w0 * bf2f(r[7 + t]) + w1 * bf2f(r[8 + t]) + w2 * bf2f(r[9 + t]) + b; }
.LBB0_684:
	ds_read_u16 v42, v156 offset:16
	ds_read_u16 v43, v156 offset:18
	ds_read_u16 v44, v156 offset:14
	s_waitcnt lgkmcnt(0)
	v_lshlrev_b32_e32 v45, 16, v42
	s_waitcnt lgkmcnt(0)
	v_lshlrev_b32_e32 v43, 16, v43
	s_waitcnt lgkmcnt(0)
	v_lshlrev_b32_e32 v42, 16, v44
	v_pk_mul_f32 v[42:43], v[64:65], v[42:43]
	s_nop 0
	v_fma_f32 v42, v186, v45, v42
	v_add_f32_e32 v42, v42, v43
	v_add_f32_e32 v42, v185, v42
	s_and_b64 vcc, exec, s[84:85]
	s_mov_b64 s[62:63], -1
	s_cbranch_vccnz .LBB0_651

; __device__ __forceinline__ float bf2f(bf16_t b) { return __uint_as_float(((unsigned)b) << 16); }
; __device__ __forceinline__ float dwl(const bf16_t* r, int t, float w0, float w1, float w2, float b) { return w0 * bf2f(r[7 + t]) + w1 * bf2f(r[8 + t]) + w2 * bf2f(r[9 + t]) + b; }
.LBB0_687:
	ds_read_u16 v40, v146 offset:16
	ds_read_u16 v41, v146 offset:18
	ds_read_u16 v42, v146 offset:14
	s_waitcnt lgkmcnt(0)
	v_lshlrev_b32_e32 v43, 16, v40
	s_waitcnt lgkmcnt(0)
	v_lshlrev_b32_e32 v41, 16, v41
	s_waitcnt lgkmcnt(0)
	v_lshlrev_b32_e32 v40, 16, v42
	v_pk_mul_f32 v[40:41], v[64:65], v[40:41]
	s_nop 0
	v_fma_f32 v40, v186, v43, v40
	v_add_f32_e32 v40, v40, v41
	v_add_f32_e32 v40, v185, v40
	s_mov_b64 s[62:63], -1
	s_and_b64 vcc, exec, s[30:31]
	s_cbranch_vccz .LBB0_656

; __device__ __forceinline__ float bf2f(bf16_t b) { return __uint_as_float(((unsigned)b) << 16); }
; __device__ __forceinline__ float dwl(const bf16_t* r, int t, float w0, float w1, float w2, float b) { return w0 * bf2f(r[7 + t]) + w1 * bf2f(r[8 + t]) + w2 * bf2f(r[9 + t]) + b; }
.LBB0_690:
	ds_read_u16 v40, v150 offset:16
	ds_read_u16 v41, v150 offset:18
	ds_read_u16 v42, v150 offset:14
	s_waitcnt lgkmcnt(0)
	v_lshlrev_b32_e32 v43, 16, v40
	s_waitcnt lgkmcnt(0)
	v_lshlrev_b32_e32 v41, 16, v41
	s_waitcnt lgkmcnt(0)
	v_lshlrev_b32_e32 v40, 16, v42
	v_pk_mul_f32 v[40:41], v[64:65], v[40:41]
	s_nop 0
	v_fma_f32 v40, v186, v43, v40
	v_add_f32_e32 v40, v40, v41
	v_add_f32_e32 v40, v185, v40
	s_and_b64 vcc, exec, s[84:85]
	s_mov_b64 s[62:63], -1
	s_cbranch_vccnz .LBB0_661

; __device__ __forceinline__ float bf2f(bf16_t b) { return __uint_as_float(((unsigned)b) << 16); }
; __device__ __forceinline__ float dwl(const bf16_t* r, int t, float w0, float w1, float w2, float b) { return w0 * bf2f(r[7 + t]) + w1 * bf2f(r[8 + t]) + w2 * bf2f(r[9 + t]) + b; }
.LBB0_693:
	ds_read_u16 v32, v154 offset:16
	ds_read_u16 v33, v154 offset:18
	ds_read_u16 v34, v154 offset:14
	s_waitcnt lgkmcnt(0)
	v_lshlrev_b32_e32 v35, 16, v32
	s_waitcnt lgkmcnt(0)
	v_lshlrev_b32_e32 v33, 16, v33
	s_waitcnt lgkmcnt(0)
	v_lshlrev_b32_e32 v32, 16, v34
	v_pk_mul_f32 v[32:33], v[64:65], v[32:33]
	s_nop 0
	v_fma_f32 v32, v186, v35, v32
	v_add_f32_e32 v32, v32, v33
	v_add_f32_e32 v32, v185, v32
	s_and_b64 vcc, exec, s[84:85]
	s_mov_b64 s[62:63], -1
	s_cbranch_vccnz .LBB0_666

; __device__ __forceinline__ float bf2f(bf16_t b) { return __uint_as_float(((unsigned)b) << 16); }
; __device__ __forceinline__ float dwl(const bf16_t* r, int t, float w0, float w1, float w2, float b) { return w0 * bf2f(r[7 + t]) + w1 * bf2f(r[8 + t]) + w2 * bf2f(r[9 + t]) + b; }
.LBB0_696:
	ds_read_u16 v18, v158 offset:16
	ds_read_u16 v19, v158 offset:18
	ds_read_u16 v20, v158 offset:14
	s_waitcnt lgkmcnt(0)
	v_lshlrev_b32_e32 v21, 16, v18
	s_waitcnt lgkmcnt(0)
	v_lshlrev_b32_e32 v19, 16, v19
	s_waitcnt lgkmcnt(0)
	v_lshlrev_b32_e32 v18, 16, v20
	v_pk_mul_f32 v[18:19], v[64:65], v[18:19]
	s_nop 0
	v_fma_f32 v18, v186, v21, v18
	v_add_f32_e32 v18, v18, v19
	v_add_f32_e32 v18, v185, v18
	s_and_b64 vcc, exec, s[84:85]
	s_mov_b64 s[62:63], -1
	s_cbranch_vccnz .LBB0_671

; __device__ __forceinline__ float bf2f(bf16_t b) { return __uint_as_float(((unsigned)b) << 16); }
; __device__ __forceinline__ float dwl(const bf16_t* r, int t, float w0, float w1, float w2, float b) { return w0 * bf2f(r[7 + t]) + w1 * bf2f(r[8 + t]) + w2 * bf2f(r[9 + t]) + b; }
.LBB0_698:
	ds_read_u16 v19, v159 offset:16
	ds_read_u16 v20, v159 offset:18
	ds_read_u16 v22, v159 offset:14
	s_waitcnt lgkmcnt(0)
	v_lshlrev_b32_e32 v19, 16, v19
	s_waitcnt lgkmcnt(0)
	v_lshlrev_b32_e32 v21, 16, v20
	s_waitcnt lgkmcnt(0)
	v_lshlrev_b32_e32 v20, 16, v22
	v_pk_mul_f32 v[20:21], v[64:65], v[20:21]
	s_nop 0
	v_fma_f32 v19, v186, v19, v20
	v_add_f32_e32 v19, v19, v21
	v_add_f32_e32 v19, v185, v19
	s_branch .LBB0_602
